# DeltaNet forward substitution: two columns (U,W) per lane with packed f32 FMA on half the waves, same per-column operation order
# speedup vs baseline: 1.0048x; 1.0048x over previous
.LBB0_356:
	v_lshlrev_b32_e32 v0, 5, v45
	v_and_b32_e32 v12, 32, v0
	s_movk_i32 s0, 0xfe
	v_mul_u32_u24_e32 v0, 0x110, v12
	v_and_b32_sdwa v1, v45, s0 dst_sel:DWORD dst_unused:UNUSED_PAD src0_sel:BYTE_0 src1_sel:DWORD
	v_lshl_add_u32 v14, v12, 2, v125
	s_waitcnt lgkmcnt(0)
	s_barrier
	v_add3_u32 v13, v122, v0, v1
	ds_read2_b32 v[0:1], v14 offset1:1
	ds_read_u16 v2, v13 offset:17408
	ds_read_u16 v3, v13 offset:17680
	s_mov_b32 s0, s26
	v_readlane_b32 s4, v254, 15
	v_or_b32_e32 v42, 16, v97
	s_waitcnt lgkmcnt(2)
	v_sub_f32_e32 v0, v98, v0
	v_sub_f32_e32 v1, v98, v1
	v_mul_f32_e32 v0, 0x3fb8aa3b, v0
	v_mul_f32_e32 v1, 0x3fb8aa3b, v1
	v_exp_f32_e32 v0, v0
	v_exp_f32_e32 v1, v1
	s_waitcnt lgkmcnt(0)
	v_lshlrev_b32_e32 v3, 16, v3
	v_lshlrev_b32_e32 v2, 16, v2
	v_or_b32_e32 v36, 32, v97
	v_pk_mul_f32 v[0:1], v[0:1], v[2:3]
	ds_read2_b32 v[2:3], v14 offset0:2 offset1:3
	v_cvt_pk_bf16_f32 v0, v0, v1
	v_or_b32_e32 v34, 48, v97
	s_movk_i32 s6, 0x90
	v_readlane_b32 s5, v254, 18
	s_waitcnt lgkmcnt(0)
	v_sub_f32_e32 v1, v98, v2
	v_mul_f32_e32 v1, 0x3fb8aa3b, v1
	v_exp_f32_e32 v2, v1
	v_sub_f32_e32 v1, v98, v3
	v_mul_f32_e32 v1, 0x3fb8aa3b, v1
	v_exp_f32_e32 v3, v1
	ds_read_u16 v1, v13 offset:17952
	ds_read_u16 v4, v13 offset:18224
	s_waitcnt lgkmcnt(0)
	v_lshlrev_b32_e32 v5, 16, v4
	v_lshlrev_b32_e32 v4, 16, v1
	v_pk_mul_f32 v[2:3], v[2:3], v[4:5]
	s_nop 0
	v_cvt_pk_bf16_f32 v1, v2, v3
	ds_read2_b32 v[2:3], v14 offset0:4 offset1:5
	ds_read_u16 v4, v13 offset:18496
	ds_read_u16 v5, v13 offset:18768
	s_waitcnt lgkmcnt(2)
	v_sub_f32_e32 v2, v98, v2
	v_sub_f32_e32 v3, v98, v3
	v_mul_f32_e32 v2, 0x3fb8aa3b, v2
	v_mul_f32_e32 v3, 0x3fb8aa3b, v3
	v_exp_f32_e32 v2, v2
	v_exp_f32_e32 v3, v3
	s_waitcnt lgkmcnt(0)
	v_lshlrev_b32_e32 v5, 16, v5
	v_lshlrev_b32_e32 v4, 16, v4
	v_pk_mul_f32 v[2:3], v[2:3], v[4:5]
	ds_read2_b32 v[4:5], v14 offset0:6 offset1:7
	v_cvt_pk_bf16_f32 v2, v2, v3
	s_waitcnt lgkmcnt(0)
	v_sub_f32_e32 v3, v98, v4
	v_mul_f32_e32 v3, 0x3fb8aa3b, v3
	v_exp_f32_e32 v4, v3
	v_sub_f32_e32 v3, v98, v5
	v_mul_f32_e32 v3, 0x3fb8aa3b, v3
	v_exp_f32_e32 v5, v3
	ds_read_u16 v3, v13 offset:19040
	ds_read_u16 v6, v13 offset:19312
	s_waitcnt lgkmcnt(0)
	v_lshlrev_b32_e32 v7, 16, v6
	v_lshlrev_b32_e32 v6, 16, v3
	v_pk_mul_f32 v[4:5], v[4:5], v[6:7]
	s_nop 0
	v_cvt_pk_bf16_f32 v3, v4, v5
	ds_read2_b32 v[4:5], v14 offset0:8 offset1:9
	ds_read_u16 v6, v13 offset:19584
	ds_read_u16 v7, v13 offset:19856
	s_waitcnt lgkmcnt(2)
	v_sub_f32_e32 v4, v98, v4
	v_sub_f32_e32 v5, v98, v5
	v_mul_f32_e32 v4, 0x3fb8aa3b, v4
	v_mul_f32_e32 v5, 0x3fb8aa3b, v5
	v_exp_f32_e32 v4, v4
	v_exp_f32_e32 v5, v5
	s_waitcnt lgkmcnt(0)
	v_lshlrev_b32_e32 v7, 16, v7
	v_lshlrev_b32_e32 v6, 16, v6
	v_pk_mul_f32 v[4:5], v[4:5], v[6:7]
	ds_read2_b32 v[6:7], v14 offset0:10 offset1:11
	v_cvt_pk_bf16_f32 v4, v4, v5
	s_waitcnt lgkmcnt(0)
	v_sub_f32_e32 v5, v98, v6
	v_mul_f32_e32 v5, 0x3fb8aa3b, v5
	v_exp_f32_e32 v6, v5
	v_sub_f32_e32 v5, v98, v7
	v_mul_f32_e32 v5, 0x3fb8aa3b, v5
	v_exp_f32_e32 v7, v5
	ds_read_u16 v5, v13 offset:20128
	ds_read_u16 v8, v13 offset:20400
	s_waitcnt lgkmcnt(0)
	v_lshlrev_b32_e32 v9, 16, v8
	v_lshlrev_b32_e32 v8, 16, v5
	v_pk_mul_f32 v[6:7], v[6:7], v[8:9]
	s_nop 0
	v_cvt_pk_bf16_f32 v5, v6, v7
	ds_read2_b32 v[6:7], v14 offset0:12 offset1:13
	ds_read_u16 v8, v13 offset:20672
	ds_read_u16 v9, v13 offset:20944
	s_waitcnt lgkmcnt(2)
	v_sub_f32_e32 v6, v98, v6
	v_sub_f32_e32 v7, v98, v7
	v_mul_f32_e32 v6, 0x3fb8aa3b, v6
	v_mul_f32_e32 v7, 0x3fb8aa3b, v7
	v_exp_f32_e32 v6, v6
	v_exp_f32_e32 v7, v7
	s_waitcnt lgkmcnt(0)
	v_lshlrev_b32_e32 v9, 16, v9
	v_lshlrev_b32_e32 v8, 16, v8
	v_pk_mul_f32 v[6:7], v[6:7], v[8:9]
	ds_read2_b32 v[8:9], v14 offset0:14 offset1:15
	v_cvt_pk_bf16_f32 v6, v6, v7
	s_waitcnt lgkmcnt(0)
	v_sub_f32_e32 v7, v98, v8
	v_mul_f32_e32 v7, 0x3fb8aa3b, v7
	v_exp_f32_e32 v8, v7
	v_sub_f32_e32 v7, v98, v9
	v_mul_f32_e32 v7, 0x3fb8aa3b, v7
	v_exp_f32_e32 v9, v7
	ds_read_u16 v7, v13 offset:21216
	ds_read_u16 v10, v13 offset:21488
	s_waitcnt lgkmcnt(0)
	v_lshlrev_b32_e32 v11, 16, v10
	v_lshlrev_b32_e32 v10, 16, v7
	v_pk_mul_f32 v[8:9], v[8:9], v[10:11]
	s_nop 0
	v_cvt_pk_bf16_f32 v7, v8, v9
	ds_read2_b32 v[8:9], v14 offset0:16 offset1:17
	ds_read_u16 v10, v13 offset:21760
	ds_read_u16 v11, v13 offset:22032
	s_waitcnt lgkmcnt(2)
	v_sub_f32_e32 v8, v98, v8
	v_sub_f32_e32 v9, v98, v9
	v_mul_f32_e32 v8, 0x3fb8aa3b, v8
	v_mul_f32_e32 v9, 0x3fb8aa3b, v9
	v_exp_f32_e32 v8, v8
	v_exp_f32_e32 v9, v9
	s_waitcnt lgkmcnt(0)
	v_lshlrev_b32_e32 v11, 16, v11
	v_lshlrev_b32_e32 v10, 16, v10
	v_pk_mul_f32 v[8:9], v[8:9], v[10:11]
	ds_read2_b32 v[10:11], v14 offset0:18 offset1:19
	v_cvt_pk_bf16_f32 v8, v8, v9
	s_waitcnt lgkmcnt(0)
	v_sub_f32_e32 v9, v98, v10
	v_mul_f32_e32 v9, 0x3fb8aa3b, v9
	v_exp_f32_e32 v10, v9
	v_sub_f32_e32 v9, v98, v11
	v_mul_f32_e32 v9, 0x3fb8aa3b, v9
	v_exp_f32_e32 v11, v9
	ds_read_u16 v9, v13 offset:22304
	ds_read_u16 v15, v13 offset:22576
	s_waitcnt lgkmcnt(1)
	v_lshlrev_b32_e32 v16, 16, v9
	s_waitcnt lgkmcnt(0)
	v_lshlrev_b32_e32 v17, 16, v15
	v_pk_mul_f32 v[10:11], v[10:11], v[16:17]
	s_nop 0
	v_cvt_pk_bf16_f32 v9, v10, v11
	ds_read2_b32 v[10:11], v14 offset0:20 offset1:21
	ds_read_u16 v15, v13 offset:22848
	ds_read_u16 v16, v13 offset:23120
	s_waitcnt lgkmcnt(2)
	v_sub_f32_e32 v10, v98, v10
	v_sub_f32_e32 v11, v98, v11
	v_mul_f32_e32 v10, 0x3fb8aa3b, v10
	v_mul_f32_e32 v11, 0x3fb8aa3b, v11
	v_exp_f32_e32 v10, v10
	v_exp_f32_e32 v11, v11
	s_waitcnt lgkmcnt(0)
	v_lshlrev_b32_e32 v17, 16, v16
	v_lshlrev_b32_e32 v16, 16, v15
	v_pk_mul_f32 v[10:11], v[10:11], v[16:17]
	ds_read2_b32 v[16:17], v14 offset0:22 offset1:23
	v_cvt_pk_bf16_f32 v10, v10, v11
	s_waitcnt lgkmcnt(0)
	v_sub_f32_e32 v11, v98, v16
	v_mul_f32_e32 v11, 0x3fb8aa3b, v11
	v_exp_f32_e32 v16, v11
	v_sub_f32_e32 v11, v98, v17
	v_mul_f32_e32 v11, 0x3fb8aa3b, v11
	v_exp_f32_e32 v17, v11
	ds_read_u16 v11, v13 offset:23392
	ds_read_u16 v15, v13 offset:23664
	s_waitcnt lgkmcnt(1)
	v_lshlrev_b32_e32 v18, 16, v11
	s_waitcnt lgkmcnt(0)
	v_lshlrev_b32_e32 v19, 16, v15
	v_pk_mul_f32 v[16:17], v[16:17], v[18:19]
	s_nop 0
	v_cvt_pk_bf16_f32 v11, v16, v17
	ds_read2_b32 v[16:17], v14 offset0:24 offset1:25
	s_waitcnt lgkmcnt(0)
	v_sub_f32_e32 v15, v98, v16
	v_mul_f32_e32 v15, 0x3fb8aa3b, v15
	v_exp_f32_e32 v16, v15
	v_sub_f32_e32 v15, v98, v17
	v_mul_f32_e32 v15, 0x3fb8aa3b, v15
	v_exp_f32_e32 v17, v15
	ds_read_u16 v15, v13 offset:23936
	ds_read_u16 v18, v13 offset:24208
	s_waitcnt lgkmcnt(0)
	v_lshlrev_b32_e32 v19, 16, v18
	v_lshlrev_b32_e32 v18, 16, v15
	v_pk_mul_f32 v[16:17], v[16:17], v[18:19]
	ds_read2_b32 v[18:19], v14 offset0:26 offset1:27
	v_cvt_pk_bf16_f32 v16, v16, v17
	s_waitcnt lgkmcnt(0)
	v_sub_f32_e32 v15, v98, v18
	v_mul_f32_e32 v15, 0x3fb8aa3b, v15
	v_exp_f32_e32 v18, v15
	v_sub_f32_e32 v15, v98, v19
	v_mul_f32_e32 v15, 0x3fb8aa3b, v15
	v_exp_f32_e32 v19, v15
	ds_read_u16 v15, v13 offset:24480
	ds_read_u16 v17, v13 offset:24752
	s_waitcnt lgkmcnt(1)
	v_lshlrev_b32_e32 v20, 16, v15
	s_waitcnt lgkmcnt(0)
	v_lshlrev_b32_e32 v21, 16, v17
	v_pk_mul_f32 v[18:19], v[18:19], v[20:21]
	s_nop 0
	v_cvt_pk_bf16_f32 v17, v18, v19
	ds_read2_b32 v[18:19], v14 offset0:28 offset1:29
	s_waitcnt lgkmcnt(0)
	v_sub_f32_e32 v15, v98, v18
	v_mul_f32_e32 v15, 0x3fb8aa3b, v15
	v_exp_f32_e32 v18, v15
	v_sub_f32_e32 v15, v98, v19
	v_mul_f32_e32 v15, 0x3fb8aa3b, v15
	v_exp_f32_e32 v19, v15
	ds_read_u16 v15, v13 offset:25024
	ds_read_u16 v20, v13 offset:25296
	s_waitcnt lgkmcnt(0)
	v_lshlrev_b32_e32 v21, 16, v20
	v_lshlrev_b32_e32 v20, 16, v15
	ds_read2_b32 v[14:15], v14 offset0:30 offset1:31
	v_pk_mul_f32 v[18:19], v[18:19], v[20:21]
	s_waitcnt lgkmcnt(0)
	v_sub_f32_e32 v14, v98, v14
	v_cvt_pk_bf16_f32 v18, v18, v19
	v_sub_f32_e32 v15, v98, v15
	ds_read_u16 v19, v13 offset:25568
	ds_read_u16 v13, v13 offset:25840
	v_mul_f32_e32 v14, 0x3fb8aa3b, v14
	v_mul_f32_e32 v15, 0x3fb8aa3b, v15
	v_exp_f32_e32 v14, v14
	v_exp_f32_e32 v15, v15
	s_ashr_i32 s1, s0, 31
	s_lshl_b64 s[0:1], s[0:1], 14
	s_waitcnt lgkmcnt(0)
	v_lshlrev_b32_e32 v21, 16, v13
	v_lshlrev_b32_e32 v20, 16, v19
	s_add_u32 s0, s4, s0
	v_readlane_b32 s4, v254, 16
	v_lshlrev_b32_sdwa v13, v168, v45 dst_sel:DWORD dst_unused:UNUSED_PAD src0_sel:DWORD src1_sel:BYTE_0
	v_pk_mul_f32 v[14:15], v[14:15], v[20:21]
	s_addc_u32 s1, s4, s1
	v_and_b32_e32 v136, 0x3f80, v13
	v_cvt_pk_bf16_f32 v19, v14, v15
	v_lshl_add_u64 v[14:15], s[0:1], 0, v[136:137]
	v_lshlrev_b32_e32 v136, 1, v12
	v_lshl_add_u64 v[12:13], v[14:15], 0, v[136:137]
	global_store_dwordx4 v[12:13], v[0:3], off
	global_store_dwordx4 v[12:13], v[4:7], off offset:16
	global_store_dwordx4 v[12:13], v[8:11], off offset:32
	global_store_dwordx4 v[12:13], v[16:19], off offset:48
	v_lshrrev_b32_e32 v0, 2, v45
	v_and_b32_e32 v32, 48, v0
	v_or_b32_e32 v0, v32, v97
	v_and_b32_e32 v1, 48, v96
	v_mul_u32_u24_e32 v0, 0x88, v0
	v_add_u32_e32 v8, v122, v1
	v_mul_u32_u24_e32 v9, 0x88, v97
	v_lshl_add_u32 v33, v0, 1, v8
	v_lshl_add_u32 v35, v9, 1, v8
	ds_read_b128 v[0:3], v33 offset:34816
	ds_read_b128 v[4:7], v33
	ds_read_b128 v[8:11], v35 offset:17408
	ds_read_b128 v[16:19], v35 offset:21760
	ds_read_b128 v[24:27], v35 offset:26112
	ds_read_b128 v[38:41], v35 offset:30464
	s_waitcnt lgkmcnt(3)
	v_mfma_f32_16x16x32_bf16 v[12:15], v[0:3], v[8:11], 0
	v_readlane_b32 s4, v254, 17
	v_mfma_f32_16x16x32_bf16 v[8:11], v[4:7], v[8:11], 0
	s_waitcnt lgkmcnt(2)
	v_mfma_f32_16x16x32_bf16 v[20:23], v[0:3], v[16:19], 0
	v_mfma_f32_16x16x32_bf16 v[16:19], v[4:7], v[16:19], 0
	s_waitcnt lgkmcnt(1)
	v_mfma_f32_16x16x32_bf16 v[28:31], v[0:3], v[24:27], 0
	v_mfma_f32_16x16x32_bf16 v[24:27], v[4:7], v[24:27], 0
	s_waitcnt lgkmcnt(0)
	v_mfma_f32_16x16x32_bf16 v[0:3], v[0:3], v[38:41], 0
	v_mfma_f32_16x16x32_bf16 v[4:7], v[4:7], v[38:41], 0
	ds_read_b128 v[38:41], v33 offset:34880
	ds_read_b128 v[46:49], v33 offset:64
	ds_read_b128 v[50:53], v35 offset:17472
	s_waitcnt lgkmcnt(0)
	v_mfma_f32_16x16x32_bf16 v[12:15], v[38:41], v[50:53], v[12:15]
	v_mfma_f32_16x16x32_bf16 v[8:11], v[46:49], v[50:53], v[8:11]
	ds_read_b128 v[50:53], v35 offset:21824
	s_waitcnt lgkmcnt(0)
	v_mfma_f32_16x16x32_bf16 v[20:23], v[38:41], v[50:53], v[20:23]
	v_mfma_f32_16x16x32_bf16 v[16:19], v[46:49], v[50:53], v[16:19]
	ds_read_b128 v[50:53], v35 offset:26176
	s_waitcnt lgkmcnt(0)
	v_mfma_f32_16x16x32_bf16 v[28:31], v[38:41], v[50:53], v[28:31]
	v_mfma_f32_16x16x32_bf16 v[24:27], v[46:49], v[50:53], v[24:27]
	ds_read_b128 v[50:53], v35 offset:30528
	s_waitcnt lgkmcnt(0)
	v_mfma_f32_16x16x32_bf16 v[0:3], v[38:41], v[50:53], v[0:3]
	v_mfma_f32_16x16x32_bf16 v[4:7], v[46:49], v[50:53], v[4:7]
	ds_read_b128 v[38:41], v33 offset:34944
	ds_read_b128 v[46:49], v33 offset:128
	ds_read_b128 v[50:53], v35 offset:17536
	s_waitcnt lgkmcnt(0)
	v_mfma_f32_16x16x32_bf16 v[12:15], v[38:41], v[50:53], v[12:15]
	v_mfma_f32_16x16x32_bf16 v[8:11], v[46:49], v[50:53], v[8:11]
	ds_read_b128 v[50:53], v35 offset:21888
	s_waitcnt lgkmcnt(0)
	v_mfma_f32_16x16x32_bf16 v[20:23], v[38:41], v[50:53], v[20:23]
	v_mfma_f32_16x16x32_bf16 v[16:19], v[46:49], v[50:53], v[16:19]
	ds_read_b128 v[50:53], v35 offset:26240
	s_waitcnt lgkmcnt(0)
	v_mfma_f32_16x16x32_bf16 v[54:57], v[38:41], v[50:53], v[28:31]
	v_mfma_f32_16x16x32_bf16 v[50:53], v[46:49], v[50:53], v[24:27]
	s_nop 2
	ds_read_b128 v[24:27], v35 offset:30592
	s_waitcnt lgkmcnt(0)
	v_mfma_f32_16x16x32_bf16 v[0:3], v[38:41], v[24:27], v[0:3]
	v_mfma_f32_16x16x32_bf16 v[38:41], v[46:49], v[24:27], v[4:7]
	s_nop 2
	ds_read_b128 v[4:7], v33 offset:35008
	ds_read_b128 v[46:49], v33 offset:192
	ds_read_b128 v[24:27], v35 offset:17600
	v_lshrrev_b32_e32 v33, 2, v96
	v_and_or_b32 v37, v33, 12, v32
	s_waitcnt lgkmcnt(0)
	v_mfma_f32_16x16x32_bf16 v[28:31], v[4:7], v[24:27], v[12:15]
	v_lshl_add_u32 v33, v37, 2, v125
	v_cmp_lt_u32_e32 vcc, v97, v37
	v_mfma_f32_16x16x32_bf16 v[24:27], v[46:49], v[24:27], v[8:11]
	s_nop 2
	ds_read_b128 v[8:11], v35 offset:21952
	s_waitcnt lgkmcnt(0)
	v_mfma_f32_16x16x32_bf16 v[20:23], v[4:7], v[8:11], v[20:23]
	v_mfma_f32_16x16x32_bf16 v[16:19], v[46:49], v[8:11], v[16:19]
	ds_read_b128 v[8:11], v35 offset:26304
	s_waitcnt lgkmcnt(0)
	v_mfma_f32_16x16x32_bf16 v[12:15], v[4:7], v[8:11], v[54:57]
	v_mfma_f32_16x16x32_bf16 v[8:11], v[46:49], v[8:11], v[50:53]
	s_nop 2
	ds_read_b128 v[50:53], v35 offset:30656
	s_waitcnt lgkmcnt(0)
	v_mfma_f32_16x16x32_bf16 v[4:7], v[4:7], v[50:53], v[0:3]
	s_barrier
	v_mfma_f32_16x16x32_bf16 v[0:3], v[46:49], v[50:53], v[38:41]
	v_lshlrev_b32_e32 v46, 2, v97
	v_add_u32_e32 v32, v125, v46
	ds_read_b32 v47, v33
	ds_read_b32 v48, v32
	v_or_b32_e32 v39, 1, v37
	v_or_b32_e32 v40, 2, v37
	s_waitcnt lgkmcnt(0)
	v_sub_f32_e32 v32, v47, v48
	v_min_f32_e32 v32, 0, v32
	v_mul_f32_e32 v32, 0x3fb8aa3b, v32
	v_exp_f32_e32 v32, v32
	s_nop 0
	v_mul_f32_e32 v28, v28, v32
	v_cndmask_b32_e32 v49, 0, v28, vcc
	v_lshlrev_b32_e32 v28, 8, v37
	v_add3_u32 v38, v122, v28, v46
	v_mul_f32_e32 v24, v24, v32
	v_mul_u32_u24_e32 v28, 0x90, v37
	v_lshlrev_b32_e32 v32, 1, v97
	v_add3_u32 v35, v122, v28, v32
	ds_read2_b32 v[32:33], v33 offset1:1
	v_cmp_gt_u32_e32 vcc, v97, v37
	v_cvt_pk_bf16_f32 v24, v24, s0
	s_waitcnt lgkmcnt(0)
	v_sub_f32_e32 v28, v33, v48
	v_min_f32_e32 v28, 0, v28
	v_mul_f32_e32 v28, 0x3fb8aa3b, v28
	v_exp_f32_e32 v28, v28
	v_cndmask_b32_e64 v24, v24, 0, vcc
	ds_write_b16 v35, v24 offset:17408
	v_lshl_add_u32 v24, v39, 2, v125
	v_mul_f32_e32 v29, v29, v28
	v_mul_f32_e32 v25, v25, v28
	v_cndmask_b32_e64 v50, v29, 0, vcc
	v_cvt_pk_bf16_f32 v25, v25, s0
	v_cmp_le_u32_e32 vcc, v97, v39
	v_lshlrev_b32_e32 v29, 8, v39
	v_add3_u32 v41, v122, v29, v46
	v_cndmask_b32_e32 v25, 0, v25, vcc
	ds_write_b16 v35, v25 offset:17552
	ds_read2_b32 v[24:25], v24 offset1:1
	v_lshl_add_u32 v28, v40, 2, v125
	v_cmp_lt_u32_e32 vcc, v97, v40
	s_waitcnt lgkmcnt(0)
	v_sub_f32_e32 v29, v25, v48
	v_min_f32_e32 v29, 0, v29
	v_mul_f32_e32 v29, 0x3fb8aa3b, v29
	v_exp_f32_e32 v29, v29
	s_nop 0
	v_mul_f32_e32 v30, v30, v29
	v_mul_f32_e32 v26, v26, v29
	ds_read2_b32 v[28:29], v28 offset1:1
	v_cndmask_b32_e32 v51, 0, v30, vcc
	v_lshlrev_b32_e32 v30, 8, v40
	v_add3_u32 v43, v122, v30, v46
	v_cvt_pk_bf16_f32 v26, v26, s0
	s_waitcnt lgkmcnt(0)
	v_sub_f32_e32 v30, v29, v48
	v_min_f32_e32 v30, 0, v30
	v_mul_f32_e32 v30, 0x3fb8aa3b, v30
	v_exp_f32_e32 v48, v30
	v_cmp_le_u32_e32 vcc, v97, v40
	v_mul_f32_e32 v30, v31, v48
	s_nop 0
	v_cndmask_b32_e32 v26, 0, v26, vcc
	ds_write_b16 v35, v26 offset:17696
	v_or_b32_e32 v26, 3, v37
	v_cmp_lt_u32_e32 vcc, v97, v26
	v_mul_f32_e32 v27, v27, v48
	v_cvt_pk_bf16_f32 v27, v27, s0
	v_cndmask_b32_e32 v31, 0, v30, vcc
	v_cmp_le_u32_e32 vcc, v97, v26
	v_lshlrev_b32_e32 v30, 8, v26
	v_add3_u32 v30, v122, v30, v46
	v_cndmask_b32_e32 v27, 0, v27, vcc
	ds_write_b16 v35, v27 offset:17840
	v_lshl_add_u32 v27, v42, 2, v125
	ds_read_b32 v27, v27
	v_cmp_lt_u32_e32 vcc, v42, v37
	v_lshl_add_u32 v52, v26, 2, v125
	s_waitcnt lgkmcnt(0)
	v_sub_f32_e32 v46, v47, v27
	v_min_f32_e32 v46, 0, v46
	v_mul_f32_e32 v46, 0x3fb8aa3b, v46
	v_exp_f32_e32 v46, v46
	s_nop 0
	v_mul_f32_e32 v20, v20, v46
	v_mul_f32_e32 v16, v16, v46
	v_cndmask_b32_e32 v20, 0, v20, vcc
	v_cmp_gt_u32_e32 vcc, v42, v37
	v_cvt_pk_bf16_f32 v16, v16, s0
	ds_write2_b32 v38, v49, v20 offset1:16
	v_cndmask_b32_e64 v16, v16, 0, vcc
	ds_write_b16 v35, v16 offset:17440
	v_sub_f32_e32 v16, v33, v27
	v_min_f32_e32 v16, 0, v16
	v_mul_f32_e32 v16, 0x3fb8aa3b, v16
	v_exp_f32_e32 v16, v16
	s_nop 0
	v_mul_f32_e32 v20, v21, v16
	v_mul_f32_e32 v16, v17, v16
	v_cndmask_b32_e64 v20, v20, 0, vcc
	v_cvt_pk_bf16_f32 v16, v16, s0
	v_cmp_le_u32_e32 vcc, v42, v39
	ds_write2_b32 v41, v50, v20 offset1:16
	s_nop 0
	v_cndmask_b32_e32 v16, 0, v16, vcc
	ds_write_b16 v35, v16 offset:17584
	v_sub_f32_e32 v16, v25, v27
	v_min_f32_e32 v16, 0, v16
	v_mul_f32_e32 v16, 0x3fb8aa3b, v16
	v_exp_f32_e32 v16, v16
	v_cmp_lt_u32_e32 vcc, v42, v40
	v_mul_f32_e32 v17, v22, v16
	v_mul_f32_e32 v16, v18, v16
	v_cndmask_b32_e32 v17, 0, v17, vcc
	v_cvt_pk_bf16_f32 v16, v16, s0
	v_cmp_le_u32_e32 vcc, v42, v40
	ds_write2_b32 v43, v51, v17 offset1:16
	s_nop 0
	v_cndmask_b32_e32 v16, 0, v16, vcc
	ds_write_b16 v35, v16 offset:17728
	v_sub_f32_e32 v16, v29, v27
	v_min_f32_e32 v16, 0, v16
	v_mul_f32_e32 v16, 0x3fb8aa3b, v16
	v_exp_f32_e32 v16, v16
	v_cmp_lt_u32_e32 vcc, v42, v26
	v_mul_f32_e32 v17, v23, v16
	v_mul_f32_e32 v16, v19, v16
	v_cndmask_b32_e32 v17, 0, v17, vcc
	v_cvt_pk_bf16_f32 v16, v16, s0
	v_cmp_le_u32_e32 vcc, v42, v26
	ds_write2_b32 v30, v31, v17 offset1:16
	s_nop 0
	v_cndmask_b32_e32 v16, 0, v16, vcc
	ds_write_b16 v35, v16 offset:17872
	v_lshl_add_u32 v16, v36, 2, v125
	ds_read_b32 v16, v16
	v_cmp_lt_u32_e32 vcc, v36, v37
	s_waitcnt lgkmcnt(0)
	v_sub_f32_e32 v17, v32, v16
	v_min_f32_e32 v17, 0, v17
	v_mul_f32_e32 v17, 0x3fb8aa3b, v17
	v_exp_f32_e32 v17, v17
	s_nop 0
	v_mul_f32_e32 v12, v12, v17
	v_mul_f32_e32 v8, v8, v17
	v_cndmask_b32_e32 v12, 0, v12, vcc
	v_cmp_gt_u32_e32 vcc, v36, v37
	v_cvt_pk_bf16_f32 v8, v8, s0
	s_nop 0
	v_cndmask_b32_e64 v8, v8, 0, vcc
	ds_write_b16 v35, v8 offset:17472
	v_sub_f32_e32 v8, v24, v16
	v_min_f32_e32 v8, 0, v8
	v_mul_f32_e32 v8, 0x3fb8aa3b, v8
	v_exp_f32_e32 v8, v8
	s_nop 0
	v_mul_f32_e32 v13, v13, v8
	v_mul_f32_e32 v8, v9, v8
	v_cndmask_b32_e64 v13, v13, 0, vcc
	v_cvt_pk_bf16_f32 v8, v8, s0
	v_cmp_le_u32_e32 vcc, v36, v39
	s_nop 1
	v_cndmask_b32_e32 v8, 0, v8, vcc
	ds_write_b16 v35, v8 offset:17616
	v_sub_f32_e32 v8, v28, v16
	v_min_f32_e32 v8, 0, v8
	v_mul_f32_e32 v8, 0x3fb8aa3b, v8
	v_exp_f32_e32 v8, v8
	v_cmp_lt_u32_e32 vcc, v36, v40
	v_mul_f32_e32 v9, v14, v8
	v_mul_f32_e32 v8, v10, v8
	v_cndmask_b32_e32 v9, 0, v9, vcc
	v_cvt_pk_bf16_f32 v8, v8, s0
	v_cmp_le_u32_e32 vcc, v36, v40
	s_nop 1
	v_cndmask_b32_e32 v8, 0, v8, vcc
	ds_write_b16 v35, v8 offset:17760
	ds_read_b32 v8, v52
	v_cmp_lt_u32_e32 vcc, v36, v26
	s_waitcnt lgkmcnt(0)
	v_sub_f32_e32 v10, v8, v16
	v_min_f32_e32 v10, 0, v10
	v_mul_f32_e32 v10, 0x3fb8aa3b, v10
	v_exp_f32_e32 v10, v10
	s_nop 0
	v_mul_f32_e32 v14, v15, v10
	v_mul_f32_e32 v10, v11, v10
	v_cndmask_b32_e32 v14, 0, v14, vcc
	v_cvt_pk_bf16_f32 v10, v10, s0
	v_cmp_le_u32_e32 vcc, v36, v26
	s_nop 1
	v_cndmask_b32_e32 v10, 0, v10, vcc
	ds_write_b16 v35, v10 offset:17904
	v_lshl_add_u32 v10, v34, 2, v125
	ds_read_b32 v10, v10
	v_cmp_lt_u32_e32 vcc, v34, v37
	s_waitcnt lgkmcnt(0)
	v_sub_f32_e32 v11, v32, v10
	v_min_f32_e32 v11, 0, v11
	v_mul_f32_e32 v11, 0x3fb8aa3b, v11
	v_exp_f32_e32 v11, v11
	s_nop 0
	v_mul_f32_e32 v4, v4, v11
	v_mul_f32_e32 v0, v0, v11
	v_cndmask_b32_e32 v4, 0, v4, vcc
	v_cmp_gt_u32_e32 vcc, v34, v37
	v_cvt_pk_bf16_f32 v0, v0, s0
	ds_write2_b32 v38, v12, v4 offset0:32 offset1:48
	v_cndmask_b32_e64 v0, v0, 0, vcc
	ds_write_b16 v35, v0 offset:17504
	v_sub_f32_e32 v0, v24, v10
	v_min_f32_e32 v0, 0, v0
	v_mul_f32_e32 v0, 0x3fb8aa3b, v0
	v_exp_f32_e32 v0, v0
	s_nop 0
	v_mul_f32_e32 v4, v5, v0
	v_mul_f32_e32 v0, v1, v0
	v_cndmask_b32_e64 v4, v4, 0, vcc
	v_cvt_pk_bf16_f32 v0, v0, s0
	v_cmp_le_u32_e32 vcc, v34, v39
	ds_write2_b32 v41, v13, v4 offset0:32 offset1:48
	v_lshrrev_b32_sdwa v4, v166, v45 dst_sel:DWORD dst_unused:UNUSED_PAD src0_sel:DWORD src1_sel:BYTE_0
	v_cndmask_b32_e32 v0, 0, v0, vcc
	ds_write_b16 v35, v0 offset:17648
	v_sub_f32_e32 v0, v28, v10
	v_min_f32_e32 v0, 0, v0
	v_mul_f32_e32 v0, 0x3fb8aa3b, v0
	v_exp_f32_e32 v0, v0
	v_cmp_lt_u32_e32 vcc, v34, v40
	v_lshlrev_b32_e32 v136, 7, v4
	v_mul_f32_e32 v1, v6, v0
	v_mul_f32_e32 v0, v2, v0
	v_cndmask_b32_e32 v1, 0, v1, vcc
	v_cvt_pk_bf16_f32 v0, v0, s0
	v_cmp_le_u32_e32 vcc, v34, v40
	ds_write2_b32 v43, v9, v1 offset0:32 offset1:48
	v_mov_b32_e32 v9, v137
	v_cndmask_b32_e32 v0, 0, v0, vcc
	ds_write_b16 v35, v0 offset:17792
	v_sub_f32_e32 v0, v8, v10
	v_min_f32_e32 v0, 0, v0
	v_mul_f32_e32 v0, 0x3fb8aa3b, v0
	v_exp_f32_e32 v0, v0
	v_cmp_lt_u32_e32 vcc, v34, v26
	v_mul_f32_e32 v1, v7, v0
	v_mul_f32_e32 v0, v3, v0
	v_cndmask_b32_e32 v1, 0, v1, vcc
	v_cvt_pk_bf16_f32 v0, v0, s0
	v_cmp_le_u32_e32 vcc, v34, v26
	s_mov_b32 s0, s26
	ds_write2_b32 v30, v14, v1 offset0:32 offset1:48
	v_cndmask_b32_e32 v0, 0, v0, vcc
	ds_write_b16 v35, v0 offset:17936
	v_and_b32_e32 v0, 56, v95
	v_lshlrev_b32_e32 v8, 1, v0
	v_add_u32_e32 v6, v122, v8
	v_mad_u32_u24 v0, v4, s6, v6
	s_waitcnt lgkmcnt(0)
	s_barrier
	ds_read_b128 v[0:3], v0 offset:17408
	s_ashr_i32 s1, s0, 31
	s_lshl_b64 s[0:1], s[0:1], 13
	s_add_u32 s0, s4, s0
	s_addc_u32 s1, s5, s1
	v_lshl_add_u64 v[4:5], s[0:1], 0, v[136:137]
	v_lshl_add_u64 v[4:5], v[4:5], 0, v[8:9]
	s_movk_i32 s0, 0x100
	s_waitcnt lgkmcnt(0)
	global_store_dwordx4 v[4:5], v[0:3], off
	s_nop 1
	v_or_b32_sdwa v2, v45, s0 dst_sel:DWORD dst_unused:UNUSED_PAD src0_sel:BYTE_0 src1_sel:DWORD
	v_lshrrev_b32_e32 v0, 3, v2
	v_mad_u32_u24 v1, v0, s6, v6
	s_mov_b32 s0, s26
	ds_read_b128 v[4:7], v1 offset:17408
	s_ashr_i32 s1, s0, 31
	s_lshl_b64 s[0:1], s[0:1], 13
	s_add_u32 s0, s4, s0
	s_addc_u32 s1, s5, s1
	v_lshlrev_b32_e32 v136, 7, v0
	v_lshl_add_u64 v[0:1], s[0:1], 0, v[136:137]
	s_movk_i32 s4, 0x7f
	v_lshl_add_u64 v[0:1], v[0:1], 0, v[8:9]
	v_cmp_gt_u32_sdwa vcc, v45, s4 src0_sel:BYTE_0 src1_sel:DWORD
	s_waitcnt lgkmcnt(0)
	global_store_dwordx4 v[0:1], v[4:7], off
	v_and_b32_e32 v0, 0x7f, v45
	v_lshlrev_b32_e32 v1, 1, v0
	v_add_u32_e32 v115, v124, v1
	v_add_u32_e32 v116, v123, v1
	v_add_u32_e32 v117, v122, v1
	v_lshlrev_b32_e32 v118, 7, v0
	v_bfe_u32 v1, v45, 7, 1
	v_lshrrev_b32_e32 v3, 8, v154
	v_cmp_eq_u32_e32 vcc, v1, v3
	s_mov_b64 s[8:9], vcc
	s_and_saveexec_b64 s[0:1], s[8:9]
	s_cbranch_execz .Lfs_skip
	ds_read_u16 v16, v115 offset:0
	ds_read_u16 v17, v116 offset:0
	ds_read_b32 v18, v126 offset:0
	ds_read_b32 v19, v127 offset:0
	ds_read_b128 v[32:35], v122 offset:256
	ds_read_u16 v20, v115 offset:272
	ds_read_u16 v21, v116 offset:272
	ds_read_b32 v22, v126 offset:4
	ds_read_b32 v23, v127 offset:4
	ds_read_b128 v[36:39], v122 offset:512
	ds_read_u16 v24, v115 offset:544
	ds_read_u16 v25, v116 offset:544
	ds_read_b32 v26, v126 offset:8
	s_waitcnt lgkmcnt(9)
	v_lshlrev_b32_e32 v16, 16, v16
	v_lshlrev_b32_e32 v17, 16, v17
	v_pk_mul_f32 v[170:171], v[18:19], v[16:17]
	ds_read_b32 v27, v127 offset:8
	s_waitcnt lgkmcnt(9)
	v_pk_mul_f32 v[4:5], v[32:33], v[170:171] op_sel_hi:[0,1]
	ds_read_b128 v[40:43], v122 offset:768
	ds_read_u16 v28, v115 offset:816
	ds_read_u16 v29, v116 offset:816
	ds_read_b32 v30, v126 offset:12
	s_waitcnt lgkmcnt(9)
	v_lshlrev_b32_e32 v20, 16, v20
	v_lshlrev_b32_e32 v21, 16, v21
	v_pk_fma_f32 v[172:173], v[22:23], v[20:21], v[4:5] neg_lo:[0,0,1] neg_hi:[0,0,1]
	ds_read_b32 v31, v127 offset:12
	s_waitcnt lgkmcnt(9)
	v_pk_mul_f32 v[4:5], v[36:37], v[170:171] op_sel_hi:[0,1]
	v_pk_mul_f32 v[6:7], v[36:37], v[172:173] op_sel:[1,0] op_sel_hi:[1,1]
	ds_read_b128 v[98:101], v122 offset:1024
	ds_read_u16 v16, v115 offset:1088
	ds_read_u16 v17, v116 offset:1088
	ds_read_b32 v18, v126 offset:16
	s_waitcnt lgkmcnt(9)
	v_lshlrev_b32_e32 v24, 16, v24
	v_lshlrev_b32_e32 v25, 16, v25
	v_pk_add_f32 v[12:13], v[4:5], v[6:7]
	s_nop 0
	v_pk_fma_f32 v[174:175], v[26:27], v[24:25], v[12:13] neg_lo:[0,0,1] neg_hi:[0,0,1]
	ds_read_b32 v19, v127 offset:16
	s_waitcnt lgkmcnt(9)
	v_pk_mul_f32 v[4:5], v[40:41], v[170:171] op_sel_hi:[0,1]
	v_pk_mul_f32 v[6:7], v[40:41], v[172:173] op_sel:[1,0] op_sel_hi:[1,1]
	v_pk_mul_f32 v[8:9], v[42:43], v[174:175] op_sel_hi:[0,1]
	ds_read_b128 v[102:105], v122 offset:1280
	ds_read_b128 v[106:109], v122 offset:1296
	ds_read_u16 v20, v115 offset:1360
	ds_read_u16 v21, v116 offset:1360
	s_waitcnt lgkmcnt(9)
	v_lshlrev_b32_e32 v28, 16, v28
	v_lshlrev_b32_e32 v29, 16, v29
	v_pk_add_f32 v[12:13], v[4:5], v[6:7]
	s_nop 0
	v_pk_add_f32 v[12:13], v[12:13], v[8:9]
	s_nop 0
	v_pk_fma_f32 v[176:177], v[30:31], v[28:29], v[12:13] neg_lo:[0,0,1] neg_hi:[0,0,1]
	ds_read_b32 v22, v126 offset:20
	s_waitcnt lgkmcnt(9)
	v_pk_mul_f32 v[4:5], v[98:99], v[170:171] op_sel_hi:[0,1]
	v_pk_mul_f32 v[6:7], v[98:99], v[172:173] op_sel:[1,0] op_sel_hi:[1,1]
	v_pk_mul_f32 v[8:9], v[100:101], v[174:175] op_sel_hi:[0,1]
	v_pk_mul_f32 v[10:11], v[100:101], v[176:177] op_sel:[1,0] op_sel_hi:[1,1]
	ds_read_b32 v23, v127 offset:20
	ds_read_b128 v[130:133], v122 offset:1536
	ds_read_b128 v[140:143], v122 offset:1552
	ds_read_u16 v24, v115 offset:1632
	s_waitcnt lgkmcnt(9)
	v_lshlrev_b32_e32 v16, 16, v16
	v_lshlrev_b32_e32 v17, 16, v17
	v_pk_add_f32 v[12:13], v[4:5], v[6:7]
	v_pk_add_f32 v[14:15], v[8:9], v[10:11]
	s_nop 0
	v_pk_add_f32 v[12:13], v[12:13], v[14:15]
	s_nop 0
	v_pk_fma_f32 v[178:179], v[18:19], v[16:17], v[12:13] neg_lo:[0,0,1] neg_hi:[0,0,1]
	ds_read_u16 v25, v116 offset:1632
	s_waitcnt lgkmcnt(9)
	v_pk_mul_f32 v[4:5], v[102:103], v[170:171] op_sel_hi:[0,1]
	v_pk_mul_f32 v[6:7], v[102:103], v[172:173] op_sel:[1,0] op_sel_hi:[1,1]
	v_pk_mul_f32 v[8:9], v[104:105], v[174:175] op_sel_hi:[0,1]
	v_pk_mul_f32 v[10:11], v[104:105], v[176:177] op_sel:[1,0] op_sel_hi:[1,1]
	ds_read_b32 v26, v126 offset:24
	s_waitcnt lgkmcnt(9)
	v_pk_fma_f32 v[4:5], v[106:107], v[178:179], v[4:5] op_sel_hi:[0,1,1]
	ds_read_b32 v27, v127 offset:24
	ds_read_b128 v[144:147], v122 offset:1792
	ds_read_b128 v[148:151], v122 offset:1808
	ds_read_u16 v28, v115 offset:1904
	s_waitcnt lgkmcnt(9)
	v_lshlrev_b32_e32 v20, 16, v20
	v_lshlrev_b32_e32 v21, 16, v21
	v_pk_add_f32 v[12:13], v[4:5], v[6:7]
	v_pk_add_f32 v[14:15], v[8:9], v[10:11]
	s_nop 0
	v_pk_add_f32 v[12:13], v[12:13], v[14:15]
	s_nop 0
	v_pk_fma_f32 v[180:181], v[22:23], v[20:21], v[12:13] neg_lo:[0,0,1] neg_hi:[0,0,1]
	ds_read_u16 v29, v116 offset:1904
	s_waitcnt lgkmcnt(9)
	v_pk_mul_f32 v[4:5], v[130:131], v[170:171] op_sel_hi:[0,1]
	v_pk_mul_f32 v[6:7], v[130:131], v[172:173] op_sel:[1,0] op_sel_hi:[1,1]
	v_pk_mul_f32 v[8:9], v[132:133], v[174:175] op_sel_hi:[0,1]
	v_pk_mul_f32 v[10:11], v[132:133], v[176:177] op_sel:[1,0] op_sel_hi:[1,1]
	ds_read_b32 v30, v126 offset:28
	s_waitcnt lgkmcnt(9)
	v_pk_fma_f32 v[4:5], v[140:141], v[178:179], v[4:5] op_sel_hi:[0,1,1]
	v_pk_fma_f32 v[6:7], v[140:141], v[180:181], v[6:7] op_sel:[1,0,0] op_sel_hi:[1,1,1]
	ds_read_b32 v31, v127 offset:28
	ds_read_b128 v[32:35], v122 offset:2048
	ds_read_b128 v[36:39], v122 offset:2064
	ds_read_u16 v16, v115 offset:2176
	s_waitcnt lgkmcnt(9)
	v_lshlrev_b32_e32 v24, 16, v24
	v_lshlrev_b32_e32 v25, 16, v25
	v_pk_add_f32 v[12:13], v[4:5], v[6:7]
	v_pk_add_f32 v[14:15], v[8:9], v[10:11]
	s_nop 0
	v_pk_add_f32 v[12:13], v[12:13], v[14:15]
	s_nop 0
	v_pk_fma_f32 v[182:183], v[26:27], v[24:25], v[12:13] neg_lo:[0,0,1] neg_hi:[0,0,1]
	ds_read_u16 v17, v116 offset:2176
	s_waitcnt lgkmcnt(9)
	v_pk_mul_f32 v[4:5], v[144:145], v[170:171] op_sel_hi:[0,1]
	v_pk_mul_f32 v[6:7], v[144:145], v[172:173] op_sel:[1,0] op_sel_hi:[1,1]
	v_pk_mul_f32 v[8:9], v[146:147], v[174:175] op_sel_hi:[0,1]
	v_pk_mul_f32 v[10:11], v[146:147], v[176:177] op_sel:[1,0] op_sel_hi:[1,1]
	ds_read_b32 v18, v126 offset:32
	s_waitcnt lgkmcnt(9)
	v_pk_fma_f32 v[4:5], v[148:149], v[178:179], v[4:5] op_sel_hi:[0,1,1]
	v_pk_fma_f32 v[6:7], v[148:149], v[180:181], v[6:7] op_sel:[1,0,0] op_sel_hi:[1,1,1]
	v_pk_fma_f32 v[8:9], v[150:151], v[182:183], v[8:9] op_sel_hi:[0,1,1]
	ds_read_b32 v19, v127 offset:32
	ds_read_b128 v[40:43], v122 offset:2304
	ds_read_b128 v[98:101], v122 offset:2320
	ds_read_b128 v[102:105], v122 offset:2336
	s_waitcnt lgkmcnt(9)
	v_lshlrev_b32_e32 v28, 16, v28
	v_lshlrev_b32_e32 v29, 16, v29
	v_pk_add_f32 v[12:13], v[4:5], v[6:7]
	v_pk_add_f32 v[14:15], v[8:9], v[10:11]
	s_nop 0
	v_pk_add_f32 v[12:13], v[12:13], v[14:15]
	s_nop 0
	v_pk_fma_f32 v[184:185], v[30:31], v[28:29], v[12:13] neg_lo:[0,0,1] neg_hi:[0,0,1]
	ds_read_u16 v20, v115 offset:2448
	s_waitcnt lgkmcnt(9)
	v_pk_mul_f32 v[4:5], v[32:33], v[170:171] op_sel_hi:[0,1]
	v_pk_mul_f32 v[6:7], v[32:33], v[172:173] op_sel:[1,0] op_sel_hi:[1,1]
	v_pk_mul_f32 v[8:9], v[34:35], v[174:175] op_sel_hi:[0,1]
	v_pk_mul_f32 v[10:11], v[34:35], v[176:177] op_sel:[1,0] op_sel_hi:[1,1]
	ds_read_u16 v21, v116 offset:2448
	s_waitcnt lgkmcnt(9)
	v_pk_fma_f32 v[4:5], v[36:37], v[178:179], v[4:5] op_sel_hi:[0,1,1]
	v_pk_fma_f32 v[6:7], v[36:37], v[180:181], v[6:7] op_sel:[1,0,0] op_sel_hi:[1,1,1]
	v_pk_fma_f32 v[8:9], v[38:39], v[182:183], v[8:9] op_sel_hi:[0,1,1]
	v_pk_fma_f32 v[10:11], v[38:39], v[184:185], v[10:11] op_sel:[1,0,0] op_sel_hi:[1,1,1]
	ds_read_b32 v22, v126 offset:36
	ds_read_b32 v23, v127 offset:36
	ds_read_b128 v[106:109], v122 offset:2560
	ds_read_b128 v[130:133], v122 offset:2576
	s_waitcnt lgkmcnt(9)
	v_lshlrev_b32_e32 v16, 16, v16
	v_lshlrev_b32_e32 v17, 16, v17
	v_pk_add_f32 v[12:13], v[4:5], v[6:7]
	v_pk_add_f32 v[14:15], v[8:9], v[10:11]
	s_nop 0
	v_pk_add_f32 v[12:13], v[12:13], v[14:15]
	s_nop 0
	v_pk_fma_f32 v[186:187], v[18:19], v[16:17], v[12:13] neg_lo:[0,0,1] neg_hi:[0,0,1]
	ds_read_b128 v[140:143], v122 offset:2592
	s_waitcnt lgkmcnt(9)
	v_pk_mul_f32 v[4:5], v[40:41], v[170:171] op_sel_hi:[0,1]
	v_pk_mul_f32 v[6:7], v[40:41], v[172:173] op_sel:[1,0] op_sel_hi:[1,1]
	v_pk_mul_f32 v[8:9], v[42:43], v[174:175] op_sel_hi:[0,1]
	v_pk_mul_f32 v[10:11], v[42:43], v[176:177] op_sel:[1,0] op_sel_hi:[1,1]
	ds_read_u16 v24, v115 offset:2720
	s_waitcnt lgkmcnt(9)
	v_pk_fma_f32 v[4:5], v[98:99], v[178:179], v[4:5] op_sel_hi:[0,1,1]
	v_pk_fma_f32 v[6:7], v[98:99], v[180:181], v[6:7] op_sel:[1,0,0] op_sel_hi:[1,1,1]
	v_pk_fma_f32 v[8:9], v[100:101], v[182:183], v[8:9] op_sel_hi:[0,1,1]
	v_pk_fma_f32 v[10:11], v[100:101], v[184:185], v[10:11] op_sel:[1,0,0] op_sel_hi:[1,1,1]
	ds_read_u16 v25, v116 offset:2720
	s_waitcnt lgkmcnt(9)
	v_pk_fma_f32 v[4:5], v[102:103], v[186:187], v[4:5] op_sel_hi:[0,1,1]
	ds_read_b32 v26, v126 offset:40
	ds_read_b32 v27, v127 offset:40
	ds_read_b128 v[144:147], v122 offset:2816
	ds_read_b128 v[148:151], v122 offset:2832
	s_waitcnt lgkmcnt(9)
	v_lshlrev_b32_e32 v20, 16, v20
	v_lshlrev_b32_e32 v21, 16, v21
	v_pk_add_f32 v[12:13], v[4:5], v[6:7]
	v_pk_add_f32 v[14:15], v[8:9], v[10:11]
	s_nop 0
	v_pk_add_f32 v[12:13], v[12:13], v[14:15]
	s_nop 0
	v_pk_fma_f32 v[188:189], v[22:23], v[20:21], v[12:13] neg_lo:[0,0,1] neg_hi:[0,0,1]
	ds_read_b128 v[32:35], v122 offset:2848
	s_waitcnt lgkmcnt(9)
	v_pk_mul_f32 v[4:5], v[106:107], v[170:171] op_sel_hi:[0,1]
	v_pk_mul_f32 v[6:7], v[106:107], v[172:173] op_sel:[1,0] op_sel_hi:[1,1]
	v_pk_mul_f32 v[8:9], v[108:109], v[174:175] op_sel_hi:[0,1]
	v_pk_mul_f32 v[10:11], v[108:109], v[176:177] op_sel:[1,0] op_sel_hi:[1,1]
	ds_read_u16 v28, v115 offset:2992
	s_waitcnt lgkmcnt(9)
	v_pk_fma_f32 v[4:5], v[130:131], v[178:179], v[4:5] op_sel_hi:[0,1,1]
	v_pk_fma_f32 v[6:7], v[130:131], v[180:181], v[6:7] op_sel:[1,0,0] op_sel_hi:[1,1,1]
	v_pk_fma_f32 v[8:9], v[132:133], v[182:183], v[8:9] op_sel_hi:[0,1,1]
	v_pk_fma_f32 v[10:11], v[132:133], v[184:185], v[10:11] op_sel:[1,0,0] op_sel_hi:[1,1,1]
	ds_read_u16 v29, v116 offset:2992
	s_waitcnt lgkmcnt(9)
	v_pk_fma_f32 v[4:5], v[140:141], v[186:187], v[4:5] op_sel_hi:[0,1,1]
	v_pk_fma_f32 v[6:7], v[140:141], v[188:189], v[6:7] op_sel:[1,0,0] op_sel_hi:[1,1,1]
	ds_read_b32 v30, v126 offset:44
	ds_read_b32 v31, v127 offset:44
	ds_read_b128 v[36:39], v122 offset:3072
	ds_read_b128 v[40:43], v122 offset:3088
	s_waitcnt lgkmcnt(9)
	v_lshlrev_b32_e32 v24, 16, v24
	v_lshlrev_b32_e32 v25, 16, v25
	v_pk_add_f32 v[12:13], v[4:5], v[6:7]
	v_pk_add_f32 v[14:15], v[8:9], v[10:11]
	s_nop 0
	v_pk_add_f32 v[12:13], v[12:13], v[14:15]
	s_nop 0
	v_pk_fma_f32 v[190:191], v[26:27], v[24:25], v[12:13] neg_lo:[0,0,1] neg_hi:[0,0,1]
	ds_read_b128 v[98:101], v122 offset:3104
	s_waitcnt lgkmcnt(9)
	v_pk_mul_f32 v[4:5], v[144:145], v[170:171] op_sel_hi:[0,1]
	v_pk_mul_f32 v[6:7], v[144:145], v[172:173] op_sel:[1,0] op_sel_hi:[1,1]
	v_pk_mul_f32 v[8:9], v[146:147], v[174:175] op_sel_hi:[0,1]
	v_pk_mul_f32 v[10:11], v[146:147], v[176:177] op_sel:[1,0] op_sel_hi:[1,1]
	ds_read_u16 v16, v115 offset:3264
	s_waitcnt lgkmcnt(9)
	v_pk_fma_f32 v[4:5], v[148:149], v[178:179], v[4:5] op_sel_hi:[0,1,1]
	v_pk_fma_f32 v[6:7], v[148:149], v[180:181], v[6:7] op_sel:[1,0,0] op_sel_hi:[1,1,1]
	v_pk_fma_f32 v[8:9], v[150:151], v[182:183], v[8:9] op_sel_hi:[0,1,1]
	v_pk_fma_f32 v[10:11], v[150:151], v[184:185], v[10:11] op_sel:[1,0,0] op_sel_hi:[1,1,1]
	ds_read_u16 v17, v116 offset:3264
	s_waitcnt lgkmcnt(9)
	v_pk_fma_f32 v[4:5], v[32:33], v[186:187], v[4:5] op_sel_hi:[0,1,1]
	v_pk_fma_f32 v[6:7], v[32:33], v[188:189], v[6:7] op_sel:[1,0,0] op_sel_hi:[1,1,1]
	v_pk_fma_f32 v[8:9], v[34:35], v[190:191], v[8:9] op_sel_hi:[0,1,1]
	ds_read_b32 v18, v126 offset:48
	ds_read_b32 v19, v127 offset:48
	ds_read_b128 v[102:105], v122 offset:3328
	ds_read_b128 v[106:109], v122 offset:3344
	s_waitcnt lgkmcnt(9)
	v_lshlrev_b32_e32 v28, 16, v28
	v_lshlrev_b32_e32 v29, 16, v29
	v_pk_add_f32 v[12:13], v[4:5], v[6:7]
	v_pk_add_f32 v[14:15], v[8:9], v[10:11]
	s_nop 0
	v_pk_add_f32 v[12:13], v[12:13], v[14:15]
	s_nop 0
	v_pk_fma_f32 v[192:193], v[30:31], v[28:29], v[12:13] neg_lo:[0,0,1] neg_hi:[0,0,1]
	ds_read_b128 v[130:133], v122 offset:3360
	s_waitcnt lgkmcnt(9)
	v_pk_mul_f32 v[4:5], v[36:37], v[170:171] op_sel_hi:[0,1]
	v_pk_mul_f32 v[6:7], v[36:37], v[172:173] op_sel:[1,0] op_sel_hi:[1,1]
	v_pk_mul_f32 v[8:9], v[38:39], v[174:175] op_sel_hi:[0,1]
	v_pk_mul_f32 v[10:11], v[38:39], v[176:177] op_sel:[1,0] op_sel_hi:[1,1]
	ds_read_b128 v[140:143], v122 offset:3376
	s_waitcnt lgkmcnt(9)
	v_pk_fma_f32 v[4:5], v[40:41], v[178:179], v[4:5] op_sel_hi:[0,1,1]
	v_pk_fma_f32 v[6:7], v[40:41], v[180:181], v[6:7] op_sel:[1,0,0] op_sel_hi:[1,1,1]
	v_pk_fma_f32 v[8:9], v[42:43], v[182:183], v[8:9] op_sel_hi:[0,1,1]
	v_pk_fma_f32 v[10:11], v[42:43], v[184:185], v[10:11] op_sel:[1,0,0] op_sel_hi:[1,1,1]
	ds_read_u16 v20, v115 offset:3536
	s_waitcnt lgkmcnt(9)
	v_pk_fma_f32 v[4:5], v[98:99], v[186:187], v[4:5] op_sel_hi:[0,1,1]
	v_pk_fma_f32 v[6:7], v[98:99], v[188:189], v[6:7] op_sel:[1,0,0] op_sel_hi:[1,1,1]
	v_pk_fma_f32 v[8:9], v[100:101], v[190:191], v[8:9] op_sel_hi:[0,1,1]
	v_pk_fma_f32 v[10:11], v[100:101], v[192:193], v[10:11] op_sel:[1,0,0] op_sel_hi:[1,1,1]
	ds_read_u16 v21, v116 offset:3536
	ds_read_b32 v22, v126 offset:52
	ds_read_b32 v23, v127 offset:52
	ds_read_b128 v[144:147], v122 offset:3584
	s_waitcnt lgkmcnt(9)
	v_lshlrev_b32_e32 v16, 16, v16
	v_lshlrev_b32_e32 v17, 16, v17
	v_pk_add_f32 v[12:13], v[4:5], v[6:7]
	v_pk_add_f32 v[14:15], v[8:9], v[10:11]
	s_nop 0
	v_pk_add_f32 v[12:13], v[12:13], v[14:15]
	s_nop 0
	v_pk_fma_f32 v[194:195], v[18:19], v[16:17], v[12:13] neg_lo:[0,0,1] neg_hi:[0,0,1]
	ds_read_b128 v[148:151], v122 offset:3600
	s_waitcnt lgkmcnt(9)
	v_pk_mul_f32 v[4:5], v[102:103], v[170:171] op_sel_hi:[0,1]
	v_pk_mul_f32 v[6:7], v[102:103], v[172:173] op_sel:[1,0] op_sel_hi:[1,1]
	v_pk_mul_f32 v[8:9], v[104:105], v[174:175] op_sel_hi:[0,1]
	v_pk_mul_f32 v[10:11], v[104:105], v[176:177] op_sel:[1,0] op_sel_hi:[1,1]
	ds_read_b128 v[32:35], v122 offset:3616
	s_waitcnt lgkmcnt(9)
	v_pk_fma_f32 v[4:5], v[106:107], v[178:179], v[4:5] op_sel_hi:[0,1,1]
	v_pk_fma_f32 v[6:7], v[106:107], v[180:181], v[6:7] op_sel:[1,0,0] op_sel_hi:[1,1,1]
	v_pk_fma_f32 v[8:9], v[108:109], v[182:183], v[8:9] op_sel_hi:[0,1,1]
	v_pk_fma_f32 v[10:11], v[108:109], v[184:185], v[10:11] op_sel:[1,0,0] op_sel_hi:[1,1,1]
	ds_read_b128 v[36:39], v122 offset:3632
	s_waitcnt lgkmcnt(9)
	v_pk_fma_f32 v[4:5], v[130:131], v[186:187], v[4:5] op_sel_hi:[0,1,1]
	v_pk_fma_f32 v[6:7], v[130:131], v[188:189], v[6:7] op_sel:[1,0,0] op_sel_hi:[1,1,1]
	v_pk_fma_f32 v[8:9], v[132:133], v[190:191], v[8:9] op_sel_hi:[0,1,1]
	v_pk_fma_f32 v[10:11], v[132:133], v[192:193], v[10:11] op_sel:[1,0,0] op_sel_hi:[1,1,1]
	ds_read_u16 v24, v115 offset:3808
	s_waitcnt lgkmcnt(9)
	v_pk_fma_f32 v[4:5], v[140:141], v[194:195], v[4:5] op_sel_hi:[0,1,1]
	ds_read_u16 v25, v116 offset:3808
	ds_read_b32 v26, v126 offset:56
	ds_read_b32 v27, v127 offset:56
	ds_read_b128 v[40:43], v122 offset:3840
	s_waitcnt lgkmcnt(9)
	v_lshlrev_b32_e32 v20, 16, v20
	v_lshlrev_b32_e32 v21, 16, v21
	v_pk_add_f32 v[12:13], v[4:5], v[6:7]
	v_pk_add_f32 v[14:15], v[8:9], v[10:11]
	s_nop 0
	v_pk_add_f32 v[12:13], v[12:13], v[14:15]
	s_nop 0
	v_pk_fma_f32 v[196:197], v[22:23], v[20:21], v[12:13] neg_lo:[0,0,1] neg_hi:[0,0,1]
	ds_read_b128 v[98:101], v122 offset:3856
	s_waitcnt lgkmcnt(9)
	v_pk_mul_f32 v[4:5], v[144:145], v[170:171] op_sel_hi:[0,1]
	v_pk_mul_f32 v[6:7], v[144:145], v[172:173] op_sel:[1,0] op_sel_hi:[1,1]
	v_pk_mul_f32 v[8:9], v[146:147], v[174:175] op_sel_hi:[0,1]
	v_pk_mul_f32 v[10:11], v[146:147], v[176:177] op_sel:[1,0] op_sel_hi:[1,1]
	ds_read_b128 v[102:105], v122 offset:3872
	s_waitcnt lgkmcnt(9)
	v_pk_fma_f32 v[4:5], v[148:149], v[178:179], v[4:5] op_sel_hi:[0,1,1]
	v_pk_fma_f32 v[6:7], v[148:149], v[180:181], v[6:7] op_sel:[1,0,0] op_sel_hi:[1,1,1]
	v_pk_fma_f32 v[8:9], v[150:151], v[182:183], v[8:9] op_sel_hi:[0,1,1]
	v_pk_fma_f32 v[10:11], v[150:151], v[184:185], v[10:11] op_sel:[1,0,0] op_sel_hi:[1,1,1]
	ds_read_b128 v[106:109], v122 offset:3888
	s_waitcnt lgkmcnt(9)
	v_pk_fma_f32 v[4:5], v[32:33], v[186:187], v[4:5] op_sel_hi:[0,1,1]
	v_pk_fma_f32 v[6:7], v[32:33], v[188:189], v[6:7] op_sel:[1,0,0] op_sel_hi:[1,1,1]
	v_pk_fma_f32 v[8:9], v[34:35], v[190:191], v[8:9] op_sel_hi:[0,1,1]
	v_pk_fma_f32 v[10:11], v[34:35], v[192:193], v[10:11] op_sel:[1,0,0] op_sel_hi:[1,1,1]
	ds_read_u16 v28, v115 offset:4080
	s_waitcnt lgkmcnt(9)
	v_pk_fma_f32 v[4:5], v[36:37], v[194:195], v[4:5] op_sel_hi:[0,1,1]
	v_pk_fma_f32 v[6:7], v[36:37], v[196:197], v[6:7] op_sel:[1,0,0] op_sel_hi:[1,1,1]
	ds_read_u16 v29, v116 offset:4080
	ds_read_b32 v30, v126 offset:60
	ds_read_b32 v31, v127 offset:60
	ds_read_b128 v[130:133], v122 offset:4096
	s_waitcnt lgkmcnt(9)
	v_lshlrev_b32_e32 v24, 16, v24
	v_lshlrev_b32_e32 v25, 16, v25
	v_pk_add_f32 v[12:13], v[4:5], v[6:7]
	v_pk_add_f32 v[14:15], v[8:9], v[10:11]
	s_nop 0
	v_pk_add_f32 v[12:13], v[12:13], v[14:15]
	s_nop 0
	v_pk_fma_f32 v[198:199], v[26:27], v[24:25], v[12:13] neg_lo:[0,0,1] neg_hi:[0,0,1]
	ds_read_b128 v[140:143], v122 offset:4112
	s_waitcnt lgkmcnt(9)
	v_pk_mul_f32 v[4:5], v[40:41], v[170:171] op_sel_hi:[0,1]
	v_pk_mul_f32 v[6:7], v[40:41], v[172:173] op_sel:[1,0] op_sel_hi:[1,1]
	v_pk_mul_f32 v[8:9], v[42:43], v[174:175] op_sel_hi:[0,1]
	v_pk_mul_f32 v[10:11], v[42:43], v[176:177] op_sel:[1,0] op_sel_hi:[1,1]
	ds_read_b128 v[144:147], v122 offset:4128
	s_waitcnt lgkmcnt(9)
	v_pk_fma_f32 v[4:5], v[98:99], v[178:179], v[4:5] op_sel_hi:[0,1,1]
	v_pk_fma_f32 v[6:7], v[98:99], v[180:181], v[6:7] op_sel:[1,0,0] op_sel_hi:[1,1,1]
	v_pk_fma_f32 v[8:9], v[100:101], v[182:183], v[8:9] op_sel_hi:[0,1,1]
	v_pk_fma_f32 v[10:11], v[100:101], v[184:185], v[10:11] op_sel:[1,0,0] op_sel_hi:[1,1,1]
	ds_read_b128 v[148:151], v122 offset:4144
	s_waitcnt lgkmcnt(9)
	v_pk_fma_f32 v[4:5], v[102:103], v[186:187], v[4:5] op_sel_hi:[0,1,1]
	v_pk_fma_f32 v[6:7], v[102:103], v[188:189], v[6:7] op_sel:[1,0,0] op_sel_hi:[1,1,1]
	v_pk_fma_f32 v[8:9], v[104:105], v[190:191], v[8:9] op_sel_hi:[0,1,1]
	v_pk_fma_f32 v[10:11], v[104:105], v[192:193], v[10:11] op_sel:[1,0,0] op_sel_hi:[1,1,1]
	ds_read_u16 v16, v115 offset:4352
	s_waitcnt lgkmcnt(9)
	v_pk_fma_f32 v[4:5], v[106:107], v[194:195], v[4:5] op_sel_hi:[0,1,1]
	v_pk_fma_f32 v[6:7], v[106:107], v[196:197], v[6:7] op_sel:[1,0,0] op_sel_hi:[1,1,1]
	v_pk_fma_f32 v[8:9], v[108:109], v[198:199], v[8:9] op_sel_hi:[0,1,1]
	ds_read_u16 v17, v116 offset:4352
	ds_read_b32 v18, v126 offset:64
	ds_read_b32 v19, v127 offset:64
	ds_read_b128 v[32:35], v122 offset:4352
	s_waitcnt lgkmcnt(9)
	v_lshlrev_b32_e32 v28, 16, v28
	v_lshlrev_b32_e32 v29, 16, v29
	v_pk_add_f32 v[12:13], v[4:5], v[6:7]
	v_pk_add_f32 v[14:15], v[8:9], v[10:11]
	s_nop 0
	v_pk_add_f32 v[12:13], v[12:13], v[14:15]
	s_nop 0
	v_pk_fma_f32 v[200:201], v[30:31], v[28:29], v[12:13] neg_lo:[0,0,1] neg_hi:[0,0,1]
	ds_read_b128 v[36:39], v122 offset:4368
	s_waitcnt lgkmcnt(9)
	v_pk_mul_f32 v[4:5], v[130:131], v[170:171] op_sel_hi:[0,1]
	v_pk_mul_f32 v[6:7], v[130:131], v[172:173] op_sel:[1,0] op_sel_hi:[1,1]
	v_pk_mul_f32 v[8:9], v[132:133], v[174:175] op_sel_hi:[0,1]
	v_pk_mul_f32 v[10:11], v[132:133], v[176:177] op_sel:[1,0] op_sel_hi:[1,1]
	ds_read_b128 v[40:43], v122 offset:4384
	s_waitcnt lgkmcnt(9)
	v_pk_fma_f32 v[4:5], v[140:141], v[178:179], v[4:5] op_sel_hi:[0,1,1]
	v_pk_fma_f32 v[6:7], v[140:141], v[180:181], v[6:7] op_sel:[1,0,0] op_sel_hi:[1,1,1]
	v_pk_fma_f32 v[8:9], v[142:143], v[182:183], v[8:9] op_sel_hi:[0,1,1]
	v_pk_fma_f32 v[10:11], v[142:143], v[184:185], v[10:11] op_sel:[1,0,0] op_sel_hi:[1,1,1]
	ds_read_b128 v[98:101], v122 offset:4400
	s_waitcnt lgkmcnt(9)
	v_pk_fma_f32 v[4:5], v[144:145], v[186:187], v[4:5] op_sel_hi:[0,1,1]
	v_pk_fma_f32 v[6:7], v[144:145], v[188:189], v[6:7] op_sel:[1,0,0] op_sel_hi:[1,1,1]
	v_pk_fma_f32 v[8:9], v[146:147], v[190:191], v[8:9] op_sel_hi:[0,1,1]
	v_pk_fma_f32 v[10:11], v[146:147], v[192:193], v[10:11] op_sel:[1,0,0] op_sel_hi:[1,1,1]
	ds_read_b128 v[102:105], v122 offset:4416
	s_waitcnt lgkmcnt(9)
	v_pk_fma_f32 v[4:5], v[148:149], v[194:195], v[4:5] op_sel_hi:[0,1,1]
	v_pk_fma_f32 v[6:7], v[148:149], v[196:197], v[6:7] op_sel:[1,0,0] op_sel_hi:[1,1,1]
	v_pk_fma_f32 v[8:9], v[150:151], v[198:199], v[8:9] op_sel_hi:[0,1,1]
	v_pk_fma_f32 v[10:11], v[150:151], v[200:201], v[10:11] op_sel:[1,0,0] op_sel_hi:[1,1,1]
	ds_read_u16 v20, v115 offset:4624
	ds_read_u16 v21, v116 offset:4624
	ds_read_b32 v22, v126 offset:68
	ds_read_b32 v23, v127 offset:68
	s_waitcnt lgkmcnt(9)
	v_lshlrev_b32_e32 v16, 16, v16
	v_lshlrev_b32_e32 v17, 16, v17
	v_pk_add_f32 v[12:13], v[4:5], v[6:7]
	v_pk_add_f32 v[14:15], v[8:9], v[10:11]
	s_nop 0
	v_pk_add_f32 v[12:13], v[12:13], v[14:15]
	s_nop 0
	v_pk_fma_f32 v[202:203], v[18:19], v[16:17], v[12:13] neg_lo:[0,0,1] neg_hi:[0,0,1]
	ds_read_b128 v[106:109], v122 offset:4608
	s_waitcnt lgkmcnt(9)
	v_pk_mul_f32 v[4:5], v[32:33], v[170:171] op_sel_hi:[0,1]
	v_pk_mul_f32 v[6:7], v[32:33], v[172:173] op_sel:[1,0] op_sel_hi:[1,1]
	v_pk_mul_f32 v[8:9], v[34:35], v[174:175] op_sel_hi:[0,1]
	v_pk_mul_f32 v[10:11], v[34:35], v[176:177] op_sel:[1,0] op_sel_hi:[1,1]
	ds_read_b128 v[130:133], v122 offset:4624
	s_waitcnt lgkmcnt(9)
	v_pk_fma_f32 v[4:5], v[36:37], v[178:179], v[4:5] op_sel_hi:[0,1,1]
	v_pk_fma_f32 v[6:7], v[36:37], v[180:181], v[6:7] op_sel:[1,0,0] op_sel_hi:[1,1,1]
	v_pk_fma_f32 v[8:9], v[38:39], v[182:183], v[8:9] op_sel_hi:[0,1,1]
	v_pk_fma_f32 v[10:11], v[38:39], v[184:185], v[10:11] op_sel:[1,0,0] op_sel_hi:[1,1,1]
	ds_read_b128 v[140:143], v122 offset:4640
	s_waitcnt lgkmcnt(9)
	v_pk_fma_f32 v[4:5], v[40:41], v[186:187], v[4:5] op_sel_hi:[0,1,1]
	v_pk_fma_f32 v[6:7], v[40:41], v[188:189], v[6:7] op_sel:[1,0,0] op_sel_hi:[1,1,1]
	v_pk_fma_f32 v[8:9], v[42:43], v[190:191], v[8:9] op_sel_hi:[0,1,1]
	v_pk_fma_f32 v[10:11], v[42:43], v[192:193], v[10:11] op_sel:[1,0,0] op_sel_hi:[1,1,1]
	ds_read_b128 v[144:147], v122 offset:4656
	s_waitcnt lgkmcnt(9)
	v_pk_fma_f32 v[4:5], v[98:99], v[194:195], v[4:5] op_sel_hi:[0,1,1]
	v_pk_fma_f32 v[6:7], v[98:99], v[196:197], v[6:7] op_sel:[1,0,0] op_sel_hi:[1,1,1]
	v_pk_fma_f32 v[8:9], v[100:101], v[198:199], v[8:9] op_sel_hi:[0,1,1]
	v_pk_fma_f32 v[10:11], v[100:101], v[200:201], v[10:11] op_sel:[1,0,0] op_sel_hi:[1,1,1]
	ds_read_b128 v[148:151], v122 offset:4672
	s_waitcnt lgkmcnt(9)
	v_pk_fma_f32 v[4:5], v[102:103], v[202:203], v[4:5] op_sel_hi:[0,1,1]
	ds_read_u16 v24, v115 offset:4896
	ds_read_u16 v25, v116 offset:4896
	ds_read_b32 v26, v126 offset:72
	ds_read_b32 v27, v127 offset:72
	s_waitcnt lgkmcnt(9)
	v_lshlrev_b32_e32 v20, 16, v20
	v_lshlrev_b32_e32 v21, 16, v21
	v_pk_add_f32 v[12:13], v[4:5], v[6:7]
	v_pk_add_f32 v[14:15], v[8:9], v[10:11]
	s_nop 0
	v_pk_add_f32 v[12:13], v[12:13], v[14:15]
	s_nop 0
	v_pk_fma_f32 v[204:205], v[22:23], v[20:21], v[12:13] neg_lo:[0,0,1] neg_hi:[0,0,1]
	ds_read_b128 v[32:35], v122 offset:4864
	s_waitcnt lgkmcnt(9)
	v_pk_mul_f32 v[4:5], v[106:107], v[170:171] op_sel_hi:[0,1]
	v_pk_mul_f32 v[6:7], v[106:107], v[172:173] op_sel:[1,0] op_sel_hi:[1,1]
	v_pk_mul_f32 v[8:9], v[108:109], v[174:175] op_sel_hi:[0,1]
	v_pk_mul_f32 v[10:11], v[108:109], v[176:177] op_sel:[1,0] op_sel_hi:[1,1]
	ds_read_b128 v[36:39], v122 offset:4880
	s_waitcnt lgkmcnt(9)
	v_pk_fma_f32 v[4:5], v[130:131], v[178:179], v[4:5] op_sel_hi:[0,1,1]
	v_pk_fma_f32 v[6:7], v[130:131], v[180:181], v[6:7] op_sel:[1,0,0] op_sel_hi:[1,1,1]
	v_pk_fma_f32 v[8:9], v[132:133], v[182:183], v[8:9] op_sel_hi:[0,1,1]
	v_pk_fma_f32 v[10:11], v[132:133], v[184:185], v[10:11] op_sel:[1,0,0] op_sel_hi:[1,1,1]
	ds_read_b128 v[40:43], v122 offset:4896
	s_waitcnt lgkmcnt(9)
	v_pk_fma_f32 v[4:5], v[140:141], v[186:187], v[4:5] op_sel_hi:[0,1,1]
	v_pk_fma_f32 v[6:7], v[140:141], v[188:189], v[6:7] op_sel:[1,0,0] op_sel_hi:[1,1,1]
	v_pk_fma_f32 v[8:9], v[142:143], v[190:191], v[8:9] op_sel_hi:[0,1,1]
	v_pk_fma_f32 v[10:11], v[142:143], v[192:193], v[10:11] op_sel:[1,0,0] op_sel_hi:[1,1,1]
	ds_read_b128 v[98:101], v122 offset:4912
	s_waitcnt lgkmcnt(9)
	v_pk_fma_f32 v[4:5], v[144:145], v[194:195], v[4:5] op_sel_hi:[0,1,1]
	v_pk_fma_f32 v[6:7], v[144:145], v[196:197], v[6:7] op_sel:[1,0,0] op_sel_hi:[1,1,1]
	v_pk_fma_f32 v[8:9], v[146:147], v[198:199], v[8:9] op_sel_hi:[0,1,1]
	v_pk_fma_f32 v[10:11], v[146:147], v[200:201], v[10:11] op_sel:[1,0,0] op_sel_hi:[1,1,1]
	ds_read_b128 v[102:105], v122 offset:4928
	s_waitcnt lgkmcnt(9)
	v_pk_fma_f32 v[4:5], v[148:149], v[202:203], v[4:5] op_sel_hi:[0,1,1]
	v_pk_fma_f32 v[6:7], v[148:149], v[204:205], v[6:7] op_sel:[1,0,0] op_sel_hi:[1,1,1]
	ds_read_u16 v28, v115 offset:5168
	ds_read_u16 v29, v116 offset:5168
	ds_read_b32 v30, v126 offset:76
	ds_read_b32 v31, v127 offset:76
	s_waitcnt lgkmcnt(9)
	v_lshlrev_b32_e32 v24, 16, v24
	v_lshlrev_b32_e32 v25, 16, v25
	v_pk_add_f32 v[12:13], v[4:5], v[6:7]
	v_pk_add_f32 v[14:15], v[8:9], v[10:11]
	s_nop 0
	v_pk_add_f32 v[12:13], v[12:13], v[14:15]
	s_nop 0
	v_pk_fma_f32 v[206:207], v[26:27], v[24:25], v[12:13] neg_lo:[0,0,1] neg_hi:[0,0,1]
	ds_read_b128 v[106:109], v122 offset:5120
	s_waitcnt lgkmcnt(9)
	v_pk_mul_f32 v[4:5], v[32:33], v[170:171] op_sel_hi:[0,1]
	v_pk_mul_f32 v[6:7], v[32:33], v[172:173] op_sel:[1,0] op_sel_hi:[1,1]
	v_pk_mul_f32 v[8:9], v[34:35], v[174:175] op_sel_hi:[0,1]
	v_pk_mul_f32 v[10:11], v[34:35], v[176:177] op_sel:[1,0] op_sel_hi:[1,1]
	ds_read_b128 v[130:133], v122 offset:5136
	s_waitcnt lgkmcnt(9)
	v_pk_fma_f32 v[4:5], v[36:37], v[178:179], v[4:5] op_sel_hi:[0,1,1]
	v_pk_fma_f32 v[6:7], v[36:37], v[180:181], v[6:7] op_sel:[1,0,0] op_sel_hi:[1,1,1]
	v_pk_fma_f32 v[8:9], v[38:39], v[182:183], v[8:9] op_sel_hi:[0,1,1]
	v_pk_fma_f32 v[10:11], v[38:39], v[184:185], v[10:11] op_sel:[1,0,0] op_sel_hi:[1,1,1]
	ds_read_b128 v[140:143], v122 offset:5152
	s_waitcnt lgkmcnt(9)
	v_pk_fma_f32 v[4:5], v[40:41], v[186:187], v[4:5] op_sel_hi:[0,1,1]
	v_pk_fma_f32 v[6:7], v[40:41], v[188:189], v[6:7] op_sel:[1,0,0] op_sel_hi:[1,1,1]
	v_pk_fma_f32 v[8:9], v[42:43], v[190:191], v[8:9] op_sel_hi:[0,1,1]
	v_pk_fma_f32 v[10:11], v[42:43], v[192:193], v[10:11] op_sel:[1,0,0] op_sel_hi:[1,1,1]
	ds_read_b128 v[144:147], v122 offset:5168
	s_waitcnt lgkmcnt(9)
	v_pk_fma_f32 v[4:5], v[98:99], v[194:195], v[4:5] op_sel_hi:[0,1,1]
	v_pk_fma_f32 v[6:7], v[98:99], v[196:197], v[6:7] op_sel:[1,0,0] op_sel_hi:[1,1,1]
	v_pk_fma_f32 v[8:9], v[100:101], v[198:199], v[8:9] op_sel_hi:[0,1,1]
	v_pk_fma_f32 v[10:11], v[100:101], v[200:201], v[10:11] op_sel:[1,0,0] op_sel_hi:[1,1,1]
	ds_read_b128 v[148:151], v122 offset:5184
	s_waitcnt lgkmcnt(9)
	v_pk_fma_f32 v[4:5], v[102:103], v[202:203], v[4:5] op_sel_hi:[0,1,1]
	v_pk_fma_f32 v[6:7], v[102:103], v[204:205], v[6:7] op_sel:[1,0,0] op_sel_hi:[1,1,1]
	v_pk_fma_f32 v[8:9], v[104:105], v[206:207], v[8:9] op_sel_hi:[0,1,1]
	ds_read_u16 v16, v115 offset:5440
	ds_read_u16 v17, v116 offset:5440
	ds_read_b32 v18, v126 offset:80
	ds_read_b32 v19, v127 offset:80
	s_waitcnt lgkmcnt(9)
	v_lshlrev_b32_e32 v28, 16, v28
	v_lshlrev_b32_e32 v29, 16, v29
	v_pk_add_f32 v[12:13], v[4:5], v[6:7]
	v_pk_add_f32 v[14:15], v[8:9], v[10:11]
	s_nop 0
	v_pk_add_f32 v[12:13], v[12:13], v[14:15]
	s_nop 0
	v_pk_fma_f32 v[208:209], v[30:31], v[28:29], v[12:13] neg_lo:[0,0,1] neg_hi:[0,0,1]
	ds_read_b128 v[32:35], v122 offset:5376
	s_waitcnt lgkmcnt(9)
	v_pk_mul_f32 v[4:5], v[106:107], v[170:171] op_sel_hi:[0,1]
	v_pk_mul_f32 v[6:7], v[106:107], v[172:173] op_sel:[1,0] op_sel_hi:[1,1]
	v_pk_mul_f32 v[8:9], v[108:109], v[174:175] op_sel_hi:[0,1]
	v_pk_mul_f32 v[10:11], v[108:109], v[176:177] op_sel:[1,0] op_sel_hi:[1,1]
	ds_read_b128 v[36:39], v122 offset:5392
	s_waitcnt lgkmcnt(9)
	v_pk_fma_f32 v[4:5], v[130:131], v[178:179], v[4:5] op_sel_hi:[0,1,1]
	v_pk_fma_f32 v[6:7], v[130:131], v[180:181], v[6:7] op_sel:[1,0,0] op_sel_hi:[1,1,1]
	v_pk_fma_f32 v[8:9], v[132:133], v[182:183], v[8:9] op_sel_hi:[0,1,1]
	v_pk_fma_f32 v[10:11], v[132:133], v[184:185], v[10:11] op_sel:[1,0,0] op_sel_hi:[1,1,1]
	ds_read_b128 v[40:43], v122 offset:5408
	s_waitcnt lgkmcnt(9)
	v_pk_fma_f32 v[4:5], v[140:141], v[186:187], v[4:5] op_sel_hi:[0,1,1]
	v_pk_fma_f32 v[6:7], v[140:141], v[188:189], v[6:7] op_sel:[1,0,0] op_sel_hi:[1,1,1]
	v_pk_fma_f32 v[8:9], v[142:143], v[190:191], v[8:9] op_sel_hi:[0,1,1]
	v_pk_fma_f32 v[10:11], v[142:143], v[192:193], v[10:11] op_sel:[1,0,0] op_sel_hi:[1,1,1]
	ds_read_b128 v[98:101], v122 offset:5424
	s_waitcnt lgkmcnt(9)
	v_pk_fma_f32 v[4:5], v[144:145], v[194:195], v[4:5] op_sel_hi:[0,1,1]
	v_pk_fma_f32 v[6:7], v[144:145], v[196:197], v[6:7] op_sel:[1,0,0] op_sel_hi:[1,1,1]
	v_pk_fma_f32 v[8:9], v[146:147], v[198:199], v[8:9] op_sel_hi:[0,1,1]
	v_pk_fma_f32 v[10:11], v[146:147], v[200:201], v[10:11] op_sel:[1,0,0] op_sel_hi:[1,1,1]
	ds_read_b128 v[102:105], v122 offset:5440
	s_waitcnt lgkmcnt(9)
	v_pk_fma_f32 v[4:5], v[148:149], v[202:203], v[4:5] op_sel_hi:[0,1,1]
	v_pk_fma_f32 v[6:7], v[148:149], v[204:205], v[6:7] op_sel:[1,0,0] op_sel_hi:[1,1,1]
	v_pk_fma_f32 v[8:9], v[150:151], v[206:207], v[8:9] op_sel_hi:[0,1,1]
	v_pk_fma_f32 v[10:11], v[150:151], v[208:209], v[10:11] op_sel:[1,0,0] op_sel_hi:[1,1,1]
	ds_read_b128 v[106:109], v122 offset:5456
	ds_read_u16 v20, v115 offset:5712
	ds_read_u16 v21, v116 offset:5712
	ds_read_b32 v22, v126 offset:84
	s_waitcnt lgkmcnt(9)
	v_lshlrev_b32_e32 v16, 16, v16
	v_lshlrev_b32_e32 v17, 16, v17
	v_pk_add_f32 v[12:13], v[4:5], v[6:7]
	v_pk_add_f32 v[14:15], v[8:9], v[10:11]
	s_nop 0
	v_pk_add_f32 v[12:13], v[12:13], v[14:15]
	s_nop 0
	v_pk_fma_f32 v[210:211], v[18:19], v[16:17], v[12:13] neg_lo:[0,0,1] neg_hi:[0,0,1]
	ds_read_b32 v23, v127 offset:84
	s_waitcnt lgkmcnt(9)
	v_pk_mul_f32 v[4:5], v[32:33], v[170:171] op_sel_hi:[0,1]
	v_pk_mul_f32 v[6:7], v[32:33], v[172:173] op_sel:[1,0] op_sel_hi:[1,1]
	v_pk_mul_f32 v[8:9], v[34:35], v[174:175] op_sel_hi:[0,1]
	v_pk_mul_f32 v[10:11], v[34:35], v[176:177] op_sel:[1,0] op_sel_hi:[1,1]
	ds_read_b128 v[130:133], v122 offset:5632
	s_waitcnt lgkmcnt(9)
	v_pk_fma_f32 v[4:5], v[36:37], v[178:179], v[4:5] op_sel_hi:[0,1,1]
	v_pk_fma_f32 v[6:7], v[36:37], v[180:181], v[6:7] op_sel:[1,0,0] op_sel_hi:[1,1,1]
	v_pk_fma_f32 v[8:9], v[38:39], v[182:183], v[8:9] op_sel_hi:[0,1,1]
	v_pk_fma_f32 v[10:11], v[38:39], v[184:185], v[10:11] op_sel:[1,0,0] op_sel_hi:[1,1,1]
	ds_read_b128 v[140:143], v122 offset:5648
	s_waitcnt lgkmcnt(9)
	v_pk_fma_f32 v[4:5], v[40:41], v[186:187], v[4:5] op_sel_hi:[0,1,1]
	v_pk_fma_f32 v[6:7], v[40:41], v[188:189], v[6:7] op_sel:[1,0,0] op_sel_hi:[1,1,1]
	v_pk_fma_f32 v[8:9], v[42:43], v[190:191], v[8:9] op_sel_hi:[0,1,1]
	v_pk_fma_f32 v[10:11], v[42:43], v[192:193], v[10:11] op_sel:[1,0,0] op_sel_hi:[1,1,1]
	ds_read_b128 v[144:147], v122 offset:5664
	s_waitcnt lgkmcnt(9)
	v_pk_fma_f32 v[4:5], v[98:99], v[194:195], v[4:5] op_sel_hi:[0,1,1]
	v_pk_fma_f32 v[6:7], v[98:99], v[196:197], v[6:7] op_sel:[1,0,0] op_sel_hi:[1,1,1]
	v_pk_fma_f32 v[8:9], v[100:101], v[198:199], v[8:9] op_sel_hi:[0,1,1]
	v_pk_fma_f32 v[10:11], v[100:101], v[200:201], v[10:11] op_sel:[1,0,0] op_sel_hi:[1,1,1]
	ds_read_b128 v[148:151], v122 offset:5680
	s_waitcnt lgkmcnt(9)
	v_pk_fma_f32 v[4:5], v[102:103], v[202:203], v[4:5] op_sel_hi:[0,1,1]
	v_pk_fma_f32 v[6:7], v[102:103], v[204:205], v[6:7] op_sel:[1,0,0] op_sel_hi:[1,1,1]
	v_pk_fma_f32 v[8:9], v[104:105], v[206:207], v[8:9] op_sel_hi:[0,1,1]
	v_pk_fma_f32 v[10:11], v[104:105], v[208:209], v[10:11] op_sel:[1,0,0] op_sel_hi:[1,1,1]
	ds_read_b128 v[32:35], v122 offset:5696
	s_waitcnt lgkmcnt(9)
	v_pk_fma_f32 v[4:5], v[106:107], v[210:211], v[4:5] op_sel_hi:[0,1,1]
	ds_read_b128 v[36:39], v122 offset:5712
	ds_read_u16 v24, v115 offset:5984
	ds_read_u16 v25, v116 offset:5984
	ds_read_b32 v26, v126 offset:88
	s_waitcnt lgkmcnt(9)
	v_lshlrev_b32_e32 v20, 16, v20
	v_lshlrev_b32_e32 v21, 16, v21
	v_pk_add_f32 v[12:13], v[4:5], v[6:7]
	v_pk_add_f32 v[14:15], v[8:9], v[10:11]
	s_nop 0
	v_pk_add_f32 v[12:13], v[12:13], v[14:15]
	s_nop 0
	v_pk_fma_f32 v[212:213], v[22:23], v[20:21], v[12:13] neg_lo:[0,0,1] neg_hi:[0,0,1]
	ds_read_b32 v27, v127 offset:88
	s_waitcnt lgkmcnt(9)
	v_pk_mul_f32 v[4:5], v[130:131], v[170:171] op_sel_hi:[0,1]
	v_pk_mul_f32 v[6:7], v[130:131], v[172:173] op_sel:[1,0] op_sel_hi:[1,1]
	v_pk_mul_f32 v[8:9], v[132:133], v[174:175] op_sel_hi:[0,1]
	v_pk_mul_f32 v[10:11], v[132:133], v[176:177] op_sel:[1,0] op_sel_hi:[1,1]
	ds_read_b128 v[40:43], v122 offset:5888
	s_waitcnt lgkmcnt(9)
	v_pk_fma_f32 v[4:5], v[140:141], v[178:179], v[4:5] op_sel_hi:[0,1,1]
	v_pk_fma_f32 v[6:7], v[140:141], v[180:181], v[6:7] op_sel:[1,0,0] op_sel_hi:[1,1,1]
	v_pk_fma_f32 v[8:9], v[142:143], v[182:183], v[8:9] op_sel_hi:[0,1,1]
	v_pk_fma_f32 v[10:11], v[142:143], v[184:185], v[10:11] op_sel:[1,0,0] op_sel_hi:[1,1,1]
	ds_read_b128 v[98:101], v122 offset:5904
	s_waitcnt lgkmcnt(9)
	v_pk_fma_f32 v[4:5], v[144:145], v[186:187], v[4:5] op_sel_hi:[0,1,1]
	v_pk_fma_f32 v[6:7], v[144:145], v[188:189], v[6:7] op_sel:[1,0,0] op_sel_hi:[1,1,1]
	v_pk_fma_f32 v[8:9], v[146:147], v[190:191], v[8:9] op_sel_hi:[0,1,1]
	v_pk_fma_f32 v[10:11], v[146:147], v[192:193], v[10:11] op_sel:[1,0,0] op_sel_hi:[1,1,1]
	ds_read_b128 v[102:105], v122 offset:5920
	s_waitcnt lgkmcnt(9)
	v_pk_fma_f32 v[4:5], v[148:149], v[194:195], v[4:5] op_sel_hi:[0,1,1]
	v_pk_fma_f32 v[6:7], v[148:149], v[196:197], v[6:7] op_sel:[1,0,0] op_sel_hi:[1,1,1]
	v_pk_fma_f32 v[8:9], v[150:151], v[198:199], v[8:9] op_sel_hi:[0,1,1]
	v_pk_fma_f32 v[10:11], v[150:151], v[200:201], v[10:11] op_sel:[1,0,0] op_sel_hi:[1,1,1]
	ds_read_b128 v[106:109], v122 offset:5936
	s_waitcnt lgkmcnt(9)
	v_pk_fma_f32 v[4:5], v[32:33], v[202:203], v[4:5] op_sel_hi:[0,1,1]
	v_pk_fma_f32 v[6:7], v[32:33], v[204:205], v[6:7] op_sel:[1,0,0] op_sel_hi:[1,1,1]
	v_pk_fma_f32 v[8:9], v[34:35], v[206:207], v[8:9] op_sel_hi:[0,1,1]
	v_pk_fma_f32 v[10:11], v[34:35], v[208:209], v[10:11] op_sel:[1,0,0] op_sel_hi:[1,1,1]
	ds_read_b128 v[130:133], v122 offset:5952
	s_waitcnt lgkmcnt(9)
	v_pk_fma_f32 v[4:5], v[36:37], v[210:211], v[4:5] op_sel_hi:[0,1,1]
	v_pk_fma_f32 v[6:7], v[36:37], v[212:213], v[6:7] op_sel:[1,0,0] op_sel_hi:[1,1,1]
	ds_read_b128 v[140:143], v122 offset:5968
	ds_read_u16 v28, v115 offset:6256
	ds_read_u16 v29, v116 offset:6256
	ds_read_b32 v30, v126 offset:92
	s_waitcnt lgkmcnt(9)
	v_lshlrev_b32_e32 v24, 16, v24
	v_lshlrev_b32_e32 v25, 16, v25
	v_pk_add_f32 v[12:13], v[4:5], v[6:7]
	v_pk_add_f32 v[14:15], v[8:9], v[10:11]
	s_nop 0
	v_pk_add_f32 v[12:13], v[12:13], v[14:15]
	s_nop 0
	v_pk_fma_f32 v[214:215], v[26:27], v[24:25], v[12:13] neg_lo:[0,0,1] neg_hi:[0,0,1]
	ds_read_b32 v31, v127 offset:92
	s_waitcnt lgkmcnt(9)
	v_pk_mul_f32 v[4:5], v[40:41], v[170:171] op_sel_hi:[0,1]
	v_pk_mul_f32 v[6:7], v[40:41], v[172:173] op_sel:[1,0] op_sel_hi:[1,1]
	v_pk_mul_f32 v[8:9], v[42:43], v[174:175] op_sel_hi:[0,1]
	v_pk_mul_f32 v[10:11], v[42:43], v[176:177] op_sel:[1,0] op_sel_hi:[1,1]
	ds_read_b128 v[144:147], v122 offset:6144
	s_waitcnt lgkmcnt(9)
	v_pk_fma_f32 v[4:5], v[98:99], v[178:179], v[4:5] op_sel_hi:[0,1,1]
	v_pk_fma_f32 v[6:7], v[98:99], v[180:181], v[6:7] op_sel:[1,0,0] op_sel_hi:[1,1,1]
	v_pk_fma_f32 v[8:9], v[100:101], v[182:183], v[8:9] op_sel_hi:[0,1,1]
	v_pk_fma_f32 v[10:11], v[100:101], v[184:185], v[10:11] op_sel:[1,0,0] op_sel_hi:[1,1,1]
	ds_read_b128 v[148:151], v122 offset:6160
	s_waitcnt lgkmcnt(9)
	v_pk_fma_f32 v[4:5], v[102:103], v[186:187], v[4:5] op_sel_hi:[0,1,1]
	v_pk_fma_f32 v[6:7], v[102:103], v[188:189], v[6:7] op_sel:[1,0,0] op_sel_hi:[1,1,1]
	v_pk_fma_f32 v[8:9], v[104:105], v[190:191], v[8:9] op_sel_hi:[0,1,1]
	v_pk_fma_f32 v[10:11], v[104:105], v[192:193], v[10:11] op_sel:[1,0,0] op_sel_hi:[1,1,1]
	ds_read_b128 v[32:35], v122 offset:6176
	s_waitcnt lgkmcnt(9)
	v_pk_fma_f32 v[4:5], v[106:107], v[194:195], v[4:5] op_sel_hi:[0,1,1]
	v_pk_fma_f32 v[6:7], v[106:107], v[196:197], v[6:7] op_sel:[1,0,0] op_sel_hi:[1,1,1]
	v_pk_fma_f32 v[8:9], v[108:109], v[198:199], v[8:9] op_sel_hi:[0,1,1]
	v_pk_fma_f32 v[10:11], v[108:109], v[200:201], v[10:11] op_sel:[1,0,0] op_sel_hi:[1,1,1]
	ds_read_b128 v[36:39], v122 offset:6192
	s_waitcnt lgkmcnt(9)
	v_pk_fma_f32 v[4:5], v[130:131], v[202:203], v[4:5] op_sel_hi:[0,1,1]
	v_pk_fma_f32 v[6:7], v[130:131], v[204:205], v[6:7] op_sel:[1,0,0] op_sel_hi:[1,1,1]
	v_pk_fma_f32 v[8:9], v[132:133], v[206:207], v[8:9] op_sel_hi:[0,1,1]
	v_pk_fma_f32 v[10:11], v[132:133], v[208:209], v[10:11] op_sel:[1,0,0] op_sel_hi:[1,1,1]
	ds_read_b128 v[40:43], v122 offset:6208
	s_waitcnt lgkmcnt(9)
	v_pk_fma_f32 v[4:5], v[140:141], v[210:211], v[4:5] op_sel_hi:[0,1,1]
	v_pk_fma_f32 v[6:7], v[140:141], v[212:213], v[6:7] op_sel:[1,0,0] op_sel_hi:[1,1,1]
	v_pk_fma_f32 v[8:9], v[142:143], v[214:215], v[8:9] op_sel_hi:[0,1,1]
	ds_read_b128 v[98:101], v122 offset:6224
	ds_read_u16 v16, v115 offset:6528
	ds_read_u16 v17, v116 offset:6528
	ds_read_b32 v18, v126 offset:96
	s_waitcnt lgkmcnt(9)
	v_lshlrev_b32_e32 v28, 16, v28
	v_lshlrev_b32_e32 v29, 16, v29
	v_pk_add_f32 v[12:13], v[4:5], v[6:7]
	v_pk_add_f32 v[14:15], v[8:9], v[10:11]
	s_nop 0
	v_pk_add_f32 v[12:13], v[12:13], v[14:15]
	s_nop 0
	v_pk_fma_f32 v[216:217], v[30:31], v[28:29], v[12:13] neg_lo:[0,0,1] neg_hi:[0,0,1]
	ds_read_b32 v19, v127 offset:96
	s_waitcnt lgkmcnt(9)
	v_pk_mul_f32 v[4:5], v[144:145], v[170:171] op_sel_hi:[0,1]
	v_pk_mul_f32 v[6:7], v[144:145], v[172:173] op_sel:[1,0] op_sel_hi:[1,1]
	v_pk_mul_f32 v[8:9], v[146:147], v[174:175] op_sel_hi:[0,1]
	v_pk_mul_f32 v[10:11], v[146:147], v[176:177] op_sel:[1,0] op_sel_hi:[1,1]
	ds_read_b128 v[102:105], v122 offset:6400
	s_waitcnt lgkmcnt(9)
	v_pk_fma_f32 v[4:5], v[148:149], v[178:179], v[4:5] op_sel_hi:[0,1,1]
	v_pk_fma_f32 v[6:7], v[148:149], v[180:181], v[6:7] op_sel:[1,0,0] op_sel_hi:[1,1,1]
	v_pk_fma_f32 v[8:9], v[150:151], v[182:183], v[8:9] op_sel_hi:[0,1,1]
	v_pk_fma_f32 v[10:11], v[150:151], v[184:185], v[10:11] op_sel:[1,0,0] op_sel_hi:[1,1,1]
	ds_read_b128 v[106:109], v122 offset:6416
	s_waitcnt lgkmcnt(9)
	v_pk_fma_f32 v[4:5], v[32:33], v[186:187], v[4:5] op_sel_hi:[0,1,1]
	v_pk_fma_f32 v[6:7], v[32:33], v[188:189], v[6:7] op_sel:[1,0,0] op_sel_hi:[1,1,1]
	v_pk_fma_f32 v[8:9], v[34:35], v[190:191], v[8:9] op_sel_hi:[0,1,1]
	v_pk_fma_f32 v[10:11], v[34:35], v[192:193], v[10:11] op_sel:[1,0,0] op_sel_hi:[1,1,1]
	ds_read_b128 v[130:133], v122 offset:6432
	s_waitcnt lgkmcnt(9)
	v_pk_fma_f32 v[4:5], v[36:37], v[194:195], v[4:5] op_sel_hi:[0,1,1]
	v_pk_fma_f32 v[6:7], v[36:37], v[196:197], v[6:7] op_sel:[1,0,0] op_sel_hi:[1,1,1]
	v_pk_fma_f32 v[8:9], v[38:39], v[198:199], v[8:9] op_sel_hi:[0,1,1]
	v_pk_fma_f32 v[10:11], v[38:39], v[200:201], v[10:11] op_sel:[1,0,0] op_sel_hi:[1,1,1]
	ds_read_b128 v[140:143], v122 offset:6448
	s_waitcnt lgkmcnt(9)
	v_pk_fma_f32 v[4:5], v[40:41], v[202:203], v[4:5] op_sel_hi:[0,1,1]
	v_pk_fma_f32 v[6:7], v[40:41], v[204:205], v[6:7] op_sel:[1,0,0] op_sel_hi:[1,1,1]
	v_pk_fma_f32 v[8:9], v[42:43], v[206:207], v[8:9] op_sel_hi:[0,1,1]
	v_pk_fma_f32 v[10:11], v[42:43], v[208:209], v[10:11] op_sel:[1,0,0] op_sel_hi:[1,1,1]
	ds_read_b128 v[144:147], v122 offset:6464
	s_waitcnt lgkmcnt(9)
	v_pk_fma_f32 v[4:5], v[98:99], v[210:211], v[4:5] op_sel_hi:[0,1,1]
	v_pk_fma_f32 v[6:7], v[98:99], v[212:213], v[6:7] op_sel:[1,0,0] op_sel_hi:[1,1,1]
	v_pk_fma_f32 v[8:9], v[100:101], v[214:215], v[8:9] op_sel_hi:[0,1,1]
	v_pk_fma_f32 v[10:11], v[100:101], v[216:217], v[10:11] op_sel:[1,0,0] op_sel_hi:[1,1,1]
	ds_read_b128 v[148:151], v122 offset:6480
	ds_read_b128 v[32:35], v122 offset:6496
	ds_read_u16 v20, v115 offset:6800
	ds_read_u16 v21, v116 offset:6800
	s_waitcnt lgkmcnt(9)
	v_lshlrev_b32_e32 v16, 16, v16
	v_lshlrev_b32_e32 v17, 16, v17
	v_pk_add_f32 v[12:13], v[4:5], v[6:7]
	v_pk_add_f32 v[14:15], v[8:9], v[10:11]
	s_nop 0
	v_pk_add_f32 v[12:13], v[12:13], v[14:15]
	s_nop 0
	v_pk_fma_f32 v[218:219], v[18:19], v[16:17], v[12:13] neg_lo:[0,0,1] neg_hi:[0,0,1]
	ds_read_b32 v22, v126 offset:100
	s_waitcnt lgkmcnt(9)
	v_pk_mul_f32 v[4:5], v[102:103], v[170:171] op_sel_hi:[0,1]
	v_pk_mul_f32 v[6:7], v[102:103], v[172:173] op_sel:[1,0] op_sel_hi:[1,1]
	v_pk_mul_f32 v[8:9], v[104:105], v[174:175] op_sel_hi:[0,1]
	v_pk_mul_f32 v[10:11], v[104:105], v[176:177] op_sel:[1,0] op_sel_hi:[1,1]
	ds_read_b32 v23, v127 offset:100
	s_waitcnt lgkmcnt(9)
	v_pk_fma_f32 v[4:5], v[106:107], v[178:179], v[4:5] op_sel_hi:[0,1,1]
	v_pk_fma_f32 v[6:7], v[106:107], v[180:181], v[6:7] op_sel:[1,0,0] op_sel_hi:[1,1,1]
	v_pk_fma_f32 v[8:9], v[108:109], v[182:183], v[8:9] op_sel_hi:[0,1,1]
	v_pk_fma_f32 v[10:11], v[108:109], v[184:185], v[10:11] op_sel:[1,0,0] op_sel_hi:[1,1,1]
	ds_read_b128 v[36:39], v122 offset:6656
	s_waitcnt lgkmcnt(9)
	v_pk_fma_f32 v[4:5], v[130:131], v[186:187], v[4:5] op_sel_hi:[0,1,1]
	v_pk_fma_f32 v[6:7], v[130:131], v[188:189], v[6:7] op_sel:[1,0,0] op_sel_hi:[1,1,1]
	v_pk_fma_f32 v[8:9], v[132:133], v[190:191], v[8:9] op_sel_hi:[0,1,1]
	v_pk_fma_f32 v[10:11], v[132:133], v[192:193], v[10:11] op_sel:[1,0,0] op_sel_hi:[1,1,1]
	ds_read_b128 v[40:43], v122 offset:6672
	s_waitcnt lgkmcnt(9)
	v_pk_fma_f32 v[4:5], v[140:141], v[194:195], v[4:5] op_sel_hi:[0,1,1]
	v_pk_fma_f32 v[6:7], v[140:141], v[196:197], v[6:7] op_sel:[1,0,0] op_sel_hi:[1,1,1]
	v_pk_fma_f32 v[8:9], v[142:143], v[198:199], v[8:9] op_sel_hi:[0,1,1]
	v_pk_fma_f32 v[10:11], v[142:143], v[200:201], v[10:11] op_sel:[1,0,0] op_sel_hi:[1,1,1]
	ds_read_b128 v[98:101], v122 offset:6688
	s_waitcnt lgkmcnt(9)
	v_pk_fma_f32 v[4:5], v[144:145], v[202:203], v[4:5] op_sel_hi:[0,1,1]
	v_pk_fma_f32 v[6:7], v[144:145], v[204:205], v[6:7] op_sel:[1,0,0] op_sel_hi:[1,1,1]
	v_pk_fma_f32 v[8:9], v[146:147], v[206:207], v[8:9] op_sel_hi:[0,1,1]
	v_pk_fma_f32 v[10:11], v[146:147], v[208:209], v[10:11] op_sel:[1,0,0] op_sel_hi:[1,1,1]
	ds_read_b128 v[102:105], v122 offset:6704
	s_waitcnt lgkmcnt(9)
	v_pk_fma_f32 v[4:5], v[148:149], v[210:211], v[4:5] op_sel_hi:[0,1,1]
	v_pk_fma_f32 v[6:7], v[148:149], v[212:213], v[6:7] op_sel:[1,0,0] op_sel_hi:[1,1,1]
	v_pk_fma_f32 v[8:9], v[150:151], v[214:215], v[8:9] op_sel_hi:[0,1,1]
	v_pk_fma_f32 v[10:11], v[150:151], v[216:217], v[10:11] op_sel:[1,0,0] op_sel_hi:[1,1,1]
	ds_read_b128 v[106:109], v122 offset:6720
	s_waitcnt lgkmcnt(9)
	v_pk_fma_f32 v[4:5], v[32:33], v[218:219], v[4:5] op_sel_hi:[0,1,1]
	ds_read_b128 v[130:133], v122 offset:6736
	ds_read_b128 v[140:143], v122 offset:6752
	ds_read_u16 v24, v115 offset:7072
	ds_read_u16 v25, v116 offset:7072
	s_waitcnt lgkmcnt(9)
	v_lshlrev_b32_e32 v20, 16, v20
	v_lshlrev_b32_e32 v21, 16, v21
	v_pk_add_f32 v[12:13], v[4:5], v[6:7]
	v_pk_add_f32 v[14:15], v[8:9], v[10:11]
	s_nop 0
	v_pk_add_f32 v[12:13], v[12:13], v[14:15]
	s_nop 0
	v_pk_fma_f32 v[220:221], v[22:23], v[20:21], v[12:13] neg_lo:[0,0,1] neg_hi:[0,0,1]
	ds_read_b32 v26, v126 offset:104
	s_waitcnt lgkmcnt(9)
	v_pk_mul_f32 v[4:5], v[36:37], v[170:171] op_sel_hi:[0,1]
	v_pk_mul_f32 v[6:7], v[36:37], v[172:173] op_sel:[1,0] op_sel_hi:[1,1]
	v_pk_mul_f32 v[8:9], v[38:39], v[174:175] op_sel_hi:[0,1]
	v_pk_mul_f32 v[10:11], v[38:39], v[176:177] op_sel:[1,0] op_sel_hi:[1,1]
	ds_read_b32 v27, v127 offset:104
	s_waitcnt lgkmcnt(9)
	v_pk_fma_f32 v[4:5], v[40:41], v[178:179], v[4:5] op_sel_hi:[0,1,1]
	v_pk_fma_f32 v[6:7], v[40:41], v[180:181], v[6:7] op_sel:[1,0,0] op_sel_hi:[1,1,1]
	v_pk_fma_f32 v[8:9], v[42:43], v[182:183], v[8:9] op_sel_hi:[0,1,1]
	v_pk_fma_f32 v[10:11], v[42:43], v[184:185], v[10:11] op_sel:[1,0,0] op_sel_hi:[1,1,1]
	ds_read_b128 v[144:147], v122 offset:6912
	s_waitcnt lgkmcnt(9)
	v_pk_fma_f32 v[4:5], v[98:99], v[186:187], v[4:5] op_sel_hi:[0,1,1]
	v_pk_fma_f32 v[6:7], v[98:99], v[188:189], v[6:7] op_sel:[1,0,0] op_sel_hi:[1,1,1]
	v_pk_fma_f32 v[8:9], v[100:101], v[190:191], v[8:9] op_sel_hi:[0,1,1]
	v_pk_fma_f32 v[10:11], v[100:101], v[192:193], v[10:11] op_sel:[1,0,0] op_sel_hi:[1,1,1]
	ds_read_b128 v[148:151], v122 offset:6928
	s_waitcnt lgkmcnt(9)
	v_pk_fma_f32 v[4:5], v[102:103], v[194:195], v[4:5] op_sel_hi:[0,1,1]
	v_pk_fma_f32 v[6:7], v[102:103], v[196:197], v[6:7] op_sel:[1,0,0] op_sel_hi:[1,1,1]
	v_pk_fma_f32 v[8:9], v[104:105], v[198:199], v[8:9] op_sel_hi:[0,1,1]
	v_pk_fma_f32 v[10:11], v[104:105], v[200:201], v[10:11] op_sel:[1,0,0] op_sel_hi:[1,1,1]
	ds_read_b128 v[32:35], v122 offset:6944
	s_waitcnt lgkmcnt(9)
	v_pk_fma_f32 v[4:5], v[106:107], v[202:203], v[4:5] op_sel_hi:[0,1,1]
	v_pk_fma_f32 v[6:7], v[106:107], v[204:205], v[6:7] op_sel:[1,0,0] op_sel_hi:[1,1,1]
	v_pk_fma_f32 v[8:9], v[108:109], v[206:207], v[8:9] op_sel_hi:[0,1,1]
	v_pk_fma_f32 v[10:11], v[108:109], v[208:209], v[10:11] op_sel:[1,0,0] op_sel_hi:[1,1,1]
	ds_read_b128 v[36:39], v122 offset:6960
	s_waitcnt lgkmcnt(9)
	v_pk_fma_f32 v[4:5], v[130:131], v[210:211], v[4:5] op_sel_hi:[0,1,1]
	v_pk_fma_f32 v[6:7], v[130:131], v[212:213], v[6:7] op_sel:[1,0,0] op_sel_hi:[1,1,1]
	v_pk_fma_f32 v[8:9], v[132:133], v[214:215], v[8:9] op_sel_hi:[0,1,1]
	v_pk_fma_f32 v[10:11], v[132:133], v[216:217], v[10:11] op_sel:[1,0,0] op_sel_hi:[1,1,1]
	ds_read_b128 v[40:43], v122 offset:6976
	s_waitcnt lgkmcnt(9)
	v_pk_fma_f32 v[4:5], v[140:141], v[218:219], v[4:5] op_sel_hi:[0,1,1]
	v_pk_fma_f32 v[6:7], v[140:141], v[220:221], v[6:7] op_sel:[1,0,0] op_sel_hi:[1,1,1]
	ds_read_b128 v[98:101], v122 offset:6992
	ds_read_b128 v[102:105], v122 offset:7008
	ds_read_u16 v28, v115 offset:7344
	ds_read_u16 v29, v116 offset:7344
	s_waitcnt lgkmcnt(9)
	v_lshlrev_b32_e32 v24, 16, v24
	v_lshlrev_b32_e32 v25, 16, v25
	v_pk_add_f32 v[12:13], v[4:5], v[6:7]
	v_pk_add_f32 v[14:15], v[8:9], v[10:11]
	s_nop 0
	v_pk_add_f32 v[12:13], v[12:13], v[14:15]
	s_nop 0
	v_pk_fma_f32 v[222:223], v[26:27], v[24:25], v[12:13] neg_lo:[0,0,1] neg_hi:[0,0,1]
	ds_read_b32 v30, v126 offset:108
	s_waitcnt lgkmcnt(9)
	v_pk_mul_f32 v[4:5], v[144:145], v[170:171] op_sel_hi:[0,1]
	v_pk_mul_f32 v[6:7], v[144:145], v[172:173] op_sel:[1,0] op_sel_hi:[1,1]
	v_pk_mul_f32 v[8:9], v[146:147], v[174:175] op_sel_hi:[0,1]
	v_pk_mul_f32 v[10:11], v[146:147], v[176:177] op_sel:[1,0] op_sel_hi:[1,1]
	ds_read_b32 v31, v127 offset:108
	s_waitcnt lgkmcnt(9)
	v_pk_fma_f32 v[4:5], v[148:149], v[178:179], v[4:5] op_sel_hi:[0,1,1]
	v_pk_fma_f32 v[6:7], v[148:149], v[180:181], v[6:7] op_sel:[1,0,0] op_sel_hi:[1,1,1]
	v_pk_fma_f32 v[8:9], v[150:151], v[182:183], v[8:9] op_sel_hi:[0,1,1]
	v_pk_fma_f32 v[10:11], v[150:151], v[184:185], v[10:11] op_sel:[1,0,0] op_sel_hi:[1,1,1]
	ds_read_b128 v[106:109], v122 offset:7168
	s_waitcnt lgkmcnt(9)
	v_pk_fma_f32 v[4:5], v[32:33], v[186:187], v[4:5] op_sel_hi:[0,1,1]
	v_pk_fma_f32 v[6:7], v[32:33], v[188:189], v[6:7] op_sel:[1,0,0] op_sel_hi:[1,1,1]
	v_pk_fma_f32 v[8:9], v[34:35], v[190:191], v[8:9] op_sel_hi:[0,1,1]
	v_pk_fma_f32 v[10:11], v[34:35], v[192:193], v[10:11] op_sel:[1,0,0] op_sel_hi:[1,1,1]
	ds_read_b128 v[130:133], v122 offset:7184
	s_waitcnt lgkmcnt(9)
	v_pk_fma_f32 v[4:5], v[36:37], v[194:195], v[4:5] op_sel_hi:[0,1,1]
	v_pk_fma_f32 v[6:7], v[36:37], v[196:197], v[6:7] op_sel:[1,0,0] op_sel_hi:[1,1,1]
	v_pk_fma_f32 v[8:9], v[38:39], v[198:199], v[8:9] op_sel_hi:[0,1,1]
	v_pk_fma_f32 v[10:11], v[38:39], v[200:201], v[10:11] op_sel:[1,0,0] op_sel_hi:[1,1,1]
	ds_read_b128 v[140:143], v122 offset:7200
	s_waitcnt lgkmcnt(9)
	v_pk_fma_f32 v[4:5], v[40:41], v[202:203], v[4:5] op_sel_hi:[0,1,1]
	v_pk_fma_f32 v[6:7], v[40:41], v[204:205], v[6:7] op_sel:[1,0,0] op_sel_hi:[1,1,1]
	v_pk_fma_f32 v[8:9], v[42:43], v[206:207], v[8:9] op_sel_hi:[0,1,1]
	v_pk_fma_f32 v[10:11], v[42:43], v[208:209], v[10:11] op_sel:[1,0,0] op_sel_hi:[1,1,1]
	ds_read_b128 v[144:147], v122 offset:7216
	s_waitcnt lgkmcnt(9)
	v_pk_fma_f32 v[4:5], v[98:99], v[210:211], v[4:5] op_sel_hi:[0,1,1]
	v_pk_fma_f32 v[6:7], v[98:99], v[212:213], v[6:7] op_sel:[1,0,0] op_sel_hi:[1,1,1]
	v_pk_fma_f32 v[8:9], v[100:101], v[214:215], v[8:9] op_sel_hi:[0,1,1]
	v_pk_fma_f32 v[10:11], v[100:101], v[216:217], v[10:11] op_sel:[1,0,0] op_sel_hi:[1,1,1]
	ds_read_b128 v[148:151], v122 offset:7232
	s_waitcnt lgkmcnt(9)
	v_pk_fma_f32 v[4:5], v[102:103], v[218:219], v[4:5] op_sel_hi:[0,1,1]
	v_pk_fma_f32 v[6:7], v[102:103], v[220:221], v[6:7] op_sel:[1,0,0] op_sel_hi:[1,1,1]
	v_pk_fma_f32 v[8:9], v[104:105], v[222:223], v[8:9] op_sel_hi:[0,1,1]
	ds_read_b128 v[32:35], v122 offset:7248
	ds_read_b128 v[36:39], v122 offset:7264
	ds_read_u16 v16, v115 offset:7616
	ds_read_u16 v17, v116 offset:7616
	s_waitcnt lgkmcnt(9)
	v_lshlrev_b32_e32 v28, 16, v28
	v_lshlrev_b32_e32 v29, 16, v29
	v_pk_add_f32 v[12:13], v[4:5], v[6:7]
	v_pk_add_f32 v[14:15], v[8:9], v[10:11]
	s_nop 0
	v_pk_add_f32 v[12:13], v[12:13], v[14:15]
	s_nop 0
	v_pk_fma_f32 v[224:225], v[30:31], v[28:29], v[12:13] neg_lo:[0,0,1] neg_hi:[0,0,1]
	ds_read_b32 v18, v126 offset:112
	s_waitcnt lgkmcnt(9)
	v_pk_mul_f32 v[4:5], v[106:107], v[170:171] op_sel_hi:[0,1]
	v_pk_mul_f32 v[6:7], v[106:107], v[172:173] op_sel:[1,0] op_sel_hi:[1,1]
	v_pk_mul_f32 v[8:9], v[108:109], v[174:175] op_sel_hi:[0,1]
	v_pk_mul_f32 v[10:11], v[108:109], v[176:177] op_sel:[1,0] op_sel_hi:[1,1]
	ds_read_b32 v19, v127 offset:112
	s_waitcnt lgkmcnt(9)
	v_pk_fma_f32 v[4:5], v[130:131], v[178:179], v[4:5] op_sel_hi:[0,1,1]
	v_pk_fma_f32 v[6:7], v[130:131], v[180:181], v[6:7] op_sel:[1,0,0] op_sel_hi:[1,1,1]
	v_pk_fma_f32 v[8:9], v[132:133], v[182:183], v[8:9] op_sel_hi:[0,1,1]
	v_pk_fma_f32 v[10:11], v[132:133], v[184:185], v[10:11] op_sel:[1,0,0] op_sel_hi:[1,1,1]
	ds_read_b128 v[40:43], v122 offset:7424
	s_waitcnt lgkmcnt(9)
	v_pk_fma_f32 v[4:5], v[140:141], v[186:187], v[4:5] op_sel_hi:[0,1,1]
	v_pk_fma_f32 v[6:7], v[140:141], v[188:189], v[6:7] op_sel:[1,0,0] op_sel_hi:[1,1,1]
	v_pk_fma_f32 v[8:9], v[142:143], v[190:191], v[8:9] op_sel_hi:[0,1,1]
	v_pk_fma_f32 v[10:11], v[142:143], v[192:193], v[10:11] op_sel:[1,0,0] op_sel_hi:[1,1,1]
	ds_read_b128 v[98:101], v122 offset:7440
	s_waitcnt lgkmcnt(9)
	v_pk_fma_f32 v[4:5], v[144:145], v[194:195], v[4:5] op_sel_hi:[0,1,1]
	v_pk_fma_f32 v[6:7], v[144:145], v[196:197], v[6:7] op_sel:[1,0,0] op_sel_hi:[1,1,1]
	v_pk_fma_f32 v[8:9], v[146:147], v[198:199], v[8:9] op_sel_hi:[0,1,1]
	v_pk_fma_f32 v[10:11], v[146:147], v[200:201], v[10:11] op_sel:[1,0,0] op_sel_hi:[1,1,1]
	ds_read_b128 v[102:105], v122 offset:7456
	s_waitcnt lgkmcnt(9)
	v_pk_fma_f32 v[4:5], v[148:149], v[202:203], v[4:5] op_sel_hi:[0,1,1]
	v_pk_fma_f32 v[6:7], v[148:149], v[204:205], v[6:7] op_sel:[1,0,0] op_sel_hi:[1,1,1]
	v_pk_fma_f32 v[8:9], v[150:151], v[206:207], v[8:9] op_sel_hi:[0,1,1]
	v_pk_fma_f32 v[10:11], v[150:151], v[208:209], v[10:11] op_sel:[1,0,0] op_sel_hi:[1,1,1]
	ds_read_b128 v[106:109], v122 offset:7472
	s_waitcnt lgkmcnt(9)
	v_pk_fma_f32 v[4:5], v[32:33], v[210:211], v[4:5] op_sel_hi:[0,1,1]
	v_pk_fma_f32 v[6:7], v[32:33], v[212:213], v[6:7] op_sel:[1,0,0] op_sel_hi:[1,1,1]
	v_pk_fma_f32 v[8:9], v[34:35], v[214:215], v[8:9] op_sel_hi:[0,1,1]
	v_pk_fma_f32 v[10:11], v[34:35], v[216:217], v[10:11] op_sel:[1,0,0] op_sel_hi:[1,1,1]
	ds_read_b128 v[130:133], v122 offset:7488
	s_waitcnt lgkmcnt(9)
	v_pk_fma_f32 v[4:5], v[36:37], v[218:219], v[4:5] op_sel_hi:[0,1,1]
	v_pk_fma_f32 v[6:7], v[36:37], v[220:221], v[6:7] op_sel:[1,0,0] op_sel_hi:[1,1,1]
	v_pk_fma_f32 v[8:9], v[38:39], v[222:223], v[8:9] op_sel_hi:[0,1,1]
	v_pk_fma_f32 v[10:11], v[38:39], v[224:225], v[10:11] op_sel:[1,0,0] op_sel_hi:[1,1,1]
	ds_read_b128 v[140:143], v122 offset:7504
	ds_read_b128 v[144:147], v122 offset:7520
	ds_read_b128 v[148:151], v122 offset:7536
	ds_read_u16 v20, v115 offset:7888
	s_waitcnt lgkmcnt(9)
	v_lshlrev_b32_e32 v16, 16, v16
	v_lshlrev_b32_e32 v17, 16, v17
	v_pk_add_f32 v[12:13], v[4:5], v[6:7]
	v_pk_add_f32 v[14:15], v[8:9], v[10:11]
	s_nop 0
	v_pk_add_f32 v[12:13], v[12:13], v[14:15]
	s_nop 0
	v_pk_fma_f32 v[226:227], v[18:19], v[16:17], v[12:13] neg_lo:[0,0,1] neg_hi:[0,0,1]
	ds_read_u16 v21, v116 offset:7888
	s_waitcnt lgkmcnt(9)
	v_pk_mul_f32 v[4:5], v[40:41], v[170:171] op_sel_hi:[0,1]
	v_pk_mul_f32 v[6:7], v[40:41], v[172:173] op_sel:[1,0] op_sel_hi:[1,1]
	v_pk_mul_f32 v[8:9], v[42:43], v[174:175] op_sel_hi:[0,1]
	v_pk_mul_f32 v[10:11], v[42:43], v[176:177] op_sel:[1,0] op_sel_hi:[1,1]
	ds_read_b32 v22, v126 offset:116
	s_waitcnt lgkmcnt(9)
	v_pk_fma_f32 v[4:5], v[98:99], v[178:179], v[4:5] op_sel_hi:[0,1,1]
	v_pk_fma_f32 v[6:7], v[98:99], v[180:181], v[6:7] op_sel:[1,0,0] op_sel_hi:[1,1,1]
	v_pk_fma_f32 v[8:9], v[100:101], v[182:183], v[8:9] op_sel_hi:[0,1,1]
	v_pk_fma_f32 v[10:11], v[100:101], v[184:185], v[10:11] op_sel:[1,0,0] op_sel_hi:[1,1,1]
	ds_read_b32 v23, v127 offset:116
	s_waitcnt lgkmcnt(9)
	v_pk_fma_f32 v[4:5], v[102:103], v[186:187], v[4:5] op_sel_hi:[0,1,1]
	v_pk_fma_f32 v[6:7], v[102:103], v[188:189], v[6:7] op_sel:[1,0,0] op_sel_hi:[1,1,1]
	v_pk_fma_f32 v[8:9], v[104:105], v[190:191], v[8:9] op_sel_hi:[0,1,1]
	v_pk_fma_f32 v[10:11], v[104:105], v[192:193], v[10:11] op_sel:[1,0,0] op_sel_hi:[1,1,1]
	ds_read_b128 v[32:35], v122 offset:7680
	s_waitcnt lgkmcnt(9)
	v_pk_fma_f32 v[4:5], v[106:107], v[194:195], v[4:5] op_sel_hi:[0,1,1]
	v_pk_fma_f32 v[6:7], v[106:107], v[196:197], v[6:7] op_sel:[1,0,0] op_sel_hi:[1,1,1]
	v_pk_fma_f32 v[8:9], v[108:109], v[198:199], v[8:9] op_sel_hi:[0,1,1]
	v_pk_fma_f32 v[10:11], v[108:109], v[200:201], v[10:11] op_sel:[1,0,0] op_sel_hi:[1,1,1]
	ds_read_b128 v[36:39], v122 offset:7696
	s_waitcnt lgkmcnt(9)
	v_pk_fma_f32 v[4:5], v[130:131], v[202:203], v[4:5] op_sel_hi:[0,1,1]
	v_pk_fma_f32 v[6:7], v[130:131], v[204:205], v[6:7] op_sel:[1,0,0] op_sel_hi:[1,1,1]
	v_pk_fma_f32 v[8:9], v[132:133], v[206:207], v[8:9] op_sel_hi:[0,1,1]
	v_pk_fma_f32 v[10:11], v[132:133], v[208:209], v[10:11] op_sel:[1,0,0] op_sel_hi:[1,1,1]
	ds_read_b128 v[40:43], v122 offset:7712
	s_waitcnt lgkmcnt(9)
	v_pk_fma_f32 v[4:5], v[140:141], v[210:211], v[4:5] op_sel_hi:[0,1,1]
	v_pk_fma_f32 v[6:7], v[140:141], v[212:213], v[6:7] op_sel:[1,0,0] op_sel_hi:[1,1,1]
	v_pk_fma_f32 v[8:9], v[142:143], v[214:215], v[8:9] op_sel_hi:[0,1,1]
	v_pk_fma_f32 v[10:11], v[142:143], v[216:217], v[10:11] op_sel:[1,0,0] op_sel_hi:[1,1,1]
	ds_read_b128 v[98:101], v122 offset:7728
	s_waitcnt lgkmcnt(9)
	v_pk_fma_f32 v[4:5], v[144:145], v[218:219], v[4:5] op_sel_hi:[0,1,1]
	v_pk_fma_f32 v[6:7], v[144:145], v[220:221], v[6:7] op_sel:[1,0,0] op_sel_hi:[1,1,1]
	v_pk_fma_f32 v[8:9], v[146:147], v[222:223], v[8:9] op_sel_hi:[0,1,1]
	v_pk_fma_f32 v[10:11], v[146:147], v[224:225], v[10:11] op_sel:[1,0,0] op_sel_hi:[1,1,1]
	ds_read_b128 v[102:105], v122 offset:7744
	s_waitcnt lgkmcnt(9)
	v_pk_fma_f32 v[4:5], v[148:149], v[226:227], v[4:5] op_sel_hi:[0,1,1]
	ds_read_b128 v[106:109], v122 offset:7760
	ds_read_b128 v[130:133], v122 offset:7776
	ds_read_b128 v[140:143], v122 offset:7792
	ds_read_u16 v24, v115 offset:8160
	s_waitcnt lgkmcnt(9)
	v_lshlrev_b32_e32 v20, 16, v20
	v_lshlrev_b32_e32 v21, 16, v21
	v_pk_add_f32 v[12:13], v[4:5], v[6:7]
	v_pk_add_f32 v[14:15], v[8:9], v[10:11]
	s_nop 0
	v_pk_add_f32 v[12:13], v[12:13], v[14:15]
	s_nop 0
	v_pk_fma_f32 v[228:229], v[22:23], v[20:21], v[12:13] neg_lo:[0,0,1] neg_hi:[0,0,1]
	ds_read_u16 v25, v116 offset:8160
	s_waitcnt lgkmcnt(9)
	v_pk_mul_f32 v[4:5], v[32:33], v[170:171] op_sel_hi:[0,1]
	v_pk_mul_f32 v[6:7], v[32:33], v[172:173] op_sel:[1,0] op_sel_hi:[1,1]
	v_pk_mul_f32 v[8:9], v[34:35], v[174:175] op_sel_hi:[0,1]
	v_pk_mul_f32 v[10:11], v[34:35], v[176:177] op_sel:[1,0] op_sel_hi:[1,1]
	ds_read_b32 v26, v126 offset:120
	s_waitcnt lgkmcnt(9)
	v_pk_fma_f32 v[4:5], v[36:37], v[178:179], v[4:5] op_sel_hi:[0,1,1]
	v_pk_fma_f32 v[6:7], v[36:37], v[180:181], v[6:7] op_sel:[1,0,0] op_sel_hi:[1,1,1]
	v_pk_fma_f32 v[8:9], v[38:39], v[182:183], v[8:9] op_sel_hi:[0,1,1]
	v_pk_fma_f32 v[10:11], v[38:39], v[184:185], v[10:11] op_sel:[1,0,0] op_sel_hi:[1,1,1]
	ds_read_b32 v27, v127 offset:120
	s_waitcnt lgkmcnt(9)
	v_pk_fma_f32 v[4:5], v[40:41], v[186:187], v[4:5] op_sel_hi:[0,1,1]
	v_pk_fma_f32 v[6:7], v[40:41], v[188:189], v[6:7] op_sel:[1,0,0] op_sel_hi:[1,1,1]
	v_pk_fma_f32 v[8:9], v[42:43], v[190:191], v[8:9] op_sel_hi:[0,1,1]
	v_pk_fma_f32 v[10:11], v[42:43], v[192:193], v[10:11] op_sel:[1,0,0] op_sel_hi:[1,1,1]
	ds_read_b128 v[144:147], v122 offset:7936
	s_waitcnt lgkmcnt(9)
	v_pk_fma_f32 v[4:5], v[98:99], v[194:195], v[4:5] op_sel_hi:[0,1,1]
	v_pk_fma_f32 v[6:7], v[98:99], v[196:197], v[6:7] op_sel:[1,0,0] op_sel_hi:[1,1,1]
	v_pk_fma_f32 v[8:9], v[100:101], v[198:199], v[8:9] op_sel_hi:[0,1,1]
	v_pk_fma_f32 v[10:11], v[100:101], v[200:201], v[10:11] op_sel:[1,0,0] op_sel_hi:[1,1,1]
	ds_read_b128 v[148:151], v122 offset:7952
	s_waitcnt lgkmcnt(9)
	v_pk_fma_f32 v[4:5], v[102:103], v[202:203], v[4:5] op_sel_hi:[0,1,1]
	v_pk_fma_f32 v[6:7], v[102:103], v[204:205], v[6:7] op_sel:[1,0,0] op_sel_hi:[1,1,1]
	v_pk_fma_f32 v[8:9], v[104:105], v[206:207], v[8:9] op_sel_hi:[0,1,1]
	v_pk_fma_f32 v[10:11], v[104:105], v[208:209], v[10:11] op_sel:[1,0,0] op_sel_hi:[1,1,1]
	ds_read_b128 v[32:35], v122 offset:7968
	s_waitcnt lgkmcnt(9)
	v_pk_fma_f32 v[4:5], v[106:107], v[210:211], v[4:5] op_sel_hi:[0,1,1]
	v_pk_fma_f32 v[6:7], v[106:107], v[212:213], v[6:7] op_sel:[1,0,0] op_sel_hi:[1,1,1]
	v_pk_fma_f32 v[8:9], v[108:109], v[214:215], v[8:9] op_sel_hi:[0,1,1]
	v_pk_fma_f32 v[10:11], v[108:109], v[216:217], v[10:11] op_sel:[1,0,0] op_sel_hi:[1,1,1]
	ds_read_b128 v[36:39], v122 offset:7984
	s_waitcnt lgkmcnt(9)
	v_pk_fma_f32 v[4:5], v[130:131], v[218:219], v[4:5] op_sel_hi:[0,1,1]
	v_pk_fma_f32 v[6:7], v[130:131], v[220:221], v[6:7] op_sel:[1,0,0] op_sel_hi:[1,1,1]
	v_pk_fma_f32 v[8:9], v[132:133], v[222:223], v[8:9] op_sel_hi:[0,1,1]
	v_pk_fma_f32 v[10:11], v[132:133], v[224:225], v[10:11] op_sel:[1,0,0] op_sel_hi:[1,1,1]
	ds_read_b128 v[40:43], v122 offset:8000
	s_waitcnt lgkmcnt(9)
	v_pk_fma_f32 v[4:5], v[140:141], v[226:227], v[4:5] op_sel_hi:[0,1,1]
	v_pk_fma_f32 v[6:7], v[140:141], v[228:229], v[6:7] op_sel:[1,0,0] op_sel_hi:[1,1,1]
	ds_read_b128 v[98:101], v122 offset:8016
	ds_read_b128 v[102:105], v122 offset:8032
	ds_read_b128 v[106:109], v122 offset:8048
	ds_read_u16 v28, v115 offset:8432
	s_waitcnt lgkmcnt(9)
	v_lshlrev_b32_e32 v24, 16, v24
	v_lshlrev_b32_e32 v25, 16, v25
	v_pk_add_f32 v[12:13], v[4:5], v[6:7]
	v_pk_add_f32 v[14:15], v[8:9], v[10:11]
	s_nop 0
	v_pk_add_f32 v[12:13], v[12:13], v[14:15]
	s_nop 0
	v_pk_fma_f32 v[230:231], v[26:27], v[24:25], v[12:13] neg_lo:[0,0,1] neg_hi:[0,0,1]
	ds_read_u16 v29, v116 offset:8432
	s_waitcnt lgkmcnt(9)
	v_pk_mul_f32 v[4:5], v[144:145], v[170:171] op_sel_hi:[0,1]
	v_pk_mul_f32 v[6:7], v[144:145], v[172:173] op_sel:[1,0] op_sel_hi:[1,1]
	v_pk_mul_f32 v[8:9], v[146:147], v[174:175] op_sel_hi:[0,1]
	v_pk_mul_f32 v[10:11], v[146:147], v[176:177] op_sel:[1,0] op_sel_hi:[1,1]
	ds_read_b32 v30, v126 offset:124
	s_waitcnt lgkmcnt(9)
	v_pk_fma_f32 v[4:5], v[148:149], v[178:179], v[4:5] op_sel_hi:[0,1,1]
	v_pk_fma_f32 v[6:7], v[148:149], v[180:181], v[6:7] op_sel:[1,0,0] op_sel_hi:[1,1,1]
	v_pk_fma_f32 v[8:9], v[150:151], v[182:183], v[8:9] op_sel_hi:[0,1,1]
	v_pk_fma_f32 v[10:11], v[150:151], v[184:185], v[10:11] op_sel:[1,0,0] op_sel_hi:[1,1,1]
	ds_read_b32 v31, v127 offset:124
	s_waitcnt lgkmcnt(9)
	v_pk_fma_f32 v[4:5], v[32:33], v[186:187], v[4:5] op_sel_hi:[0,1,1]
	v_pk_fma_f32 v[6:7], v[32:33], v[188:189], v[6:7] op_sel:[1,0,0] op_sel_hi:[1,1,1]
	v_pk_fma_f32 v[8:9], v[34:35], v[190:191], v[8:9] op_sel_hi:[0,1,1]
	v_pk_fma_f32 v[10:11], v[34:35], v[192:193], v[10:11] op_sel:[1,0,0] op_sel_hi:[1,1,1]
	ds_read_b128 v[130:133], v122 offset:8192
	s_waitcnt lgkmcnt(9)
	v_pk_fma_f32 v[4:5], v[36:37], v[194:195], v[4:5] op_sel_hi:[0,1,1]
	v_pk_fma_f32 v[6:7], v[36:37], v[196:197], v[6:7] op_sel:[1,0,0] op_sel_hi:[1,1,1]
	v_pk_fma_f32 v[8:9], v[38:39], v[198:199], v[8:9] op_sel_hi:[0,1,1]
	v_pk_fma_f32 v[10:11], v[38:39], v[200:201], v[10:11] op_sel:[1,0,0] op_sel_hi:[1,1,1]
	ds_read_b128 v[140:143], v122 offset:8208
	s_waitcnt lgkmcnt(9)
	v_pk_fma_f32 v[4:5], v[40:41], v[202:203], v[4:5] op_sel_hi:[0,1,1]
	v_pk_fma_f32 v[6:7], v[40:41], v[204:205], v[6:7] op_sel:[1,0,0] op_sel_hi:[1,1,1]
	v_pk_fma_f32 v[8:9], v[42:43], v[206:207], v[8:9] op_sel_hi:[0,1,1]
	v_pk_fma_f32 v[10:11], v[42:43], v[208:209], v[10:11] op_sel:[1,0,0] op_sel_hi:[1,1,1]
	ds_read_b128 v[144:147], v122 offset:8224
	s_waitcnt lgkmcnt(9)
	v_pk_fma_f32 v[4:5], v[98:99], v[210:211], v[4:5] op_sel_hi:[0,1,1]
	v_pk_fma_f32 v[6:7], v[98:99], v[212:213], v[6:7] op_sel:[1,0,0] op_sel_hi:[1,1,1]
	v_pk_fma_f32 v[8:9], v[100:101], v[214:215], v[8:9] op_sel_hi:[0,1,1]
	v_pk_fma_f32 v[10:11], v[100:101], v[216:217], v[10:11] op_sel:[1,0,0] op_sel_hi:[1,1,1]
	ds_read_b128 v[148:151], v122 offset:8240
	s_waitcnt lgkmcnt(9)
	v_pk_fma_f32 v[4:5], v[102:103], v[218:219], v[4:5] op_sel_hi:[0,1,1]
	v_pk_fma_f32 v[6:7], v[102:103], v[220:221], v[6:7] op_sel:[1,0,0] op_sel_hi:[1,1,1]
	v_pk_fma_f32 v[8:9], v[104:105], v[222:223], v[8:9] op_sel_hi:[0,1,1]
	v_pk_fma_f32 v[10:11], v[104:105], v[224:225], v[10:11] op_sel:[1,0,0] op_sel_hi:[1,1,1]
	ds_read_b128 v[32:35], v122 offset:8256
	s_waitcnt lgkmcnt(9)
	v_pk_fma_f32 v[4:5], v[106:107], v[226:227], v[4:5] op_sel_hi:[0,1,1]
	v_pk_fma_f32 v[6:7], v[106:107], v[228:229], v[6:7] op_sel:[1,0,0] op_sel_hi:[1,1,1]
	v_pk_fma_f32 v[8:9], v[108:109], v[230:231], v[8:9] op_sel_hi:[0,1,1]
	ds_read_b128 v[36:39], v122 offset:8272
	ds_read_b128 v[40:43], v122 offset:8288
	ds_read_b128 v[98:101], v122 offset:8304
	ds_read_u16 v16, v115 offset:8704
	s_waitcnt lgkmcnt(9)
	v_lshlrev_b32_e32 v28, 16, v28
	v_lshlrev_b32_e32 v29, 16, v29
	v_pk_add_f32 v[12:13], v[4:5], v[6:7]
	v_pk_add_f32 v[14:15], v[8:9], v[10:11]
	s_nop 0
	v_pk_add_f32 v[12:13], v[12:13], v[14:15]
	s_nop 0
	v_pk_fma_f32 v[232:233], v[30:31], v[28:29], v[12:13] neg_lo:[0,0,1] neg_hi:[0,0,1]
	ds_read_u16 v17, v116 offset:8704
	s_waitcnt lgkmcnt(9)
	v_pk_mul_f32 v[4:5], v[130:131], v[170:171] op_sel_hi:[0,1]
	v_pk_mul_f32 v[6:7], v[130:131], v[172:173] op_sel:[1,0] op_sel_hi:[1,1]
	v_pk_mul_f32 v[8:9], v[132:133], v[174:175] op_sel_hi:[0,1]
	v_pk_mul_f32 v[10:11], v[132:133], v[176:177] op_sel:[1,0] op_sel_hi:[1,1]
	ds_read_b32 v18, v126 offset:128
	s_waitcnt lgkmcnt(9)
	v_pk_fma_f32 v[4:5], v[140:141], v[178:179], v[4:5] op_sel_hi:[0,1,1]
	v_pk_fma_f32 v[6:7], v[140:141], v[180:181], v[6:7] op_sel:[1,0,0] op_sel_hi:[1,1,1]
	v_pk_fma_f32 v[8:9], v[142:143], v[182:183], v[8:9] op_sel_hi:[0,1,1]
	v_pk_fma_f32 v[10:11], v[142:143], v[184:185], v[10:11] op_sel:[1,0,0] op_sel_hi:[1,1,1]
	ds_read_b32 v19, v127 offset:128
	s_waitcnt lgkmcnt(9)
	v_pk_fma_f32 v[4:5], v[144:145], v[186:187], v[4:5] op_sel_hi:[0,1,1]
	v_pk_fma_f32 v[6:7], v[144:145], v[188:189], v[6:7] op_sel:[1,0,0] op_sel_hi:[1,1,1]
	v_pk_fma_f32 v[8:9], v[146:147], v[190:191], v[8:9] op_sel_hi:[0,1,1]
	v_pk_fma_f32 v[10:11], v[146:147], v[192:193], v[10:11] op_sel:[1,0,0] op_sel_hi:[1,1,1]
	ds_read_b128 v[102:105], v122 offset:8448
	s_waitcnt lgkmcnt(9)
	v_pk_fma_f32 v[4:5], v[148:149], v[194:195], v[4:5] op_sel_hi:[0,1,1]
	v_pk_fma_f32 v[6:7], v[148:149], v[196:197], v[6:7] op_sel:[1,0,0] op_sel_hi:[1,1,1]
	v_pk_fma_f32 v[8:9], v[150:151], v[198:199], v[8:9] op_sel_hi:[0,1,1]
	v_pk_fma_f32 v[10:11], v[150:151], v[200:201], v[10:11] op_sel:[1,0,0] op_sel_hi:[1,1,1]
	ds_read_b128 v[106:109], v122 offset:8464
	s_waitcnt lgkmcnt(9)
	v_pk_fma_f32 v[4:5], v[32:33], v[202:203], v[4:5] op_sel_hi:[0,1,1]
	v_pk_fma_f32 v[6:7], v[32:33], v[204:205], v[6:7] op_sel:[1,0,0] op_sel_hi:[1,1,1]
	v_pk_fma_f32 v[8:9], v[34:35], v[206:207], v[8:9] op_sel_hi:[0,1,1]
	v_pk_fma_f32 v[10:11], v[34:35], v[208:209], v[10:11] op_sel:[1,0,0] op_sel_hi:[1,1,1]
	ds_read_b128 v[130:133], v122 offset:8480
	s_waitcnt lgkmcnt(9)
	v_pk_fma_f32 v[4:5], v[36:37], v[210:211], v[4:5] op_sel_hi:[0,1,1]
	v_pk_fma_f32 v[6:7], v[36:37], v[212:213], v[6:7] op_sel:[1,0,0] op_sel_hi:[1,1,1]
	v_pk_fma_f32 v[8:9], v[38:39], v[214:215], v[8:9] op_sel_hi:[0,1,1]
	v_pk_fma_f32 v[10:11], v[38:39], v[216:217], v[10:11] op_sel:[1,0,0] op_sel_hi:[1,1,1]
	ds_read_b128 v[140:143], v122 offset:8496
	s_waitcnt lgkmcnt(9)
	v_pk_fma_f32 v[4:5], v[40:41], v[218:219], v[4:5] op_sel_hi:[0,1,1]
	v_pk_fma_f32 v[6:7], v[40:41], v[220:221], v[6:7] op_sel:[1,0,0] op_sel_hi:[1,1,1]
	v_pk_fma_f32 v[8:9], v[42:43], v[222:223], v[8:9] op_sel_hi:[0,1,1]
	v_pk_fma_f32 v[10:11], v[42:43], v[224:225], v[10:11] op_sel:[1,0,0] op_sel_hi:[1,1,1]
	ds_read_b128 v[144:147], v122 offset:8512
	s_waitcnt lgkmcnt(9)
	v_pk_fma_f32 v[4:5], v[98:99], v[226:227], v[4:5] op_sel_hi:[0,1,1]
	v_pk_fma_f32 v[6:7], v[98:99], v[228:229], v[6:7] op_sel:[1,0,0] op_sel_hi:[1,1,1]
	v_pk_fma_f32 v[8:9], v[100:101], v[230:231], v[8:9] op_sel_hi:[0,1,1]
	v_pk_fma_f32 v[10:11], v[100:101], v[232:233], v[10:11] op_sel:[1,0,0] op_sel_hi:[1,1,1]
	ds_read_b128 v[148:151], v122 offset:8528
	ds_read_b128 v[32:35], v122 offset:8544
	ds_read_b128 v[36:39], v122 offset:8560
	ds_read_b128 v[40:43], v122 offset:8576
	s_waitcnt lgkmcnt(9)
	v_lshlrev_b32_e32 v16, 16, v16
	v_lshlrev_b32_e32 v17, 16, v17
	v_pk_add_f32 v[12:13], v[4:5], v[6:7]
	v_pk_add_f32 v[14:15], v[8:9], v[10:11]
	s_nop 0
	v_pk_add_f32 v[12:13], v[12:13], v[14:15]
	s_nop 0
	v_pk_fma_f32 v[234:235], v[18:19], v[16:17], v[12:13] neg_lo:[0,0,1] neg_hi:[0,0,1]
	ds_read_u16 v20, v115 offset:8976
	s_waitcnt lgkmcnt(9)
	v_pk_mul_f32 v[4:5], v[102:103], v[170:171] op_sel_hi:[0,1]
	v_pk_mul_f32 v[6:7], v[102:103], v[172:173] op_sel:[1,0] op_sel_hi:[1,1]
	v_pk_mul_f32 v[8:9], v[104:105], v[174:175] op_sel_hi:[0,1]
	v_pk_mul_f32 v[10:11], v[104:105], v[176:177] op_sel:[1,0] op_sel_hi:[1,1]
	ds_read_u16 v21, v116 offset:8976
	s_waitcnt lgkmcnt(9)
	v_pk_fma_f32 v[4:5], v[106:107], v[178:179], v[4:5] op_sel_hi:[0,1,1]
	v_pk_fma_f32 v[6:7], v[106:107], v[180:181], v[6:7] op_sel:[1,0,0] op_sel_hi:[1,1,1]
	v_pk_fma_f32 v[8:9], v[108:109], v[182:183], v[8:9] op_sel_hi:[0,1,1]
	v_pk_fma_f32 v[10:11], v[108:109], v[184:185], v[10:11] op_sel:[1,0,0] op_sel_hi:[1,1,1]
	ds_read_b32 v22, v126 offset:132
	s_waitcnt lgkmcnt(9)
	v_pk_fma_f32 v[4:5], v[130:131], v[186:187], v[4:5] op_sel_hi:[0,1,1]
	v_pk_fma_f32 v[6:7], v[130:131], v[188:189], v[6:7] op_sel:[1,0,0] op_sel_hi:[1,1,1]
	v_pk_fma_f32 v[8:9], v[132:133], v[190:191], v[8:9] op_sel_hi:[0,1,1]
	v_pk_fma_f32 v[10:11], v[132:133], v[192:193], v[10:11] op_sel:[1,0,0] op_sel_hi:[1,1,1]
	ds_read_b32 v23, v127 offset:132
	s_waitcnt lgkmcnt(9)
	v_pk_fma_f32 v[4:5], v[140:141], v[194:195], v[4:5] op_sel_hi:[0,1,1]
	v_pk_fma_f32 v[6:7], v[140:141], v[196:197], v[6:7] op_sel:[1,0,0] op_sel_hi:[1,1,1]
	v_pk_fma_f32 v[8:9], v[142:143], v[198:199], v[8:9] op_sel_hi:[0,1,1]
	v_pk_fma_f32 v[10:11], v[142:143], v[200:201], v[10:11] op_sel:[1,0,0] op_sel_hi:[1,1,1]
	ds_read_b128 v[98:101], v122 offset:8704
	s_waitcnt lgkmcnt(9)
	v_pk_fma_f32 v[4:5], v[144:145], v[202:203], v[4:5] op_sel_hi:[0,1,1]
	v_pk_fma_f32 v[6:7], v[144:145], v[204:205], v[6:7] op_sel:[1,0,0] op_sel_hi:[1,1,1]
	v_pk_fma_f32 v[8:9], v[146:147], v[206:207], v[8:9] op_sel_hi:[0,1,1]
	v_pk_fma_f32 v[10:11], v[146:147], v[208:209], v[10:11] op_sel:[1,0,0] op_sel_hi:[1,1,1]
	ds_read_b128 v[102:105], v122 offset:8720
	s_waitcnt lgkmcnt(9)
	v_pk_fma_f32 v[4:5], v[148:149], v[210:211], v[4:5] op_sel_hi:[0,1,1]
	v_pk_fma_f32 v[6:7], v[148:149], v[212:213], v[6:7] op_sel:[1,0,0] op_sel_hi:[1,1,1]
	v_pk_fma_f32 v[8:9], v[150:151], v[214:215], v[8:9] op_sel_hi:[0,1,1]
	v_pk_fma_f32 v[10:11], v[150:151], v[216:217], v[10:11] op_sel:[1,0,0] op_sel_hi:[1,1,1]
	ds_read_b128 v[106:109], v122 offset:8736
	s_waitcnt lgkmcnt(9)
	v_pk_fma_f32 v[4:5], v[32:33], v[218:219], v[4:5] op_sel_hi:[0,1,1]
	v_pk_fma_f32 v[6:7], v[32:33], v[220:221], v[6:7] op_sel:[1,0,0] op_sel_hi:[1,1,1]
	v_pk_fma_f32 v[8:9], v[34:35], v[222:223], v[8:9] op_sel_hi:[0,1,1]
	v_pk_fma_f32 v[10:11], v[34:35], v[224:225], v[10:11] op_sel:[1,0,0] op_sel_hi:[1,1,1]
	ds_read_b128 v[130:133], v122 offset:8752
	s_waitcnt lgkmcnt(9)
	v_pk_fma_f32 v[4:5], v[36:37], v[226:227], v[4:5] op_sel_hi:[0,1,1]
	v_pk_fma_f32 v[6:7], v[36:37], v[228:229], v[6:7] op_sel:[1,0,0] op_sel_hi:[1,1,1]
	v_pk_fma_f32 v[8:9], v[38:39], v[230:231], v[8:9] op_sel_hi:[0,1,1]
	v_pk_fma_f32 v[10:11], v[38:39], v[232:233], v[10:11] op_sel:[1,0,0] op_sel_hi:[1,1,1]
	ds_read_b128 v[140:143], v122 offset:8768
	s_waitcnt lgkmcnt(9)
	v_pk_fma_f32 v[4:5], v[40:41], v[234:235], v[4:5] op_sel_hi:[0,1,1]
	ds_read_b128 v[144:147], v122 offset:8784
	ds_read_b128 v[148:151], v122 offset:8800
	ds_read_b128 v[32:35], v122 offset:8816
	ds_read_b128 v[36:39], v122 offset:8832
	s_waitcnt lgkmcnt(9)
	v_lshlrev_b32_e32 v20, 16, v20
	v_lshlrev_b32_e32 v21, 16, v21
	v_pk_add_f32 v[12:13], v[4:5], v[6:7]
	v_pk_add_f32 v[14:15], v[8:9], v[10:11]
	s_nop 0
	v_pk_add_f32 v[12:13], v[12:13], v[14:15]
	s_nop 0
	v_pk_fma_f32 v[236:237], v[22:23], v[20:21], v[12:13] neg_lo:[0,0,1] neg_hi:[0,0,1]
	ds_read_u16 v24, v115 offset:9248
	s_waitcnt lgkmcnt(9)
	v_pk_mul_f32 v[4:5], v[98:99], v[170:171] op_sel_hi:[0,1]
	v_pk_mul_f32 v[6:7], v[98:99], v[172:173] op_sel:[1,0] op_sel_hi:[1,1]
	v_pk_mul_f32 v[8:9], v[100:101], v[174:175] op_sel_hi:[0,1]
	v_pk_mul_f32 v[10:11], v[100:101], v[176:177] op_sel:[1,0] op_sel_hi:[1,1]
	ds_read_u16 v25, v116 offset:9248
	s_waitcnt lgkmcnt(9)
	v_pk_fma_f32 v[4:5], v[102:103], v[178:179], v[4:5] op_sel_hi:[0,1,1]
	v_pk_fma_f32 v[6:7], v[102:103], v[180:181], v[6:7] op_sel:[1,0,0] op_sel_hi:[1,1,1]
	v_pk_fma_f32 v[8:9], v[104:105], v[182:183], v[8:9] op_sel_hi:[0,1,1]
	v_pk_fma_f32 v[10:11], v[104:105], v[184:185], v[10:11] op_sel:[1,0,0] op_sel_hi:[1,1,1]
	ds_read_b32 v26, v126 offset:136
	s_waitcnt lgkmcnt(9)
	v_pk_fma_f32 v[4:5], v[106:107], v[186:187], v[4:5] op_sel_hi:[0,1,1]
	v_pk_fma_f32 v[6:7], v[106:107], v[188:189], v[6:7] op_sel:[1,0,0] op_sel_hi:[1,1,1]
	v_pk_fma_f32 v[8:9], v[108:109], v[190:191], v[8:9] op_sel_hi:[0,1,1]
	v_pk_fma_f32 v[10:11], v[108:109], v[192:193], v[10:11] op_sel:[1,0,0] op_sel_hi:[1,1,1]
	ds_read_b32 v27, v127 offset:136
	s_waitcnt lgkmcnt(9)
	v_pk_fma_f32 v[4:5], v[130:131], v[194:195], v[4:5] op_sel_hi:[0,1,1]
	v_pk_fma_f32 v[6:7], v[130:131], v[196:197], v[6:7] op_sel:[1,0,0] op_sel_hi:[1,1,1]
	v_pk_fma_f32 v[8:9], v[132:133], v[198:199], v[8:9] op_sel_hi:[0,1,1]
	v_pk_fma_f32 v[10:11], v[132:133], v[200:201], v[10:11] op_sel:[1,0,0] op_sel_hi:[1,1,1]
	ds_read_b128 v[40:43], v122 offset:8960
	s_waitcnt lgkmcnt(9)
	v_pk_fma_f32 v[4:5], v[140:141], v[202:203], v[4:5] op_sel_hi:[0,1,1]
	v_pk_fma_f32 v[6:7], v[140:141], v[204:205], v[6:7] op_sel:[1,0,0] op_sel_hi:[1,1,1]
	v_pk_fma_f32 v[8:9], v[142:143], v[206:207], v[8:9] op_sel_hi:[0,1,1]
	v_pk_fma_f32 v[10:11], v[142:143], v[208:209], v[10:11] op_sel:[1,0,0] op_sel_hi:[1,1,1]
	ds_read_b128 v[98:101], v122 offset:8976
	s_waitcnt lgkmcnt(9)
	v_pk_fma_f32 v[4:5], v[144:145], v[210:211], v[4:5] op_sel_hi:[0,1,1]
	v_pk_fma_f32 v[6:7], v[144:145], v[212:213], v[6:7] op_sel:[1,0,0] op_sel_hi:[1,1,1]
	v_pk_fma_f32 v[8:9], v[146:147], v[214:215], v[8:9] op_sel_hi:[0,1,1]
	v_pk_fma_f32 v[10:11], v[146:147], v[216:217], v[10:11] op_sel:[1,0,0] op_sel_hi:[1,1,1]
	ds_read_b128 v[102:105], v122 offset:8992
	s_waitcnt lgkmcnt(9)
	v_pk_fma_f32 v[4:5], v[148:149], v[218:219], v[4:5] op_sel_hi:[0,1,1]
	v_pk_fma_f32 v[6:7], v[148:149], v[220:221], v[6:7] op_sel:[1,0,0] op_sel_hi:[1,1,1]
	v_pk_fma_f32 v[8:9], v[150:151], v[222:223], v[8:9] op_sel_hi:[0,1,1]
	v_pk_fma_f32 v[10:11], v[150:151], v[224:225], v[10:11] op_sel:[1,0,0] op_sel_hi:[1,1,1]
	ds_read_b128 v[106:109], v122 offset:9008
	s_waitcnt lgkmcnt(9)
	v_pk_fma_f32 v[4:5], v[32:33], v[226:227], v[4:5] op_sel_hi:[0,1,1]
	v_pk_fma_f32 v[6:7], v[32:33], v[228:229], v[6:7] op_sel:[1,0,0] op_sel_hi:[1,1,1]
	v_pk_fma_f32 v[8:9], v[34:35], v[230:231], v[8:9] op_sel_hi:[0,1,1]
	v_pk_fma_f32 v[10:11], v[34:35], v[232:233], v[10:11] op_sel:[1,0,0] op_sel_hi:[1,1,1]
	ds_read_b128 v[130:133], v122 offset:9024
	s_waitcnt lgkmcnt(9)
	v_pk_fma_f32 v[4:5], v[36:37], v[234:235], v[4:5] op_sel_hi:[0,1,1]
	v_pk_fma_f32 v[6:7], v[36:37], v[236:237], v[6:7] op_sel:[1,0,0] op_sel_hi:[1,1,1]
	ds_read_b128 v[140:143], v122 offset:9040
	ds_read_b128 v[144:147], v122 offset:9056
	ds_read_b128 v[148:151], v122 offset:9072
	ds_read_b128 v[32:35], v122 offset:9088
	s_waitcnt lgkmcnt(9)
	v_lshlrev_b32_e32 v24, 16, v24
	v_lshlrev_b32_e32 v25, 16, v25
	v_pk_add_f32 v[12:13], v[4:5], v[6:7]
	v_pk_add_f32 v[14:15], v[8:9], v[10:11]
	s_nop 0
	v_pk_add_f32 v[12:13], v[12:13], v[14:15]
	s_nop 0
	v_pk_fma_f32 v[238:239], v[26:27], v[24:25], v[12:13] neg_lo:[0,0,1] neg_hi:[0,0,1]
	ds_read_u16 v28, v115 offset:9520
	s_waitcnt lgkmcnt(9)
	v_pk_mul_f32 v[4:5], v[40:41], v[170:171] op_sel_hi:[0,1]
	v_pk_mul_f32 v[6:7], v[40:41], v[172:173] op_sel:[1,0] op_sel_hi:[1,1]
	v_pk_mul_f32 v[8:9], v[42:43], v[174:175] op_sel_hi:[0,1]
	v_pk_mul_f32 v[10:11], v[42:43], v[176:177] op_sel:[1,0] op_sel_hi:[1,1]
	ds_read_u16 v29, v116 offset:9520
	s_waitcnt lgkmcnt(9)
	v_pk_fma_f32 v[4:5], v[98:99], v[178:179], v[4:5] op_sel_hi:[0,1,1]
	v_pk_fma_f32 v[6:7], v[98:99], v[180:181], v[6:7] op_sel:[1,0,0] op_sel_hi:[1,1,1]
	v_pk_fma_f32 v[8:9], v[100:101], v[182:183], v[8:9] op_sel_hi:[0,1,1]
	v_pk_fma_f32 v[10:11], v[100:101], v[184:185], v[10:11] op_sel:[1,0,0] op_sel_hi:[1,1,1]
	ds_read_b32 v30, v126 offset:140
	s_waitcnt lgkmcnt(9)
	v_pk_fma_f32 v[4:5], v[102:103], v[186:187], v[4:5] op_sel_hi:[0,1,1]
	v_pk_fma_f32 v[6:7], v[102:103], v[188:189], v[6:7] op_sel:[1,0,0] op_sel_hi:[1,1,1]
	v_pk_fma_f32 v[8:9], v[104:105], v[190:191], v[8:9] op_sel_hi:[0,1,1]
	v_pk_fma_f32 v[10:11], v[104:105], v[192:193], v[10:11] op_sel:[1,0,0] op_sel_hi:[1,1,1]
	ds_read_b32 v31, v127 offset:140
	s_waitcnt lgkmcnt(9)
	v_pk_fma_f32 v[4:5], v[106:107], v[194:195], v[4:5] op_sel_hi:[0,1,1]
	v_pk_fma_f32 v[6:7], v[106:107], v[196:197], v[6:7] op_sel:[1,0,0] op_sel_hi:[1,1,1]
	v_pk_fma_f32 v[8:9], v[108:109], v[198:199], v[8:9] op_sel_hi:[0,1,1]
	v_pk_fma_f32 v[10:11], v[108:109], v[200:201], v[10:11] op_sel:[1,0,0] op_sel_hi:[1,1,1]
	ds_read_b128 v[36:39], v122 offset:9216
	s_waitcnt lgkmcnt(9)
	v_pk_fma_f32 v[4:5], v[130:131], v[202:203], v[4:5] op_sel_hi:[0,1,1]
	v_pk_fma_f32 v[6:7], v[130:131], v[204:205], v[6:7] op_sel:[1,0,0] op_sel_hi:[1,1,1]
	v_pk_fma_f32 v[8:9], v[132:133], v[206:207], v[8:9] op_sel_hi:[0,1,1]
	v_pk_fma_f32 v[10:11], v[132:133], v[208:209], v[10:11] op_sel:[1,0,0] op_sel_hi:[1,1,1]
	ds_read_b128 v[40:43], v122 offset:9232
	s_waitcnt lgkmcnt(9)
	v_pk_fma_f32 v[4:5], v[140:141], v[210:211], v[4:5] op_sel_hi:[0,1,1]
	v_pk_fma_f32 v[6:7], v[140:141], v[212:213], v[6:7] op_sel:[1,0,0] op_sel_hi:[1,1,1]
	v_pk_fma_f32 v[8:9], v[142:143], v[214:215], v[8:9] op_sel_hi:[0,1,1]
	v_pk_fma_f32 v[10:11], v[142:143], v[216:217], v[10:11] op_sel:[1,0,0] op_sel_hi:[1,1,1]
	ds_read_b128 v[98:101], v122 offset:9248
	s_waitcnt lgkmcnt(9)
	v_pk_fma_f32 v[4:5], v[144:145], v[218:219], v[4:5] op_sel_hi:[0,1,1]
	v_pk_fma_f32 v[6:7], v[144:145], v[220:221], v[6:7] op_sel:[1,0,0] op_sel_hi:[1,1,1]
	v_pk_fma_f32 v[8:9], v[146:147], v[222:223], v[8:9] op_sel_hi:[0,1,1]
	v_pk_fma_f32 v[10:11], v[146:147], v[224:225], v[10:11] op_sel:[1,0,0] op_sel_hi:[1,1,1]
	ds_read_b128 v[102:105], v122 offset:9264
	s_waitcnt lgkmcnt(9)
	v_pk_fma_f32 v[4:5], v[148:149], v[226:227], v[4:5] op_sel_hi:[0,1,1]
	v_pk_fma_f32 v[6:7], v[148:149], v[228:229], v[6:7] op_sel:[1,0,0] op_sel_hi:[1,1,1]
	v_pk_fma_f32 v[8:9], v[150:151], v[230:231], v[8:9] op_sel_hi:[0,1,1]
	v_pk_fma_f32 v[10:11], v[150:151], v[232:233], v[10:11] op_sel:[1,0,0] op_sel_hi:[1,1,1]
	ds_read_b128 v[106:109], v122 offset:9280
	s_waitcnt lgkmcnt(9)
	v_pk_fma_f32 v[4:5], v[32:33], v[234:235], v[4:5] op_sel_hi:[0,1,1]
	v_pk_fma_f32 v[6:7], v[32:33], v[236:237], v[6:7] op_sel:[1,0,0] op_sel_hi:[1,1,1]
	v_pk_fma_f32 v[8:9], v[34:35], v[238:239], v[8:9] op_sel_hi:[0,1,1]
	ds_read_b128 v[130:133], v122 offset:9296
	ds_read_b128 v[140:143], v122 offset:9312
	ds_read_b128 v[144:147], v122 offset:9328
	ds_read_b128 v[148:151], v122 offset:9344
	s_waitcnt lgkmcnt(9)
	v_lshlrev_b32_e32 v28, 16, v28
	v_lshlrev_b32_e32 v29, 16, v29
	v_pk_add_f32 v[12:13], v[4:5], v[6:7]
	v_pk_add_f32 v[14:15], v[8:9], v[10:11]
	s_nop 0
	v_pk_add_f32 v[12:13], v[12:13], v[14:15]
	s_nop 0
	v_pk_fma_f32 v[240:241], v[30:31], v[28:29], v[12:13] neg_lo:[0,0,1] neg_hi:[0,0,1]
	ds_read_u16 v16, v115 offset:9792
	s_waitcnt lgkmcnt(9)
	v_pk_mul_f32 v[4:5], v[36:37], v[170:171] op_sel_hi:[0,1]
	v_pk_mul_f32 v[6:7], v[36:37], v[172:173] op_sel:[1,0] op_sel_hi:[1,1]
	v_pk_mul_f32 v[8:9], v[38:39], v[174:175] op_sel_hi:[0,1]
	v_pk_mul_f32 v[10:11], v[38:39], v[176:177] op_sel:[1,0] op_sel_hi:[1,1]
	ds_read_u16 v17, v116 offset:9792
	s_waitcnt lgkmcnt(9)
	v_pk_fma_f32 v[4:5], v[40:41], v[178:179], v[4:5] op_sel_hi:[0,1,1]
	v_pk_fma_f32 v[6:7], v[40:41], v[180:181], v[6:7] op_sel:[1,0,0] op_sel_hi:[1,1,1]
	v_pk_fma_f32 v[8:9], v[42:43], v[182:183], v[8:9] op_sel_hi:[0,1,1]
	v_pk_fma_f32 v[10:11], v[42:43], v[184:185], v[10:11] op_sel:[1,0,0] op_sel_hi:[1,1,1]
	ds_read_b32 v18, v126 offset:144
	s_waitcnt lgkmcnt(9)
	v_pk_fma_f32 v[4:5], v[98:99], v[186:187], v[4:5] op_sel_hi:[0,1,1]
	v_pk_fma_f32 v[6:7], v[98:99], v[188:189], v[6:7] op_sel:[1,0,0] op_sel_hi:[1,1,1]
	v_pk_fma_f32 v[8:9], v[100:101], v[190:191], v[8:9] op_sel_hi:[0,1,1]
	v_pk_fma_f32 v[10:11], v[100:101], v[192:193], v[10:11] op_sel:[1,0,0] op_sel_hi:[1,1,1]
	ds_read_b32 v19, v127 offset:144
	s_waitcnt lgkmcnt(9)
	v_pk_fma_f32 v[4:5], v[102:103], v[194:195], v[4:5] op_sel_hi:[0,1,1]
	v_pk_fma_f32 v[6:7], v[102:103], v[196:197], v[6:7] op_sel:[1,0,0] op_sel_hi:[1,1,1]
	v_pk_fma_f32 v[8:9], v[104:105], v[198:199], v[8:9] op_sel_hi:[0,1,1]
	v_pk_fma_f32 v[10:11], v[104:105], v[200:201], v[10:11] op_sel:[1,0,0] op_sel_hi:[1,1,1]
	ds_read_b128 v[32:35], v122 offset:9472
	s_waitcnt lgkmcnt(9)
	v_pk_fma_f32 v[4:5], v[106:107], v[202:203], v[4:5] op_sel_hi:[0,1,1]
	v_pk_fma_f32 v[6:7], v[106:107], v[204:205], v[6:7] op_sel:[1,0,0] op_sel_hi:[1,1,1]
	v_pk_fma_f32 v[8:9], v[108:109], v[206:207], v[8:9] op_sel_hi:[0,1,1]
	v_pk_fma_f32 v[10:11], v[108:109], v[208:209], v[10:11] op_sel:[1,0,0] op_sel_hi:[1,1,1]
	ds_read_b128 v[36:39], v122 offset:9488
	s_waitcnt lgkmcnt(9)
	v_pk_fma_f32 v[4:5], v[130:131], v[210:211], v[4:5] op_sel_hi:[0,1,1]
	v_pk_fma_f32 v[6:7], v[130:131], v[212:213], v[6:7] op_sel:[1,0,0] op_sel_hi:[1,1,1]
	v_pk_fma_f32 v[8:9], v[132:133], v[214:215], v[8:9] op_sel_hi:[0,1,1]
	v_pk_fma_f32 v[10:11], v[132:133], v[216:217], v[10:11] op_sel:[1,0,0] op_sel_hi:[1,1,1]
	ds_read_b128 v[40:43], v122 offset:9504
	s_waitcnt lgkmcnt(9)
	v_pk_fma_f32 v[4:5], v[140:141], v[218:219], v[4:5] op_sel_hi:[0,1,1]
	v_pk_fma_f32 v[6:7], v[140:141], v[220:221], v[6:7] op_sel:[1,0,0] op_sel_hi:[1,1,1]
	v_pk_fma_f32 v[8:9], v[142:143], v[222:223], v[8:9] op_sel_hi:[0,1,1]
	v_pk_fma_f32 v[10:11], v[142:143], v[224:225], v[10:11] op_sel:[1,0,0] op_sel_hi:[1,1,1]
	ds_read_b128 v[98:101], v122 offset:9520
	s_waitcnt lgkmcnt(9)
	v_pk_fma_f32 v[4:5], v[144:145], v[226:227], v[4:5] op_sel_hi:[0,1,1]
	v_pk_fma_f32 v[6:7], v[144:145], v[228:229], v[6:7] op_sel:[1,0,0] op_sel_hi:[1,1,1]
	v_pk_fma_f32 v[8:9], v[146:147], v[230:231], v[8:9] op_sel_hi:[0,1,1]
	v_pk_fma_f32 v[10:11], v[146:147], v[232:233], v[10:11] op_sel:[1,0,0] op_sel_hi:[1,1,1]
	ds_read_b128 v[102:105], v122 offset:9536
	s_waitcnt lgkmcnt(9)
	v_pk_fma_f32 v[4:5], v[148:149], v[234:235], v[4:5] op_sel_hi:[0,1,1]
	v_pk_fma_f32 v[6:7], v[148:149], v[236:237], v[6:7] op_sel:[1,0,0] op_sel_hi:[1,1,1]
	v_pk_fma_f32 v[8:9], v[150:151], v[238:239], v[8:9] op_sel_hi:[0,1,1]
	v_pk_fma_f32 v[10:11], v[150:151], v[240:241], v[10:11] op_sel:[1,0,0] op_sel_hi:[1,1,1]
	ds_read_b128 v[106:109], v122 offset:9552
	ds_read_b128 v[130:133], v122 offset:9568
	ds_read_b128 v[140:143], v122 offset:9584
	ds_read_b128 v[144:147], v122 offset:9600
	s_waitcnt lgkmcnt(9)
	v_lshlrev_b32_e32 v16, 16, v16
	v_lshlrev_b32_e32 v17, 16, v17
	v_pk_add_f32 v[12:13], v[4:5], v[6:7]
	v_pk_add_f32 v[14:15], v[8:9], v[10:11]
	s_nop 0
	v_pk_add_f32 v[12:13], v[12:13], v[14:15]
	s_nop 0
	v_pk_fma_f32 v[242:243], v[18:19], v[16:17], v[12:13] neg_lo:[0,0,1] neg_hi:[0,0,1]
	ds_read_b128 v[148:151], v122 offset:9616
	s_waitcnt lgkmcnt(9)
	v_pk_mul_f32 v[4:5], v[32:33], v[170:171] op_sel_hi:[0,1]
	v_pk_mul_f32 v[6:7], v[32:33], v[172:173] op_sel:[1,0] op_sel_hi:[1,1]
	v_pk_mul_f32 v[8:9], v[34:35], v[174:175] op_sel_hi:[0,1]
	v_pk_mul_f32 v[10:11], v[34:35], v[176:177] op_sel:[1,0] op_sel_hi:[1,1]
	ds_read_u16 v20, v115 offset:10064
	s_waitcnt lgkmcnt(9)
	v_pk_fma_f32 v[4:5], v[36:37], v[178:179], v[4:5] op_sel_hi:[0,1,1]
	v_pk_fma_f32 v[6:7], v[36:37], v[180:181], v[6:7] op_sel:[1,0,0] op_sel_hi:[1,1,1]
	v_pk_fma_f32 v[8:9], v[38:39], v[182:183], v[8:9] op_sel_hi:[0,1,1]
	v_pk_fma_f32 v[10:11], v[38:39], v[184:185], v[10:11] op_sel:[1,0,0] op_sel_hi:[1,1,1]
	ds_read_u16 v21, v116 offset:10064
	s_waitcnt lgkmcnt(9)
	v_pk_fma_f32 v[4:5], v[40:41], v[186:187], v[4:5] op_sel_hi:[0,1,1]
	v_pk_fma_f32 v[6:7], v[40:41], v[188:189], v[6:7] op_sel:[1,0,0] op_sel_hi:[1,1,1]
	v_pk_fma_f32 v[8:9], v[42:43], v[190:191], v[8:9] op_sel_hi:[0,1,1]
	v_pk_fma_f32 v[10:11], v[42:43], v[192:193], v[10:11] op_sel:[1,0,0] op_sel_hi:[1,1,1]
	ds_read_b32 v22, v126 offset:148
	s_waitcnt lgkmcnt(9)
	v_pk_fma_f32 v[4:5], v[98:99], v[194:195], v[4:5] op_sel_hi:[0,1,1]
	v_pk_fma_f32 v[6:7], v[98:99], v[196:197], v[6:7] op_sel:[1,0,0] op_sel_hi:[1,1,1]
	v_pk_fma_f32 v[8:9], v[100:101], v[198:199], v[8:9] op_sel_hi:[0,1,1]
	v_pk_fma_f32 v[10:11], v[100:101], v[200:201], v[10:11] op_sel:[1,0,0] op_sel_hi:[1,1,1]
	ds_read_b32 v23, v127 offset:148
	s_waitcnt lgkmcnt(9)
	v_pk_fma_f32 v[4:5], v[102:103], v[202:203], v[4:5] op_sel_hi:[0,1,1]
	v_pk_fma_f32 v[6:7], v[102:103], v[204:205], v[6:7] op_sel:[1,0,0] op_sel_hi:[1,1,1]
	v_pk_fma_f32 v[8:9], v[104:105], v[206:207], v[8:9] op_sel_hi:[0,1,1]
	v_pk_fma_f32 v[10:11], v[104:105], v[208:209], v[10:11] op_sel:[1,0,0] op_sel_hi:[1,1,1]
	ds_read_b128 v[32:35], v122 offset:9728
	s_waitcnt lgkmcnt(9)
	v_pk_fma_f32 v[4:5], v[106:107], v[210:211], v[4:5] op_sel_hi:[0,1,1]
	v_pk_fma_f32 v[6:7], v[106:107], v[212:213], v[6:7] op_sel:[1,0,0] op_sel_hi:[1,1,1]
	v_pk_fma_f32 v[8:9], v[108:109], v[214:215], v[8:9] op_sel_hi:[0,1,1]
	v_pk_fma_f32 v[10:11], v[108:109], v[216:217], v[10:11] op_sel:[1,0,0] op_sel_hi:[1,1,1]
	ds_read_b128 v[36:39], v122 offset:9744
	s_waitcnt lgkmcnt(9)
	v_pk_fma_f32 v[4:5], v[130:131], v[218:219], v[4:5] op_sel_hi:[0,1,1]
	v_pk_fma_f32 v[6:7], v[130:131], v[220:221], v[6:7] op_sel:[1,0,0] op_sel_hi:[1,1,1]
	v_pk_fma_f32 v[8:9], v[132:133], v[222:223], v[8:9] op_sel_hi:[0,1,1]
	v_pk_fma_f32 v[10:11], v[132:133], v[224:225], v[10:11] op_sel:[1,0,0] op_sel_hi:[1,1,1]
	ds_read_b128 v[40:43], v122 offset:9760
	s_waitcnt lgkmcnt(9)
	v_pk_fma_f32 v[4:5], v[140:141], v[226:227], v[4:5] op_sel_hi:[0,1,1]
	v_pk_fma_f32 v[6:7], v[140:141], v[228:229], v[6:7] op_sel:[1,0,0] op_sel_hi:[1,1,1]
	v_pk_fma_f32 v[8:9], v[142:143], v[230:231], v[8:9] op_sel_hi:[0,1,1]
	v_pk_fma_f32 v[10:11], v[142:143], v[232:233], v[10:11] op_sel:[1,0,0] op_sel_hi:[1,1,1]
	ds_read_b128 v[98:101], v122 offset:9776
	s_waitcnt lgkmcnt(9)
	v_pk_fma_f32 v[4:5], v[144:145], v[234:235], v[4:5] op_sel_hi:[0,1,1]
	v_pk_fma_f32 v[6:7], v[144:145], v[236:237], v[6:7] op_sel:[1,0,0] op_sel_hi:[1,1,1]
	v_pk_fma_f32 v[8:9], v[146:147], v[238:239], v[8:9] op_sel_hi:[0,1,1]
	v_pk_fma_f32 v[10:11], v[146:147], v[240:241], v[10:11] op_sel:[1,0,0] op_sel_hi:[1,1,1]
	ds_read_b128 v[102:105], v122 offset:9792
	s_waitcnt lgkmcnt(9)
	v_pk_fma_f32 v[4:5], v[148:149], v[242:243], v[4:5] op_sel_hi:[0,1,1]
	ds_read_b128 v[106:109], v122 offset:9808
	ds_read_b128 v[130:133], v122 offset:9824
	ds_read_b128 v[140:143], v122 offset:9840
	ds_read_b128 v[144:147], v122 offset:9856
	s_waitcnt lgkmcnt(9)
	v_lshlrev_b32_e32 v20, 16, v20
	v_lshlrev_b32_e32 v21, 16, v21
	v_pk_add_f32 v[12:13], v[4:5], v[6:7]
	v_pk_add_f32 v[14:15], v[8:9], v[10:11]
	s_nop 0
	v_pk_add_f32 v[12:13], v[12:13], v[14:15]
	s_nop 0
	v_pk_fma_f32 v[244:245], v[22:23], v[20:21], v[12:13] neg_lo:[0,0,1] neg_hi:[0,0,1]
	ds_read_b128 v[148:151], v122 offset:9872
	s_waitcnt lgkmcnt(9)
	v_pk_mul_f32 v[4:5], v[32:33], v[170:171] op_sel_hi:[0,1]
	v_pk_mul_f32 v[6:7], v[32:33], v[172:173] op_sel:[1,0] op_sel_hi:[1,1]
	v_pk_mul_f32 v[8:9], v[34:35], v[174:175] op_sel_hi:[0,1]
	v_pk_mul_f32 v[10:11], v[34:35], v[176:177] op_sel:[1,0] op_sel_hi:[1,1]
	ds_read_u16 v24, v115 offset:10336
	s_waitcnt lgkmcnt(9)
	v_pk_fma_f32 v[4:5], v[36:37], v[178:179], v[4:5] op_sel_hi:[0,1,1]
	v_pk_fma_f32 v[6:7], v[36:37], v[180:181], v[6:7] op_sel:[1,0,0] op_sel_hi:[1,1,1]
	v_pk_fma_f32 v[8:9], v[38:39], v[182:183], v[8:9] op_sel_hi:[0,1,1]
	v_pk_fma_f32 v[10:11], v[38:39], v[184:185], v[10:11] op_sel:[1,0,0] op_sel_hi:[1,1,1]
	ds_read_u16 v25, v116 offset:10336
	s_waitcnt lgkmcnt(9)
	v_pk_fma_f32 v[4:5], v[40:41], v[186:187], v[4:5] op_sel_hi:[0,1,1]
	v_pk_fma_f32 v[6:7], v[40:41], v[188:189], v[6:7] op_sel:[1,0,0] op_sel_hi:[1,1,1]
	v_pk_fma_f32 v[8:9], v[42:43], v[190:191], v[8:9] op_sel_hi:[0,1,1]
	v_pk_fma_f32 v[10:11], v[42:43], v[192:193], v[10:11] op_sel:[1,0,0] op_sel_hi:[1,1,1]
	ds_read_b32 v26, v126 offset:152
	s_waitcnt lgkmcnt(9)
	v_pk_fma_f32 v[4:5], v[98:99], v[194:195], v[4:5] op_sel_hi:[0,1,1]
	v_pk_fma_f32 v[6:7], v[98:99], v[196:197], v[6:7] op_sel:[1,0,0] op_sel_hi:[1,1,1]
	v_pk_fma_f32 v[8:9], v[100:101], v[198:199], v[8:9] op_sel_hi:[0,1,1]
	v_pk_fma_f32 v[10:11], v[100:101], v[200:201], v[10:11] op_sel:[1,0,0] op_sel_hi:[1,1,1]
	ds_read_b32 v27, v127 offset:152
	s_waitcnt lgkmcnt(9)
	v_pk_fma_f32 v[4:5], v[102:103], v[202:203], v[4:5] op_sel_hi:[0,1,1]
	v_pk_fma_f32 v[6:7], v[102:103], v[204:205], v[6:7] op_sel:[1,0,0] op_sel_hi:[1,1,1]
	v_pk_fma_f32 v[8:9], v[104:105], v[206:207], v[8:9] op_sel_hi:[0,1,1]
	v_pk_fma_f32 v[10:11], v[104:105], v[208:209], v[10:11] op_sel:[1,0,0] op_sel_hi:[1,1,1]
	ds_read_b128 v[32:35], v122 offset:9984
	s_waitcnt lgkmcnt(9)
	v_pk_fma_f32 v[4:5], v[106:107], v[210:211], v[4:5] op_sel_hi:[0,1,1]
	v_pk_fma_f32 v[6:7], v[106:107], v[212:213], v[6:7] op_sel:[1,0,0] op_sel_hi:[1,1,1]
	v_pk_fma_f32 v[8:9], v[108:109], v[214:215], v[8:9] op_sel_hi:[0,1,1]
	v_pk_fma_f32 v[10:11], v[108:109], v[216:217], v[10:11] op_sel:[1,0,0] op_sel_hi:[1,1,1]
	ds_read_b128 v[36:39], v122 offset:10000
	s_waitcnt lgkmcnt(9)
	v_pk_fma_f32 v[4:5], v[130:131], v[218:219], v[4:5] op_sel_hi:[0,1,1]
	v_pk_fma_f32 v[6:7], v[130:131], v[220:221], v[6:7] op_sel:[1,0,0] op_sel_hi:[1,1,1]
	v_pk_fma_f32 v[8:9], v[132:133], v[222:223], v[8:9] op_sel_hi:[0,1,1]
	v_pk_fma_f32 v[10:11], v[132:133], v[224:225], v[10:11] op_sel:[1,0,0] op_sel_hi:[1,1,1]
	ds_read_b128 v[40:43], v122 offset:10016
	s_waitcnt lgkmcnt(9)
	v_pk_fma_f32 v[4:5], v[140:141], v[226:227], v[4:5] op_sel_hi:[0,1,1]
	v_pk_fma_f32 v[6:7], v[140:141], v[228:229], v[6:7] op_sel:[1,0,0] op_sel_hi:[1,1,1]
	v_pk_fma_f32 v[8:9], v[142:143], v[230:231], v[8:9] op_sel_hi:[0,1,1]
	v_pk_fma_f32 v[10:11], v[142:143], v[232:233], v[10:11] op_sel:[1,0,0] op_sel_hi:[1,1,1]
	ds_read_b128 v[98:101], v122 offset:10032
	s_waitcnt lgkmcnt(9)
	v_pk_fma_f32 v[4:5], v[144:145], v[234:235], v[4:5] op_sel_hi:[0,1,1]
	v_pk_fma_f32 v[6:7], v[144:145], v[236:237], v[6:7] op_sel:[1,0,0] op_sel_hi:[1,1,1]
	v_pk_fma_f32 v[8:9], v[146:147], v[238:239], v[8:9] op_sel_hi:[0,1,1]
	v_pk_fma_f32 v[10:11], v[146:147], v[240:241], v[10:11] op_sel:[1,0,0] op_sel_hi:[1,1,1]
	ds_read_b128 v[102:105], v122 offset:10048
	s_waitcnt lgkmcnt(9)
	v_pk_fma_f32 v[4:5], v[148:149], v[242:243], v[4:5] op_sel_hi:[0,1,1]
	v_pk_fma_f32 v[6:7], v[148:149], v[244:245], v[6:7] op_sel:[1,0,0] op_sel_hi:[1,1,1]
	ds_read_b128 v[106:109], v122 offset:10064
	ds_read_b128 v[130:133], v122 offset:10080
	ds_read_b128 v[140:143], v122 offset:10096
	ds_read_b128 v[144:147], v122 offset:10112
	s_waitcnt lgkmcnt(9)
	v_lshlrev_b32_e32 v24, 16, v24
	v_lshlrev_b32_e32 v25, 16, v25
	v_pk_add_f32 v[12:13], v[4:5], v[6:7]
	v_pk_add_f32 v[14:15], v[8:9], v[10:11]
	s_nop 0
	v_pk_add_f32 v[12:13], v[12:13], v[14:15]
	s_nop 0
	v_pk_fma_f32 v[246:247], v[26:27], v[24:25], v[12:13] neg_lo:[0,0,1] neg_hi:[0,0,1]
	ds_read_b128 v[148:151], v122 offset:10128
	s_waitcnt lgkmcnt(9)
	v_pk_mul_f32 v[4:5], v[32:33], v[170:171] op_sel_hi:[0,1]
	v_pk_mul_f32 v[6:7], v[32:33], v[172:173] op_sel:[1,0] op_sel_hi:[1,1]
	v_pk_mul_f32 v[8:9], v[34:35], v[174:175] op_sel_hi:[0,1]
	v_pk_mul_f32 v[10:11], v[34:35], v[176:177] op_sel:[1,0] op_sel_hi:[1,1]
	ds_read_u16 v28, v115 offset:10608
	s_waitcnt lgkmcnt(9)
	v_pk_fma_f32 v[4:5], v[36:37], v[178:179], v[4:5] op_sel_hi:[0,1,1]
	v_pk_fma_f32 v[6:7], v[36:37], v[180:181], v[6:7] op_sel:[1,0,0] op_sel_hi:[1,1,1]
	v_pk_fma_f32 v[8:9], v[38:39], v[182:183], v[8:9] op_sel_hi:[0,1,1]
	v_pk_fma_f32 v[10:11], v[38:39], v[184:185], v[10:11] op_sel:[1,0,0] op_sel_hi:[1,1,1]
	ds_read_u16 v29, v116 offset:10608
	s_waitcnt lgkmcnt(9)
	v_pk_fma_f32 v[4:5], v[40:41], v[186:187], v[4:5] op_sel_hi:[0,1,1]
	v_pk_fma_f32 v[6:7], v[40:41], v[188:189], v[6:7] op_sel:[1,0,0] op_sel_hi:[1,1,1]
	v_pk_fma_f32 v[8:9], v[42:43], v[190:191], v[8:9] op_sel_hi:[0,1,1]
	v_pk_fma_f32 v[10:11], v[42:43], v[192:193], v[10:11] op_sel:[1,0,0] op_sel_hi:[1,1,1]
	ds_read_b32 v30, v126 offset:156
	s_waitcnt lgkmcnt(9)
	v_pk_fma_f32 v[4:5], v[98:99], v[194:195], v[4:5] op_sel_hi:[0,1,1]
	v_pk_fma_f32 v[6:7], v[98:99], v[196:197], v[6:7] op_sel:[1,0,0] op_sel_hi:[1,1,1]
	v_pk_fma_f32 v[8:9], v[100:101], v[198:199], v[8:9] op_sel_hi:[0,1,1]
	v_pk_fma_f32 v[10:11], v[100:101], v[200:201], v[10:11] op_sel:[1,0,0] op_sel_hi:[1,1,1]
	ds_read_b32 v31, v127 offset:156
	s_waitcnt lgkmcnt(9)
	v_pk_fma_f32 v[4:5], v[102:103], v[202:203], v[4:5] op_sel_hi:[0,1,1]
	v_pk_fma_f32 v[6:7], v[102:103], v[204:205], v[6:7] op_sel:[1,0,0] op_sel_hi:[1,1,1]
	v_pk_fma_f32 v[8:9], v[104:105], v[206:207], v[8:9] op_sel_hi:[0,1,1]
	v_pk_fma_f32 v[10:11], v[104:105], v[208:209], v[10:11] op_sel:[1,0,0] op_sel_hi:[1,1,1]
	ds_read_b128 v[32:35], v122 offset:10240
	s_waitcnt lgkmcnt(9)
	v_pk_fma_f32 v[4:5], v[106:107], v[210:211], v[4:5] op_sel_hi:[0,1,1]
	v_pk_fma_f32 v[6:7], v[106:107], v[212:213], v[6:7] op_sel:[1,0,0] op_sel_hi:[1,1,1]
	v_pk_fma_f32 v[8:9], v[108:109], v[214:215], v[8:9] op_sel_hi:[0,1,1]
	v_pk_fma_f32 v[10:11], v[108:109], v[216:217], v[10:11] op_sel:[1,0,0] op_sel_hi:[1,1,1]
	ds_read_b128 v[36:39], v122 offset:10256
	s_waitcnt lgkmcnt(9)
	v_pk_fma_f32 v[4:5], v[130:131], v[218:219], v[4:5] op_sel_hi:[0,1,1]
	v_pk_fma_f32 v[6:7], v[130:131], v[220:221], v[6:7] op_sel:[1,0,0] op_sel_hi:[1,1,1]
	v_pk_fma_f32 v[8:9], v[132:133], v[222:223], v[8:9] op_sel_hi:[0,1,1]
	v_pk_fma_f32 v[10:11], v[132:133], v[224:225], v[10:11] op_sel:[1,0,0] op_sel_hi:[1,1,1]
	ds_read_b128 v[40:43], v122 offset:10272
	s_waitcnt lgkmcnt(9)
	v_pk_fma_f32 v[4:5], v[140:141], v[226:227], v[4:5] op_sel_hi:[0,1,1]
	v_pk_fma_f32 v[6:7], v[140:141], v[228:229], v[6:7] op_sel:[1,0,0] op_sel_hi:[1,1,1]
	v_pk_fma_f32 v[8:9], v[142:143], v[230:231], v[8:9] op_sel_hi:[0,1,1]
	v_pk_fma_f32 v[10:11], v[142:143], v[232:233], v[10:11] op_sel:[1,0,0] op_sel_hi:[1,1,1]
	ds_read_b128 v[98:101], v122 offset:10288
	s_waitcnt lgkmcnt(9)
	v_pk_fma_f32 v[4:5], v[144:145], v[234:235], v[4:5] op_sel_hi:[0,1,1]
	v_pk_fma_f32 v[6:7], v[144:145], v[236:237], v[6:7] op_sel:[1,0,0] op_sel_hi:[1,1,1]
	v_pk_fma_f32 v[8:9], v[146:147], v[238:239], v[8:9] op_sel_hi:[0,1,1]
	v_pk_fma_f32 v[10:11], v[146:147], v[240:241], v[10:11] op_sel:[1,0,0] op_sel_hi:[1,1,1]
	ds_read_b128 v[102:105], v122 offset:10304
	s_waitcnt lgkmcnt(9)
	v_pk_fma_f32 v[4:5], v[148:149], v[242:243], v[4:5] op_sel_hi:[0,1,1]
	v_pk_fma_f32 v[6:7], v[148:149], v[244:245], v[6:7] op_sel:[1,0,0] op_sel_hi:[1,1,1]
	v_pk_fma_f32 v[8:9], v[150:151], v[246:247], v[8:9] op_sel_hi:[0,1,1]
	ds_read_b128 v[106:109], v122 offset:10320
	ds_read_b128 v[130:133], v122 offset:10336
	ds_read_b128 v[140:143], v122 offset:10352
	ds_read_b128 v[144:147], v122 offset:10368
	s_waitcnt lgkmcnt(9)
	v_lshlrev_b32_e32 v28, 16, v28
	v_lshlrev_b32_e32 v29, 16, v29
	v_pk_add_f32 v[12:13], v[4:5], v[6:7]
	v_pk_add_f32 v[14:15], v[8:9], v[10:11]
	s_nop 0
	v_pk_add_f32 v[12:13], v[12:13], v[14:15]
	s_nop 0
	v_pk_fma_f32 v[248:249], v[30:31], v[28:29], v[12:13] neg_lo:[0,0,1] neg_hi:[0,0,1]
	ds_read_b128 v[148:151], v122 offset:10384
	s_waitcnt lgkmcnt(9)
	v_pk_mul_f32 v[4:5], v[32:33], v[170:171] op_sel_hi:[0,1]
	v_pk_mul_f32 v[6:7], v[32:33], v[172:173] op_sel:[1,0] op_sel_hi:[1,1]
	v_pk_mul_f32 v[8:9], v[34:35], v[174:175] op_sel_hi:[0,1]
	v_pk_mul_f32 v[10:11], v[34:35], v[176:177] op_sel:[1,0] op_sel_hi:[1,1]
	ds_read_u16 v16, v115 offset:10880
	s_waitcnt lgkmcnt(9)
	v_pk_fma_f32 v[4:5], v[36:37], v[178:179], v[4:5] op_sel_hi:[0,1,1]
	v_pk_fma_f32 v[6:7], v[36:37], v[180:181], v[6:7] op_sel:[1,0,0] op_sel_hi:[1,1,1]
	v_pk_fma_f32 v[8:9], v[38:39], v[182:183], v[8:9] op_sel_hi:[0,1,1]
	v_pk_fma_f32 v[10:11], v[38:39], v[184:185], v[10:11] op_sel:[1,0,0] op_sel_hi:[1,1,1]
	ds_read_u16 v17, v116 offset:10880
	s_waitcnt lgkmcnt(9)
	v_pk_fma_f32 v[4:5], v[40:41], v[186:187], v[4:5] op_sel_hi:[0,1,1]
	v_pk_fma_f32 v[6:7], v[40:41], v[188:189], v[6:7] op_sel:[1,0,0] op_sel_hi:[1,1,1]
	v_pk_fma_f32 v[8:9], v[42:43], v[190:191], v[8:9] op_sel_hi:[0,1,1]
	v_pk_fma_f32 v[10:11], v[42:43], v[192:193], v[10:11] op_sel:[1,0,0] op_sel_hi:[1,1,1]
	ds_read_b32 v18, v126 offset:160
	s_waitcnt lgkmcnt(9)
	v_pk_fma_f32 v[4:5], v[98:99], v[194:195], v[4:5] op_sel_hi:[0,1,1]
	v_pk_fma_f32 v[6:7], v[98:99], v[196:197], v[6:7] op_sel:[1,0,0] op_sel_hi:[1,1,1]
	v_pk_fma_f32 v[8:9], v[100:101], v[198:199], v[8:9] op_sel_hi:[0,1,1]
	v_pk_fma_f32 v[10:11], v[100:101], v[200:201], v[10:11] op_sel:[1,0,0] op_sel_hi:[1,1,1]
	ds_read_b32 v19, v127 offset:160
	s_waitcnt lgkmcnt(9)
	v_pk_fma_f32 v[4:5], v[102:103], v[202:203], v[4:5] op_sel_hi:[0,1,1]
	v_pk_fma_f32 v[6:7], v[102:103], v[204:205], v[6:7] op_sel:[1,0,0] op_sel_hi:[1,1,1]
	v_pk_fma_f32 v[8:9], v[104:105], v[206:207], v[8:9] op_sel_hi:[0,1,1]
	v_pk_fma_f32 v[10:11], v[104:105], v[208:209], v[10:11] op_sel:[1,0,0] op_sel_hi:[1,1,1]
	ds_read_b128 v[32:35], v122 offset:10496
	s_waitcnt lgkmcnt(9)
	v_pk_fma_f32 v[4:5], v[106:107], v[210:211], v[4:5] op_sel_hi:[0,1,1]
	v_pk_fma_f32 v[6:7], v[106:107], v[212:213], v[6:7] op_sel:[1,0,0] op_sel_hi:[1,1,1]
	v_pk_fma_f32 v[8:9], v[108:109], v[214:215], v[8:9] op_sel_hi:[0,1,1]
	v_pk_fma_f32 v[10:11], v[108:109], v[216:217], v[10:11] op_sel:[1,0,0] op_sel_hi:[1,1,1]
	ds_read_b128 v[36:39], v122 offset:10512
	s_waitcnt lgkmcnt(9)
	v_pk_fma_f32 v[4:5], v[130:131], v[218:219], v[4:5] op_sel_hi:[0,1,1]
	v_pk_fma_f32 v[6:7], v[130:131], v[220:221], v[6:7] op_sel:[1,0,0] op_sel_hi:[1,1,1]
	v_pk_fma_f32 v[8:9], v[132:133], v[222:223], v[8:9] op_sel_hi:[0,1,1]
	v_pk_fma_f32 v[10:11], v[132:133], v[224:225], v[10:11] op_sel:[1,0,0] op_sel_hi:[1,1,1]
	ds_read_b128 v[40:43], v122 offset:10528
	s_waitcnt lgkmcnt(9)
	v_pk_fma_f32 v[4:5], v[140:141], v[226:227], v[4:5] op_sel_hi:[0,1,1]
	v_pk_fma_f32 v[6:7], v[140:141], v[228:229], v[6:7] op_sel:[1,0,0] op_sel_hi:[1,1,1]
	v_pk_fma_f32 v[8:9], v[142:143], v[230:231], v[8:9] op_sel_hi:[0,1,1]
	v_pk_fma_f32 v[10:11], v[142:143], v[232:233], v[10:11] op_sel:[1,0,0] op_sel_hi:[1,1,1]
	ds_read_b128 v[98:101], v122 offset:10544
	s_waitcnt lgkmcnt(9)
	v_pk_fma_f32 v[4:5], v[144:145], v[234:235], v[4:5] op_sel_hi:[0,1,1]
	v_pk_fma_f32 v[6:7], v[144:145], v[236:237], v[6:7] op_sel:[1,0,0] op_sel_hi:[1,1,1]
	v_pk_fma_f32 v[8:9], v[146:147], v[238:239], v[8:9] op_sel_hi:[0,1,1]
	v_pk_fma_f32 v[10:11], v[146:147], v[240:241], v[10:11] op_sel:[1,0,0] op_sel_hi:[1,1,1]
	ds_read_b128 v[102:105], v122 offset:10560
	s_waitcnt lgkmcnt(9)
	v_pk_fma_f32 v[4:5], v[148:149], v[242:243], v[4:5] op_sel_hi:[0,1,1]
	v_pk_fma_f32 v[6:7], v[148:149], v[244:245], v[6:7] op_sel:[1,0,0] op_sel_hi:[1,1,1]
	v_pk_fma_f32 v[8:9], v[150:151], v[246:247], v[8:9] op_sel_hi:[0,1,1]
	v_pk_fma_f32 v[10:11], v[150:151], v[248:249], v[10:11] op_sel:[1,0,0] op_sel_hi:[1,1,1]
	ds_read_b128 v[106:109], v122 offset:10576
	ds_read_b128 v[130:133], v122 offset:10592
	ds_read_b128 v[140:143], v122 offset:10608
	ds_read_b128 v[144:147], v122 offset:10624
	s_waitcnt lgkmcnt(9)
	v_lshlrev_b32_e32 v16, 16, v16
	v_lshlrev_b32_e32 v17, 16, v17
	v_pk_add_f32 v[12:13], v[4:5], v[6:7]
	v_pk_add_f32 v[14:15], v[8:9], v[10:11]
	s_nop 0
	v_pk_add_f32 v[12:13], v[12:13], v[14:15]
	s_nop 0
	v_pk_fma_f32 v[46:47], v[18:19], v[16:17], v[12:13] neg_lo:[0,0,1] neg_hi:[0,0,1]
	ds_read_b128 v[148:151], v122 offset:10640
	s_waitcnt lgkmcnt(9)
	v_pk_mul_f32 v[4:5], v[32:33], v[170:171] op_sel_hi:[0,1]
	v_pk_mul_f32 v[6:7], v[32:33], v[172:173] op_sel:[1,0] op_sel_hi:[1,1]
	v_pk_mul_f32 v[8:9], v[34:35], v[174:175] op_sel_hi:[0,1]
	v_pk_mul_f32 v[10:11], v[34:35], v[176:177] op_sel:[1,0] op_sel_hi:[1,1]
	ds_read_b128 v[32:35], v122 offset:10656
	s_waitcnt lgkmcnt(9)
	v_pk_fma_f32 v[4:5], v[36:37], v[178:179], v[4:5] op_sel_hi:[0,1,1]
	v_pk_fma_f32 v[6:7], v[36:37], v[180:181], v[6:7] op_sel:[1,0,0] op_sel_hi:[1,1,1]
	v_pk_fma_f32 v[8:9], v[38:39], v[182:183], v[8:9] op_sel_hi:[0,1,1]
	v_pk_fma_f32 v[10:11], v[38:39], v[184:185], v[10:11] op_sel:[1,0,0] op_sel_hi:[1,1,1]
	ds_read_u16 v20, v115 offset:11152
	s_waitcnt lgkmcnt(9)
	v_pk_fma_f32 v[4:5], v[40:41], v[186:187], v[4:5] op_sel_hi:[0,1,1]
	v_pk_fma_f32 v[6:7], v[40:41], v[188:189], v[6:7] op_sel:[1,0,0] op_sel_hi:[1,1,1]
	v_pk_fma_f32 v[8:9], v[42:43], v[190:191], v[8:9] op_sel_hi:[0,1,1]
	v_pk_fma_f32 v[10:11], v[42:43], v[192:193], v[10:11] op_sel:[1,0,0] op_sel_hi:[1,1,1]
	ds_read_u16 v21, v116 offset:11152
	s_waitcnt lgkmcnt(9)
	v_pk_fma_f32 v[4:5], v[98:99], v[194:195], v[4:5] op_sel_hi:[0,1,1]
	v_pk_fma_f32 v[6:7], v[98:99], v[196:197], v[6:7] op_sel:[1,0,0] op_sel_hi:[1,1,1]
	v_pk_fma_f32 v[8:9], v[100:101], v[198:199], v[8:9] op_sel_hi:[0,1,1]
	v_pk_fma_f32 v[10:11], v[100:101], v[200:201], v[10:11] op_sel:[1,0,0] op_sel_hi:[1,1,1]
	ds_read_b32 v22, v126 offset:164
	s_waitcnt lgkmcnt(9)
	v_pk_fma_f32 v[4:5], v[102:103], v[202:203], v[4:5] op_sel_hi:[0,1,1]
	v_pk_fma_f32 v[6:7], v[102:103], v[204:205], v[6:7] op_sel:[1,0,0] op_sel_hi:[1,1,1]
	v_pk_fma_f32 v[8:9], v[104:105], v[206:207], v[8:9] op_sel_hi:[0,1,1]
	v_pk_fma_f32 v[10:11], v[104:105], v[208:209], v[10:11] op_sel:[1,0,0] op_sel_hi:[1,1,1]
	ds_read_b32 v23, v127 offset:164
	s_waitcnt lgkmcnt(9)
	v_pk_fma_f32 v[4:5], v[106:107], v[210:211], v[4:5] op_sel_hi:[0,1,1]
	v_pk_fma_f32 v[6:7], v[106:107], v[212:213], v[6:7] op_sel:[1,0,0] op_sel_hi:[1,1,1]
	v_pk_fma_f32 v[8:9], v[108:109], v[214:215], v[8:9] op_sel_hi:[0,1,1]
	v_pk_fma_f32 v[10:11], v[108:109], v[216:217], v[10:11] op_sel:[1,0,0] op_sel_hi:[1,1,1]
	ds_read_b128 v[36:39], v122 offset:10752
	s_waitcnt lgkmcnt(9)
	v_pk_fma_f32 v[4:5], v[130:131], v[218:219], v[4:5] op_sel_hi:[0,1,1]
	v_pk_fma_f32 v[6:7], v[130:131], v[220:221], v[6:7] op_sel:[1,0,0] op_sel_hi:[1,1,1]
	v_pk_fma_f32 v[8:9], v[132:133], v[222:223], v[8:9] op_sel_hi:[0,1,1]
	v_pk_fma_f32 v[10:11], v[132:133], v[224:225], v[10:11] op_sel:[1,0,0] op_sel_hi:[1,1,1]
	ds_read_b128 v[40:43], v122 offset:10768
	s_waitcnt lgkmcnt(9)
	v_pk_fma_f32 v[4:5], v[140:141], v[226:227], v[4:5] op_sel_hi:[0,1,1]
	v_pk_fma_f32 v[6:7], v[140:141], v[228:229], v[6:7] op_sel:[1,0,0] op_sel_hi:[1,1,1]
	v_pk_fma_f32 v[8:9], v[142:143], v[230:231], v[8:9] op_sel_hi:[0,1,1]
	v_pk_fma_f32 v[10:11], v[142:143], v[232:233], v[10:11] op_sel:[1,0,0] op_sel_hi:[1,1,1]
	ds_read_b128 v[98:101], v122 offset:10784
	s_waitcnt lgkmcnt(9)
	v_pk_fma_f32 v[4:5], v[144:145], v[234:235], v[4:5] op_sel_hi:[0,1,1]
	v_pk_fma_f32 v[6:7], v[144:145], v[236:237], v[6:7] op_sel:[1,0,0] op_sel_hi:[1,1,1]
	v_pk_fma_f32 v[8:9], v[146:147], v[238:239], v[8:9] op_sel_hi:[0,1,1]
	v_pk_fma_f32 v[10:11], v[146:147], v[240:241], v[10:11] op_sel:[1,0,0] op_sel_hi:[1,1,1]
	ds_read_b128 v[102:105], v122 offset:10800
	s_waitcnt lgkmcnt(9)
	v_pk_fma_f32 v[4:5], v[148:149], v[242:243], v[4:5] op_sel_hi:[0,1,1]
	v_pk_fma_f32 v[6:7], v[148:149], v[244:245], v[6:7] op_sel:[1,0,0] op_sel_hi:[1,1,1]
	v_pk_fma_f32 v[8:9], v[150:151], v[246:247], v[8:9] op_sel_hi:[0,1,1]
	v_pk_fma_f32 v[10:11], v[150:151], v[248:249], v[10:11] op_sel:[1,0,0] op_sel_hi:[1,1,1]
	ds_read_b128 v[106:109], v122 offset:10816
	s_waitcnt lgkmcnt(9)
	v_pk_fma_f32 v[4:5], v[32:33], v[46:47], v[4:5] op_sel_hi:[0,1,1]
	ds_read_b128 v[130:133], v122 offset:10832
	ds_read_b128 v[140:143], v122 offset:10848
	ds_read_b128 v[144:147], v122 offset:10864
	ds_read_b128 v[148:151], v122 offset:10880
	s_waitcnt lgkmcnt(9)
	v_lshlrev_b32_e32 v20, 16, v20
	v_lshlrev_b32_e32 v21, 16, v21
	v_pk_add_f32 v[12:13], v[4:5], v[6:7]
	v_pk_add_f32 v[14:15], v[8:9], v[10:11]
	s_nop 0
	v_pk_add_f32 v[12:13], v[12:13], v[14:15]
	s_nop 0
	v_pk_fma_f32 v[48:49], v[22:23], v[20:21], v[12:13] neg_lo:[0,0,1] neg_hi:[0,0,1]
	ds_read_b128 v[32:35], v122 offset:10896
	s_waitcnt lgkmcnt(9)
	v_pk_mul_f32 v[4:5], v[36:37], v[170:171] op_sel_hi:[0,1]
	v_pk_mul_f32 v[6:7], v[36:37], v[172:173] op_sel:[1,0] op_sel_hi:[1,1]
	v_pk_mul_f32 v[8:9], v[38:39], v[174:175] op_sel_hi:[0,1]
	v_pk_mul_f32 v[10:11], v[38:39], v[176:177] op_sel:[1,0] op_sel_hi:[1,1]
	ds_read_b128 v[36:39], v122 offset:10912
	s_waitcnt lgkmcnt(9)
	v_pk_fma_f32 v[4:5], v[40:41], v[178:179], v[4:5] op_sel_hi:[0,1,1]
	v_pk_fma_f32 v[6:7], v[40:41], v[180:181], v[6:7] op_sel:[1,0,0] op_sel_hi:[1,1,1]
	v_pk_fma_f32 v[8:9], v[42:43], v[182:183], v[8:9] op_sel_hi:[0,1,1]
	v_pk_fma_f32 v[10:11], v[42:43], v[184:185], v[10:11] op_sel:[1,0,0] op_sel_hi:[1,1,1]
	ds_read_u16 v24, v115 offset:11424
	s_waitcnt lgkmcnt(9)
	v_pk_fma_f32 v[4:5], v[98:99], v[186:187], v[4:5] op_sel_hi:[0,1,1]
	v_pk_fma_f32 v[6:7], v[98:99], v[188:189], v[6:7] op_sel:[1,0,0] op_sel_hi:[1,1,1]
	v_pk_fma_f32 v[8:9], v[100:101], v[190:191], v[8:9] op_sel_hi:[0,1,1]
	v_pk_fma_f32 v[10:11], v[100:101], v[192:193], v[10:11] op_sel:[1,0,0] op_sel_hi:[1,1,1]
	ds_read_u16 v25, v116 offset:11424
	s_waitcnt lgkmcnt(9)
	v_pk_fma_f32 v[4:5], v[102:103], v[194:195], v[4:5] op_sel_hi:[0,1,1]
	v_pk_fma_f32 v[6:7], v[102:103], v[196:197], v[6:7] op_sel:[1,0,0] op_sel_hi:[1,1,1]
	v_pk_fma_f32 v[8:9], v[104:105], v[198:199], v[8:9] op_sel_hi:[0,1,1]
	v_pk_fma_f32 v[10:11], v[104:105], v[200:201], v[10:11] op_sel:[1,0,0] op_sel_hi:[1,1,1]
	ds_read_b32 v26, v126 offset:168
	s_waitcnt lgkmcnt(9)
	v_pk_fma_f32 v[4:5], v[106:107], v[202:203], v[4:5] op_sel_hi:[0,1,1]
	v_pk_fma_f32 v[6:7], v[106:107], v[204:205], v[6:7] op_sel:[1,0,0] op_sel_hi:[1,1,1]
	v_pk_fma_f32 v[8:9], v[108:109], v[206:207], v[8:9] op_sel_hi:[0,1,1]
	v_pk_fma_f32 v[10:11], v[108:109], v[208:209], v[10:11] op_sel:[1,0,0] op_sel_hi:[1,1,1]
	ds_read_b32 v27, v127 offset:168
	s_waitcnt lgkmcnt(9)
	v_pk_fma_f32 v[4:5], v[130:131], v[210:211], v[4:5] op_sel_hi:[0,1,1]
	v_pk_fma_f32 v[6:7], v[130:131], v[212:213], v[6:7] op_sel:[1,0,0] op_sel_hi:[1,1,1]
	v_pk_fma_f32 v[8:9], v[132:133], v[214:215], v[8:9] op_sel_hi:[0,1,1]
	v_pk_fma_f32 v[10:11], v[132:133], v[216:217], v[10:11] op_sel:[1,0,0] op_sel_hi:[1,1,1]
	ds_read_b128 v[40:43], v122 offset:11008
	s_waitcnt lgkmcnt(9)
	v_pk_fma_f32 v[4:5], v[140:141], v[218:219], v[4:5] op_sel_hi:[0,1,1]
	v_pk_fma_f32 v[6:7], v[140:141], v[220:221], v[6:7] op_sel:[1,0,0] op_sel_hi:[1,1,1]
	v_pk_fma_f32 v[8:9], v[142:143], v[222:223], v[8:9] op_sel_hi:[0,1,1]
	v_pk_fma_f32 v[10:11], v[142:143], v[224:225], v[10:11] op_sel:[1,0,0] op_sel_hi:[1,1,1]
	ds_read_b128 v[98:101], v122 offset:11024
	s_waitcnt lgkmcnt(9)
	v_pk_fma_f32 v[4:5], v[144:145], v[226:227], v[4:5] op_sel_hi:[0,1,1]
	v_pk_fma_f32 v[6:7], v[144:145], v[228:229], v[6:7] op_sel:[1,0,0] op_sel_hi:[1,1,1]
	v_pk_fma_f32 v[8:9], v[146:147], v[230:231], v[8:9] op_sel_hi:[0,1,1]
	v_pk_fma_f32 v[10:11], v[146:147], v[232:233], v[10:11] op_sel:[1,0,0] op_sel_hi:[1,1,1]
	ds_read_b128 v[102:105], v122 offset:11040
	s_waitcnt lgkmcnt(9)
	v_pk_fma_f32 v[4:5], v[148:149], v[234:235], v[4:5] op_sel_hi:[0,1,1]
	v_pk_fma_f32 v[6:7], v[148:149], v[236:237], v[6:7] op_sel:[1,0,0] op_sel_hi:[1,1,1]
	v_pk_fma_f32 v[8:9], v[150:151], v[238:239], v[8:9] op_sel_hi:[0,1,1]
	v_pk_fma_f32 v[10:11], v[150:151], v[240:241], v[10:11] op_sel:[1,0,0] op_sel_hi:[1,1,1]
	ds_read_b128 v[106:109], v122 offset:11056
	s_waitcnt lgkmcnt(9)
	v_pk_fma_f32 v[4:5], v[32:33], v[242:243], v[4:5] op_sel_hi:[0,1,1]
	v_pk_fma_f32 v[6:7], v[32:33], v[244:245], v[6:7] op_sel:[1,0,0] op_sel_hi:[1,1,1]
	v_pk_fma_f32 v[8:9], v[34:35], v[246:247], v[8:9] op_sel_hi:[0,1,1]
	v_pk_fma_f32 v[10:11], v[34:35], v[248:249], v[10:11] op_sel:[1,0,0] op_sel_hi:[1,1,1]
	ds_read_b128 v[130:133], v122 offset:11072
	s_waitcnt lgkmcnt(9)
	v_pk_fma_f32 v[4:5], v[36:37], v[46:47], v[4:5] op_sel_hi:[0,1,1]
	v_pk_fma_f32 v[6:7], v[36:37], v[48:49], v[6:7] op_sel:[1,0,0] op_sel_hi:[1,1,1]
	ds_read_b128 v[140:143], v122 offset:11088
	ds_read_b128 v[144:147], v122 offset:11104
	ds_read_b128 v[148:151], v122 offset:11120
	ds_read_b128 v[32:35], v122 offset:11136
	s_waitcnt lgkmcnt(9)
	v_lshlrev_b32_e32 v24, 16, v24
	v_lshlrev_b32_e32 v25, 16, v25
	v_pk_add_f32 v[12:13], v[4:5], v[6:7]
	v_pk_add_f32 v[14:15], v[8:9], v[10:11]
	s_nop 0
	v_pk_add_f32 v[12:13], v[12:13], v[14:15]
	s_nop 0
	v_pk_fma_f32 v[50:51], v[26:27], v[24:25], v[12:13] neg_lo:[0,0,1] neg_hi:[0,0,1]
	ds_read_b128 v[36:39], v122 offset:11152
	s_waitcnt lgkmcnt(9)
	v_pk_mul_f32 v[4:5], v[40:41], v[170:171] op_sel_hi:[0,1]
	v_pk_mul_f32 v[6:7], v[40:41], v[172:173] op_sel:[1,0] op_sel_hi:[1,1]
	v_pk_mul_f32 v[8:9], v[42:43], v[174:175] op_sel_hi:[0,1]
	v_pk_mul_f32 v[10:11], v[42:43], v[176:177] op_sel:[1,0] op_sel_hi:[1,1]
	ds_read_b128 v[40:43], v122 offset:11168
	s_waitcnt lgkmcnt(9)
	v_pk_fma_f32 v[4:5], v[98:99], v[178:179], v[4:5] op_sel_hi:[0,1,1]
	v_pk_fma_f32 v[6:7], v[98:99], v[180:181], v[6:7] op_sel:[1,0,0] op_sel_hi:[1,1,1]
	v_pk_fma_f32 v[8:9], v[100:101], v[182:183], v[8:9] op_sel_hi:[0,1,1]
	v_pk_fma_f32 v[10:11], v[100:101], v[184:185], v[10:11] op_sel:[1,0,0] op_sel_hi:[1,1,1]
	ds_read_u16 v28, v115 offset:11696
	s_waitcnt lgkmcnt(9)
	v_pk_fma_f32 v[4:5], v[102:103], v[186:187], v[4:5] op_sel_hi:[0,1,1]
	v_pk_fma_f32 v[6:7], v[102:103], v[188:189], v[6:7] op_sel:[1,0,0] op_sel_hi:[1,1,1]
	v_pk_fma_f32 v[8:9], v[104:105], v[190:191], v[8:9] op_sel_hi:[0,1,1]
	v_pk_fma_f32 v[10:11], v[104:105], v[192:193], v[10:11] op_sel:[1,0,0] op_sel_hi:[1,1,1]
	ds_read_u16 v29, v116 offset:11696
	s_waitcnt lgkmcnt(9)
	v_pk_fma_f32 v[4:5], v[106:107], v[194:195], v[4:5] op_sel_hi:[0,1,1]
	v_pk_fma_f32 v[6:7], v[106:107], v[196:197], v[6:7] op_sel:[1,0,0] op_sel_hi:[1,1,1]
	v_pk_fma_f32 v[8:9], v[108:109], v[198:199], v[8:9] op_sel_hi:[0,1,1]
	v_pk_fma_f32 v[10:11], v[108:109], v[200:201], v[10:11] op_sel:[1,0,0] op_sel_hi:[1,1,1]
	ds_read_b32 v30, v126 offset:172
	s_waitcnt lgkmcnt(9)
	v_pk_fma_f32 v[4:5], v[130:131], v[202:203], v[4:5] op_sel_hi:[0,1,1]
	v_pk_fma_f32 v[6:7], v[130:131], v[204:205], v[6:7] op_sel:[1,0,0] op_sel_hi:[1,1,1]
	v_pk_fma_f32 v[8:9], v[132:133], v[206:207], v[8:9] op_sel_hi:[0,1,1]
	v_pk_fma_f32 v[10:11], v[132:133], v[208:209], v[10:11] op_sel:[1,0,0] op_sel_hi:[1,1,1]
	ds_read_b32 v31, v127 offset:172
	s_waitcnt lgkmcnt(9)
	v_pk_fma_f32 v[4:5], v[140:141], v[210:211], v[4:5] op_sel_hi:[0,1,1]
	v_pk_fma_f32 v[6:7], v[140:141], v[212:213], v[6:7] op_sel:[1,0,0] op_sel_hi:[1,1,1]
	v_pk_fma_f32 v[8:9], v[142:143], v[214:215], v[8:9] op_sel_hi:[0,1,1]
	v_pk_fma_f32 v[10:11], v[142:143], v[216:217], v[10:11] op_sel:[1,0,0] op_sel_hi:[1,1,1]
	ds_read_b128 v[98:101], v122 offset:11264
	s_waitcnt lgkmcnt(9)
	v_pk_fma_f32 v[4:5], v[144:145], v[218:219], v[4:5] op_sel_hi:[0,1,1]
	v_pk_fma_f32 v[6:7], v[144:145], v[220:221], v[6:7] op_sel:[1,0,0] op_sel_hi:[1,1,1]
	v_pk_fma_f32 v[8:9], v[146:147], v[222:223], v[8:9] op_sel_hi:[0,1,1]
	v_pk_fma_f32 v[10:11], v[146:147], v[224:225], v[10:11] op_sel:[1,0,0] op_sel_hi:[1,1,1]
	ds_read_b128 v[102:105], v122 offset:11280
	s_waitcnt lgkmcnt(9)
	v_pk_fma_f32 v[4:5], v[148:149], v[226:227], v[4:5] op_sel_hi:[0,1,1]
	v_pk_fma_f32 v[6:7], v[148:149], v[228:229], v[6:7] op_sel:[1,0,0] op_sel_hi:[1,1,1]
	v_pk_fma_f32 v[8:9], v[150:151], v[230:231], v[8:9] op_sel_hi:[0,1,1]
	v_pk_fma_f32 v[10:11], v[150:151], v[232:233], v[10:11] op_sel:[1,0,0] op_sel_hi:[1,1,1]
	ds_read_b128 v[106:109], v122 offset:11296
	s_waitcnt lgkmcnt(9)
	v_pk_fma_f32 v[4:5], v[32:33], v[234:235], v[4:5] op_sel_hi:[0,1,1]
	v_pk_fma_f32 v[6:7], v[32:33], v[236:237], v[6:7] op_sel:[1,0,0] op_sel_hi:[1,1,1]
	v_pk_fma_f32 v[8:9], v[34:35], v[238:239], v[8:9] op_sel_hi:[0,1,1]
	v_pk_fma_f32 v[10:11], v[34:35], v[240:241], v[10:11] op_sel:[1,0,0] op_sel_hi:[1,1,1]
	ds_read_b128 v[130:133], v122 offset:11312
	s_waitcnt lgkmcnt(9)
	v_pk_fma_f32 v[4:5], v[36:37], v[242:243], v[4:5] op_sel_hi:[0,1,1]
	v_pk_fma_f32 v[6:7], v[36:37], v[244:245], v[6:7] op_sel:[1,0,0] op_sel_hi:[1,1,1]
	v_pk_fma_f32 v[8:9], v[38:39], v[246:247], v[8:9] op_sel_hi:[0,1,1]
	v_pk_fma_f32 v[10:11], v[38:39], v[248:249], v[10:11] op_sel:[1,0,0] op_sel_hi:[1,1,1]
	ds_read_b128 v[140:143], v122 offset:11328
	s_waitcnt lgkmcnt(9)
	v_pk_fma_f32 v[4:5], v[40:41], v[46:47], v[4:5] op_sel_hi:[0,1,1]
	v_pk_fma_f32 v[6:7], v[40:41], v[48:49], v[6:7] op_sel:[1,0,0] op_sel_hi:[1,1,1]
	v_pk_fma_f32 v[8:9], v[42:43], v[50:51], v[8:9] op_sel_hi:[0,1,1]
	ds_read_b128 v[144:147], v122 offset:11344
	ds_read_b128 v[148:151], v122 offset:11360
	ds_read_b128 v[32:35], v122 offset:11376
	ds_read_b128 v[36:39], v122 offset:11392
	s_waitcnt lgkmcnt(9)
	v_lshlrev_b32_e32 v28, 16, v28
	v_lshlrev_b32_e32 v29, 16, v29
	v_pk_add_f32 v[12:13], v[4:5], v[6:7]
	v_pk_add_f32 v[14:15], v[8:9], v[10:11]
	s_nop 0
	v_pk_add_f32 v[12:13], v[12:13], v[14:15]
	s_nop 0
	v_pk_fma_f32 v[52:53], v[30:31], v[28:29], v[12:13] neg_lo:[0,0,1] neg_hi:[0,0,1]
	ds_read_b128 v[40:43], v122 offset:11408
	s_waitcnt lgkmcnt(9)
	v_pk_mul_f32 v[4:5], v[98:99], v[170:171] op_sel_hi:[0,1]
	v_pk_mul_f32 v[6:7], v[98:99], v[172:173] op_sel:[1,0] op_sel_hi:[1,1]
	v_pk_mul_f32 v[8:9], v[100:101], v[174:175] op_sel_hi:[0,1]
	v_pk_mul_f32 v[10:11], v[100:101], v[176:177] op_sel:[1,0] op_sel_hi:[1,1]
	ds_read_b128 v[98:101], v122 offset:11424
	s_waitcnt lgkmcnt(9)
	v_pk_fma_f32 v[4:5], v[102:103], v[178:179], v[4:5] op_sel_hi:[0,1,1]
	v_pk_fma_f32 v[6:7], v[102:103], v[180:181], v[6:7] op_sel:[1,0,0] op_sel_hi:[1,1,1]
	v_pk_fma_f32 v[8:9], v[104:105], v[182:183], v[8:9] op_sel_hi:[0,1,1]
	v_pk_fma_f32 v[10:11], v[104:105], v[184:185], v[10:11] op_sel:[1,0,0] op_sel_hi:[1,1,1]
	ds_read_u16 v16, v115 offset:11968
	s_waitcnt lgkmcnt(9)
	v_pk_fma_f32 v[4:5], v[106:107], v[186:187], v[4:5] op_sel_hi:[0,1,1]
	v_pk_fma_f32 v[6:7], v[106:107], v[188:189], v[6:7] op_sel:[1,0,0] op_sel_hi:[1,1,1]
	v_pk_fma_f32 v[8:9], v[108:109], v[190:191], v[8:9] op_sel_hi:[0,1,1]
	v_pk_fma_f32 v[10:11], v[108:109], v[192:193], v[10:11] op_sel:[1,0,0] op_sel_hi:[1,1,1]
	ds_read_u16 v17, v116 offset:11968
	s_waitcnt lgkmcnt(9)
	v_pk_fma_f32 v[4:5], v[130:131], v[194:195], v[4:5] op_sel_hi:[0,1,1]
	v_pk_fma_f32 v[6:7], v[130:131], v[196:197], v[6:7] op_sel:[1,0,0] op_sel_hi:[1,1,1]
	v_pk_fma_f32 v[8:9], v[132:133], v[198:199], v[8:9] op_sel_hi:[0,1,1]
	v_pk_fma_f32 v[10:11], v[132:133], v[200:201], v[10:11] op_sel:[1,0,0] op_sel_hi:[1,1,1]
	ds_read_b32 v18, v126 offset:176
	s_waitcnt lgkmcnt(9)
	v_pk_fma_f32 v[4:5], v[140:141], v[202:203], v[4:5] op_sel_hi:[0,1,1]
	v_pk_fma_f32 v[6:7], v[140:141], v[204:205], v[6:7] op_sel:[1,0,0] op_sel_hi:[1,1,1]
	v_pk_fma_f32 v[8:9], v[142:143], v[206:207], v[8:9] op_sel_hi:[0,1,1]
	v_pk_fma_f32 v[10:11], v[142:143], v[208:209], v[10:11] op_sel:[1,0,0] op_sel_hi:[1,1,1]
	ds_read_b32 v19, v127 offset:176
	s_waitcnt lgkmcnt(9)
	v_pk_fma_f32 v[4:5], v[144:145], v[210:211], v[4:5] op_sel_hi:[0,1,1]
	v_pk_fma_f32 v[6:7], v[144:145], v[212:213], v[6:7] op_sel:[1,0,0] op_sel_hi:[1,1,1]
	v_pk_fma_f32 v[8:9], v[146:147], v[214:215], v[8:9] op_sel_hi:[0,1,1]
	v_pk_fma_f32 v[10:11], v[146:147], v[216:217], v[10:11] op_sel:[1,0,0] op_sel_hi:[1,1,1]
	ds_read_b128 v[102:105], v122 offset:11520
	s_waitcnt lgkmcnt(9)
	v_pk_fma_f32 v[4:5], v[148:149], v[218:219], v[4:5] op_sel_hi:[0,1,1]
	v_pk_fma_f32 v[6:7], v[148:149], v[220:221], v[6:7] op_sel:[1,0,0] op_sel_hi:[1,1,1]
	v_pk_fma_f32 v[8:9], v[150:151], v[222:223], v[8:9] op_sel_hi:[0,1,1]
	v_pk_fma_f32 v[10:11], v[150:151], v[224:225], v[10:11] op_sel:[1,0,0] op_sel_hi:[1,1,1]
	ds_read_b128 v[106:109], v122 offset:11536
	s_waitcnt lgkmcnt(9)
	v_pk_fma_f32 v[4:5], v[32:33], v[226:227], v[4:5] op_sel_hi:[0,1,1]
	v_pk_fma_f32 v[6:7], v[32:33], v[228:229], v[6:7] op_sel:[1,0,0] op_sel_hi:[1,1,1]
	v_pk_fma_f32 v[8:9], v[34:35], v[230:231], v[8:9] op_sel_hi:[0,1,1]
	v_pk_fma_f32 v[10:11], v[34:35], v[232:233], v[10:11] op_sel:[1,0,0] op_sel_hi:[1,1,1]
	ds_read_b128 v[130:133], v122 offset:11552
	s_waitcnt lgkmcnt(9)
	v_pk_fma_f32 v[4:5], v[36:37], v[234:235], v[4:5] op_sel_hi:[0,1,1]
	v_pk_fma_f32 v[6:7], v[36:37], v[236:237], v[6:7] op_sel:[1,0,0] op_sel_hi:[1,1,1]
	v_pk_fma_f32 v[8:9], v[38:39], v[238:239], v[8:9] op_sel_hi:[0,1,1]
	v_pk_fma_f32 v[10:11], v[38:39], v[240:241], v[10:11] op_sel:[1,0,0] op_sel_hi:[1,1,1]
	ds_read_b128 v[140:143], v122 offset:11568
	s_waitcnt lgkmcnt(9)
	v_pk_fma_f32 v[4:5], v[40:41], v[242:243], v[4:5] op_sel_hi:[0,1,1]
	v_pk_fma_f32 v[6:7], v[40:41], v[244:245], v[6:7] op_sel:[1,0,0] op_sel_hi:[1,1,1]
	v_pk_fma_f32 v[8:9], v[42:43], v[246:247], v[8:9] op_sel_hi:[0,1,1]
	v_pk_fma_f32 v[10:11], v[42:43], v[248:249], v[10:11] op_sel:[1,0,0] op_sel_hi:[1,1,1]
	ds_read_b128 v[144:147], v122 offset:11584
	s_waitcnt lgkmcnt(9)
	v_pk_fma_f32 v[4:5], v[98:99], v[46:47], v[4:5] op_sel_hi:[0,1,1]
	v_pk_fma_f32 v[6:7], v[98:99], v[48:49], v[6:7] op_sel:[1,0,0] op_sel_hi:[1,1,1]
	v_pk_fma_f32 v[8:9], v[100:101], v[50:51], v[8:9] op_sel_hi:[0,1,1]
	v_pk_fma_f32 v[10:11], v[100:101], v[52:53], v[10:11] op_sel:[1,0,0] op_sel_hi:[1,1,1]
	ds_read_b128 v[148:151], v122 offset:11600
	ds_read_b128 v[32:35], v122 offset:11616
	ds_read_b128 v[36:39], v122 offset:11632
	ds_read_b128 v[40:43], v122 offset:11648
	s_waitcnt lgkmcnt(9)
	v_lshlrev_b32_e32 v16, 16, v16
	v_lshlrev_b32_e32 v17, 16, v17
	v_pk_add_f32 v[12:13], v[4:5], v[6:7]
	v_pk_add_f32 v[14:15], v[8:9], v[10:11]
	s_nop 0
	v_pk_add_f32 v[12:13], v[12:13], v[14:15]
	s_nop 0
	v_pk_fma_f32 v[54:55], v[18:19], v[16:17], v[12:13] neg_lo:[0,0,1] neg_hi:[0,0,1]
	ds_read_b128 v[98:101], v122 offset:11664
	s_waitcnt lgkmcnt(9)
	v_pk_mul_f32 v[4:5], v[102:103], v[170:171] op_sel_hi:[0,1]
	v_pk_mul_f32 v[6:7], v[102:103], v[172:173] op_sel:[1,0] op_sel_hi:[1,1]
	v_pk_mul_f32 v[8:9], v[104:105], v[174:175] op_sel_hi:[0,1]
	v_pk_mul_f32 v[10:11], v[104:105], v[176:177] op_sel:[1,0] op_sel_hi:[1,1]
	ds_read_b128 v[102:105], v122 offset:11680
	s_waitcnt lgkmcnt(9)
	v_pk_fma_f32 v[4:5], v[106:107], v[178:179], v[4:5] op_sel_hi:[0,1,1]
	v_pk_fma_f32 v[6:7], v[106:107], v[180:181], v[6:7] op_sel:[1,0,0] op_sel_hi:[1,1,1]
	v_pk_fma_f32 v[8:9], v[108:109], v[182:183], v[8:9] op_sel_hi:[0,1,1]
	v_pk_fma_f32 v[10:11], v[108:109], v[184:185], v[10:11] op_sel:[1,0,0] op_sel_hi:[1,1,1]
	ds_read_b128 v[106:109], v122 offset:11696
	s_waitcnt lgkmcnt(9)
	v_pk_fma_f32 v[4:5], v[130:131], v[186:187], v[4:5] op_sel_hi:[0,1,1]
	v_pk_fma_f32 v[6:7], v[130:131], v[188:189], v[6:7] op_sel:[1,0,0] op_sel_hi:[1,1,1]
	v_pk_fma_f32 v[8:9], v[132:133], v[190:191], v[8:9] op_sel_hi:[0,1,1]
	v_pk_fma_f32 v[10:11], v[132:133], v[192:193], v[10:11] op_sel:[1,0,0] op_sel_hi:[1,1,1]
	ds_read_u16 v20, v115 offset:12240
	s_waitcnt lgkmcnt(9)
	v_pk_fma_f32 v[4:5], v[140:141], v[194:195], v[4:5] op_sel_hi:[0,1,1]
	v_pk_fma_f32 v[6:7], v[140:141], v[196:197], v[6:7] op_sel:[1,0,0] op_sel_hi:[1,1,1]
	v_pk_fma_f32 v[8:9], v[142:143], v[198:199], v[8:9] op_sel_hi:[0,1,1]
	v_pk_fma_f32 v[10:11], v[142:143], v[200:201], v[10:11] op_sel:[1,0,0] op_sel_hi:[1,1,1]
	ds_read_u16 v21, v116 offset:12240
	s_waitcnt lgkmcnt(9)
	v_pk_fma_f32 v[4:5], v[144:145], v[202:203], v[4:5] op_sel_hi:[0,1,1]
	v_pk_fma_f32 v[6:7], v[144:145], v[204:205], v[6:7] op_sel:[1,0,0] op_sel_hi:[1,1,1]
	v_pk_fma_f32 v[8:9], v[146:147], v[206:207], v[8:9] op_sel_hi:[0,1,1]
	v_pk_fma_f32 v[10:11], v[146:147], v[208:209], v[10:11] op_sel:[1,0,0] op_sel_hi:[1,1,1]
	ds_read_b32 v22, v126 offset:180
	s_waitcnt lgkmcnt(9)
	v_pk_fma_f32 v[4:5], v[148:149], v[210:211], v[4:5] op_sel_hi:[0,1,1]
	v_pk_fma_f32 v[6:7], v[148:149], v[212:213], v[6:7] op_sel:[1,0,0] op_sel_hi:[1,1,1]
	v_pk_fma_f32 v[8:9], v[150:151], v[214:215], v[8:9] op_sel_hi:[0,1,1]
	v_pk_fma_f32 v[10:11], v[150:151], v[216:217], v[10:11] op_sel:[1,0,0] op_sel_hi:[1,1,1]
	ds_read_b32 v23, v127 offset:180
	s_waitcnt lgkmcnt(9)
	v_pk_fma_f32 v[4:5], v[32:33], v[218:219], v[4:5] op_sel_hi:[0,1,1]
	v_pk_fma_f32 v[6:7], v[32:33], v[220:221], v[6:7] op_sel:[1,0,0] op_sel_hi:[1,1,1]
	v_pk_fma_f32 v[8:9], v[34:35], v[222:223], v[8:9] op_sel_hi:[0,1,1]
	v_pk_fma_f32 v[10:11], v[34:35], v[224:225], v[10:11] op_sel:[1,0,0] op_sel_hi:[1,1,1]
	ds_read_b128 v[130:133], v122 offset:11776
	s_waitcnt lgkmcnt(9)
	v_pk_fma_f32 v[4:5], v[36:37], v[226:227], v[4:5] op_sel_hi:[0,1,1]
	v_pk_fma_f32 v[6:7], v[36:37], v[228:229], v[6:7] op_sel:[1,0,0] op_sel_hi:[1,1,1]
	v_pk_fma_f32 v[8:9], v[38:39], v[230:231], v[8:9] op_sel_hi:[0,1,1]
	v_pk_fma_f32 v[10:11], v[38:39], v[232:233], v[10:11] op_sel:[1,0,0] op_sel_hi:[1,1,1]
	ds_read_b128 v[140:143], v122 offset:11792
	s_waitcnt lgkmcnt(9)
	v_pk_fma_f32 v[4:5], v[40:41], v[234:235], v[4:5] op_sel_hi:[0,1,1]
	v_pk_fma_f32 v[6:7], v[40:41], v[236:237], v[6:7] op_sel:[1,0,0] op_sel_hi:[1,1,1]
	v_pk_fma_f32 v[8:9], v[42:43], v[238:239], v[8:9] op_sel_hi:[0,1,1]
	v_pk_fma_f32 v[10:11], v[42:43], v[240:241], v[10:11] op_sel:[1,0,0] op_sel_hi:[1,1,1]
	ds_read_b128 v[144:147], v122 offset:11808
	s_waitcnt lgkmcnt(9)
	v_pk_fma_f32 v[4:5], v[98:99], v[242:243], v[4:5] op_sel_hi:[0,1,1]
	v_pk_fma_f32 v[6:7], v[98:99], v[244:245], v[6:7] op_sel:[1,0,0] op_sel_hi:[1,1,1]
	v_pk_fma_f32 v[8:9], v[100:101], v[246:247], v[8:9] op_sel_hi:[0,1,1]
	v_pk_fma_f32 v[10:11], v[100:101], v[248:249], v[10:11] op_sel:[1,0,0] op_sel_hi:[1,1,1]
	ds_read_b128 v[148:151], v122 offset:11824
	s_waitcnt lgkmcnt(9)
	v_pk_fma_f32 v[4:5], v[102:103], v[46:47], v[4:5] op_sel_hi:[0,1,1]
	v_pk_fma_f32 v[6:7], v[102:103], v[48:49], v[6:7] op_sel:[1,0,0] op_sel_hi:[1,1,1]
	v_pk_fma_f32 v[8:9], v[104:105], v[50:51], v[8:9] op_sel_hi:[0,1,1]
	v_pk_fma_f32 v[10:11], v[104:105], v[52:53], v[10:11] op_sel:[1,0,0] op_sel_hi:[1,1,1]
	ds_read_b128 v[32:35], v122 offset:11840
	s_waitcnt lgkmcnt(9)
	v_pk_fma_f32 v[4:5], v[106:107], v[54:55], v[4:5] op_sel_hi:[0,1,1]
	ds_read_b128 v[36:39], v122 offset:11856
	ds_read_b128 v[40:43], v122 offset:11872
	ds_read_b128 v[98:101], v122 offset:11888
	ds_read_b128 v[102:105], v122 offset:11904
	s_waitcnt lgkmcnt(9)
	v_lshlrev_b32_e32 v20, 16, v20
	v_lshlrev_b32_e32 v21, 16, v21
	v_pk_add_f32 v[12:13], v[4:5], v[6:7]
	v_pk_add_f32 v[14:15], v[8:9], v[10:11]
	s_nop 0
	v_pk_add_f32 v[12:13], v[12:13], v[14:15]
	s_nop 0
	v_pk_fma_f32 v[56:57], v[22:23], v[20:21], v[12:13] neg_lo:[0,0,1] neg_hi:[0,0,1]
	ds_read_b128 v[106:109], v122 offset:11920
	s_waitcnt lgkmcnt(9)
	v_pk_mul_f32 v[4:5], v[130:131], v[170:171] op_sel_hi:[0,1]
	v_pk_mul_f32 v[6:7], v[130:131], v[172:173] op_sel:[1,0] op_sel_hi:[1,1]
	v_pk_mul_f32 v[8:9], v[132:133], v[174:175] op_sel_hi:[0,1]
	v_pk_mul_f32 v[10:11], v[132:133], v[176:177] op_sel:[1,0] op_sel_hi:[1,1]
	ds_read_b128 v[130:133], v122 offset:11936
	s_waitcnt lgkmcnt(9)
	v_pk_fma_f32 v[4:5], v[140:141], v[178:179], v[4:5] op_sel_hi:[0,1,1]
	v_pk_fma_f32 v[6:7], v[140:141], v[180:181], v[6:7] op_sel:[1,0,0] op_sel_hi:[1,1,1]
	v_pk_fma_f32 v[8:9], v[142:143], v[182:183], v[8:9] op_sel_hi:[0,1,1]
	v_pk_fma_f32 v[10:11], v[142:143], v[184:185], v[10:11] op_sel:[1,0,0] op_sel_hi:[1,1,1]
	ds_read_b128 v[140:143], v122 offset:11952
	s_waitcnt lgkmcnt(9)
	v_pk_fma_f32 v[4:5], v[144:145], v[186:187], v[4:5] op_sel_hi:[0,1,1]
	v_pk_fma_f32 v[6:7], v[144:145], v[188:189], v[6:7] op_sel:[1,0,0] op_sel_hi:[1,1,1]
	v_pk_fma_f32 v[8:9], v[146:147], v[190:191], v[8:9] op_sel_hi:[0,1,1]
	v_pk_fma_f32 v[10:11], v[146:147], v[192:193], v[10:11] op_sel:[1,0,0] op_sel_hi:[1,1,1]
	ds_read_u16 v24, v115 offset:12512
	s_waitcnt lgkmcnt(9)
	v_pk_fma_f32 v[4:5], v[148:149], v[194:195], v[4:5] op_sel_hi:[0,1,1]
	v_pk_fma_f32 v[6:7], v[148:149], v[196:197], v[6:7] op_sel:[1,0,0] op_sel_hi:[1,1,1]
	v_pk_fma_f32 v[8:9], v[150:151], v[198:199], v[8:9] op_sel_hi:[0,1,1]
	v_pk_fma_f32 v[10:11], v[150:151], v[200:201], v[10:11] op_sel:[1,0,0] op_sel_hi:[1,1,1]
	ds_read_u16 v25, v116 offset:12512
	s_waitcnt lgkmcnt(9)
	v_pk_fma_f32 v[4:5], v[32:33], v[202:203], v[4:5] op_sel_hi:[0,1,1]
	v_pk_fma_f32 v[6:7], v[32:33], v[204:205], v[6:7] op_sel:[1,0,0] op_sel_hi:[1,1,1]
	v_pk_fma_f32 v[8:9], v[34:35], v[206:207], v[8:9] op_sel_hi:[0,1,1]
	v_pk_fma_f32 v[10:11], v[34:35], v[208:209], v[10:11] op_sel:[1,0,0] op_sel_hi:[1,1,1]
	ds_read_b32 v26, v126 offset:184
	s_waitcnt lgkmcnt(9)
	v_pk_fma_f32 v[4:5], v[36:37], v[210:211], v[4:5] op_sel_hi:[0,1,1]
	v_pk_fma_f32 v[6:7], v[36:37], v[212:213], v[6:7] op_sel:[1,0,0] op_sel_hi:[1,1,1]
	v_pk_fma_f32 v[8:9], v[38:39], v[214:215], v[8:9] op_sel_hi:[0,1,1]
	v_pk_fma_f32 v[10:11], v[38:39], v[216:217], v[10:11] op_sel:[1,0,0] op_sel_hi:[1,1,1]
	ds_read_b32 v27, v127 offset:184
	s_waitcnt lgkmcnt(9)
	v_pk_fma_f32 v[4:5], v[40:41], v[218:219], v[4:5] op_sel_hi:[0,1,1]
	v_pk_fma_f32 v[6:7], v[40:41], v[220:221], v[6:7] op_sel:[1,0,0] op_sel_hi:[1,1,1]
	v_pk_fma_f32 v[8:9], v[42:43], v[222:223], v[8:9] op_sel_hi:[0,1,1]
	v_pk_fma_f32 v[10:11], v[42:43], v[224:225], v[10:11] op_sel:[1,0,0] op_sel_hi:[1,1,1]
	ds_read_b128 v[144:147], v122 offset:12032
	s_waitcnt lgkmcnt(9)
	v_pk_fma_f32 v[4:5], v[98:99], v[226:227], v[4:5] op_sel_hi:[0,1,1]
	v_pk_fma_f32 v[6:7], v[98:99], v[228:229], v[6:7] op_sel:[1,0,0] op_sel_hi:[1,1,1]
	v_pk_fma_f32 v[8:9], v[100:101], v[230:231], v[8:9] op_sel_hi:[0,1,1]
	v_pk_fma_f32 v[10:11], v[100:101], v[232:233], v[10:11] op_sel:[1,0,0] op_sel_hi:[1,1,1]
	ds_read_b128 v[148:151], v122 offset:12048
	s_waitcnt lgkmcnt(9)
	v_pk_fma_f32 v[4:5], v[102:103], v[234:235], v[4:5] op_sel_hi:[0,1,1]
	v_pk_fma_f32 v[6:7], v[102:103], v[236:237], v[6:7] op_sel:[1,0,0] op_sel_hi:[1,1,1]
	v_pk_fma_f32 v[8:9], v[104:105], v[238:239], v[8:9] op_sel_hi:[0,1,1]
	v_pk_fma_f32 v[10:11], v[104:105], v[240:241], v[10:11] op_sel:[1,0,0] op_sel_hi:[1,1,1]
	ds_read_b128 v[32:35], v122 offset:12064
	s_waitcnt lgkmcnt(9)
	v_pk_fma_f32 v[4:5], v[106:107], v[242:243], v[4:5] op_sel_hi:[0,1,1]
	v_pk_fma_f32 v[6:7], v[106:107], v[244:245], v[6:7] op_sel:[1,0,0] op_sel_hi:[1,1,1]
	v_pk_fma_f32 v[8:9], v[108:109], v[246:247], v[8:9] op_sel_hi:[0,1,1]
	v_pk_fma_f32 v[10:11], v[108:109], v[248:249], v[10:11] op_sel:[1,0,0] op_sel_hi:[1,1,1]
	ds_read_b128 v[36:39], v122 offset:12080
	s_waitcnt lgkmcnt(9)
	v_pk_fma_f32 v[4:5], v[130:131], v[46:47], v[4:5] op_sel_hi:[0,1,1]
	v_pk_fma_f32 v[6:7], v[130:131], v[48:49], v[6:7] op_sel:[1,0,0] op_sel_hi:[1,1,1]
	v_pk_fma_f32 v[8:9], v[132:133], v[50:51], v[8:9] op_sel_hi:[0,1,1]
	v_pk_fma_f32 v[10:11], v[132:133], v[52:53], v[10:11] op_sel:[1,0,0] op_sel_hi:[1,1,1]
	ds_read_b128 v[40:43], v122 offset:12096
	s_waitcnt lgkmcnt(9)
	v_pk_fma_f32 v[4:5], v[140:141], v[54:55], v[4:5] op_sel_hi:[0,1,1]
	v_pk_fma_f32 v[6:7], v[140:141], v[56:57], v[6:7] op_sel:[1,0,0] op_sel_hi:[1,1,1]
	ds_read_b128 v[98:101], v122 offset:12112
	ds_read_b128 v[102:105], v122 offset:12128
	ds_read_b128 v[106:109], v122 offset:12144
	ds_read_b128 v[130:133], v122 offset:12160
	s_waitcnt lgkmcnt(9)
	v_lshlrev_b32_e32 v24, 16, v24
	v_lshlrev_b32_e32 v25, 16, v25
	v_pk_add_f32 v[12:13], v[4:5], v[6:7]
	v_pk_add_f32 v[14:15], v[8:9], v[10:11]
	s_nop 0
	v_pk_add_f32 v[12:13], v[12:13], v[14:15]
	s_nop 0
	v_pk_fma_f32 v[58:59], v[26:27], v[24:25], v[12:13] neg_lo:[0,0,1] neg_hi:[0,0,1]
	ds_read_b128 v[140:143], v122 offset:12176
	s_waitcnt lgkmcnt(9)
	v_pk_mul_f32 v[4:5], v[144:145], v[170:171] op_sel_hi:[0,1]
	v_pk_mul_f32 v[6:7], v[144:145], v[172:173] op_sel:[1,0] op_sel_hi:[1,1]
	v_pk_mul_f32 v[8:9], v[146:147], v[174:175] op_sel_hi:[0,1]
	v_pk_mul_f32 v[10:11], v[146:147], v[176:177] op_sel:[1,0] op_sel_hi:[1,1]
	ds_read_b128 v[144:147], v122 offset:12192
	s_waitcnt lgkmcnt(9)
	v_pk_fma_f32 v[4:5], v[148:149], v[178:179], v[4:5] op_sel_hi:[0,1,1]
	v_pk_fma_f32 v[6:7], v[148:149], v[180:181], v[6:7] op_sel:[1,0,0] op_sel_hi:[1,1,1]
	v_pk_fma_f32 v[8:9], v[150:151], v[182:183], v[8:9] op_sel_hi:[0,1,1]
	v_pk_fma_f32 v[10:11], v[150:151], v[184:185], v[10:11] op_sel:[1,0,0] op_sel_hi:[1,1,1]
	ds_read_b128 v[148:151], v122 offset:12208
	s_waitcnt lgkmcnt(9)
	v_pk_fma_f32 v[4:5], v[32:33], v[186:187], v[4:5] op_sel_hi:[0,1,1]
	v_pk_fma_f32 v[6:7], v[32:33], v[188:189], v[6:7] op_sel:[1,0,0] op_sel_hi:[1,1,1]
	v_pk_fma_f32 v[8:9], v[34:35], v[190:191], v[8:9] op_sel_hi:[0,1,1]
	v_pk_fma_f32 v[10:11], v[34:35], v[192:193], v[10:11] op_sel:[1,0,0] op_sel_hi:[1,1,1]
	ds_read_u16 v28, v115 offset:12784
	s_waitcnt lgkmcnt(9)
	v_pk_fma_f32 v[4:5], v[36:37], v[194:195], v[4:5] op_sel_hi:[0,1,1]
	v_pk_fma_f32 v[6:7], v[36:37], v[196:197], v[6:7] op_sel:[1,0,0] op_sel_hi:[1,1,1]
	v_pk_fma_f32 v[8:9], v[38:39], v[198:199], v[8:9] op_sel_hi:[0,1,1]
	v_pk_fma_f32 v[10:11], v[38:39], v[200:201], v[10:11] op_sel:[1,0,0] op_sel_hi:[1,1,1]
	ds_read_u16 v29, v116 offset:12784
	s_waitcnt lgkmcnt(9)
	v_pk_fma_f32 v[4:5], v[40:41], v[202:203], v[4:5] op_sel_hi:[0,1,1]
	v_pk_fma_f32 v[6:7], v[40:41], v[204:205], v[6:7] op_sel:[1,0,0] op_sel_hi:[1,1,1]
	v_pk_fma_f32 v[8:9], v[42:43], v[206:207], v[8:9] op_sel_hi:[0,1,1]
	v_pk_fma_f32 v[10:11], v[42:43], v[208:209], v[10:11] op_sel:[1,0,0] op_sel_hi:[1,1,1]
	ds_read_b32 v30, v126 offset:188
	s_waitcnt lgkmcnt(9)
	v_pk_fma_f32 v[4:5], v[98:99], v[210:211], v[4:5] op_sel_hi:[0,1,1]
	v_pk_fma_f32 v[6:7], v[98:99], v[212:213], v[6:7] op_sel:[1,0,0] op_sel_hi:[1,1,1]
	v_pk_fma_f32 v[8:9], v[100:101], v[214:215], v[8:9] op_sel_hi:[0,1,1]
	v_pk_fma_f32 v[10:11], v[100:101], v[216:217], v[10:11] op_sel:[1,0,0] op_sel_hi:[1,1,1]
	ds_read_b32 v31, v127 offset:188
	s_waitcnt lgkmcnt(9)
	v_pk_fma_f32 v[4:5], v[102:103], v[218:219], v[4:5] op_sel_hi:[0,1,1]
	v_pk_fma_f32 v[6:7], v[102:103], v[220:221], v[6:7] op_sel:[1,0,0] op_sel_hi:[1,1,1]
	v_pk_fma_f32 v[8:9], v[104:105], v[222:223], v[8:9] op_sel_hi:[0,1,1]
	v_pk_fma_f32 v[10:11], v[104:105], v[224:225], v[10:11] op_sel:[1,0,0] op_sel_hi:[1,1,1]
	ds_read_b128 v[32:35], v122 offset:12288
	s_waitcnt lgkmcnt(9)
	v_pk_fma_f32 v[4:5], v[106:107], v[226:227], v[4:5] op_sel_hi:[0,1,1]
	v_pk_fma_f32 v[6:7], v[106:107], v[228:229], v[6:7] op_sel:[1,0,0] op_sel_hi:[1,1,1]
	v_pk_fma_f32 v[8:9], v[108:109], v[230:231], v[8:9] op_sel_hi:[0,1,1]
	v_pk_fma_f32 v[10:11], v[108:109], v[232:233], v[10:11] op_sel:[1,0,0] op_sel_hi:[1,1,1]
	ds_read_b128 v[36:39], v122 offset:12304
	s_waitcnt lgkmcnt(9)
	v_pk_fma_f32 v[4:5], v[130:131], v[234:235], v[4:5] op_sel_hi:[0,1,1]
	v_pk_fma_f32 v[6:7], v[130:131], v[236:237], v[6:7] op_sel:[1,0,0] op_sel_hi:[1,1,1]
	v_pk_fma_f32 v[8:9], v[132:133], v[238:239], v[8:9] op_sel_hi:[0,1,1]
	v_pk_fma_f32 v[10:11], v[132:133], v[240:241], v[10:11] op_sel:[1,0,0] op_sel_hi:[1,1,1]
	ds_read_b128 v[40:43], v122 offset:12320
	s_waitcnt lgkmcnt(9)
	v_pk_fma_f32 v[4:5], v[140:141], v[242:243], v[4:5] op_sel_hi:[0,1,1]
	v_pk_fma_f32 v[6:7], v[140:141], v[244:245], v[6:7] op_sel:[1,0,0] op_sel_hi:[1,1,1]
	v_pk_fma_f32 v[8:9], v[142:143], v[246:247], v[8:9] op_sel_hi:[0,1,1]
	v_pk_fma_f32 v[10:11], v[142:143], v[248:249], v[10:11] op_sel:[1,0,0] op_sel_hi:[1,1,1]
	ds_read_b128 v[98:101], v122 offset:12336
	s_waitcnt lgkmcnt(9)
	v_pk_fma_f32 v[4:5], v[144:145], v[46:47], v[4:5] op_sel_hi:[0,1,1]
	v_pk_fma_f32 v[6:7], v[144:145], v[48:49], v[6:7] op_sel:[1,0,0] op_sel_hi:[1,1,1]
	v_pk_fma_f32 v[8:9], v[146:147], v[50:51], v[8:9] op_sel_hi:[0,1,1]
	v_pk_fma_f32 v[10:11], v[146:147], v[52:53], v[10:11] op_sel:[1,0,0] op_sel_hi:[1,1,1]
	ds_read_b128 v[102:105], v122 offset:12352
	s_waitcnt lgkmcnt(9)
	v_pk_fma_f32 v[4:5], v[148:149], v[54:55], v[4:5] op_sel_hi:[0,1,1]
	v_pk_fma_f32 v[6:7], v[148:149], v[56:57], v[6:7] op_sel:[1,0,0] op_sel_hi:[1,1,1]
	v_pk_fma_f32 v[8:9], v[150:151], v[58:59], v[8:9] op_sel_hi:[0,1,1]
	ds_read_b128 v[106:109], v122 offset:12368
	ds_read_b128 v[130:133], v122 offset:12384
	ds_read_b128 v[140:143], v122 offset:12400
	ds_read_b128 v[144:147], v122 offset:12416
	s_waitcnt lgkmcnt(9)
	v_lshlrev_b32_e32 v28, 16, v28
	v_lshlrev_b32_e32 v29, 16, v29
	v_pk_add_f32 v[12:13], v[4:5], v[6:7]
	v_pk_add_f32 v[14:15], v[8:9], v[10:11]
	s_nop 0
	v_pk_add_f32 v[12:13], v[12:13], v[14:15]
	s_nop 0
	v_pk_fma_f32 v[60:61], v[30:31], v[28:29], v[12:13] neg_lo:[0,0,1] neg_hi:[0,0,1]
	ds_read_b128 v[148:151], v122 offset:12432
	s_waitcnt lgkmcnt(9)
	v_pk_mul_f32 v[4:5], v[32:33], v[170:171] op_sel_hi:[0,1]
	v_pk_mul_f32 v[6:7], v[32:33], v[172:173] op_sel:[1,0] op_sel_hi:[1,1]
	v_pk_mul_f32 v[8:9], v[34:35], v[174:175] op_sel_hi:[0,1]
	v_pk_mul_f32 v[10:11], v[34:35], v[176:177] op_sel:[1,0] op_sel_hi:[1,1]
	ds_read_b128 v[32:35], v122 offset:12448
	s_waitcnt lgkmcnt(9)
	v_pk_fma_f32 v[4:5], v[36:37], v[178:179], v[4:5] op_sel_hi:[0,1,1]
	v_pk_fma_f32 v[6:7], v[36:37], v[180:181], v[6:7] op_sel:[1,0,0] op_sel_hi:[1,1,1]
	v_pk_fma_f32 v[8:9], v[38:39], v[182:183], v[8:9] op_sel_hi:[0,1,1]
	v_pk_fma_f32 v[10:11], v[38:39], v[184:185], v[10:11] op_sel:[1,0,0] op_sel_hi:[1,1,1]
	ds_read_b128 v[36:39], v122 offset:12464
	s_waitcnt lgkmcnt(9)
	v_pk_fma_f32 v[4:5], v[40:41], v[186:187], v[4:5] op_sel_hi:[0,1,1]
	v_pk_fma_f32 v[6:7], v[40:41], v[188:189], v[6:7] op_sel:[1,0,0] op_sel_hi:[1,1,1]
	v_pk_fma_f32 v[8:9], v[42:43], v[190:191], v[8:9] op_sel_hi:[0,1,1]
	v_pk_fma_f32 v[10:11], v[42:43], v[192:193], v[10:11] op_sel:[1,0,0] op_sel_hi:[1,1,1]
	ds_read_u16 v16, v115 offset:13056
	s_waitcnt lgkmcnt(9)
	v_pk_fma_f32 v[4:5], v[98:99], v[194:195], v[4:5] op_sel_hi:[0,1,1]
	v_pk_fma_f32 v[6:7], v[98:99], v[196:197], v[6:7] op_sel:[1,0,0] op_sel_hi:[1,1,1]
	v_pk_fma_f32 v[8:9], v[100:101], v[198:199], v[8:9] op_sel_hi:[0,1,1]
	v_pk_fma_f32 v[10:11], v[100:101], v[200:201], v[10:11] op_sel:[1,0,0] op_sel_hi:[1,1,1]
	ds_read_u16 v17, v116 offset:13056
	s_waitcnt lgkmcnt(9)
	v_pk_fma_f32 v[4:5], v[102:103], v[202:203], v[4:5] op_sel_hi:[0,1,1]
	v_pk_fma_f32 v[6:7], v[102:103], v[204:205], v[6:7] op_sel:[1,0,0] op_sel_hi:[1,1,1]
	v_pk_fma_f32 v[8:9], v[104:105], v[206:207], v[8:9] op_sel_hi:[0,1,1]
	v_pk_fma_f32 v[10:11], v[104:105], v[208:209], v[10:11] op_sel:[1,0,0] op_sel_hi:[1,1,1]
	ds_read_b32 v18, v126 offset:192
	s_waitcnt lgkmcnt(9)
	v_pk_fma_f32 v[4:5], v[106:107], v[210:211], v[4:5] op_sel_hi:[0,1,1]
	v_pk_fma_f32 v[6:7], v[106:107], v[212:213], v[6:7] op_sel:[1,0,0] op_sel_hi:[1,1,1]
	v_pk_fma_f32 v[8:9], v[108:109], v[214:215], v[8:9] op_sel_hi:[0,1,1]
	v_pk_fma_f32 v[10:11], v[108:109], v[216:217], v[10:11] op_sel:[1,0,0] op_sel_hi:[1,1,1]
	ds_read_b32 v19, v127 offset:192
	s_waitcnt lgkmcnt(9)
	v_pk_fma_f32 v[4:5], v[130:131], v[218:219], v[4:5] op_sel_hi:[0,1,1]
	v_pk_fma_f32 v[6:7], v[130:131], v[220:221], v[6:7] op_sel:[1,0,0] op_sel_hi:[1,1,1]
	v_pk_fma_f32 v[8:9], v[132:133], v[222:223], v[8:9] op_sel_hi:[0,1,1]
	v_pk_fma_f32 v[10:11], v[132:133], v[224:225], v[10:11] op_sel:[1,0,0] op_sel_hi:[1,1,1]
	ds_read_b128 v[40:43], v122 offset:12544
	s_waitcnt lgkmcnt(9)
	v_pk_fma_f32 v[4:5], v[140:141], v[226:227], v[4:5] op_sel_hi:[0,1,1]
	v_pk_fma_f32 v[6:7], v[140:141], v[228:229], v[6:7] op_sel:[1,0,0] op_sel_hi:[1,1,1]
	v_pk_fma_f32 v[8:9], v[142:143], v[230:231], v[8:9] op_sel_hi:[0,1,1]
	v_pk_fma_f32 v[10:11], v[142:143], v[232:233], v[10:11] op_sel:[1,0,0] op_sel_hi:[1,1,1]
	ds_read_b128 v[98:101], v122 offset:12560
	s_waitcnt lgkmcnt(9)
	v_pk_fma_f32 v[4:5], v[144:145], v[234:235], v[4:5] op_sel_hi:[0,1,1]
	v_pk_fma_f32 v[6:7], v[144:145], v[236:237], v[6:7] op_sel:[1,0,0] op_sel_hi:[1,1,1]
	v_pk_fma_f32 v[8:9], v[146:147], v[238:239], v[8:9] op_sel_hi:[0,1,1]
	v_pk_fma_f32 v[10:11], v[146:147], v[240:241], v[10:11] op_sel:[1,0,0] op_sel_hi:[1,1,1]
	ds_read_b128 v[102:105], v122 offset:12576
	s_waitcnt lgkmcnt(9)
	v_pk_fma_f32 v[4:5], v[148:149], v[242:243], v[4:5] op_sel_hi:[0,1,1]
	v_pk_fma_f32 v[6:7], v[148:149], v[244:245], v[6:7] op_sel:[1,0,0] op_sel_hi:[1,1,1]
	v_pk_fma_f32 v[8:9], v[150:151], v[246:247], v[8:9] op_sel_hi:[0,1,1]
	v_pk_fma_f32 v[10:11], v[150:151], v[248:249], v[10:11] op_sel:[1,0,0] op_sel_hi:[1,1,1]
	ds_read_b128 v[106:109], v122 offset:12592
	s_waitcnt lgkmcnt(9)
	v_pk_fma_f32 v[4:5], v[32:33], v[46:47], v[4:5] op_sel_hi:[0,1,1]
	v_pk_fma_f32 v[6:7], v[32:33], v[48:49], v[6:7] op_sel:[1,0,0] op_sel_hi:[1,1,1]
	v_pk_fma_f32 v[8:9], v[34:35], v[50:51], v[8:9] op_sel_hi:[0,1,1]
	v_pk_fma_f32 v[10:11], v[34:35], v[52:53], v[10:11] op_sel:[1,0,0] op_sel_hi:[1,1,1]
	ds_read_b128 v[130:133], v122 offset:12608
	s_waitcnt lgkmcnt(9)
	v_pk_fma_f32 v[4:5], v[36:37], v[54:55], v[4:5] op_sel_hi:[0,1,1]
	v_pk_fma_f32 v[6:7], v[36:37], v[56:57], v[6:7] op_sel:[1,0,0] op_sel_hi:[1,1,1]
	v_pk_fma_f32 v[8:9], v[38:39], v[58:59], v[8:9] op_sel_hi:[0,1,1]
	v_pk_fma_f32 v[10:11], v[38:39], v[60:61], v[10:11] op_sel:[1,0,0] op_sel_hi:[1,1,1]
	ds_read_b128 v[140:143], v122 offset:12624
	ds_read_b128 v[144:147], v122 offset:12640
	ds_read_b128 v[148:151], v122 offset:12656
	ds_read_b128 v[32:35], v122 offset:12672
	s_waitcnt lgkmcnt(9)
	v_lshlrev_b32_e32 v16, 16, v16
	v_lshlrev_b32_e32 v17, 16, v17
	v_pk_add_f32 v[12:13], v[4:5], v[6:7]
	v_pk_add_f32 v[14:15], v[8:9], v[10:11]
	s_nop 0
	v_pk_add_f32 v[12:13], v[12:13], v[14:15]
	s_nop 0
	v_pk_fma_f32 v[62:63], v[18:19], v[16:17], v[12:13] neg_lo:[0,0,1] neg_hi:[0,0,1]
	ds_read_b128 v[36:39], v122 offset:12688
	s_waitcnt lgkmcnt(9)
	v_pk_mul_f32 v[4:5], v[40:41], v[170:171] op_sel_hi:[0,1]
	v_pk_mul_f32 v[6:7], v[40:41], v[172:173] op_sel:[1,0] op_sel_hi:[1,1]
	v_pk_mul_f32 v[8:9], v[42:43], v[174:175] op_sel_hi:[0,1]
	v_pk_mul_f32 v[10:11], v[42:43], v[176:177] op_sel:[1,0] op_sel_hi:[1,1]
	ds_read_b128 v[40:43], v122 offset:12704
	s_waitcnt lgkmcnt(9)
	v_pk_fma_f32 v[4:5], v[98:99], v[178:179], v[4:5] op_sel_hi:[0,1,1]
	v_pk_fma_f32 v[6:7], v[98:99], v[180:181], v[6:7] op_sel:[1,0,0] op_sel_hi:[1,1,1]
	v_pk_fma_f32 v[8:9], v[100:101], v[182:183], v[8:9] op_sel_hi:[0,1,1]
	v_pk_fma_f32 v[10:11], v[100:101], v[184:185], v[10:11] op_sel:[1,0,0] op_sel_hi:[1,1,1]
	ds_read_b128 v[98:101], v122 offset:12720
	s_waitcnt lgkmcnt(9)
	v_pk_fma_f32 v[4:5], v[102:103], v[186:187], v[4:5] op_sel_hi:[0,1,1]
	v_pk_fma_f32 v[6:7], v[102:103], v[188:189], v[6:7] op_sel:[1,0,0] op_sel_hi:[1,1,1]
	v_pk_fma_f32 v[8:9], v[104:105], v[190:191], v[8:9] op_sel_hi:[0,1,1]
	v_pk_fma_f32 v[10:11], v[104:105], v[192:193], v[10:11] op_sel:[1,0,0] op_sel_hi:[1,1,1]
	ds_read_b128 v[102:105], v122 offset:12736
	s_waitcnt lgkmcnt(9)
	v_pk_fma_f32 v[4:5], v[106:107], v[194:195], v[4:5] op_sel_hi:[0,1,1]
	v_pk_fma_f32 v[6:7], v[106:107], v[196:197], v[6:7] op_sel:[1,0,0] op_sel_hi:[1,1,1]
	v_pk_fma_f32 v[8:9], v[108:109], v[198:199], v[8:9] op_sel_hi:[0,1,1]
	v_pk_fma_f32 v[10:11], v[108:109], v[200:201], v[10:11] op_sel:[1,0,0] op_sel_hi:[1,1,1]
	ds_read_u16 v20, v115 offset:13328
	s_waitcnt lgkmcnt(9)
	v_pk_fma_f32 v[4:5], v[130:131], v[202:203], v[4:5] op_sel_hi:[0,1,1]
	v_pk_fma_f32 v[6:7], v[130:131], v[204:205], v[6:7] op_sel:[1,0,0] op_sel_hi:[1,1,1]
	v_pk_fma_f32 v[8:9], v[132:133], v[206:207], v[8:9] op_sel_hi:[0,1,1]
	v_pk_fma_f32 v[10:11], v[132:133], v[208:209], v[10:11] op_sel:[1,0,0] op_sel_hi:[1,1,1]
	ds_read_u16 v21, v116 offset:13328
	s_waitcnt lgkmcnt(9)
	v_pk_fma_f32 v[4:5], v[140:141], v[210:211], v[4:5] op_sel_hi:[0,1,1]
	v_pk_fma_f32 v[6:7], v[140:141], v[212:213], v[6:7] op_sel:[1,0,0] op_sel_hi:[1,1,1]
	v_pk_fma_f32 v[8:9], v[142:143], v[214:215], v[8:9] op_sel_hi:[0,1,1]
	v_pk_fma_f32 v[10:11], v[142:143], v[216:217], v[10:11] op_sel:[1,0,0] op_sel_hi:[1,1,1]
	ds_read_b32 v22, v126 offset:196
	s_waitcnt lgkmcnt(9)
	v_pk_fma_f32 v[4:5], v[144:145], v[218:219], v[4:5] op_sel_hi:[0,1,1]
	v_pk_fma_f32 v[6:7], v[144:145], v[220:221], v[6:7] op_sel:[1,0,0] op_sel_hi:[1,1,1]
	v_pk_fma_f32 v[8:9], v[146:147], v[222:223], v[8:9] op_sel_hi:[0,1,1]
	v_pk_fma_f32 v[10:11], v[146:147], v[224:225], v[10:11] op_sel:[1,0,0] op_sel_hi:[1,1,1]
	ds_read_b32 v23, v127 offset:196
	s_waitcnt lgkmcnt(9)
	v_pk_fma_f32 v[4:5], v[148:149], v[226:227], v[4:5] op_sel_hi:[0,1,1]
	v_pk_fma_f32 v[6:7], v[148:149], v[228:229], v[6:7] op_sel:[1,0,0] op_sel_hi:[1,1,1]
	v_pk_fma_f32 v[8:9], v[150:151], v[230:231], v[8:9] op_sel_hi:[0,1,1]
	v_pk_fma_f32 v[10:11], v[150:151], v[232:233], v[10:11] op_sel:[1,0,0] op_sel_hi:[1,1,1]
	ds_read_b128 v[106:109], v122 offset:12800
	s_waitcnt lgkmcnt(9)
	v_pk_fma_f32 v[4:5], v[32:33], v[234:235], v[4:5] op_sel_hi:[0,1,1]
	v_pk_fma_f32 v[6:7], v[32:33], v[236:237], v[6:7] op_sel:[1,0,0] op_sel_hi:[1,1,1]
	v_pk_fma_f32 v[8:9], v[34:35], v[238:239], v[8:9] op_sel_hi:[0,1,1]
	v_pk_fma_f32 v[10:11], v[34:35], v[240:241], v[10:11] op_sel:[1,0,0] op_sel_hi:[1,1,1]
	ds_read_b128 v[130:133], v122 offset:12816
	s_waitcnt lgkmcnt(9)
	v_pk_fma_f32 v[4:5], v[36:37], v[242:243], v[4:5] op_sel_hi:[0,1,1]
	v_pk_fma_f32 v[6:7], v[36:37], v[244:245], v[6:7] op_sel:[1,0,0] op_sel_hi:[1,1,1]
	v_pk_fma_f32 v[8:9], v[38:39], v[246:247], v[8:9] op_sel_hi:[0,1,1]
	v_pk_fma_f32 v[10:11], v[38:39], v[248:249], v[10:11] op_sel:[1,0,0] op_sel_hi:[1,1,1]
	ds_read_b128 v[140:143], v122 offset:12832
	s_waitcnt lgkmcnt(9)
	v_pk_fma_f32 v[4:5], v[40:41], v[46:47], v[4:5] op_sel_hi:[0,1,1]
	v_pk_fma_f32 v[6:7], v[40:41], v[48:49], v[6:7] op_sel:[1,0,0] op_sel_hi:[1,1,1]
	v_pk_fma_f32 v[8:9], v[42:43], v[50:51], v[8:9] op_sel_hi:[0,1,1]
	v_pk_fma_f32 v[10:11], v[42:43], v[52:53], v[10:11] op_sel:[1,0,0] op_sel_hi:[1,1,1]
	ds_read_b128 v[144:147], v122 offset:12848
	s_waitcnt lgkmcnt(9)
	v_pk_fma_f32 v[4:5], v[98:99], v[54:55], v[4:5] op_sel_hi:[0,1,1]
	v_pk_fma_f32 v[6:7], v[98:99], v[56:57], v[6:7] op_sel:[1,0,0] op_sel_hi:[1,1,1]
	v_pk_fma_f32 v[8:9], v[100:101], v[58:59], v[8:9] op_sel_hi:[0,1,1]
	v_pk_fma_f32 v[10:11], v[100:101], v[60:61], v[10:11] op_sel:[1,0,0] op_sel_hi:[1,1,1]
	ds_read_b128 v[148:151], v122 offset:12864
	s_waitcnt lgkmcnt(9)
	v_pk_fma_f32 v[4:5], v[102:103], v[62:63], v[4:5] op_sel_hi:[0,1,1]
	ds_read_b128 v[32:35], v122 offset:12880
	ds_read_b128 v[36:39], v122 offset:12896
	ds_read_b128 v[40:43], v122 offset:12912
	ds_read_b128 v[98:101], v122 offset:12928
	s_waitcnt lgkmcnt(9)
	v_lshlrev_b32_e32 v20, 16, v20
	v_lshlrev_b32_e32 v21, 16, v21
	v_pk_add_f32 v[12:13], v[4:5], v[6:7]
	v_pk_add_f32 v[14:15], v[8:9], v[10:11]
	s_nop 0
	v_pk_add_f32 v[12:13], v[12:13], v[14:15]
	s_nop 0
	v_pk_fma_f32 v[64:65], v[22:23], v[20:21], v[12:13] neg_lo:[0,0,1] neg_hi:[0,0,1]
	ds_read_b128 v[102:105], v122 offset:12944
	s_waitcnt lgkmcnt(9)
	v_pk_mul_f32 v[4:5], v[106:107], v[170:171] op_sel_hi:[0,1]
	v_pk_mul_f32 v[6:7], v[106:107], v[172:173] op_sel:[1,0] op_sel_hi:[1,1]
	v_pk_mul_f32 v[8:9], v[108:109], v[174:175] op_sel_hi:[0,1]
	v_pk_mul_f32 v[10:11], v[108:109], v[176:177] op_sel:[1,0] op_sel_hi:[1,1]
	ds_read_b128 v[106:109], v122 offset:12960
	s_waitcnt lgkmcnt(9)
	v_pk_fma_f32 v[4:5], v[130:131], v[178:179], v[4:5] op_sel_hi:[0,1,1]
	v_pk_fma_f32 v[6:7], v[130:131], v[180:181], v[6:7] op_sel:[1,0,0] op_sel_hi:[1,1,1]
	v_pk_fma_f32 v[8:9], v[132:133], v[182:183], v[8:9] op_sel_hi:[0,1,1]
	v_pk_fma_f32 v[10:11], v[132:133], v[184:185], v[10:11] op_sel:[1,0,0] op_sel_hi:[1,1,1]
	ds_read_b128 v[130:133], v122 offset:12976
	s_waitcnt lgkmcnt(9)
	v_pk_fma_f32 v[4:5], v[140:141], v[186:187], v[4:5] op_sel_hi:[0,1,1]
	v_pk_fma_f32 v[6:7], v[140:141], v[188:189], v[6:7] op_sel:[1,0,0] op_sel_hi:[1,1,1]
	v_pk_fma_f32 v[8:9], v[142:143], v[190:191], v[8:9] op_sel_hi:[0,1,1]
	v_pk_fma_f32 v[10:11], v[142:143], v[192:193], v[10:11] op_sel:[1,0,0] op_sel_hi:[1,1,1]
	ds_read_b128 v[140:143], v122 offset:12992
	s_waitcnt lgkmcnt(9)
	v_pk_fma_f32 v[4:5], v[144:145], v[194:195], v[4:5] op_sel_hi:[0,1,1]
	v_pk_fma_f32 v[6:7], v[144:145], v[196:197], v[6:7] op_sel:[1,0,0] op_sel_hi:[1,1,1]
	v_pk_fma_f32 v[8:9], v[146:147], v[198:199], v[8:9] op_sel_hi:[0,1,1]
	v_pk_fma_f32 v[10:11], v[146:147], v[200:201], v[10:11] op_sel:[1,0,0] op_sel_hi:[1,1,1]
	ds_read_u16 v24, v115 offset:13600
	s_waitcnt lgkmcnt(9)
	v_pk_fma_f32 v[4:5], v[148:149], v[202:203], v[4:5] op_sel_hi:[0,1,1]
	v_pk_fma_f32 v[6:7], v[148:149], v[204:205], v[6:7] op_sel:[1,0,0] op_sel_hi:[1,1,1]
	v_pk_fma_f32 v[8:9], v[150:151], v[206:207], v[8:9] op_sel_hi:[0,1,1]
	v_pk_fma_f32 v[10:11], v[150:151], v[208:209], v[10:11] op_sel:[1,0,0] op_sel_hi:[1,1,1]
	ds_read_u16 v25, v116 offset:13600
	s_waitcnt lgkmcnt(9)
	v_pk_fma_f32 v[4:5], v[32:33], v[210:211], v[4:5] op_sel_hi:[0,1,1]
	v_pk_fma_f32 v[6:7], v[32:33], v[212:213], v[6:7] op_sel:[1,0,0] op_sel_hi:[1,1,1]
	v_pk_fma_f32 v[8:9], v[34:35], v[214:215], v[8:9] op_sel_hi:[0,1,1]
	v_pk_fma_f32 v[10:11], v[34:35], v[216:217], v[10:11] op_sel:[1,0,0] op_sel_hi:[1,1,1]
	ds_read_b32 v26, v126 offset:200
	s_waitcnt lgkmcnt(9)
	v_pk_fma_f32 v[4:5], v[36:37], v[218:219], v[4:5] op_sel_hi:[0,1,1]
	v_pk_fma_f32 v[6:7], v[36:37], v[220:221], v[6:7] op_sel:[1,0,0] op_sel_hi:[1,1,1]
	v_pk_fma_f32 v[8:9], v[38:39], v[222:223], v[8:9] op_sel_hi:[0,1,1]
	v_pk_fma_f32 v[10:11], v[38:39], v[224:225], v[10:11] op_sel:[1,0,0] op_sel_hi:[1,1,1]
	ds_read_b32 v27, v127 offset:200
	s_waitcnt lgkmcnt(9)
	v_pk_fma_f32 v[4:5], v[40:41], v[226:227], v[4:5] op_sel_hi:[0,1,1]
	v_pk_fma_f32 v[6:7], v[40:41], v[228:229], v[6:7] op_sel:[1,0,0] op_sel_hi:[1,1,1]
	v_pk_fma_f32 v[8:9], v[42:43], v[230:231], v[8:9] op_sel_hi:[0,1,1]
	v_pk_fma_f32 v[10:11], v[42:43], v[232:233], v[10:11] op_sel:[1,0,0] op_sel_hi:[1,1,1]
	ds_read_b128 v[144:147], v122 offset:13056
	s_waitcnt lgkmcnt(9)
	v_pk_fma_f32 v[4:5], v[98:99], v[234:235], v[4:5] op_sel_hi:[0,1,1]
	v_pk_fma_f32 v[6:7], v[98:99], v[236:237], v[6:7] op_sel:[1,0,0] op_sel_hi:[1,1,1]
	v_pk_fma_f32 v[8:9], v[100:101], v[238:239], v[8:9] op_sel_hi:[0,1,1]
	v_pk_fma_f32 v[10:11], v[100:101], v[240:241], v[10:11] op_sel:[1,0,0] op_sel_hi:[1,1,1]
	ds_read_b128 v[148:151], v122 offset:13072
	s_waitcnt lgkmcnt(9)
	v_pk_fma_f32 v[4:5], v[102:103], v[242:243], v[4:5] op_sel_hi:[0,1,1]
	v_pk_fma_f32 v[6:7], v[102:103], v[244:245], v[6:7] op_sel:[1,0,0] op_sel_hi:[1,1,1]
	v_pk_fma_f32 v[8:9], v[104:105], v[246:247], v[8:9] op_sel_hi:[0,1,1]
	v_pk_fma_f32 v[10:11], v[104:105], v[248:249], v[10:11] op_sel:[1,0,0] op_sel_hi:[1,1,1]
	ds_read_b128 v[32:35], v122 offset:13088
	s_waitcnt lgkmcnt(9)
	v_pk_fma_f32 v[4:5], v[106:107], v[46:47], v[4:5] op_sel_hi:[0,1,1]
	v_pk_fma_f32 v[6:7], v[106:107], v[48:49], v[6:7] op_sel:[1,0,0] op_sel_hi:[1,1,1]
	v_pk_fma_f32 v[8:9], v[108:109], v[50:51], v[8:9] op_sel_hi:[0,1,1]
	v_pk_fma_f32 v[10:11], v[108:109], v[52:53], v[10:11] op_sel:[1,0,0] op_sel_hi:[1,1,1]
	ds_read_b128 v[36:39], v122 offset:13104
	s_waitcnt lgkmcnt(9)
	v_pk_fma_f32 v[4:5], v[130:131], v[54:55], v[4:5] op_sel_hi:[0,1,1]
	v_pk_fma_f32 v[6:7], v[130:131], v[56:57], v[6:7] op_sel:[1,0,0] op_sel_hi:[1,1,1]
	v_pk_fma_f32 v[8:9], v[132:133], v[58:59], v[8:9] op_sel_hi:[0,1,1]
	v_pk_fma_f32 v[10:11], v[132:133], v[60:61], v[10:11] op_sel:[1,0,0] op_sel_hi:[1,1,1]
	ds_read_b128 v[40:43], v122 offset:13120
	s_waitcnt lgkmcnt(9)
	v_pk_fma_f32 v[4:5], v[140:141], v[62:63], v[4:5] op_sel_hi:[0,1,1]
	v_pk_fma_f32 v[6:7], v[140:141], v[64:65], v[6:7] op_sel:[1,0,0] op_sel_hi:[1,1,1]
	ds_read_b128 v[98:101], v122 offset:13136
	ds_read_b128 v[102:105], v122 offset:13152
	ds_read_b128 v[106:109], v122 offset:13168
	ds_read_b128 v[130:133], v122 offset:13184
	s_waitcnt lgkmcnt(9)
	v_lshlrev_b32_e32 v24, 16, v24
	v_lshlrev_b32_e32 v25, 16, v25
	v_pk_add_f32 v[12:13], v[4:5], v[6:7]
	v_pk_add_f32 v[14:15], v[8:9], v[10:11]
	s_nop 0
	v_pk_add_f32 v[12:13], v[12:13], v[14:15]
	s_nop 0
	v_pk_fma_f32 v[66:67], v[26:27], v[24:25], v[12:13] neg_lo:[0,0,1] neg_hi:[0,0,1]
	ds_read_b128 v[140:143], v122 offset:13200
	s_waitcnt lgkmcnt(9)
	v_pk_mul_f32 v[4:5], v[144:145], v[170:171] op_sel_hi:[0,1]
	v_pk_mul_f32 v[6:7], v[144:145], v[172:173] op_sel:[1,0] op_sel_hi:[1,1]
	v_pk_mul_f32 v[8:9], v[146:147], v[174:175] op_sel_hi:[0,1]
	v_pk_mul_f32 v[10:11], v[146:147], v[176:177] op_sel:[1,0] op_sel_hi:[1,1]
	ds_read_b128 v[144:147], v122 offset:13216
	s_waitcnt lgkmcnt(9)
	v_pk_fma_f32 v[4:5], v[148:149], v[178:179], v[4:5] op_sel_hi:[0,1,1]
	v_pk_fma_f32 v[6:7], v[148:149], v[180:181], v[6:7] op_sel:[1,0,0] op_sel_hi:[1,1,1]
	v_pk_fma_f32 v[8:9], v[150:151], v[182:183], v[8:9] op_sel_hi:[0,1,1]
	v_pk_fma_f32 v[10:11], v[150:151], v[184:185], v[10:11] op_sel:[1,0,0] op_sel_hi:[1,1,1]
	ds_read_b128 v[148:151], v122 offset:13232
	s_waitcnt lgkmcnt(9)
	v_pk_fma_f32 v[4:5], v[32:33], v[186:187], v[4:5] op_sel_hi:[0,1,1]
	v_pk_fma_f32 v[6:7], v[32:33], v[188:189], v[6:7] op_sel:[1,0,0] op_sel_hi:[1,1,1]
	v_pk_fma_f32 v[8:9], v[34:35], v[190:191], v[8:9] op_sel_hi:[0,1,1]
	v_pk_fma_f32 v[10:11], v[34:35], v[192:193], v[10:11] op_sel:[1,0,0] op_sel_hi:[1,1,1]
	ds_read_b128 v[32:35], v122 offset:13248
	s_waitcnt lgkmcnt(9)
	v_pk_fma_f32 v[4:5], v[36:37], v[194:195], v[4:5] op_sel_hi:[0,1,1]
	v_pk_fma_f32 v[6:7], v[36:37], v[196:197], v[6:7] op_sel:[1,0,0] op_sel_hi:[1,1,1]
	v_pk_fma_f32 v[8:9], v[38:39], v[198:199], v[8:9] op_sel_hi:[0,1,1]
	v_pk_fma_f32 v[10:11], v[38:39], v[200:201], v[10:11] op_sel:[1,0,0] op_sel_hi:[1,1,1]
	ds_read_u16 v28, v115 offset:13872
	s_waitcnt lgkmcnt(9)
	v_pk_fma_f32 v[4:5], v[40:41], v[202:203], v[4:5] op_sel_hi:[0,1,1]
	v_pk_fma_f32 v[6:7], v[40:41], v[204:205], v[6:7] op_sel:[1,0,0] op_sel_hi:[1,1,1]
	v_pk_fma_f32 v[8:9], v[42:43], v[206:207], v[8:9] op_sel_hi:[0,1,1]
	v_pk_fma_f32 v[10:11], v[42:43], v[208:209], v[10:11] op_sel:[1,0,0] op_sel_hi:[1,1,1]
	ds_read_u16 v29, v116 offset:13872
	s_waitcnt lgkmcnt(9)
	v_pk_fma_f32 v[4:5], v[98:99], v[210:211], v[4:5] op_sel_hi:[0,1,1]
	v_pk_fma_f32 v[6:7], v[98:99], v[212:213], v[6:7] op_sel:[1,0,0] op_sel_hi:[1,1,1]
	v_pk_fma_f32 v[8:9], v[100:101], v[214:215], v[8:9] op_sel_hi:[0,1,1]
	v_pk_fma_f32 v[10:11], v[100:101], v[216:217], v[10:11] op_sel:[1,0,0] op_sel_hi:[1,1,1]
	ds_read_b32 v30, v126 offset:204
	s_waitcnt lgkmcnt(9)
	v_pk_fma_f32 v[4:5], v[102:103], v[218:219], v[4:5] op_sel_hi:[0,1,1]
	v_pk_fma_f32 v[6:7], v[102:103], v[220:221], v[6:7] op_sel:[1,0,0] op_sel_hi:[1,1,1]
	v_pk_fma_f32 v[8:9], v[104:105], v[222:223], v[8:9] op_sel_hi:[0,1,1]
	v_pk_fma_f32 v[10:11], v[104:105], v[224:225], v[10:11] op_sel:[1,0,0] op_sel_hi:[1,1,1]
	ds_read_b32 v31, v127 offset:204
	s_waitcnt lgkmcnt(9)
	v_pk_fma_f32 v[4:5], v[106:107], v[226:227], v[4:5] op_sel_hi:[0,1,1]
	v_pk_fma_f32 v[6:7], v[106:107], v[228:229], v[6:7] op_sel:[1,0,0] op_sel_hi:[1,1,1]
	v_pk_fma_f32 v[8:9], v[108:109], v[230:231], v[8:9] op_sel_hi:[0,1,1]
	v_pk_fma_f32 v[10:11], v[108:109], v[232:233], v[10:11] op_sel:[1,0,0] op_sel_hi:[1,1,1]
	ds_read_b128 v[36:39], v122 offset:13312
	s_waitcnt lgkmcnt(9)
	v_pk_fma_f32 v[4:5], v[130:131], v[234:235], v[4:5] op_sel_hi:[0,1,1]
	v_pk_fma_f32 v[6:7], v[130:131], v[236:237], v[6:7] op_sel:[1,0,0] op_sel_hi:[1,1,1]
	v_pk_fma_f32 v[8:9], v[132:133], v[238:239], v[8:9] op_sel_hi:[0,1,1]
	v_pk_fma_f32 v[10:11], v[132:133], v[240:241], v[10:11] op_sel:[1,0,0] op_sel_hi:[1,1,1]
	ds_read_b128 v[40:43], v122 offset:13328
	s_waitcnt lgkmcnt(9)
	v_pk_fma_f32 v[4:5], v[140:141], v[242:243], v[4:5] op_sel_hi:[0,1,1]
	v_pk_fma_f32 v[6:7], v[140:141], v[244:245], v[6:7] op_sel:[1,0,0] op_sel_hi:[1,1,1]
	v_pk_fma_f32 v[8:9], v[142:143], v[246:247], v[8:9] op_sel_hi:[0,1,1]
	v_pk_fma_f32 v[10:11], v[142:143], v[248:249], v[10:11] op_sel:[1,0,0] op_sel_hi:[1,1,1]
	ds_read_b128 v[98:101], v122 offset:13344
	s_waitcnt lgkmcnt(9)
	v_pk_fma_f32 v[4:5], v[144:145], v[46:47], v[4:5] op_sel_hi:[0,1,1]
	v_pk_fma_f32 v[6:7], v[144:145], v[48:49], v[6:7] op_sel:[1,0,0] op_sel_hi:[1,1,1]
	v_pk_fma_f32 v[8:9], v[146:147], v[50:51], v[8:9] op_sel_hi:[0,1,1]
	v_pk_fma_f32 v[10:11], v[146:147], v[52:53], v[10:11] op_sel:[1,0,0] op_sel_hi:[1,1,1]
	ds_read_b128 v[102:105], v122 offset:13360
	s_waitcnt lgkmcnt(9)
	v_pk_fma_f32 v[4:5], v[148:149], v[54:55], v[4:5] op_sel_hi:[0,1,1]
	v_pk_fma_f32 v[6:7], v[148:149], v[56:57], v[6:7] op_sel:[1,0,0] op_sel_hi:[1,1,1]
	v_pk_fma_f32 v[8:9], v[150:151], v[58:59], v[8:9] op_sel_hi:[0,1,1]
	v_pk_fma_f32 v[10:11], v[150:151], v[60:61], v[10:11] op_sel:[1,0,0] op_sel_hi:[1,1,1]
	ds_read_b128 v[106:109], v122 offset:13376
	s_waitcnt lgkmcnt(9)
	v_pk_fma_f32 v[4:5], v[32:33], v[62:63], v[4:5] op_sel_hi:[0,1,1]
	v_pk_fma_f32 v[6:7], v[32:33], v[64:65], v[6:7] op_sel:[1,0,0] op_sel_hi:[1,1,1]
	v_pk_fma_f32 v[8:9], v[34:35], v[66:67], v[8:9] op_sel_hi:[0,1,1]
	ds_read_b128 v[130:133], v122 offset:13392
	ds_read_b128 v[140:143], v122 offset:13408
	ds_read_b128 v[144:147], v122 offset:13424
	ds_read_b128 v[148:151], v122 offset:13440
	s_waitcnt lgkmcnt(9)
	v_lshlrev_b32_e32 v28, 16, v28
	v_lshlrev_b32_e32 v29, 16, v29
	v_pk_add_f32 v[12:13], v[4:5], v[6:7]
	v_pk_add_f32 v[14:15], v[8:9], v[10:11]
	s_nop 0
	v_pk_add_f32 v[12:13], v[12:13], v[14:15]
	s_nop 0
	v_pk_fma_f32 v[68:69], v[30:31], v[28:29], v[12:13] neg_lo:[0,0,1] neg_hi:[0,0,1]
	ds_read_b128 v[32:35], v122 offset:13456
	s_waitcnt lgkmcnt(9)
	v_pk_mul_f32 v[4:5], v[36:37], v[170:171] op_sel_hi:[0,1]
	v_pk_mul_f32 v[6:7], v[36:37], v[172:173] op_sel:[1,0] op_sel_hi:[1,1]
	v_pk_mul_f32 v[8:9], v[38:39], v[174:175] op_sel_hi:[0,1]
	v_pk_mul_f32 v[10:11], v[38:39], v[176:177] op_sel:[1,0] op_sel_hi:[1,1]
	ds_read_b128 v[36:39], v122 offset:13472
	s_waitcnt lgkmcnt(9)
	v_pk_fma_f32 v[4:5], v[40:41], v[178:179], v[4:5] op_sel_hi:[0,1,1]
	v_pk_fma_f32 v[6:7], v[40:41], v[180:181], v[6:7] op_sel:[1,0,0] op_sel_hi:[1,1,1]
	v_pk_fma_f32 v[8:9], v[42:43], v[182:183], v[8:9] op_sel_hi:[0,1,1]
	v_pk_fma_f32 v[10:11], v[42:43], v[184:185], v[10:11] op_sel:[1,0,0] op_sel_hi:[1,1,1]
	ds_read_b128 v[40:43], v122 offset:13488
	s_waitcnt lgkmcnt(9)
	v_pk_fma_f32 v[4:5], v[98:99], v[186:187], v[4:5] op_sel_hi:[0,1,1]
	v_pk_fma_f32 v[6:7], v[98:99], v[188:189], v[6:7] op_sel:[1,0,0] op_sel_hi:[1,1,1]
	v_pk_fma_f32 v[8:9], v[100:101], v[190:191], v[8:9] op_sel_hi:[0,1,1]
	v_pk_fma_f32 v[10:11], v[100:101], v[192:193], v[10:11] op_sel:[1,0,0] op_sel_hi:[1,1,1]
	ds_read_b128 v[98:101], v122 offset:13504
	s_waitcnt lgkmcnt(9)
	v_pk_fma_f32 v[4:5], v[102:103], v[194:195], v[4:5] op_sel_hi:[0,1,1]
	v_pk_fma_f32 v[6:7], v[102:103], v[196:197], v[6:7] op_sel:[1,0,0] op_sel_hi:[1,1,1]
	v_pk_fma_f32 v[8:9], v[104:105], v[198:199], v[8:9] op_sel_hi:[0,1,1]
	v_pk_fma_f32 v[10:11], v[104:105], v[200:201], v[10:11] op_sel:[1,0,0] op_sel_hi:[1,1,1]
	ds_read_u16 v16, v115 offset:14144
	s_waitcnt lgkmcnt(9)
	v_pk_fma_f32 v[4:5], v[106:107], v[202:203], v[4:5] op_sel_hi:[0,1,1]
	v_pk_fma_f32 v[6:7], v[106:107], v[204:205], v[6:7] op_sel:[1,0,0] op_sel_hi:[1,1,1]
	v_pk_fma_f32 v[8:9], v[108:109], v[206:207], v[8:9] op_sel_hi:[0,1,1]
	v_pk_fma_f32 v[10:11], v[108:109], v[208:209], v[10:11] op_sel:[1,0,0] op_sel_hi:[1,1,1]
	ds_read_u16 v17, v116 offset:14144
	s_waitcnt lgkmcnt(9)
	v_pk_fma_f32 v[4:5], v[130:131], v[210:211], v[4:5] op_sel_hi:[0,1,1]
	v_pk_fma_f32 v[6:7], v[130:131], v[212:213], v[6:7] op_sel:[1,0,0] op_sel_hi:[1,1,1]
	v_pk_fma_f32 v[8:9], v[132:133], v[214:215], v[8:9] op_sel_hi:[0,1,1]
	v_pk_fma_f32 v[10:11], v[132:133], v[216:217], v[10:11] op_sel:[1,0,0] op_sel_hi:[1,1,1]
	ds_read_b32 v18, v126 offset:208
	s_waitcnt lgkmcnt(9)
	v_pk_fma_f32 v[4:5], v[140:141], v[218:219], v[4:5] op_sel_hi:[0,1,1]
	v_pk_fma_f32 v[6:7], v[140:141], v[220:221], v[6:7] op_sel:[1,0,0] op_sel_hi:[1,1,1]
	v_pk_fma_f32 v[8:9], v[142:143], v[222:223], v[8:9] op_sel_hi:[0,1,1]
	v_pk_fma_f32 v[10:11], v[142:143], v[224:225], v[10:11] op_sel:[1,0,0] op_sel_hi:[1,1,1]
	ds_read_b32 v19, v127 offset:208
	s_waitcnt lgkmcnt(9)
	v_pk_fma_f32 v[4:5], v[144:145], v[226:227], v[4:5] op_sel_hi:[0,1,1]
	v_pk_fma_f32 v[6:7], v[144:145], v[228:229], v[6:7] op_sel:[1,0,0] op_sel_hi:[1,1,1]
	v_pk_fma_f32 v[8:9], v[146:147], v[230:231], v[8:9] op_sel_hi:[0,1,1]
	v_pk_fma_f32 v[10:11], v[146:147], v[232:233], v[10:11] op_sel:[1,0,0] op_sel_hi:[1,1,1]
	ds_read_b128 v[102:105], v122 offset:13568
	s_waitcnt lgkmcnt(9)
	v_pk_fma_f32 v[4:5], v[148:149], v[234:235], v[4:5] op_sel_hi:[0,1,1]
	v_pk_fma_f32 v[6:7], v[148:149], v[236:237], v[6:7] op_sel:[1,0,0] op_sel_hi:[1,1,1]
	v_pk_fma_f32 v[8:9], v[150:151], v[238:239], v[8:9] op_sel_hi:[0,1,1]
	v_pk_fma_f32 v[10:11], v[150:151], v[240:241], v[10:11] op_sel:[1,0,0] op_sel_hi:[1,1,1]
	ds_read_b128 v[106:109], v122 offset:13584
	s_waitcnt lgkmcnt(9)
	v_pk_fma_f32 v[4:5], v[32:33], v[242:243], v[4:5] op_sel_hi:[0,1,1]
	v_pk_fma_f32 v[6:7], v[32:33], v[244:245], v[6:7] op_sel:[1,0,0] op_sel_hi:[1,1,1]
	v_pk_fma_f32 v[8:9], v[34:35], v[246:247], v[8:9] op_sel_hi:[0,1,1]
	v_pk_fma_f32 v[10:11], v[34:35], v[248:249], v[10:11] op_sel:[1,0,0] op_sel_hi:[1,1,1]
	ds_read_b128 v[130:133], v122 offset:13600
	s_waitcnt lgkmcnt(9)
	v_pk_fma_f32 v[4:5], v[36:37], v[46:47], v[4:5] op_sel_hi:[0,1,1]
	v_pk_fma_f32 v[6:7], v[36:37], v[48:49], v[6:7] op_sel:[1,0,0] op_sel_hi:[1,1,1]
	v_pk_fma_f32 v[8:9], v[38:39], v[50:51], v[8:9] op_sel_hi:[0,1,1]
	v_pk_fma_f32 v[10:11], v[38:39], v[52:53], v[10:11] op_sel:[1,0,0] op_sel_hi:[1,1,1]
	ds_read_b128 v[140:143], v122 offset:13616
	s_waitcnt lgkmcnt(9)
	v_pk_fma_f32 v[4:5], v[40:41], v[54:55], v[4:5] op_sel_hi:[0,1,1]
	v_pk_fma_f32 v[6:7], v[40:41], v[56:57], v[6:7] op_sel:[1,0,0] op_sel_hi:[1,1,1]
	v_pk_fma_f32 v[8:9], v[42:43], v[58:59], v[8:9] op_sel_hi:[0,1,1]
	v_pk_fma_f32 v[10:11], v[42:43], v[60:61], v[10:11] op_sel:[1,0,0] op_sel_hi:[1,1,1]
	ds_read_b128 v[144:147], v122 offset:13632
	s_waitcnt lgkmcnt(9)
	v_pk_fma_f32 v[4:5], v[98:99], v[62:63], v[4:5] op_sel_hi:[0,1,1]
	v_pk_fma_f32 v[6:7], v[98:99], v[64:65], v[6:7] op_sel:[1,0,0] op_sel_hi:[1,1,1]
	v_pk_fma_f32 v[8:9], v[100:101], v[66:67], v[8:9] op_sel_hi:[0,1,1]
	v_pk_fma_f32 v[10:11], v[100:101], v[68:69], v[10:11] op_sel:[1,0,0] op_sel_hi:[1,1,1]
	ds_read_b128 v[148:151], v122 offset:13648
	ds_read_b128 v[32:35], v122 offset:13664
	ds_read_b128 v[36:39], v122 offset:13680
	ds_read_b128 v[40:43], v122 offset:13696
	s_waitcnt lgkmcnt(9)
	v_lshlrev_b32_e32 v16, 16, v16
	v_lshlrev_b32_e32 v17, 16, v17
	v_pk_add_f32 v[12:13], v[4:5], v[6:7]
	v_pk_add_f32 v[14:15], v[8:9], v[10:11]
	s_nop 0
	v_pk_add_f32 v[12:13], v[12:13], v[14:15]
	s_nop 0
	v_pk_fma_f32 v[70:71], v[18:19], v[16:17], v[12:13] neg_lo:[0,0,1] neg_hi:[0,0,1]
	ds_read_b128 v[98:101], v122 offset:13712
	s_waitcnt lgkmcnt(9)
	v_pk_mul_f32 v[4:5], v[102:103], v[170:171] op_sel_hi:[0,1]
	v_pk_mul_f32 v[6:7], v[102:103], v[172:173] op_sel:[1,0] op_sel_hi:[1,1]
	v_pk_mul_f32 v[8:9], v[104:105], v[174:175] op_sel_hi:[0,1]
	v_pk_mul_f32 v[10:11], v[104:105], v[176:177] op_sel:[1,0] op_sel_hi:[1,1]
	ds_read_b128 v[102:105], v122 offset:13728
	s_waitcnt lgkmcnt(9)
	v_pk_fma_f32 v[4:5], v[106:107], v[178:179], v[4:5] op_sel_hi:[0,1,1]
	v_pk_fma_f32 v[6:7], v[106:107], v[180:181], v[6:7] op_sel:[1,0,0] op_sel_hi:[1,1,1]
	v_pk_fma_f32 v[8:9], v[108:109], v[182:183], v[8:9] op_sel_hi:[0,1,1]
	v_pk_fma_f32 v[10:11], v[108:109], v[184:185], v[10:11] op_sel:[1,0,0] op_sel_hi:[1,1,1]
	ds_read_b128 v[106:109], v122 offset:13744
	s_waitcnt lgkmcnt(9)
	v_pk_fma_f32 v[4:5], v[130:131], v[186:187], v[4:5] op_sel_hi:[0,1,1]
	v_pk_fma_f32 v[6:7], v[130:131], v[188:189], v[6:7] op_sel:[1,0,0] op_sel_hi:[1,1,1]
	v_pk_fma_f32 v[8:9], v[132:133], v[190:191], v[8:9] op_sel_hi:[0,1,1]
	v_pk_fma_f32 v[10:11], v[132:133], v[192:193], v[10:11] op_sel:[1,0,0] op_sel_hi:[1,1,1]
	ds_read_b128 v[130:133], v122 offset:13760
	s_waitcnt lgkmcnt(9)
	v_pk_fma_f32 v[4:5], v[140:141], v[194:195], v[4:5] op_sel_hi:[0,1,1]
	v_pk_fma_f32 v[6:7], v[140:141], v[196:197], v[6:7] op_sel:[1,0,0] op_sel_hi:[1,1,1]
	v_pk_fma_f32 v[8:9], v[142:143], v[198:199], v[8:9] op_sel_hi:[0,1,1]
	v_pk_fma_f32 v[10:11], v[142:143], v[200:201], v[10:11] op_sel:[1,0,0] op_sel_hi:[1,1,1]
	ds_read_b128 v[140:143], v122 offset:13776
	s_waitcnt lgkmcnt(9)
	v_pk_fma_f32 v[4:5], v[144:145], v[202:203], v[4:5] op_sel_hi:[0,1,1]
	v_pk_fma_f32 v[6:7], v[144:145], v[204:205], v[6:7] op_sel:[1,0,0] op_sel_hi:[1,1,1]
	v_pk_fma_f32 v[8:9], v[146:147], v[206:207], v[8:9] op_sel_hi:[0,1,1]
	v_pk_fma_f32 v[10:11], v[146:147], v[208:209], v[10:11] op_sel:[1,0,0] op_sel_hi:[1,1,1]
	ds_read_u16 v20, v115 offset:14416
	s_waitcnt lgkmcnt(9)
	v_pk_fma_f32 v[4:5], v[148:149], v[210:211], v[4:5] op_sel_hi:[0,1,1]
	v_pk_fma_f32 v[6:7], v[148:149], v[212:213], v[6:7] op_sel:[1,0,0] op_sel_hi:[1,1,1]
	v_pk_fma_f32 v[8:9], v[150:151], v[214:215], v[8:9] op_sel_hi:[0,1,1]
	v_pk_fma_f32 v[10:11], v[150:151], v[216:217], v[10:11] op_sel:[1,0,0] op_sel_hi:[1,1,1]
	ds_read_u16 v21, v116 offset:14416
	s_waitcnt lgkmcnt(9)
	v_pk_fma_f32 v[4:5], v[32:33], v[218:219], v[4:5] op_sel_hi:[0,1,1]
	v_pk_fma_f32 v[6:7], v[32:33], v[220:221], v[6:7] op_sel:[1,0,0] op_sel_hi:[1,1,1]
	v_pk_fma_f32 v[8:9], v[34:35], v[222:223], v[8:9] op_sel_hi:[0,1,1]
	v_pk_fma_f32 v[10:11], v[34:35], v[224:225], v[10:11] op_sel:[1,0,0] op_sel_hi:[1,1,1]
	ds_read_b32 v22, v126 offset:212
	s_waitcnt lgkmcnt(9)
	v_pk_fma_f32 v[4:5], v[36:37], v[226:227], v[4:5] op_sel_hi:[0,1,1]
	v_pk_fma_f32 v[6:7], v[36:37], v[228:229], v[6:7] op_sel:[1,0,0] op_sel_hi:[1,1,1]
	v_pk_fma_f32 v[8:9], v[38:39], v[230:231], v[8:9] op_sel_hi:[0,1,1]
	v_pk_fma_f32 v[10:11], v[38:39], v[232:233], v[10:11] op_sel:[1,0,0] op_sel_hi:[1,1,1]
	ds_read_b32 v23, v127 offset:212
	s_waitcnt lgkmcnt(9)
	v_pk_fma_f32 v[4:5], v[40:41], v[234:235], v[4:5] op_sel_hi:[0,1,1]
	v_pk_fma_f32 v[6:7], v[40:41], v[236:237], v[6:7] op_sel:[1,0,0] op_sel_hi:[1,1,1]
	v_pk_fma_f32 v[8:9], v[42:43], v[238:239], v[8:9] op_sel_hi:[0,1,1]
	v_pk_fma_f32 v[10:11], v[42:43], v[240:241], v[10:11] op_sel:[1,0,0] op_sel_hi:[1,1,1]
	ds_read_b128 v[144:147], v122 offset:13824
	s_waitcnt lgkmcnt(9)
	v_pk_fma_f32 v[4:5], v[98:99], v[242:243], v[4:5] op_sel_hi:[0,1,1]
	v_pk_fma_f32 v[6:7], v[98:99], v[244:245], v[6:7] op_sel:[1,0,0] op_sel_hi:[1,1,1]
	v_pk_fma_f32 v[8:9], v[100:101], v[246:247], v[8:9] op_sel_hi:[0,1,1]
	v_pk_fma_f32 v[10:11], v[100:101], v[248:249], v[10:11] op_sel:[1,0,0] op_sel_hi:[1,1,1]
	ds_read_b128 v[148:151], v122 offset:13840
	s_waitcnt lgkmcnt(9)
	v_pk_fma_f32 v[4:5], v[102:103], v[46:47], v[4:5] op_sel_hi:[0,1,1]
	v_pk_fma_f32 v[6:7], v[102:103], v[48:49], v[6:7] op_sel:[1,0,0] op_sel_hi:[1,1,1]
	v_pk_fma_f32 v[8:9], v[104:105], v[50:51], v[8:9] op_sel_hi:[0,1,1]
	v_pk_fma_f32 v[10:11], v[104:105], v[52:53], v[10:11] op_sel:[1,0,0] op_sel_hi:[1,1,1]
	ds_read_b128 v[32:35], v122 offset:13856
	s_waitcnt lgkmcnt(9)
	v_pk_fma_f32 v[4:5], v[106:107], v[54:55], v[4:5] op_sel_hi:[0,1,1]
	v_pk_fma_f32 v[6:7], v[106:107], v[56:57], v[6:7] op_sel:[1,0,0] op_sel_hi:[1,1,1]
	v_pk_fma_f32 v[8:9], v[108:109], v[58:59], v[8:9] op_sel_hi:[0,1,1]
	v_pk_fma_f32 v[10:11], v[108:109], v[60:61], v[10:11] op_sel:[1,0,0] op_sel_hi:[1,1,1]
	ds_read_b128 v[36:39], v122 offset:13872
	s_waitcnt lgkmcnt(9)
	v_pk_fma_f32 v[4:5], v[130:131], v[62:63], v[4:5] op_sel_hi:[0,1,1]
	v_pk_fma_f32 v[6:7], v[130:131], v[64:65], v[6:7] op_sel:[1,0,0] op_sel_hi:[1,1,1]
	v_pk_fma_f32 v[8:9], v[132:133], v[66:67], v[8:9] op_sel_hi:[0,1,1]
	v_pk_fma_f32 v[10:11], v[132:133], v[68:69], v[10:11] op_sel:[1,0,0] op_sel_hi:[1,1,1]
	ds_read_b128 v[40:43], v122 offset:13888
	s_waitcnt lgkmcnt(9)
	v_pk_fma_f32 v[4:5], v[140:141], v[70:71], v[4:5] op_sel_hi:[0,1,1]
	ds_read_b128 v[98:101], v122 offset:13904
	ds_read_b128 v[102:105], v122 offset:13920
	ds_read_b128 v[106:109], v122 offset:13936
	ds_read_b128 v[130:133], v122 offset:13952
	s_waitcnt lgkmcnt(9)
	v_lshlrev_b32_e32 v20, 16, v20
	v_lshlrev_b32_e32 v21, 16, v21
	v_pk_add_f32 v[12:13], v[4:5], v[6:7]
	v_pk_add_f32 v[14:15], v[8:9], v[10:11]
	s_nop 0
	v_pk_add_f32 v[12:13], v[12:13], v[14:15]
	s_nop 0
	v_pk_fma_f32 v[72:73], v[22:23], v[20:21], v[12:13] neg_lo:[0,0,1] neg_hi:[0,0,1]
	ds_read_b128 v[140:143], v122 offset:13968
	s_waitcnt lgkmcnt(9)
	v_pk_mul_f32 v[4:5], v[144:145], v[170:171] op_sel_hi:[0,1]
	v_pk_mul_f32 v[6:7], v[144:145], v[172:173] op_sel:[1,0] op_sel_hi:[1,1]
	v_pk_mul_f32 v[8:9], v[146:147], v[174:175] op_sel_hi:[0,1]
	v_pk_mul_f32 v[10:11], v[146:147], v[176:177] op_sel:[1,0] op_sel_hi:[1,1]
	ds_read_b128 v[144:147], v122 offset:13984
	s_waitcnt lgkmcnt(9)
	v_pk_fma_f32 v[4:5], v[148:149], v[178:179], v[4:5] op_sel_hi:[0,1,1]
	v_pk_fma_f32 v[6:7], v[148:149], v[180:181], v[6:7] op_sel:[1,0,0] op_sel_hi:[1,1,1]
	v_pk_fma_f32 v[8:9], v[150:151], v[182:183], v[8:9] op_sel_hi:[0,1,1]
	v_pk_fma_f32 v[10:11], v[150:151], v[184:185], v[10:11] op_sel:[1,0,0] op_sel_hi:[1,1,1]
	ds_read_b128 v[148:151], v122 offset:14000
	s_waitcnt lgkmcnt(9)
	v_pk_fma_f32 v[4:5], v[32:33], v[186:187], v[4:5] op_sel_hi:[0,1,1]
	v_pk_fma_f32 v[6:7], v[32:33], v[188:189], v[6:7] op_sel:[1,0,0] op_sel_hi:[1,1,1]
	v_pk_fma_f32 v[8:9], v[34:35], v[190:191], v[8:9] op_sel_hi:[0,1,1]
	v_pk_fma_f32 v[10:11], v[34:35], v[192:193], v[10:11] op_sel:[1,0,0] op_sel_hi:[1,1,1]
	ds_read_b128 v[32:35], v122 offset:14016
	s_waitcnt lgkmcnt(9)
	v_pk_fma_f32 v[4:5], v[36:37], v[194:195], v[4:5] op_sel_hi:[0,1,1]
	v_pk_fma_f32 v[6:7], v[36:37], v[196:197], v[6:7] op_sel:[1,0,0] op_sel_hi:[1,1,1]
	v_pk_fma_f32 v[8:9], v[38:39], v[198:199], v[8:9] op_sel_hi:[0,1,1]
	v_pk_fma_f32 v[10:11], v[38:39], v[200:201], v[10:11] op_sel:[1,0,0] op_sel_hi:[1,1,1]
	ds_read_b128 v[36:39], v122 offset:14032
	s_waitcnt lgkmcnt(9)
	v_pk_fma_f32 v[4:5], v[40:41], v[202:203], v[4:5] op_sel_hi:[0,1,1]
	v_pk_fma_f32 v[6:7], v[40:41], v[204:205], v[6:7] op_sel:[1,0,0] op_sel_hi:[1,1,1]
	v_pk_fma_f32 v[8:9], v[42:43], v[206:207], v[8:9] op_sel_hi:[0,1,1]
	v_pk_fma_f32 v[10:11], v[42:43], v[208:209], v[10:11] op_sel:[1,0,0] op_sel_hi:[1,1,1]
	ds_read_u16 v24, v115 offset:14688
	s_waitcnt lgkmcnt(9)
	v_pk_fma_f32 v[4:5], v[98:99], v[210:211], v[4:5] op_sel_hi:[0,1,1]
	v_pk_fma_f32 v[6:7], v[98:99], v[212:213], v[6:7] op_sel:[1,0,0] op_sel_hi:[1,1,1]
	v_pk_fma_f32 v[8:9], v[100:101], v[214:215], v[8:9] op_sel_hi:[0,1,1]
	v_pk_fma_f32 v[10:11], v[100:101], v[216:217], v[10:11] op_sel:[1,0,0] op_sel_hi:[1,1,1]
	ds_read_u16 v25, v116 offset:14688
	s_waitcnt lgkmcnt(9)
	v_pk_fma_f32 v[4:5], v[102:103], v[218:219], v[4:5] op_sel_hi:[0,1,1]
	v_pk_fma_f32 v[6:7], v[102:103], v[220:221], v[6:7] op_sel:[1,0,0] op_sel_hi:[1,1,1]
	v_pk_fma_f32 v[8:9], v[104:105], v[222:223], v[8:9] op_sel_hi:[0,1,1]
	v_pk_fma_f32 v[10:11], v[104:105], v[224:225], v[10:11] op_sel:[1,0,0] op_sel_hi:[1,1,1]
	ds_read_b32 v26, v126 offset:216
	s_waitcnt lgkmcnt(9)
	v_pk_fma_f32 v[4:5], v[106:107], v[226:227], v[4:5] op_sel_hi:[0,1,1]
	v_pk_fma_f32 v[6:7], v[106:107], v[228:229], v[6:7] op_sel:[1,0,0] op_sel_hi:[1,1,1]
	v_pk_fma_f32 v[8:9], v[108:109], v[230:231], v[8:9] op_sel_hi:[0,1,1]
	v_pk_fma_f32 v[10:11], v[108:109], v[232:233], v[10:11] op_sel:[1,0,0] op_sel_hi:[1,1,1]
	ds_read_b32 v27, v127 offset:216
	s_waitcnt lgkmcnt(9)
	v_pk_fma_f32 v[4:5], v[130:131], v[234:235], v[4:5] op_sel_hi:[0,1,1]
	v_pk_fma_f32 v[6:7], v[130:131], v[236:237], v[6:7] op_sel:[1,0,0] op_sel_hi:[1,1,1]
	v_pk_fma_f32 v[8:9], v[132:133], v[238:239], v[8:9] op_sel_hi:[0,1,1]
	v_pk_fma_f32 v[10:11], v[132:133], v[240:241], v[10:11] op_sel:[1,0,0] op_sel_hi:[1,1,1]
	ds_read_b128 v[40:43], v122 offset:14080
	s_waitcnt lgkmcnt(9)
	v_pk_fma_f32 v[4:5], v[140:141], v[242:243], v[4:5] op_sel_hi:[0,1,1]
	v_pk_fma_f32 v[6:7], v[140:141], v[244:245], v[6:7] op_sel:[1,0,0] op_sel_hi:[1,1,1]
	v_pk_fma_f32 v[8:9], v[142:143], v[246:247], v[8:9] op_sel_hi:[0,1,1]
	v_pk_fma_f32 v[10:11], v[142:143], v[248:249], v[10:11] op_sel:[1,0,0] op_sel_hi:[1,1,1]
	ds_read_b128 v[98:101], v122 offset:14096
	s_waitcnt lgkmcnt(9)
	v_pk_fma_f32 v[4:5], v[144:145], v[46:47], v[4:5] op_sel_hi:[0,1,1]
	v_pk_fma_f32 v[6:7], v[144:145], v[48:49], v[6:7] op_sel:[1,0,0] op_sel_hi:[1,1,1]
	v_pk_fma_f32 v[8:9], v[146:147], v[50:51], v[8:9] op_sel_hi:[0,1,1]
	v_pk_fma_f32 v[10:11], v[146:147], v[52:53], v[10:11] op_sel:[1,0,0] op_sel_hi:[1,1,1]
	ds_read_b128 v[102:105], v122 offset:14112
	s_waitcnt lgkmcnt(9)
	v_pk_fma_f32 v[4:5], v[148:149], v[54:55], v[4:5] op_sel_hi:[0,1,1]
	v_pk_fma_f32 v[6:7], v[148:149], v[56:57], v[6:7] op_sel:[1,0,0] op_sel_hi:[1,1,1]
	v_pk_fma_f32 v[8:9], v[150:151], v[58:59], v[8:9] op_sel_hi:[0,1,1]
	v_pk_fma_f32 v[10:11], v[150:151], v[60:61], v[10:11] op_sel:[1,0,0] op_sel_hi:[1,1,1]
	ds_read_b128 v[106:109], v122 offset:14128
	s_waitcnt lgkmcnt(9)
	v_pk_fma_f32 v[4:5], v[32:33], v[62:63], v[4:5] op_sel_hi:[0,1,1]
	v_pk_fma_f32 v[6:7], v[32:33], v[64:65], v[6:7] op_sel:[1,0,0] op_sel_hi:[1,1,1]
	v_pk_fma_f32 v[8:9], v[34:35], v[66:67], v[8:9] op_sel_hi:[0,1,1]
	v_pk_fma_f32 v[10:11], v[34:35], v[68:69], v[10:11] op_sel:[1,0,0] op_sel_hi:[1,1,1]
	ds_read_b128 v[130:133], v122 offset:14144
	s_waitcnt lgkmcnt(9)
	v_pk_fma_f32 v[4:5], v[36:37], v[70:71], v[4:5] op_sel_hi:[0,1,1]
	v_pk_fma_f32 v[6:7], v[36:37], v[72:73], v[6:7] op_sel:[1,0,0] op_sel_hi:[1,1,1]
	ds_read_b128 v[140:143], v122 offset:14160
	ds_read_b128 v[144:147], v122 offset:14176
	ds_read_b128 v[148:151], v122 offset:14192
	ds_read_b128 v[32:35], v122 offset:14208
	s_waitcnt lgkmcnt(9)
	v_lshlrev_b32_e32 v24, 16, v24
	v_lshlrev_b32_e32 v25, 16, v25
	v_pk_add_f32 v[12:13], v[4:5], v[6:7]
	v_pk_add_f32 v[14:15], v[8:9], v[10:11]
	s_nop 0
	v_pk_add_f32 v[12:13], v[12:13], v[14:15]
	s_nop 0
	v_pk_fma_f32 v[74:75], v[26:27], v[24:25], v[12:13] neg_lo:[0,0,1] neg_hi:[0,0,1]
	ds_read_b128 v[36:39], v122 offset:14224
	s_waitcnt lgkmcnt(9)
	v_pk_mul_f32 v[4:5], v[40:41], v[170:171] op_sel_hi:[0,1]
	v_pk_mul_f32 v[6:7], v[40:41], v[172:173] op_sel:[1,0] op_sel_hi:[1,1]
	v_pk_mul_f32 v[8:9], v[42:43], v[174:175] op_sel_hi:[0,1]
	v_pk_mul_f32 v[10:11], v[42:43], v[176:177] op_sel:[1,0] op_sel_hi:[1,1]
	ds_read_b128 v[40:43], v122 offset:14240
	s_waitcnt lgkmcnt(9)
	v_pk_fma_f32 v[4:5], v[98:99], v[178:179], v[4:5] op_sel_hi:[0,1,1]
	v_pk_fma_f32 v[6:7], v[98:99], v[180:181], v[6:7] op_sel:[1,0,0] op_sel_hi:[1,1,1]
	v_pk_fma_f32 v[8:9], v[100:101], v[182:183], v[8:9] op_sel_hi:[0,1,1]
	v_pk_fma_f32 v[10:11], v[100:101], v[184:185], v[10:11] op_sel:[1,0,0] op_sel_hi:[1,1,1]
	ds_read_b128 v[98:101], v122 offset:14256
	s_waitcnt lgkmcnt(9)
	v_pk_fma_f32 v[4:5], v[102:103], v[186:187], v[4:5] op_sel_hi:[0,1,1]
	v_pk_fma_f32 v[6:7], v[102:103], v[188:189], v[6:7] op_sel:[1,0,0] op_sel_hi:[1,1,1]
	v_pk_fma_f32 v[8:9], v[104:105], v[190:191], v[8:9] op_sel_hi:[0,1,1]
	v_pk_fma_f32 v[10:11], v[104:105], v[192:193], v[10:11] op_sel:[1,0,0] op_sel_hi:[1,1,1]
	ds_read_b128 v[102:105], v122 offset:14272
	s_waitcnt lgkmcnt(9)
	v_pk_fma_f32 v[4:5], v[106:107], v[194:195], v[4:5] op_sel_hi:[0,1,1]
	v_pk_fma_f32 v[6:7], v[106:107], v[196:197], v[6:7] op_sel:[1,0,0] op_sel_hi:[1,1,1]
	v_pk_fma_f32 v[8:9], v[108:109], v[198:199], v[8:9] op_sel_hi:[0,1,1]
	v_pk_fma_f32 v[10:11], v[108:109], v[200:201], v[10:11] op_sel:[1,0,0] op_sel_hi:[1,1,1]
	ds_read_b128 v[106:109], v122 offset:14288
	s_waitcnt lgkmcnt(9)
	v_pk_fma_f32 v[4:5], v[130:131], v[202:203], v[4:5] op_sel_hi:[0,1,1]
	v_pk_fma_f32 v[6:7], v[130:131], v[204:205], v[6:7] op_sel:[1,0,0] op_sel_hi:[1,1,1]
	v_pk_fma_f32 v[8:9], v[132:133], v[206:207], v[8:9] op_sel_hi:[0,1,1]
	v_pk_fma_f32 v[10:11], v[132:133], v[208:209], v[10:11] op_sel:[1,0,0] op_sel_hi:[1,1,1]
	ds_read_u16 v28, v115 offset:14960
	s_waitcnt lgkmcnt(9)
	v_pk_fma_f32 v[4:5], v[140:141], v[210:211], v[4:5] op_sel_hi:[0,1,1]
	v_pk_fma_f32 v[6:7], v[140:141], v[212:213], v[6:7] op_sel:[1,0,0] op_sel_hi:[1,1,1]
	v_pk_fma_f32 v[8:9], v[142:143], v[214:215], v[8:9] op_sel_hi:[0,1,1]
	v_pk_fma_f32 v[10:11], v[142:143], v[216:217], v[10:11] op_sel:[1,0,0] op_sel_hi:[1,1,1]
	ds_read_u16 v29, v116 offset:14960
	s_waitcnt lgkmcnt(9)
	v_pk_fma_f32 v[4:5], v[144:145], v[218:219], v[4:5] op_sel_hi:[0,1,1]
	v_pk_fma_f32 v[6:7], v[144:145], v[220:221], v[6:7] op_sel:[1,0,0] op_sel_hi:[1,1,1]
	v_pk_fma_f32 v[8:9], v[146:147], v[222:223], v[8:9] op_sel_hi:[0,1,1]
	v_pk_fma_f32 v[10:11], v[146:147], v[224:225], v[10:11] op_sel:[1,0,0] op_sel_hi:[1,1,1]
	ds_read_b32 v30, v126 offset:220
	s_waitcnt lgkmcnt(9)
	v_pk_fma_f32 v[4:5], v[148:149], v[226:227], v[4:5] op_sel_hi:[0,1,1]
	v_pk_fma_f32 v[6:7], v[148:149], v[228:229], v[6:7] op_sel:[1,0,0] op_sel_hi:[1,1,1]
	v_pk_fma_f32 v[8:9], v[150:151], v[230:231], v[8:9] op_sel_hi:[0,1,1]
	v_pk_fma_f32 v[10:11], v[150:151], v[232:233], v[10:11] op_sel:[1,0,0] op_sel_hi:[1,1,1]
	ds_read_b32 v31, v127 offset:220
	s_waitcnt lgkmcnt(9)
	v_pk_fma_f32 v[4:5], v[32:33], v[234:235], v[4:5] op_sel_hi:[0,1,1]
	v_pk_fma_f32 v[6:7], v[32:33], v[236:237], v[6:7] op_sel:[1,0,0] op_sel_hi:[1,1,1]
	v_pk_fma_f32 v[8:9], v[34:35], v[238:239], v[8:9] op_sel_hi:[0,1,1]
	v_pk_fma_f32 v[10:11], v[34:35], v[240:241], v[10:11] op_sel:[1,0,0] op_sel_hi:[1,1,1]
	ds_read_b128 v[130:133], v122 offset:14336
	s_waitcnt lgkmcnt(9)
	v_pk_fma_f32 v[4:5], v[36:37], v[242:243], v[4:5] op_sel_hi:[0,1,1]
	v_pk_fma_f32 v[6:7], v[36:37], v[244:245], v[6:7] op_sel:[1,0,0] op_sel_hi:[1,1,1]
	v_pk_fma_f32 v[8:9], v[38:39], v[246:247], v[8:9] op_sel_hi:[0,1,1]
	v_pk_fma_f32 v[10:11], v[38:39], v[248:249], v[10:11] op_sel:[1,0,0] op_sel_hi:[1,1,1]
	ds_read_b128 v[140:143], v122 offset:14352
	s_waitcnt lgkmcnt(9)
	v_pk_fma_f32 v[4:5], v[40:41], v[46:47], v[4:5] op_sel_hi:[0,1,1]
	v_pk_fma_f32 v[6:7], v[40:41], v[48:49], v[6:7] op_sel:[1,0,0] op_sel_hi:[1,1,1]
	v_pk_fma_f32 v[8:9], v[42:43], v[50:51], v[8:9] op_sel_hi:[0,1,1]
	v_pk_fma_f32 v[10:11], v[42:43], v[52:53], v[10:11] op_sel:[1,0,0] op_sel_hi:[1,1,1]
	ds_read_b128 v[144:147], v122 offset:14368
	s_waitcnt lgkmcnt(9)
	v_pk_fma_f32 v[4:5], v[98:99], v[54:55], v[4:5] op_sel_hi:[0,1,1]
	v_pk_fma_f32 v[6:7], v[98:99], v[56:57], v[6:7] op_sel:[1,0,0] op_sel_hi:[1,1,1]
	v_pk_fma_f32 v[8:9], v[100:101], v[58:59], v[8:9] op_sel_hi:[0,1,1]
	v_pk_fma_f32 v[10:11], v[100:101], v[60:61], v[10:11] op_sel:[1,0,0] op_sel_hi:[1,1,1]
	ds_read_b128 v[148:151], v122 offset:14384
	s_waitcnt lgkmcnt(9)
	v_pk_fma_f32 v[4:5], v[102:103], v[62:63], v[4:5] op_sel_hi:[0,1,1]
	v_pk_fma_f32 v[6:7], v[102:103], v[64:65], v[6:7] op_sel:[1,0,0] op_sel_hi:[1,1,1]
	v_pk_fma_f32 v[8:9], v[104:105], v[66:67], v[8:9] op_sel_hi:[0,1,1]
	v_pk_fma_f32 v[10:11], v[104:105], v[68:69], v[10:11] op_sel:[1,0,0] op_sel_hi:[1,1,1]
	ds_read_b128 v[32:35], v122 offset:14400
	s_waitcnt lgkmcnt(9)
	v_pk_fma_f32 v[4:5], v[106:107], v[70:71], v[4:5] op_sel_hi:[0,1,1]
	v_pk_fma_f32 v[6:7], v[106:107], v[72:73], v[6:7] op_sel:[1,0,0] op_sel_hi:[1,1,1]
	v_pk_fma_f32 v[8:9], v[108:109], v[74:75], v[8:9] op_sel_hi:[0,1,1]
	ds_read_b128 v[36:39], v122 offset:14416
	ds_read_b128 v[40:43], v122 offset:14432
	ds_read_b128 v[98:101], v122 offset:14448
	ds_read_b128 v[102:105], v122 offset:14464
	s_waitcnt lgkmcnt(9)
	v_lshlrev_b32_e32 v28, 16, v28
	v_lshlrev_b32_e32 v29, 16, v29
	v_pk_add_f32 v[12:13], v[4:5], v[6:7]
	v_pk_add_f32 v[14:15], v[8:9], v[10:11]
	s_nop 0
	v_pk_add_f32 v[12:13], v[12:13], v[14:15]
	s_nop 0
	v_pk_fma_f32 v[76:77], v[30:31], v[28:29], v[12:13] neg_lo:[0,0,1] neg_hi:[0,0,1]
	ds_read_b128 v[106:109], v122 offset:14480
	s_waitcnt lgkmcnt(9)
	v_pk_mul_f32 v[4:5], v[130:131], v[170:171] op_sel_hi:[0,1]
	v_pk_mul_f32 v[6:7], v[130:131], v[172:173] op_sel:[1,0] op_sel_hi:[1,1]
	v_pk_mul_f32 v[8:9], v[132:133], v[174:175] op_sel_hi:[0,1]
	v_pk_mul_f32 v[10:11], v[132:133], v[176:177] op_sel:[1,0] op_sel_hi:[1,1]
	ds_read_b128 v[130:133], v122 offset:14496
	s_waitcnt lgkmcnt(9)
	v_pk_fma_f32 v[4:5], v[140:141], v[178:179], v[4:5] op_sel_hi:[0,1,1]
	v_pk_fma_f32 v[6:7], v[140:141], v[180:181], v[6:7] op_sel:[1,0,0] op_sel_hi:[1,1,1]
	v_pk_fma_f32 v[8:9], v[142:143], v[182:183], v[8:9] op_sel_hi:[0,1,1]
	v_pk_fma_f32 v[10:11], v[142:143], v[184:185], v[10:11] op_sel:[1,0,0] op_sel_hi:[1,1,1]
	ds_read_b128 v[140:143], v122 offset:14512
	s_waitcnt lgkmcnt(9)
	v_pk_fma_f32 v[4:5], v[144:145], v[186:187], v[4:5] op_sel_hi:[0,1,1]
	v_pk_fma_f32 v[6:7], v[144:145], v[188:189], v[6:7] op_sel:[1,0,0] op_sel_hi:[1,1,1]
	v_pk_fma_f32 v[8:9], v[146:147], v[190:191], v[8:9] op_sel_hi:[0,1,1]
	v_pk_fma_f32 v[10:11], v[146:147], v[192:193], v[10:11] op_sel:[1,0,0] op_sel_hi:[1,1,1]
	ds_read_b128 v[144:147], v122 offset:14528
	s_waitcnt lgkmcnt(9)
	v_pk_fma_f32 v[4:5], v[148:149], v[194:195], v[4:5] op_sel_hi:[0,1,1]
	v_pk_fma_f32 v[6:7], v[148:149], v[196:197], v[6:7] op_sel:[1,0,0] op_sel_hi:[1,1,1]
	v_pk_fma_f32 v[8:9], v[150:151], v[198:199], v[8:9] op_sel_hi:[0,1,1]
	v_pk_fma_f32 v[10:11], v[150:151], v[200:201], v[10:11] op_sel:[1,0,0] op_sel_hi:[1,1,1]
	ds_read_b128 v[148:151], v122 offset:14544
	s_waitcnt lgkmcnt(9)
	v_pk_fma_f32 v[4:5], v[32:33], v[202:203], v[4:5] op_sel_hi:[0,1,1]
	v_pk_fma_f32 v[6:7], v[32:33], v[204:205], v[6:7] op_sel:[1,0,0] op_sel_hi:[1,1,1]
	v_pk_fma_f32 v[8:9], v[34:35], v[206:207], v[8:9] op_sel_hi:[0,1,1]
	v_pk_fma_f32 v[10:11], v[34:35], v[208:209], v[10:11] op_sel:[1,0,0] op_sel_hi:[1,1,1]
	ds_read_u16 v16, v115 offset:15232
	s_waitcnt lgkmcnt(9)
	v_pk_fma_f32 v[4:5], v[36:37], v[210:211], v[4:5] op_sel_hi:[0,1,1]
	v_pk_fma_f32 v[6:7], v[36:37], v[212:213], v[6:7] op_sel:[1,0,0] op_sel_hi:[1,1,1]
	v_pk_fma_f32 v[8:9], v[38:39], v[214:215], v[8:9] op_sel_hi:[0,1,1]
	v_pk_fma_f32 v[10:11], v[38:39], v[216:217], v[10:11] op_sel:[1,0,0] op_sel_hi:[1,1,1]
	ds_read_u16 v17, v116 offset:15232
	s_waitcnt lgkmcnt(9)
	v_pk_fma_f32 v[4:5], v[40:41], v[218:219], v[4:5] op_sel_hi:[0,1,1]
	v_pk_fma_f32 v[6:7], v[40:41], v[220:221], v[6:7] op_sel:[1,0,0] op_sel_hi:[1,1,1]
	v_pk_fma_f32 v[8:9], v[42:43], v[222:223], v[8:9] op_sel_hi:[0,1,1]
	v_pk_fma_f32 v[10:11], v[42:43], v[224:225], v[10:11] op_sel:[1,0,0] op_sel_hi:[1,1,1]
	ds_read_b32 v18, v126 offset:224
	s_waitcnt lgkmcnt(9)
	v_pk_fma_f32 v[4:5], v[98:99], v[226:227], v[4:5] op_sel_hi:[0,1,1]
	v_pk_fma_f32 v[6:7], v[98:99], v[228:229], v[6:7] op_sel:[1,0,0] op_sel_hi:[1,1,1]
	v_pk_fma_f32 v[8:9], v[100:101], v[230:231], v[8:9] op_sel_hi:[0,1,1]
	v_pk_fma_f32 v[10:11], v[100:101], v[232:233], v[10:11] op_sel:[1,0,0] op_sel_hi:[1,1,1]
	ds_read_b32 v19, v127 offset:224
	s_waitcnt lgkmcnt(9)
	v_pk_fma_f32 v[4:5], v[102:103], v[234:235], v[4:5] op_sel_hi:[0,1,1]
	v_pk_fma_f32 v[6:7], v[102:103], v[236:237], v[6:7] op_sel:[1,0,0] op_sel_hi:[1,1,1]
	v_pk_fma_f32 v[8:9], v[104:105], v[238:239], v[8:9] op_sel_hi:[0,1,1]
	v_pk_fma_f32 v[10:11], v[104:105], v[240:241], v[10:11] op_sel:[1,0,0] op_sel_hi:[1,1,1]
	ds_read_b128 v[32:35], v122 offset:14592
	s_waitcnt lgkmcnt(9)
	v_pk_fma_f32 v[4:5], v[106:107], v[242:243], v[4:5] op_sel_hi:[0,1,1]
	v_pk_fma_f32 v[6:7], v[106:107], v[244:245], v[6:7] op_sel:[1,0,0] op_sel_hi:[1,1,1]
	v_pk_fma_f32 v[8:9], v[108:109], v[246:247], v[8:9] op_sel_hi:[0,1,1]
	v_pk_fma_f32 v[10:11], v[108:109], v[248:249], v[10:11] op_sel:[1,0,0] op_sel_hi:[1,1,1]
	ds_read_b128 v[36:39], v122 offset:14608
	s_waitcnt lgkmcnt(9)
	v_pk_fma_f32 v[4:5], v[130:131], v[46:47], v[4:5] op_sel_hi:[0,1,1]
	v_pk_fma_f32 v[6:7], v[130:131], v[48:49], v[6:7] op_sel:[1,0,0] op_sel_hi:[1,1,1]
	v_pk_fma_f32 v[8:9], v[132:133], v[50:51], v[8:9] op_sel_hi:[0,1,1]
	v_pk_fma_f32 v[10:11], v[132:133], v[52:53], v[10:11] op_sel:[1,0,0] op_sel_hi:[1,1,1]
	ds_read_b128 v[40:43], v122 offset:14624
	s_waitcnt lgkmcnt(9)
	v_pk_fma_f32 v[4:5], v[140:141], v[54:55], v[4:5] op_sel_hi:[0,1,1]
	v_pk_fma_f32 v[6:7], v[140:141], v[56:57], v[6:7] op_sel:[1,0,0] op_sel_hi:[1,1,1]
	v_pk_fma_f32 v[8:9], v[142:143], v[58:59], v[8:9] op_sel_hi:[0,1,1]
	v_pk_fma_f32 v[10:11], v[142:143], v[60:61], v[10:11] op_sel:[1,0,0] op_sel_hi:[1,1,1]
	ds_read_b128 v[98:101], v122 offset:14640
	s_waitcnt lgkmcnt(9)
	v_pk_fma_f32 v[4:5], v[144:145], v[62:63], v[4:5] op_sel_hi:[0,1,1]
	v_pk_fma_f32 v[6:7], v[144:145], v[64:65], v[6:7] op_sel:[1,0,0] op_sel_hi:[1,1,1]
	v_pk_fma_f32 v[8:9], v[146:147], v[66:67], v[8:9] op_sel_hi:[0,1,1]
	v_pk_fma_f32 v[10:11], v[146:147], v[68:69], v[10:11] op_sel:[1,0,0] op_sel_hi:[1,1,1]
	ds_read_b128 v[102:105], v122 offset:14656
	s_waitcnt lgkmcnt(9)
	v_pk_fma_f32 v[4:5], v[148:149], v[70:71], v[4:5] op_sel_hi:[0,1,1]
	v_pk_fma_f32 v[6:7], v[148:149], v[72:73], v[6:7] op_sel:[1,0,0] op_sel_hi:[1,1,1]
	v_pk_fma_f32 v[8:9], v[150:151], v[74:75], v[8:9] op_sel_hi:[0,1,1]
	v_pk_fma_f32 v[10:11], v[150:151], v[76:77], v[10:11] op_sel:[1,0,0] op_sel_hi:[1,1,1]
	ds_read_b128 v[106:109], v122 offset:14672
	ds_read_b128 v[130:133], v122 offset:14688
	ds_read_b128 v[140:143], v122 offset:14704
	ds_read_b128 v[144:147], v122 offset:14720
	s_waitcnt lgkmcnt(9)
	v_lshlrev_b32_e32 v16, 16, v16
	v_lshlrev_b32_e32 v17, 16, v17
	v_pk_add_f32 v[12:13], v[4:5], v[6:7]
	v_pk_add_f32 v[14:15], v[8:9], v[10:11]
	s_nop 0
	v_pk_add_f32 v[12:13], v[12:13], v[14:15]
	s_nop 0
	v_pk_fma_f32 v[78:79], v[18:19], v[16:17], v[12:13] neg_lo:[0,0,1] neg_hi:[0,0,1]
	ds_read_b128 v[148:151], v122 offset:14736
	s_waitcnt lgkmcnt(9)
	v_pk_mul_f32 v[4:5], v[32:33], v[170:171] op_sel_hi:[0,1]
	v_pk_mul_f32 v[6:7], v[32:33], v[172:173] op_sel:[1,0] op_sel_hi:[1,1]
	v_pk_mul_f32 v[8:9], v[34:35], v[174:175] op_sel_hi:[0,1]
	v_pk_mul_f32 v[10:11], v[34:35], v[176:177] op_sel:[1,0] op_sel_hi:[1,1]
	ds_read_b128 v[32:35], v122 offset:14752
	s_waitcnt lgkmcnt(9)
	v_pk_fma_f32 v[4:5], v[36:37], v[178:179], v[4:5] op_sel_hi:[0,1,1]
	v_pk_fma_f32 v[6:7], v[36:37], v[180:181], v[6:7] op_sel:[1,0,0] op_sel_hi:[1,1,1]
	v_pk_fma_f32 v[8:9], v[38:39], v[182:183], v[8:9] op_sel_hi:[0,1,1]
	v_pk_fma_f32 v[10:11], v[38:39], v[184:185], v[10:11] op_sel:[1,0,0] op_sel_hi:[1,1,1]
	ds_read_b128 v[36:39], v122 offset:14768
	s_waitcnt lgkmcnt(9)
	v_pk_fma_f32 v[4:5], v[40:41], v[186:187], v[4:5] op_sel_hi:[0,1,1]
	v_pk_fma_f32 v[6:7], v[40:41], v[188:189], v[6:7] op_sel:[1,0,0] op_sel_hi:[1,1,1]
	v_pk_fma_f32 v[8:9], v[42:43], v[190:191], v[8:9] op_sel_hi:[0,1,1]
	v_pk_fma_f32 v[10:11], v[42:43], v[192:193], v[10:11] op_sel:[1,0,0] op_sel_hi:[1,1,1]
	ds_read_b128 v[40:43], v122 offset:14784
	s_waitcnt lgkmcnt(9)
	v_pk_fma_f32 v[4:5], v[98:99], v[194:195], v[4:5] op_sel_hi:[0,1,1]
	v_pk_fma_f32 v[6:7], v[98:99], v[196:197], v[6:7] op_sel:[1,0,0] op_sel_hi:[1,1,1]
	v_pk_fma_f32 v[8:9], v[100:101], v[198:199], v[8:9] op_sel_hi:[0,1,1]
	v_pk_fma_f32 v[10:11], v[100:101], v[200:201], v[10:11] op_sel:[1,0,0] op_sel_hi:[1,1,1]
	ds_read_b128 v[98:101], v122 offset:14800
	s_waitcnt lgkmcnt(9)
	v_pk_fma_f32 v[4:5], v[102:103], v[202:203], v[4:5] op_sel_hi:[0,1,1]
	v_pk_fma_f32 v[6:7], v[102:103], v[204:205], v[6:7] op_sel:[1,0,0] op_sel_hi:[1,1,1]
	v_pk_fma_f32 v[8:9], v[104:105], v[206:207], v[8:9] op_sel_hi:[0,1,1]
	v_pk_fma_f32 v[10:11], v[104:105], v[208:209], v[10:11] op_sel:[1,0,0] op_sel_hi:[1,1,1]
	ds_read_b128 v[102:105], v122 offset:14816
	s_waitcnt lgkmcnt(9)
	v_pk_fma_f32 v[4:5], v[106:107], v[210:211], v[4:5] op_sel_hi:[0,1,1]
	v_pk_fma_f32 v[6:7], v[106:107], v[212:213], v[6:7] op_sel:[1,0,0] op_sel_hi:[1,1,1]
	v_pk_fma_f32 v[8:9], v[108:109], v[214:215], v[8:9] op_sel_hi:[0,1,1]
	v_pk_fma_f32 v[10:11], v[108:109], v[216:217], v[10:11] op_sel:[1,0,0] op_sel_hi:[1,1,1]
	ds_read_u16 v20, v115 offset:15504
	s_waitcnt lgkmcnt(9)
	v_pk_fma_f32 v[4:5], v[130:131], v[218:219], v[4:5] op_sel_hi:[0,1,1]
	v_pk_fma_f32 v[6:7], v[130:131], v[220:221], v[6:7] op_sel:[1,0,0] op_sel_hi:[1,1,1]
	v_pk_fma_f32 v[8:9], v[132:133], v[222:223], v[8:9] op_sel_hi:[0,1,1]
	v_pk_fma_f32 v[10:11], v[132:133], v[224:225], v[10:11] op_sel:[1,0,0] op_sel_hi:[1,1,1]
	ds_read_u16 v21, v116 offset:15504
	s_waitcnt lgkmcnt(9)
	v_pk_fma_f32 v[4:5], v[140:141], v[226:227], v[4:5] op_sel_hi:[0,1,1]
	v_pk_fma_f32 v[6:7], v[140:141], v[228:229], v[6:7] op_sel:[1,0,0] op_sel_hi:[1,1,1]
	v_pk_fma_f32 v[8:9], v[142:143], v[230:231], v[8:9] op_sel_hi:[0,1,1]
	v_pk_fma_f32 v[10:11], v[142:143], v[232:233], v[10:11] op_sel:[1,0,0] op_sel_hi:[1,1,1]
	ds_read_b32 v22, v126 offset:228
	s_waitcnt lgkmcnt(9)
	v_pk_fma_f32 v[4:5], v[144:145], v[234:235], v[4:5] op_sel_hi:[0,1,1]
	v_pk_fma_f32 v[6:7], v[144:145], v[236:237], v[6:7] op_sel:[1,0,0] op_sel_hi:[1,1,1]
	v_pk_fma_f32 v[8:9], v[146:147], v[238:239], v[8:9] op_sel_hi:[0,1,1]
	v_pk_fma_f32 v[10:11], v[146:147], v[240:241], v[10:11] op_sel:[1,0,0] op_sel_hi:[1,1,1]
	ds_read_b32 v23, v127 offset:228
	s_waitcnt lgkmcnt(9)
	v_pk_fma_f32 v[4:5], v[148:149], v[242:243], v[4:5] op_sel_hi:[0,1,1]
	v_pk_fma_f32 v[6:7], v[148:149], v[244:245], v[6:7] op_sel:[1,0,0] op_sel_hi:[1,1,1]
	v_pk_fma_f32 v[8:9], v[150:151], v[246:247], v[8:9] op_sel_hi:[0,1,1]
	v_pk_fma_f32 v[10:11], v[150:151], v[248:249], v[10:11] op_sel:[1,0,0] op_sel_hi:[1,1,1]
	ds_read_b128 v[106:109], v122 offset:14848
	s_waitcnt lgkmcnt(9)
	v_pk_fma_f32 v[4:5], v[32:33], v[46:47], v[4:5] op_sel_hi:[0,1,1]
	v_pk_fma_f32 v[6:7], v[32:33], v[48:49], v[6:7] op_sel:[1,0,0] op_sel_hi:[1,1,1]
	v_pk_fma_f32 v[8:9], v[34:35], v[50:51], v[8:9] op_sel_hi:[0,1,1]
	v_pk_fma_f32 v[10:11], v[34:35], v[52:53], v[10:11] op_sel:[1,0,0] op_sel_hi:[1,1,1]
	ds_read_b128 v[130:133], v122 offset:14864
	s_waitcnt lgkmcnt(9)
	v_pk_fma_f32 v[4:5], v[36:37], v[54:55], v[4:5] op_sel_hi:[0,1,1]
	v_pk_fma_f32 v[6:7], v[36:37], v[56:57], v[6:7] op_sel:[1,0,0] op_sel_hi:[1,1,1]
	v_pk_fma_f32 v[8:9], v[38:39], v[58:59], v[8:9] op_sel_hi:[0,1,1]
	v_pk_fma_f32 v[10:11], v[38:39], v[60:61], v[10:11] op_sel:[1,0,0] op_sel_hi:[1,1,1]
	ds_read_b128 v[140:143], v122 offset:14880
	s_waitcnt lgkmcnt(9)
	v_pk_fma_f32 v[4:5], v[40:41], v[62:63], v[4:5] op_sel_hi:[0,1,1]
	v_pk_fma_f32 v[6:7], v[40:41], v[64:65], v[6:7] op_sel:[1,0,0] op_sel_hi:[1,1,1]
	v_pk_fma_f32 v[8:9], v[42:43], v[66:67], v[8:9] op_sel_hi:[0,1,1]
	v_pk_fma_f32 v[10:11], v[42:43], v[68:69], v[10:11] op_sel:[1,0,0] op_sel_hi:[1,1,1]
	ds_read_b128 v[144:147], v122 offset:14896
	s_waitcnt lgkmcnt(9)
	v_pk_fma_f32 v[4:5], v[98:99], v[70:71], v[4:5] op_sel_hi:[0,1,1]
	v_pk_fma_f32 v[6:7], v[98:99], v[72:73], v[6:7] op_sel:[1,0,0] op_sel_hi:[1,1,1]
	v_pk_fma_f32 v[8:9], v[100:101], v[74:75], v[8:9] op_sel_hi:[0,1,1]
	v_pk_fma_f32 v[10:11], v[100:101], v[76:77], v[10:11] op_sel:[1,0,0] op_sel_hi:[1,1,1]
	ds_read_b128 v[148:151], v122 offset:14912
	s_waitcnt lgkmcnt(9)
	v_pk_fma_f32 v[4:5], v[102:103], v[78:79], v[4:5] op_sel_hi:[0,1,1]
	ds_read_b128 v[32:35], v122 offset:14928
	ds_read_b128 v[36:39], v122 offset:14944
	ds_read_b128 v[40:43], v122 offset:14960
	ds_read_b128 v[98:101], v122 offset:14976
	s_waitcnt lgkmcnt(9)
	v_lshlrev_b32_e32 v20, 16, v20
	v_lshlrev_b32_e32 v21, 16, v21
	v_pk_add_f32 v[12:13], v[4:5], v[6:7]
	v_pk_add_f32 v[14:15], v[8:9], v[10:11]
	s_nop 0
	v_pk_add_f32 v[12:13], v[12:13], v[14:15]
	s_nop 0
	v_pk_fma_f32 v[80:81], v[22:23], v[20:21], v[12:13] neg_lo:[0,0,1] neg_hi:[0,0,1]
	ds_read_b128 v[102:105], v122 offset:14992
	s_waitcnt lgkmcnt(9)
	v_pk_mul_f32 v[4:5], v[106:107], v[170:171] op_sel_hi:[0,1]
	v_pk_mul_f32 v[6:7], v[106:107], v[172:173] op_sel:[1,0] op_sel_hi:[1,1]
	v_pk_mul_f32 v[8:9], v[108:109], v[174:175] op_sel_hi:[0,1]
	v_pk_mul_f32 v[10:11], v[108:109], v[176:177] op_sel:[1,0] op_sel_hi:[1,1]
	ds_read_b128 v[106:109], v122 offset:15008
	s_waitcnt lgkmcnt(9)
	v_pk_fma_f32 v[4:5], v[130:131], v[178:179], v[4:5] op_sel_hi:[0,1,1]
	v_pk_fma_f32 v[6:7], v[130:131], v[180:181], v[6:7] op_sel:[1,0,0] op_sel_hi:[1,1,1]
	v_pk_fma_f32 v[8:9], v[132:133], v[182:183], v[8:9] op_sel_hi:[0,1,1]
	v_pk_fma_f32 v[10:11], v[132:133], v[184:185], v[10:11] op_sel:[1,0,0] op_sel_hi:[1,1,1]
	ds_read_b128 v[130:133], v122 offset:15024
	s_waitcnt lgkmcnt(9)
	v_pk_fma_f32 v[4:5], v[140:141], v[186:187], v[4:5] op_sel_hi:[0,1,1]
	v_pk_fma_f32 v[6:7], v[140:141], v[188:189], v[6:7] op_sel:[1,0,0] op_sel_hi:[1,1,1]
	v_pk_fma_f32 v[8:9], v[142:143], v[190:191], v[8:9] op_sel_hi:[0,1,1]
	v_pk_fma_f32 v[10:11], v[142:143], v[192:193], v[10:11] op_sel:[1,0,0] op_sel_hi:[1,1,1]
	ds_read_b128 v[140:143], v122 offset:15040
	s_waitcnt lgkmcnt(9)
	v_pk_fma_f32 v[4:5], v[144:145], v[194:195], v[4:5] op_sel_hi:[0,1,1]
	v_pk_fma_f32 v[6:7], v[144:145], v[196:197], v[6:7] op_sel:[1,0,0] op_sel_hi:[1,1,1]
	v_pk_fma_f32 v[8:9], v[146:147], v[198:199], v[8:9] op_sel_hi:[0,1,1]
	v_pk_fma_f32 v[10:11], v[146:147], v[200:201], v[10:11] op_sel:[1,0,0] op_sel_hi:[1,1,1]
	ds_read_b128 v[144:147], v122 offset:15056
	s_waitcnt lgkmcnt(9)
	v_pk_fma_f32 v[4:5], v[148:149], v[202:203], v[4:5] op_sel_hi:[0,1,1]
	v_pk_fma_f32 v[6:7], v[148:149], v[204:205], v[6:7] op_sel:[1,0,0] op_sel_hi:[1,1,1]
	v_pk_fma_f32 v[8:9], v[150:151], v[206:207], v[8:9] op_sel_hi:[0,1,1]
	v_pk_fma_f32 v[10:11], v[150:151], v[208:209], v[10:11] op_sel:[1,0,0] op_sel_hi:[1,1,1]
	ds_read_b128 v[148:151], v122 offset:15072
	s_waitcnt lgkmcnt(9)
	v_pk_fma_f32 v[4:5], v[32:33], v[210:211], v[4:5] op_sel_hi:[0,1,1]
	v_pk_fma_f32 v[6:7], v[32:33], v[212:213], v[6:7] op_sel:[1,0,0] op_sel_hi:[1,1,1]
	v_pk_fma_f32 v[8:9], v[34:35], v[214:215], v[8:9] op_sel_hi:[0,1,1]
	v_pk_fma_f32 v[10:11], v[34:35], v[216:217], v[10:11] op_sel:[1,0,0] op_sel_hi:[1,1,1]
	ds_read_u16 v24, v115 offset:15776
	s_waitcnt lgkmcnt(9)
	v_pk_fma_f32 v[4:5], v[36:37], v[218:219], v[4:5] op_sel_hi:[0,1,1]
	v_pk_fma_f32 v[6:7], v[36:37], v[220:221], v[6:7] op_sel:[1,0,0] op_sel_hi:[1,1,1]
	v_pk_fma_f32 v[8:9], v[38:39], v[222:223], v[8:9] op_sel_hi:[0,1,1]
	v_pk_fma_f32 v[10:11], v[38:39], v[224:225], v[10:11] op_sel:[1,0,0] op_sel_hi:[1,1,1]
	ds_read_u16 v25, v116 offset:15776
	s_waitcnt lgkmcnt(9)
	v_pk_fma_f32 v[4:5], v[40:41], v[226:227], v[4:5] op_sel_hi:[0,1,1]
	v_pk_fma_f32 v[6:7], v[40:41], v[228:229], v[6:7] op_sel:[1,0,0] op_sel_hi:[1,1,1]
	v_pk_fma_f32 v[8:9], v[42:43], v[230:231], v[8:9] op_sel_hi:[0,1,1]
	v_pk_fma_f32 v[10:11], v[42:43], v[232:233], v[10:11] op_sel:[1,0,0] op_sel_hi:[1,1,1]
	ds_read_b32 v26, v126 offset:232
	s_waitcnt lgkmcnt(9)
	v_pk_fma_f32 v[4:5], v[98:99], v[234:235], v[4:5] op_sel_hi:[0,1,1]
	v_pk_fma_f32 v[6:7], v[98:99], v[236:237], v[6:7] op_sel:[1,0,0] op_sel_hi:[1,1,1]
	v_pk_fma_f32 v[8:9], v[100:101], v[238:239], v[8:9] op_sel_hi:[0,1,1]
	v_pk_fma_f32 v[10:11], v[100:101], v[240:241], v[10:11] op_sel:[1,0,0] op_sel_hi:[1,1,1]
	ds_read_b32 v27, v127 offset:232
	s_waitcnt lgkmcnt(9)
	v_pk_fma_f32 v[4:5], v[102:103], v[242:243], v[4:5] op_sel_hi:[0,1,1]
	v_pk_fma_f32 v[6:7], v[102:103], v[244:245], v[6:7] op_sel:[1,0,0] op_sel_hi:[1,1,1]
	v_pk_fma_f32 v[8:9], v[104:105], v[246:247], v[8:9] op_sel_hi:[0,1,1]
	v_pk_fma_f32 v[10:11], v[104:105], v[248:249], v[10:11] op_sel:[1,0,0] op_sel_hi:[1,1,1]
	ds_read_b128 v[32:35], v122 offset:15104
	s_waitcnt lgkmcnt(9)
	v_pk_fma_f32 v[4:5], v[106:107], v[46:47], v[4:5] op_sel_hi:[0,1,1]
	v_pk_fma_f32 v[6:7], v[106:107], v[48:49], v[6:7] op_sel:[1,0,0] op_sel_hi:[1,1,1]
	v_pk_fma_f32 v[8:9], v[108:109], v[50:51], v[8:9] op_sel_hi:[0,1,1]
	v_pk_fma_f32 v[10:11], v[108:109], v[52:53], v[10:11] op_sel:[1,0,0] op_sel_hi:[1,1,1]
	ds_read_b128 v[36:39], v122 offset:15120
	s_waitcnt lgkmcnt(9)
	v_pk_fma_f32 v[4:5], v[130:131], v[54:55], v[4:5] op_sel_hi:[0,1,1]
	v_pk_fma_f32 v[6:7], v[130:131], v[56:57], v[6:7] op_sel:[1,0,0] op_sel_hi:[1,1,1]
	v_pk_fma_f32 v[8:9], v[132:133], v[58:59], v[8:9] op_sel_hi:[0,1,1]
	v_pk_fma_f32 v[10:11], v[132:133], v[60:61], v[10:11] op_sel:[1,0,0] op_sel_hi:[1,1,1]
	ds_read_b128 v[40:43], v122 offset:15136
	s_waitcnt lgkmcnt(9)
	v_pk_fma_f32 v[4:5], v[140:141], v[62:63], v[4:5] op_sel_hi:[0,1,1]
	v_pk_fma_f32 v[6:7], v[140:141], v[64:65], v[6:7] op_sel:[1,0,0] op_sel_hi:[1,1,1]
	v_pk_fma_f32 v[8:9], v[142:143], v[66:67], v[8:9] op_sel_hi:[0,1,1]
	v_pk_fma_f32 v[10:11], v[142:143], v[68:69], v[10:11] op_sel:[1,0,0] op_sel_hi:[1,1,1]
	ds_read_b128 v[98:101], v122 offset:15152
	s_waitcnt lgkmcnt(9)
	v_pk_fma_f32 v[4:5], v[144:145], v[70:71], v[4:5] op_sel_hi:[0,1,1]
	v_pk_fma_f32 v[6:7], v[144:145], v[72:73], v[6:7] op_sel:[1,0,0] op_sel_hi:[1,1,1]
	v_pk_fma_f32 v[8:9], v[146:147], v[74:75], v[8:9] op_sel_hi:[0,1,1]
	v_pk_fma_f32 v[10:11], v[146:147], v[76:77], v[10:11] op_sel:[1,0,0] op_sel_hi:[1,1,1]
	ds_read_b128 v[102:105], v122 offset:15168
	s_waitcnt lgkmcnt(9)
	v_pk_fma_f32 v[4:5], v[148:149], v[78:79], v[4:5] op_sel_hi:[0,1,1]
	v_pk_fma_f32 v[6:7], v[148:149], v[80:81], v[6:7] op_sel:[1,0,0] op_sel_hi:[1,1,1]
	ds_read_b128 v[106:109], v122 offset:15184
	ds_read_b128 v[130:133], v122 offset:15200
	ds_read_b128 v[140:143], v122 offset:15216
	ds_read_b128 v[144:147], v122 offset:15232
	s_waitcnt lgkmcnt(9)
	v_lshlrev_b32_e32 v24, 16, v24
	v_lshlrev_b32_e32 v25, 16, v25
	v_pk_add_f32 v[12:13], v[4:5], v[6:7]
	v_pk_add_f32 v[14:15], v[8:9], v[10:11]
	s_nop 0
	v_pk_add_f32 v[12:13], v[12:13], v[14:15]
	s_nop 0
	v_pk_fma_f32 v[82:83], v[26:27], v[24:25], v[12:13] neg_lo:[0,0,1] neg_hi:[0,0,1]
	ds_read_b128 v[148:151], v122 offset:15248
	s_waitcnt lgkmcnt(9)
	v_pk_mul_f32 v[4:5], v[32:33], v[170:171] op_sel_hi:[0,1]
	v_pk_mul_f32 v[6:7], v[32:33], v[172:173] op_sel:[1,0] op_sel_hi:[1,1]
	v_pk_mul_f32 v[8:9], v[34:35], v[174:175] op_sel_hi:[0,1]
	v_pk_mul_f32 v[10:11], v[34:35], v[176:177] op_sel:[1,0] op_sel_hi:[1,1]
	ds_read_b128 v[32:35], v122 offset:15264
	s_waitcnt lgkmcnt(9)
	v_pk_fma_f32 v[4:5], v[36:37], v[178:179], v[4:5] op_sel_hi:[0,1,1]
	v_pk_fma_f32 v[6:7], v[36:37], v[180:181], v[6:7] op_sel:[1,0,0] op_sel_hi:[1,1,1]
	v_pk_fma_f32 v[8:9], v[38:39], v[182:183], v[8:9] op_sel_hi:[0,1,1]
	v_pk_fma_f32 v[10:11], v[38:39], v[184:185], v[10:11] op_sel:[1,0,0] op_sel_hi:[1,1,1]
	ds_read_b128 v[36:39], v122 offset:15280
	s_waitcnt lgkmcnt(9)
	v_pk_fma_f32 v[4:5], v[40:41], v[186:187], v[4:5] op_sel_hi:[0,1,1]
	v_pk_fma_f32 v[6:7], v[40:41], v[188:189], v[6:7] op_sel:[1,0,0] op_sel_hi:[1,1,1]
	v_pk_fma_f32 v[8:9], v[42:43], v[190:191], v[8:9] op_sel_hi:[0,1,1]
	v_pk_fma_f32 v[10:11], v[42:43], v[192:193], v[10:11] op_sel:[1,0,0] op_sel_hi:[1,1,1]
	ds_read_b128 v[40:43], v122 offset:15296
	s_waitcnt lgkmcnt(9)
	v_pk_fma_f32 v[4:5], v[98:99], v[194:195], v[4:5] op_sel_hi:[0,1,1]
	v_pk_fma_f32 v[6:7], v[98:99], v[196:197], v[6:7] op_sel:[1,0,0] op_sel_hi:[1,1,1]
	v_pk_fma_f32 v[8:9], v[100:101], v[198:199], v[8:9] op_sel_hi:[0,1,1]
	v_pk_fma_f32 v[10:11], v[100:101], v[200:201], v[10:11] op_sel:[1,0,0] op_sel_hi:[1,1,1]
	ds_read_b128 v[98:101], v122 offset:15312
	s_waitcnt lgkmcnt(9)
	v_pk_fma_f32 v[4:5], v[102:103], v[202:203], v[4:5] op_sel_hi:[0,1,1]
	v_pk_fma_f32 v[6:7], v[102:103], v[204:205], v[6:7] op_sel:[1,0,0] op_sel_hi:[1,1,1]
	v_pk_fma_f32 v[8:9], v[104:105], v[206:207], v[8:9] op_sel_hi:[0,1,1]
	v_pk_fma_f32 v[10:11], v[104:105], v[208:209], v[10:11] op_sel:[1,0,0] op_sel_hi:[1,1,1]
	ds_read_b128 v[102:105], v122 offset:15328
	s_waitcnt lgkmcnt(9)
	v_pk_fma_f32 v[4:5], v[106:107], v[210:211], v[4:5] op_sel_hi:[0,1,1]
	v_pk_fma_f32 v[6:7], v[106:107], v[212:213], v[6:7] op_sel:[1,0,0] op_sel_hi:[1,1,1]
	v_pk_fma_f32 v[8:9], v[108:109], v[214:215], v[8:9] op_sel_hi:[0,1,1]
	v_pk_fma_f32 v[10:11], v[108:109], v[216:217], v[10:11] op_sel:[1,0,0] op_sel_hi:[1,1,1]
	ds_read_u16 v28, v115 offset:16048
	s_waitcnt lgkmcnt(9)
	v_pk_fma_f32 v[4:5], v[130:131], v[218:219], v[4:5] op_sel_hi:[0,1,1]
	v_pk_fma_f32 v[6:7], v[130:131], v[220:221], v[6:7] op_sel:[1,0,0] op_sel_hi:[1,1,1]
	v_pk_fma_f32 v[8:9], v[132:133], v[222:223], v[8:9] op_sel_hi:[0,1,1]
	v_pk_fma_f32 v[10:11], v[132:133], v[224:225], v[10:11] op_sel:[1,0,0] op_sel_hi:[1,1,1]
	ds_read_u16 v29, v116 offset:16048
	s_waitcnt lgkmcnt(9)
	v_pk_fma_f32 v[4:5], v[140:141], v[226:227], v[4:5] op_sel_hi:[0,1,1]
	v_pk_fma_f32 v[6:7], v[140:141], v[228:229], v[6:7] op_sel:[1,0,0] op_sel_hi:[1,1,1]
	v_pk_fma_f32 v[8:9], v[142:143], v[230:231], v[8:9] op_sel_hi:[0,1,1]
	v_pk_fma_f32 v[10:11], v[142:143], v[232:233], v[10:11] op_sel:[1,0,0] op_sel_hi:[1,1,1]
	ds_read_b32 v30, v126 offset:236
	s_waitcnt lgkmcnt(9)
	v_pk_fma_f32 v[4:5], v[144:145], v[234:235], v[4:5] op_sel_hi:[0,1,1]
	v_pk_fma_f32 v[6:7], v[144:145], v[236:237], v[6:7] op_sel:[1,0,0] op_sel_hi:[1,1,1]
	v_pk_fma_f32 v[8:9], v[146:147], v[238:239], v[8:9] op_sel_hi:[0,1,1]
	v_pk_fma_f32 v[10:11], v[146:147], v[240:241], v[10:11] op_sel:[1,0,0] op_sel_hi:[1,1,1]
	ds_read_b32 v31, v127 offset:236
	s_waitcnt lgkmcnt(9)
	v_pk_fma_f32 v[4:5], v[148:149], v[242:243], v[4:5] op_sel_hi:[0,1,1]
	v_pk_fma_f32 v[6:7], v[148:149], v[244:245], v[6:7] op_sel:[1,0,0] op_sel_hi:[1,1,1]
	v_pk_fma_f32 v[8:9], v[150:151], v[246:247], v[8:9] op_sel_hi:[0,1,1]
	v_pk_fma_f32 v[10:11], v[150:151], v[248:249], v[10:11] op_sel:[1,0,0] op_sel_hi:[1,1,1]
	ds_read_b128 v[106:109], v122 offset:15360
	s_waitcnt lgkmcnt(9)
	v_pk_fma_f32 v[4:5], v[32:33], v[46:47], v[4:5] op_sel_hi:[0,1,1]
	v_pk_fma_f32 v[6:7], v[32:33], v[48:49], v[6:7] op_sel:[1,0,0] op_sel_hi:[1,1,1]
	v_pk_fma_f32 v[8:9], v[34:35], v[50:51], v[8:9] op_sel_hi:[0,1,1]
	v_pk_fma_f32 v[10:11], v[34:35], v[52:53], v[10:11] op_sel:[1,0,0] op_sel_hi:[1,1,1]
	ds_read_b128 v[130:133], v122 offset:15376
	s_waitcnt lgkmcnt(9)
	v_pk_fma_f32 v[4:5], v[36:37], v[54:55], v[4:5] op_sel_hi:[0,1,1]
	v_pk_fma_f32 v[6:7], v[36:37], v[56:57], v[6:7] op_sel:[1,0,0] op_sel_hi:[1,1,1]
	v_pk_fma_f32 v[8:9], v[38:39], v[58:59], v[8:9] op_sel_hi:[0,1,1]
	v_pk_fma_f32 v[10:11], v[38:39], v[60:61], v[10:11] op_sel:[1,0,0] op_sel_hi:[1,1,1]
	ds_read_b128 v[140:143], v122 offset:15392
	s_waitcnt lgkmcnt(9)
	v_pk_fma_f32 v[4:5], v[40:41], v[62:63], v[4:5] op_sel_hi:[0,1,1]
	v_pk_fma_f32 v[6:7], v[40:41], v[64:65], v[6:7] op_sel:[1,0,0] op_sel_hi:[1,1,1]
	v_pk_fma_f32 v[8:9], v[42:43], v[66:67], v[8:9] op_sel_hi:[0,1,1]
	v_pk_fma_f32 v[10:11], v[42:43], v[68:69], v[10:11] op_sel:[1,0,0] op_sel_hi:[1,1,1]
	ds_read_b128 v[144:147], v122 offset:15408
	s_waitcnt lgkmcnt(9)
	v_pk_fma_f32 v[4:5], v[98:99], v[70:71], v[4:5] op_sel_hi:[0,1,1]
	v_pk_fma_f32 v[6:7], v[98:99], v[72:73], v[6:7] op_sel:[1,0,0] op_sel_hi:[1,1,1]
	v_pk_fma_f32 v[8:9], v[100:101], v[74:75], v[8:9] op_sel_hi:[0,1,1]
	v_pk_fma_f32 v[10:11], v[100:101], v[76:77], v[10:11] op_sel:[1,0,0] op_sel_hi:[1,1,1]
	ds_read_b128 v[148:151], v122 offset:15424
	s_waitcnt lgkmcnt(9)
	v_pk_fma_f32 v[4:5], v[102:103], v[78:79], v[4:5] op_sel_hi:[0,1,1]
	v_pk_fma_f32 v[6:7], v[102:103], v[80:81], v[6:7] op_sel:[1,0,0] op_sel_hi:[1,1,1]
	v_pk_fma_f32 v[8:9], v[104:105], v[82:83], v[8:9] op_sel_hi:[0,1,1]
	ds_read_b128 v[32:35], v122 offset:15440
	ds_read_b128 v[36:39], v122 offset:15456
	ds_read_b128 v[40:43], v122 offset:15472
	ds_read_b128 v[98:101], v122 offset:15488
	s_waitcnt lgkmcnt(9)
	v_lshlrev_b32_e32 v28, 16, v28
	v_lshlrev_b32_e32 v29, 16, v29
	v_pk_add_f32 v[12:13], v[4:5], v[6:7]
	v_pk_add_f32 v[14:15], v[8:9], v[10:11]
	s_nop 0
	v_pk_add_f32 v[12:13], v[12:13], v[14:15]
	s_nop 0
	v_pk_fma_f32 v[84:85], v[30:31], v[28:29], v[12:13] neg_lo:[0,0,1] neg_hi:[0,0,1]
	ds_read_b128 v[102:105], v122 offset:15504
	s_waitcnt lgkmcnt(9)
	v_pk_mul_f32 v[4:5], v[106:107], v[170:171] op_sel_hi:[0,1]
	v_pk_mul_f32 v[6:7], v[106:107], v[172:173] op_sel:[1,0] op_sel_hi:[1,1]
	v_pk_mul_f32 v[8:9], v[108:109], v[174:175] op_sel_hi:[0,1]
	v_pk_mul_f32 v[10:11], v[108:109], v[176:177] op_sel:[1,0] op_sel_hi:[1,1]
	ds_read_b128 v[106:109], v122 offset:15520
	s_waitcnt lgkmcnt(9)
	v_pk_fma_f32 v[4:5], v[130:131], v[178:179], v[4:5] op_sel_hi:[0,1,1]
	v_pk_fma_f32 v[6:7], v[130:131], v[180:181], v[6:7] op_sel:[1,0,0] op_sel_hi:[1,1,1]
	v_pk_fma_f32 v[8:9], v[132:133], v[182:183], v[8:9] op_sel_hi:[0,1,1]
	v_pk_fma_f32 v[10:11], v[132:133], v[184:185], v[10:11] op_sel:[1,0,0] op_sel_hi:[1,1,1]
	ds_read_b128 v[130:133], v122 offset:15536
	s_waitcnt lgkmcnt(9)
	v_pk_fma_f32 v[4:5], v[140:141], v[186:187], v[4:5] op_sel_hi:[0,1,1]
	v_pk_fma_f32 v[6:7], v[140:141], v[188:189], v[6:7] op_sel:[1,0,0] op_sel_hi:[1,1,1]
	v_pk_fma_f32 v[8:9], v[142:143], v[190:191], v[8:9] op_sel_hi:[0,1,1]
	v_pk_fma_f32 v[10:11], v[142:143], v[192:193], v[10:11] op_sel:[1,0,0] op_sel_hi:[1,1,1]
	ds_read_b128 v[140:143], v122 offset:15552
	s_waitcnt lgkmcnt(9)
	v_pk_fma_f32 v[4:5], v[144:145], v[194:195], v[4:5] op_sel_hi:[0,1,1]
	v_pk_fma_f32 v[6:7], v[144:145], v[196:197], v[6:7] op_sel:[1,0,0] op_sel_hi:[1,1,1]
	v_pk_fma_f32 v[8:9], v[146:147], v[198:199], v[8:9] op_sel_hi:[0,1,1]
	v_pk_fma_f32 v[10:11], v[146:147], v[200:201], v[10:11] op_sel:[1,0,0] op_sel_hi:[1,1,1]
	ds_read_b128 v[144:147], v122 offset:15568
	s_waitcnt lgkmcnt(9)
	v_pk_fma_f32 v[4:5], v[148:149], v[202:203], v[4:5] op_sel_hi:[0,1,1]
	v_pk_fma_f32 v[6:7], v[148:149], v[204:205], v[6:7] op_sel:[1,0,0] op_sel_hi:[1,1,1]
	v_pk_fma_f32 v[8:9], v[150:151], v[206:207], v[8:9] op_sel_hi:[0,1,1]
	v_pk_fma_f32 v[10:11], v[150:151], v[208:209], v[10:11] op_sel:[1,0,0] op_sel_hi:[1,1,1]
	ds_read_b128 v[148:151], v122 offset:15584
	s_waitcnt lgkmcnt(9)
	v_pk_fma_f32 v[4:5], v[32:33], v[210:211], v[4:5] op_sel_hi:[0,1,1]
	v_pk_fma_f32 v[6:7], v[32:33], v[212:213], v[6:7] op_sel:[1,0,0] op_sel_hi:[1,1,1]
	v_pk_fma_f32 v[8:9], v[34:35], v[214:215], v[8:9] op_sel_hi:[0,1,1]
	v_pk_fma_f32 v[10:11], v[34:35], v[216:217], v[10:11] op_sel:[1,0,0] op_sel_hi:[1,1,1]
	ds_read_u16 v16, v115 offset:16320
	s_waitcnt lgkmcnt(9)
	v_pk_fma_f32 v[4:5], v[36:37], v[218:219], v[4:5] op_sel_hi:[0,1,1]
	v_pk_fma_f32 v[6:7], v[36:37], v[220:221], v[6:7] op_sel:[1,0,0] op_sel_hi:[1,1,1]
	v_pk_fma_f32 v[8:9], v[38:39], v[222:223], v[8:9] op_sel_hi:[0,1,1]
	v_pk_fma_f32 v[10:11], v[38:39], v[224:225], v[10:11] op_sel:[1,0,0] op_sel_hi:[1,1,1]
	ds_read_u16 v17, v116 offset:16320
	s_waitcnt lgkmcnt(9)
	v_pk_fma_f32 v[4:5], v[40:41], v[226:227], v[4:5] op_sel_hi:[0,1,1]
	v_pk_fma_f32 v[6:7], v[40:41], v[228:229], v[6:7] op_sel:[1,0,0] op_sel_hi:[1,1,1]
	v_pk_fma_f32 v[8:9], v[42:43], v[230:231], v[8:9] op_sel_hi:[0,1,1]
	v_pk_fma_f32 v[10:11], v[42:43], v[232:233], v[10:11] op_sel:[1,0,0] op_sel_hi:[1,1,1]
	ds_read_b32 v18, v126 offset:240
	s_waitcnt lgkmcnt(9)
	v_pk_fma_f32 v[4:5], v[98:99], v[234:235], v[4:5] op_sel_hi:[0,1,1]
	v_pk_fma_f32 v[6:7], v[98:99], v[236:237], v[6:7] op_sel:[1,0,0] op_sel_hi:[1,1,1]
	v_pk_fma_f32 v[8:9], v[100:101], v[238:239], v[8:9] op_sel_hi:[0,1,1]
	v_pk_fma_f32 v[10:11], v[100:101], v[240:241], v[10:11] op_sel:[1,0,0] op_sel_hi:[1,1,1]
	ds_read_b32 v19, v127 offset:240
	s_waitcnt lgkmcnt(9)
	v_pk_fma_f32 v[4:5], v[102:103], v[242:243], v[4:5] op_sel_hi:[0,1,1]
	v_pk_fma_f32 v[6:7], v[102:103], v[244:245], v[6:7] op_sel:[1,0,0] op_sel_hi:[1,1,1]
	v_pk_fma_f32 v[8:9], v[104:105], v[246:247], v[8:9] op_sel_hi:[0,1,1]
	v_pk_fma_f32 v[10:11], v[104:105], v[248:249], v[10:11] op_sel:[1,0,0] op_sel_hi:[1,1,1]
	ds_read_b128 v[32:35], v122 offset:15616
	s_waitcnt lgkmcnt(9)
	v_pk_fma_f32 v[4:5], v[106:107], v[46:47], v[4:5] op_sel_hi:[0,1,1]
	v_pk_fma_f32 v[6:7], v[106:107], v[48:49], v[6:7] op_sel:[1,0,0] op_sel_hi:[1,1,1]
	v_pk_fma_f32 v[8:9], v[108:109], v[50:51], v[8:9] op_sel_hi:[0,1,1]
	v_pk_fma_f32 v[10:11], v[108:109], v[52:53], v[10:11] op_sel:[1,0,0] op_sel_hi:[1,1,1]
	ds_read_b128 v[36:39], v122 offset:15632
	s_waitcnt lgkmcnt(9)
	v_pk_fma_f32 v[4:5], v[130:131], v[54:55], v[4:5] op_sel_hi:[0,1,1]
	v_pk_fma_f32 v[6:7], v[130:131], v[56:57], v[6:7] op_sel:[1,0,0] op_sel_hi:[1,1,1]
	v_pk_fma_f32 v[8:9], v[132:133], v[58:59], v[8:9] op_sel_hi:[0,1,1]
	v_pk_fma_f32 v[10:11], v[132:133], v[60:61], v[10:11] op_sel:[1,0,0] op_sel_hi:[1,1,1]
	ds_read_b128 v[40:43], v122 offset:15648
	s_waitcnt lgkmcnt(9)
	v_pk_fma_f32 v[4:5], v[140:141], v[62:63], v[4:5] op_sel_hi:[0,1,1]
	v_pk_fma_f32 v[6:7], v[140:141], v[64:65], v[6:7] op_sel:[1,0,0] op_sel_hi:[1,1,1]
	v_pk_fma_f32 v[8:9], v[142:143], v[66:67], v[8:9] op_sel_hi:[0,1,1]
	v_pk_fma_f32 v[10:11], v[142:143], v[68:69], v[10:11] op_sel:[1,0,0] op_sel_hi:[1,1,1]
	ds_read_b128 v[98:101], v122 offset:15664
	s_waitcnt lgkmcnt(9)
	v_pk_fma_f32 v[4:5], v[144:145], v[70:71], v[4:5] op_sel_hi:[0,1,1]
	v_pk_fma_f32 v[6:7], v[144:145], v[72:73], v[6:7] op_sel:[1,0,0] op_sel_hi:[1,1,1]
	v_pk_fma_f32 v[8:9], v[146:147], v[74:75], v[8:9] op_sel_hi:[0,1,1]
	v_pk_fma_f32 v[10:11], v[146:147], v[76:77], v[10:11] op_sel:[1,0,0] op_sel_hi:[1,1,1]
	ds_read_b128 v[102:105], v122 offset:15680
	s_waitcnt lgkmcnt(9)
	v_pk_fma_f32 v[4:5], v[148:149], v[78:79], v[4:5] op_sel_hi:[0,1,1]
	v_pk_fma_f32 v[6:7], v[148:149], v[80:81], v[6:7] op_sel:[1,0,0] op_sel_hi:[1,1,1]
	v_pk_fma_f32 v[8:9], v[150:151], v[82:83], v[8:9] op_sel_hi:[0,1,1]
	v_pk_fma_f32 v[10:11], v[150:151], v[84:85], v[10:11] op_sel:[1,0,0] op_sel_hi:[1,1,1]
	ds_read_b128 v[106:109], v122 offset:15696
	ds_read_b128 v[130:133], v122 offset:15712
	ds_read_b128 v[140:143], v122 offset:15728
	ds_read_b128 v[144:147], v122 offset:15744
	s_waitcnt lgkmcnt(9)
	v_lshlrev_b32_e32 v16, 16, v16
	v_lshlrev_b32_e32 v17, 16, v17
	v_pk_add_f32 v[12:13], v[4:5], v[6:7]
	v_pk_add_f32 v[14:15], v[8:9], v[10:11]
	s_nop 0
	v_pk_add_f32 v[12:13], v[12:13], v[14:15]
	s_nop 0
	v_pk_fma_f32 v[86:87], v[18:19], v[16:17], v[12:13] neg_lo:[0,0,1] neg_hi:[0,0,1]
	ds_read_b128 v[148:151], v122 offset:15760
	s_waitcnt lgkmcnt(9)
	v_pk_mul_f32 v[4:5], v[32:33], v[170:171] op_sel_hi:[0,1]
	v_pk_mul_f32 v[6:7], v[32:33], v[172:173] op_sel:[1,0] op_sel_hi:[1,1]
	v_pk_mul_f32 v[8:9], v[34:35], v[174:175] op_sel_hi:[0,1]
	v_pk_mul_f32 v[10:11], v[34:35], v[176:177] op_sel:[1,0] op_sel_hi:[1,1]
	ds_read_b128 v[32:35], v122 offset:15776
	s_waitcnt lgkmcnt(9)
	v_pk_fma_f32 v[4:5], v[36:37], v[178:179], v[4:5] op_sel_hi:[0,1,1]
	v_pk_fma_f32 v[6:7], v[36:37], v[180:181], v[6:7] op_sel:[1,0,0] op_sel_hi:[1,1,1]
	v_pk_fma_f32 v[8:9], v[38:39], v[182:183], v[8:9] op_sel_hi:[0,1,1]
	v_pk_fma_f32 v[10:11], v[38:39], v[184:185], v[10:11] op_sel:[1,0,0] op_sel_hi:[1,1,1]
	ds_read_b128 v[36:39], v122 offset:15792
	s_waitcnt lgkmcnt(9)
	v_pk_fma_f32 v[4:5], v[40:41], v[186:187], v[4:5] op_sel_hi:[0,1,1]
	v_pk_fma_f32 v[6:7], v[40:41], v[188:189], v[6:7] op_sel:[1,0,0] op_sel_hi:[1,1,1]
	v_pk_fma_f32 v[8:9], v[42:43], v[190:191], v[8:9] op_sel_hi:[0,1,1]
	v_pk_fma_f32 v[10:11], v[42:43], v[192:193], v[10:11] op_sel:[1,0,0] op_sel_hi:[1,1,1]
	ds_read_b128 v[40:43], v122 offset:15808
	s_waitcnt lgkmcnt(9)
	v_pk_fma_f32 v[4:5], v[98:99], v[194:195], v[4:5] op_sel_hi:[0,1,1]
	v_pk_fma_f32 v[6:7], v[98:99], v[196:197], v[6:7] op_sel:[1,0,0] op_sel_hi:[1,1,1]
	v_pk_fma_f32 v[8:9], v[100:101], v[198:199], v[8:9] op_sel_hi:[0,1,1]
	v_pk_fma_f32 v[10:11], v[100:101], v[200:201], v[10:11] op_sel:[1,0,0] op_sel_hi:[1,1,1]
	ds_read_b128 v[98:101], v122 offset:15824
	s_waitcnt lgkmcnt(9)
	v_pk_fma_f32 v[4:5], v[102:103], v[202:203], v[4:5] op_sel_hi:[0,1,1]
	v_pk_fma_f32 v[6:7], v[102:103], v[204:205], v[6:7] op_sel:[1,0,0] op_sel_hi:[1,1,1]
	v_pk_fma_f32 v[8:9], v[104:105], v[206:207], v[8:9] op_sel_hi:[0,1,1]
	v_pk_fma_f32 v[10:11], v[104:105], v[208:209], v[10:11] op_sel:[1,0,0] op_sel_hi:[1,1,1]
	ds_read_b128 v[102:105], v122 offset:15840
	s_waitcnt lgkmcnt(9)
	v_pk_fma_f32 v[4:5], v[106:107], v[210:211], v[4:5] op_sel_hi:[0,1,1]
	v_pk_fma_f32 v[6:7], v[106:107], v[212:213], v[6:7] op_sel:[1,0,0] op_sel_hi:[1,1,1]
	v_pk_fma_f32 v[8:9], v[108:109], v[214:215], v[8:9] op_sel_hi:[0,1,1]
	v_pk_fma_f32 v[10:11], v[108:109], v[216:217], v[10:11] op_sel:[1,0,0] op_sel_hi:[1,1,1]
	ds_read_b128 v[106:109], v122 offset:15856
	s_waitcnt lgkmcnt(9)
	v_pk_fma_f32 v[4:5], v[130:131], v[218:219], v[4:5] op_sel_hi:[0,1,1]
	v_pk_fma_f32 v[6:7], v[130:131], v[220:221], v[6:7] op_sel:[1,0,0] op_sel_hi:[1,1,1]
	v_pk_fma_f32 v[8:9], v[132:133], v[222:223], v[8:9] op_sel_hi:[0,1,1]
	v_pk_fma_f32 v[10:11], v[132:133], v[224:225], v[10:11] op_sel:[1,0,0] op_sel_hi:[1,1,1]
	ds_read_u16 v20, v115 offset:16592
	s_waitcnt lgkmcnt(9)
	v_pk_fma_f32 v[4:5], v[140:141], v[226:227], v[4:5] op_sel_hi:[0,1,1]
	v_pk_fma_f32 v[6:7], v[140:141], v[228:229], v[6:7] op_sel:[1,0,0] op_sel_hi:[1,1,1]
	v_pk_fma_f32 v[8:9], v[142:143], v[230:231], v[8:9] op_sel_hi:[0,1,1]
	v_pk_fma_f32 v[10:11], v[142:143], v[232:233], v[10:11] op_sel:[1,0,0] op_sel_hi:[1,1,1]
	ds_read_u16 v21, v116 offset:16592
	s_waitcnt lgkmcnt(9)
	v_pk_fma_f32 v[4:5], v[144:145], v[234:235], v[4:5] op_sel_hi:[0,1,1]
	v_pk_fma_f32 v[6:7], v[144:145], v[236:237], v[6:7] op_sel:[1,0,0] op_sel_hi:[1,1,1]
	v_pk_fma_f32 v[8:9], v[146:147], v[238:239], v[8:9] op_sel_hi:[0,1,1]
	v_pk_fma_f32 v[10:11], v[146:147], v[240:241], v[10:11] op_sel:[1,0,0] op_sel_hi:[1,1,1]
	ds_read_b32 v22, v126 offset:244
	s_waitcnt lgkmcnt(9)
	v_pk_fma_f32 v[4:5], v[148:149], v[242:243], v[4:5] op_sel_hi:[0,1,1]
	v_pk_fma_f32 v[6:7], v[148:149], v[244:245], v[6:7] op_sel:[1,0,0] op_sel_hi:[1,1,1]
	v_pk_fma_f32 v[8:9], v[150:151], v[246:247], v[8:9] op_sel_hi:[0,1,1]
	v_pk_fma_f32 v[10:11], v[150:151], v[248:249], v[10:11] op_sel:[1,0,0] op_sel_hi:[1,1,1]
	ds_read_b32 v23, v127 offset:244
	s_waitcnt lgkmcnt(9)
	v_pk_fma_f32 v[4:5], v[32:33], v[46:47], v[4:5] op_sel_hi:[0,1,1]
	v_pk_fma_f32 v[6:7], v[32:33], v[48:49], v[6:7] op_sel:[1,0,0] op_sel_hi:[1,1,1]
	v_pk_fma_f32 v[8:9], v[34:35], v[50:51], v[8:9] op_sel_hi:[0,1,1]
	v_pk_fma_f32 v[10:11], v[34:35], v[52:53], v[10:11] op_sel:[1,0,0] op_sel_hi:[1,1,1]
	ds_read_b128 v[130:133], v122 offset:15872
	s_waitcnt lgkmcnt(9)
	v_pk_fma_f32 v[4:5], v[36:37], v[54:55], v[4:5] op_sel_hi:[0,1,1]
	v_pk_fma_f32 v[6:7], v[36:37], v[56:57], v[6:7] op_sel:[1,0,0] op_sel_hi:[1,1,1]
	v_pk_fma_f32 v[8:9], v[38:39], v[58:59], v[8:9] op_sel_hi:[0,1,1]
	v_pk_fma_f32 v[10:11], v[38:39], v[60:61], v[10:11] op_sel:[1,0,0] op_sel_hi:[1,1,1]
	ds_read_b128 v[140:143], v122 offset:15888
	s_waitcnt lgkmcnt(9)
	v_pk_fma_f32 v[4:5], v[40:41], v[62:63], v[4:5] op_sel_hi:[0,1,1]
	v_pk_fma_f32 v[6:7], v[40:41], v[64:65], v[6:7] op_sel:[1,0,0] op_sel_hi:[1,1,1]
	v_pk_fma_f32 v[8:9], v[42:43], v[66:67], v[8:9] op_sel_hi:[0,1,1]
	v_pk_fma_f32 v[10:11], v[42:43], v[68:69], v[10:11] op_sel:[1,0,0] op_sel_hi:[1,1,1]
	ds_read_b128 v[144:147], v122 offset:15904
	s_waitcnt lgkmcnt(9)
	v_pk_fma_f32 v[4:5], v[98:99], v[70:71], v[4:5] op_sel_hi:[0,1,1]
	v_pk_fma_f32 v[6:7], v[98:99], v[72:73], v[6:7] op_sel:[1,0,0] op_sel_hi:[1,1,1]
	v_pk_fma_f32 v[8:9], v[100:101], v[74:75], v[8:9] op_sel_hi:[0,1,1]
	v_pk_fma_f32 v[10:11], v[100:101], v[76:77], v[10:11] op_sel:[1,0,0] op_sel_hi:[1,1,1]
	ds_read_b128 v[148:151], v122 offset:15920
	s_waitcnt lgkmcnt(9)
	v_pk_fma_f32 v[4:5], v[102:103], v[78:79], v[4:5] op_sel_hi:[0,1,1]
	v_pk_fma_f32 v[6:7], v[102:103], v[80:81], v[6:7] op_sel:[1,0,0] op_sel_hi:[1,1,1]
	v_pk_fma_f32 v[8:9], v[104:105], v[82:83], v[8:9] op_sel_hi:[0,1,1]
	v_pk_fma_f32 v[10:11], v[104:105], v[84:85], v[10:11] op_sel:[1,0,0] op_sel_hi:[1,1,1]
	ds_read_b128 v[32:35], v122 offset:15936
	s_waitcnt lgkmcnt(9)
	v_pk_fma_f32 v[4:5], v[106:107], v[86:87], v[4:5] op_sel_hi:[0,1,1]
	ds_read_b128 v[36:39], v122 offset:15952
	ds_read_b128 v[40:43], v122 offset:15968
	ds_read_b128 v[98:101], v122 offset:15984
	ds_read_b128 v[102:105], v122 offset:16000
	s_waitcnt lgkmcnt(9)
	v_lshlrev_b32_e32 v20, 16, v20
	v_lshlrev_b32_e32 v21, 16, v21
	v_pk_add_f32 v[12:13], v[4:5], v[6:7]
	v_pk_add_f32 v[14:15], v[8:9], v[10:11]
	s_nop 0
	v_pk_add_f32 v[12:13], v[12:13], v[14:15]
	s_nop 0
	v_pk_fma_f32 v[88:89], v[22:23], v[20:21], v[12:13] neg_lo:[0,0,1] neg_hi:[0,0,1]
	ds_read_b128 v[106:109], v122 offset:16016
	s_waitcnt lgkmcnt(9)
	v_pk_mul_f32 v[4:5], v[130:131], v[170:171] op_sel_hi:[0,1]
	v_pk_mul_f32 v[6:7], v[130:131], v[172:173] op_sel:[1,0] op_sel_hi:[1,1]
	v_pk_mul_f32 v[8:9], v[132:133], v[174:175] op_sel_hi:[0,1]
	v_pk_mul_f32 v[10:11], v[132:133], v[176:177] op_sel:[1,0] op_sel_hi:[1,1]
	ds_read_b128 v[130:133], v122 offset:16032
	s_waitcnt lgkmcnt(9)
	v_pk_fma_f32 v[4:5], v[140:141], v[178:179], v[4:5] op_sel_hi:[0,1,1]
	v_pk_fma_f32 v[6:7], v[140:141], v[180:181], v[6:7] op_sel:[1,0,0] op_sel_hi:[1,1,1]
	v_pk_fma_f32 v[8:9], v[142:143], v[182:183], v[8:9] op_sel_hi:[0,1,1]
	v_pk_fma_f32 v[10:11], v[142:143], v[184:185], v[10:11] op_sel:[1,0,0] op_sel_hi:[1,1,1]
	ds_read_b128 v[140:143], v122 offset:16048
	s_waitcnt lgkmcnt(9)
	v_pk_fma_f32 v[4:5], v[144:145], v[186:187], v[4:5] op_sel_hi:[0,1,1]
	v_pk_fma_f32 v[6:7], v[144:145], v[188:189], v[6:7] op_sel:[1,0,0] op_sel_hi:[1,1,1]
	v_pk_fma_f32 v[8:9], v[146:147], v[190:191], v[8:9] op_sel_hi:[0,1,1]
	v_pk_fma_f32 v[10:11], v[146:147], v[192:193], v[10:11] op_sel:[1,0,0] op_sel_hi:[1,1,1]
	ds_read_b128 v[144:147], v122 offset:16064
	s_waitcnt lgkmcnt(9)
	v_pk_fma_f32 v[4:5], v[148:149], v[194:195], v[4:5] op_sel_hi:[0,1,1]
	v_pk_fma_f32 v[6:7], v[148:149], v[196:197], v[6:7] op_sel:[1,0,0] op_sel_hi:[1,1,1]
	v_pk_fma_f32 v[8:9], v[150:151], v[198:199], v[8:9] op_sel_hi:[0,1,1]
	v_pk_fma_f32 v[10:11], v[150:151], v[200:201], v[10:11] op_sel:[1,0,0] op_sel_hi:[1,1,1]
	ds_read_b128 v[148:151], v122 offset:16080
	s_waitcnt lgkmcnt(9)
	v_pk_fma_f32 v[4:5], v[32:33], v[202:203], v[4:5] op_sel_hi:[0,1,1]
	v_pk_fma_f32 v[6:7], v[32:33], v[204:205], v[6:7] op_sel:[1,0,0] op_sel_hi:[1,1,1]
	v_pk_fma_f32 v[8:9], v[34:35], v[206:207], v[8:9] op_sel_hi:[0,1,1]
	v_pk_fma_f32 v[10:11], v[34:35], v[208:209], v[10:11] op_sel:[1,0,0] op_sel_hi:[1,1,1]
	ds_read_b128 v[32:35], v122 offset:16096
	s_waitcnt lgkmcnt(9)
	v_pk_fma_f32 v[4:5], v[36:37], v[210:211], v[4:5] op_sel_hi:[0,1,1]
	v_pk_fma_f32 v[6:7], v[36:37], v[212:213], v[6:7] op_sel:[1,0,0] op_sel_hi:[1,1,1]
	v_pk_fma_f32 v[8:9], v[38:39], v[214:215], v[8:9] op_sel_hi:[0,1,1]
	v_pk_fma_f32 v[10:11], v[38:39], v[216:217], v[10:11] op_sel:[1,0,0] op_sel_hi:[1,1,1]
	ds_read_b128 v[36:39], v122 offset:16112
	s_waitcnt lgkmcnt(9)
	v_pk_fma_f32 v[4:5], v[40:41], v[218:219], v[4:5] op_sel_hi:[0,1,1]
	v_pk_fma_f32 v[6:7], v[40:41], v[220:221], v[6:7] op_sel:[1,0,0] op_sel_hi:[1,1,1]
	v_pk_fma_f32 v[8:9], v[42:43], v[222:223], v[8:9] op_sel_hi:[0,1,1]
	v_pk_fma_f32 v[10:11], v[42:43], v[224:225], v[10:11] op_sel:[1,0,0] op_sel_hi:[1,1,1]
	ds_read_u16 v24, v115 offset:16864
	s_waitcnt lgkmcnt(9)
	v_pk_fma_f32 v[4:5], v[98:99], v[226:227], v[4:5] op_sel_hi:[0,1,1]
	v_pk_fma_f32 v[6:7], v[98:99], v[228:229], v[6:7] op_sel:[1,0,0] op_sel_hi:[1,1,1]
	v_pk_fma_f32 v[8:9], v[100:101], v[230:231], v[8:9] op_sel_hi:[0,1,1]
	v_pk_fma_f32 v[10:11], v[100:101], v[232:233], v[10:11] op_sel:[1,0,0] op_sel_hi:[1,1,1]
	ds_read_u16 v25, v116 offset:16864
	s_waitcnt lgkmcnt(9)
	v_pk_fma_f32 v[4:5], v[102:103], v[234:235], v[4:5] op_sel_hi:[0,1,1]
	v_pk_fma_f32 v[6:7], v[102:103], v[236:237], v[6:7] op_sel:[1,0,0] op_sel_hi:[1,1,1]
	v_pk_fma_f32 v[8:9], v[104:105], v[238:239], v[8:9] op_sel_hi:[0,1,1]
	v_pk_fma_f32 v[10:11], v[104:105], v[240:241], v[10:11] op_sel:[1,0,0] op_sel_hi:[1,1,1]
	ds_read_b32 v26, v126 offset:248
	s_waitcnt lgkmcnt(9)
	v_pk_fma_f32 v[4:5], v[106:107], v[242:243], v[4:5] op_sel_hi:[0,1,1]
	v_pk_fma_f32 v[6:7], v[106:107], v[244:245], v[6:7] op_sel:[1,0,0] op_sel_hi:[1,1,1]
	v_pk_fma_f32 v[8:9], v[108:109], v[246:247], v[8:9] op_sel_hi:[0,1,1]
	v_pk_fma_f32 v[10:11], v[108:109], v[248:249], v[10:11] op_sel:[1,0,0] op_sel_hi:[1,1,1]
	ds_read_b32 v27, v127 offset:248
	s_waitcnt lgkmcnt(9)
	v_pk_fma_f32 v[4:5], v[130:131], v[46:47], v[4:5] op_sel_hi:[0,1,1]
	v_pk_fma_f32 v[6:7], v[130:131], v[48:49], v[6:7] op_sel:[1,0,0] op_sel_hi:[1,1,1]
	v_pk_fma_f32 v[8:9], v[132:133], v[50:51], v[8:9] op_sel_hi:[0,1,1]
	v_pk_fma_f32 v[10:11], v[132:133], v[52:53], v[10:11] op_sel:[1,0,0] op_sel_hi:[1,1,1]
	ds_read_b128 v[40:43], v122 offset:16128
	s_waitcnt lgkmcnt(9)
	v_pk_fma_f32 v[4:5], v[140:141], v[54:55], v[4:5] op_sel_hi:[0,1,1]
	v_pk_fma_f32 v[6:7], v[140:141], v[56:57], v[6:7] op_sel:[1,0,0] op_sel_hi:[1,1,1]
	v_pk_fma_f32 v[8:9], v[142:143], v[58:59], v[8:9] op_sel_hi:[0,1,1]
	v_pk_fma_f32 v[10:11], v[142:143], v[60:61], v[10:11] op_sel:[1,0,0] op_sel_hi:[1,1,1]
	ds_read_b128 v[98:101], v122 offset:16144
	s_waitcnt lgkmcnt(9)
	v_pk_fma_f32 v[4:5], v[144:145], v[62:63], v[4:5] op_sel_hi:[0,1,1]
	v_pk_fma_f32 v[6:7], v[144:145], v[64:65], v[6:7] op_sel:[1,0,0] op_sel_hi:[1,1,1]
	v_pk_fma_f32 v[8:9], v[146:147], v[66:67], v[8:9] op_sel_hi:[0,1,1]
	v_pk_fma_f32 v[10:11], v[146:147], v[68:69], v[10:11] op_sel:[1,0,0] op_sel_hi:[1,1,1]
	ds_read_b128 v[102:105], v122 offset:16160
	s_waitcnt lgkmcnt(9)
	v_pk_fma_f32 v[4:5], v[148:149], v[70:71], v[4:5] op_sel_hi:[0,1,1]
	v_pk_fma_f32 v[6:7], v[148:149], v[72:73], v[6:7] op_sel:[1,0,0] op_sel_hi:[1,1,1]
	v_pk_fma_f32 v[8:9], v[150:151], v[74:75], v[8:9] op_sel_hi:[0,1,1]
	v_pk_fma_f32 v[10:11], v[150:151], v[76:77], v[10:11] op_sel:[1,0,0] op_sel_hi:[1,1,1]
	ds_read_b128 v[106:109], v122 offset:16176
	s_waitcnt lgkmcnt(9)
	v_pk_fma_f32 v[4:5], v[32:33], v[78:79], v[4:5] op_sel_hi:[0,1,1]
	v_pk_fma_f32 v[6:7], v[32:33], v[80:81], v[6:7] op_sel:[1,0,0] op_sel_hi:[1,1,1]
	v_pk_fma_f32 v[8:9], v[34:35], v[82:83], v[8:9] op_sel_hi:[0,1,1]
	v_pk_fma_f32 v[10:11], v[34:35], v[84:85], v[10:11] op_sel:[1,0,0] op_sel_hi:[1,1,1]
	ds_read_b128 v[130:133], v122 offset:16192
	s_waitcnt lgkmcnt(9)
	v_pk_fma_f32 v[4:5], v[36:37], v[86:87], v[4:5] op_sel_hi:[0,1,1]
	v_pk_fma_f32 v[6:7], v[36:37], v[88:89], v[6:7] op_sel:[1,0,0] op_sel_hi:[1,1,1]
	ds_read_b128 v[140:143], v122 offset:16208
	ds_read_b128 v[144:147], v122 offset:16224
	ds_read_b128 v[148:151], v122 offset:16240
	ds_read_b128 v[32:35], v122 offset:16256
	s_waitcnt lgkmcnt(9)
	v_lshlrev_b32_e32 v24, 16, v24
	v_lshlrev_b32_e32 v25, 16, v25
	v_pk_add_f32 v[12:13], v[4:5], v[6:7]
	v_pk_add_f32 v[14:15], v[8:9], v[10:11]
	s_nop 0
	v_pk_add_f32 v[12:13], v[12:13], v[14:15]
	s_nop 0
	v_pk_fma_f32 v[90:91], v[26:27], v[24:25], v[12:13] neg_lo:[0,0,1] neg_hi:[0,0,1]
	ds_read_b128 v[36:39], v122 offset:16272
	s_waitcnt lgkmcnt(9)
	v_pk_mul_f32 v[4:5], v[40:41], v[170:171] op_sel_hi:[0,1]
	v_pk_mul_f32 v[6:7], v[40:41], v[172:173] op_sel:[1,0] op_sel_hi:[1,1]
	v_pk_mul_f32 v[8:9], v[42:43], v[174:175] op_sel_hi:[0,1]
	v_pk_mul_f32 v[10:11], v[42:43], v[176:177] op_sel:[1,0] op_sel_hi:[1,1]
	ds_read_b128 v[40:43], v122 offset:16288
	s_waitcnt lgkmcnt(9)
	v_pk_fma_f32 v[4:5], v[98:99], v[178:179], v[4:5] op_sel_hi:[0,1,1]
	v_pk_fma_f32 v[6:7], v[98:99], v[180:181], v[6:7] op_sel:[1,0,0] op_sel_hi:[1,1,1]
	v_pk_fma_f32 v[8:9], v[100:101], v[182:183], v[8:9] op_sel_hi:[0,1,1]
	v_pk_fma_f32 v[10:11], v[100:101], v[184:185], v[10:11] op_sel:[1,0,0] op_sel_hi:[1,1,1]
	ds_read_b128 v[98:101], v122 offset:16304
	s_waitcnt lgkmcnt(9)
	v_pk_fma_f32 v[4:5], v[102:103], v[186:187], v[4:5] op_sel_hi:[0,1,1]
	v_pk_fma_f32 v[6:7], v[102:103], v[188:189], v[6:7] op_sel:[1,0,0] op_sel_hi:[1,1,1]
	v_pk_fma_f32 v[8:9], v[104:105], v[190:191], v[8:9] op_sel_hi:[0,1,1]
	v_pk_fma_f32 v[10:11], v[104:105], v[192:193], v[10:11] op_sel:[1,0,0] op_sel_hi:[1,1,1]
	ds_read_b128 v[102:105], v122 offset:16320
	s_waitcnt lgkmcnt(9)
	v_pk_fma_f32 v[4:5], v[106:107], v[194:195], v[4:5] op_sel_hi:[0,1,1]
	v_pk_fma_f32 v[6:7], v[106:107], v[196:197], v[6:7] op_sel:[1,0,0] op_sel_hi:[1,1,1]
	v_pk_fma_f32 v[8:9], v[108:109], v[198:199], v[8:9] op_sel_hi:[0,1,1]
	v_pk_fma_f32 v[10:11], v[108:109], v[200:201], v[10:11] op_sel:[1,0,0] op_sel_hi:[1,1,1]
	ds_read_b128 v[106:109], v122 offset:16336
	s_waitcnt lgkmcnt(9)
	v_pk_fma_f32 v[4:5], v[130:131], v[202:203], v[4:5] op_sel_hi:[0,1,1]
	v_pk_fma_f32 v[6:7], v[130:131], v[204:205], v[6:7] op_sel:[1,0,0] op_sel_hi:[1,1,1]
	v_pk_fma_f32 v[8:9], v[132:133], v[206:207], v[8:9] op_sel_hi:[0,1,1]
	v_pk_fma_f32 v[10:11], v[132:133], v[208:209], v[10:11] op_sel:[1,0,0] op_sel_hi:[1,1,1]
	ds_read_b128 v[130:133], v122 offset:16352
	s_waitcnt lgkmcnt(9)
	v_pk_fma_f32 v[4:5], v[140:141], v[210:211], v[4:5] op_sel_hi:[0,1,1]
	v_pk_fma_f32 v[6:7], v[140:141], v[212:213], v[6:7] op_sel:[1,0,0] op_sel_hi:[1,1,1]
	v_pk_fma_f32 v[8:9], v[142:143], v[214:215], v[8:9] op_sel_hi:[0,1,1]
	v_pk_fma_f32 v[10:11], v[142:143], v[216:217], v[10:11] op_sel:[1,0,0] op_sel_hi:[1,1,1]
	ds_read_b128 v[140:143], v122 offset:16368
	s_waitcnt lgkmcnt(9)
	v_pk_fma_f32 v[4:5], v[144:145], v[218:219], v[4:5] op_sel_hi:[0,1,1]
	v_pk_fma_f32 v[6:7], v[144:145], v[220:221], v[6:7] op_sel:[1,0,0] op_sel_hi:[1,1,1]
	v_pk_fma_f32 v[8:9], v[146:147], v[222:223], v[8:9] op_sel_hi:[0,1,1]
	v_pk_fma_f32 v[10:11], v[146:147], v[224:225], v[10:11] op_sel:[1,0,0] op_sel_hi:[1,1,1]
	ds_read_u16 v28, v115 offset:17136
	s_waitcnt lgkmcnt(9)
	v_pk_fma_f32 v[4:5], v[148:149], v[226:227], v[4:5] op_sel_hi:[0,1,1]
	v_pk_fma_f32 v[6:7], v[148:149], v[228:229], v[6:7] op_sel:[1,0,0] op_sel_hi:[1,1,1]
	v_pk_fma_f32 v[8:9], v[150:151], v[230:231], v[8:9] op_sel_hi:[0,1,1]
	v_pk_fma_f32 v[10:11], v[150:151], v[232:233], v[10:11] op_sel:[1,0,0] op_sel_hi:[1,1,1]
	ds_read_u16 v29, v116 offset:17136
	s_waitcnt lgkmcnt(9)
	v_pk_fma_f32 v[4:5], v[32:33], v[234:235], v[4:5] op_sel_hi:[0,1,1]
	v_pk_fma_f32 v[6:7], v[32:33], v[236:237], v[6:7] op_sel:[1,0,0] op_sel_hi:[1,1,1]
	v_pk_fma_f32 v[8:9], v[34:35], v[238:239], v[8:9] op_sel_hi:[0,1,1]
	v_pk_fma_f32 v[10:11], v[34:35], v[240:241], v[10:11] op_sel:[1,0,0] op_sel_hi:[1,1,1]
	ds_read_b32 v30, v126 offset:252
	s_waitcnt lgkmcnt(9)
	v_pk_fma_f32 v[4:5], v[36:37], v[242:243], v[4:5] op_sel_hi:[0,1,1]
	v_pk_fma_f32 v[6:7], v[36:37], v[244:245], v[6:7] op_sel:[1,0,0] op_sel_hi:[1,1,1]
	v_pk_fma_f32 v[8:9], v[38:39], v[246:247], v[8:9] op_sel_hi:[0,1,1]
	v_pk_fma_f32 v[10:11], v[38:39], v[248:249], v[10:11] op_sel:[1,0,0] op_sel_hi:[1,1,1]
	ds_read_b32 v31, v127 offset:252
	s_waitcnt lgkmcnt(9)
	v_pk_fma_f32 v[4:5], v[40:41], v[46:47], v[4:5] op_sel_hi:[0,1,1]
	v_pk_fma_f32 v[6:7], v[40:41], v[48:49], v[6:7] op_sel:[1,0,0] op_sel_hi:[1,1,1]
	v_pk_fma_f32 v[8:9], v[42:43], v[50:51], v[8:9] op_sel_hi:[0,1,1]
	v_pk_fma_f32 v[10:11], v[42:43], v[52:53], v[10:11] op_sel:[1,0,0] op_sel_hi:[1,1,1]
	s_waitcnt lgkmcnt(8)
	v_pk_fma_f32 v[4:5], v[98:99], v[54:55], v[4:5] op_sel_hi:[0,1,1]
	v_pk_fma_f32 v[6:7], v[98:99], v[56:57], v[6:7] op_sel:[1,0,0] op_sel_hi:[1,1,1]
	v_pk_fma_f32 v[8:9], v[100:101], v[58:59], v[8:9] op_sel_hi:[0,1,1]
	v_pk_fma_f32 v[10:11], v[100:101], v[60:61], v[10:11] op_sel:[1,0,0] op_sel_hi:[1,1,1]
	s_waitcnt lgkmcnt(7)
	v_pk_fma_f32 v[4:5], v[102:103], v[62:63], v[4:5] op_sel_hi:[0,1,1]
	v_pk_fma_f32 v[6:7], v[102:103], v[64:65], v[6:7] op_sel:[1,0,0] op_sel_hi:[1,1,1]
	v_pk_fma_f32 v[8:9], v[104:105], v[66:67], v[8:9] op_sel_hi:[0,1,1]
	v_pk_fma_f32 v[10:11], v[104:105], v[68:69], v[10:11] op_sel:[1,0,0] op_sel_hi:[1,1,1]
	s_waitcnt lgkmcnt(6)
	v_pk_fma_f32 v[4:5], v[106:107], v[70:71], v[4:5] op_sel_hi:[0,1,1]
	v_pk_fma_f32 v[6:7], v[106:107], v[72:73], v[6:7] op_sel:[1,0,0] op_sel_hi:[1,1,1]
	v_pk_fma_f32 v[8:9], v[108:109], v[74:75], v[8:9] op_sel_hi:[0,1,1]
	v_pk_fma_f32 v[10:11], v[108:109], v[76:77], v[10:11] op_sel:[1,0,0] op_sel_hi:[1,1,1]
	s_waitcnt lgkmcnt(5)
	v_pk_fma_f32 v[4:5], v[130:131], v[78:79], v[4:5] op_sel_hi:[0,1,1]
	v_pk_fma_f32 v[6:7], v[130:131], v[80:81], v[6:7] op_sel:[1,0,0] op_sel_hi:[1,1,1]
	v_pk_fma_f32 v[8:9], v[132:133], v[82:83], v[8:9] op_sel_hi:[0,1,1]
	v_pk_fma_f32 v[10:11], v[132:133], v[84:85], v[10:11] op_sel:[1,0,0] op_sel_hi:[1,1,1]
	s_waitcnt lgkmcnt(4)
	v_pk_fma_f32 v[4:5], v[140:141], v[86:87], v[4:5] op_sel_hi:[0,1,1]
	v_pk_fma_f32 v[6:7], v[140:141], v[88:89], v[6:7] op_sel:[1,0,0] op_sel_hi:[1,1,1]
	v_pk_fma_f32 v[8:9], v[142:143], v[90:91], v[8:9] op_sel_hi:[0,1,1]
	s_waitcnt lgkmcnt(0)
	v_lshlrev_b32_e32 v28, 16, v28
	v_lshlrev_b32_e32 v29, 16, v29
	v_pk_add_f32 v[12:13], v[4:5], v[6:7]
	v_pk_add_f32 v[14:15], v[8:9], v[10:11]
	s_nop 0
	v_pk_add_f32 v[12:13], v[12:13], v[14:15]
	s_nop 0
	v_pk_fma_f32 v[96:97], v[30:31], v[28:29], v[12:13] neg_lo:[0,0,1] neg_hi:[0,0,1]
	s_nop 0
	s_mov_b32 s10, s26
	s_ashr_i32 s11, s10, 31
	s_lshl_b64 s[10:11], s[10:11], 14
	v_readlane_b32 s12, v254, 19
	v_readlane_b32 s13, v254, 20
	s_add_u32 s10, s12, s10
	s_addc_u32 s11, s13, s11
	v_cvt_pk_bf16_f32 v32, v170, v172
	v_cvt_pk_bf16_f32 v33, v174, v176
	v_cvt_pk_bf16_f32 v34, v178, v180
	v_cvt_pk_bf16_f32 v35, v182, v184
	global_store_dwordx4 v118, v[32:35], s[10:11]
	v_cvt_pk_bf16_f32 v36, v186, v188
	v_cvt_pk_bf16_f32 v37, v190, v192
	v_cvt_pk_bf16_f32 v38, v194, v196
	v_cvt_pk_bf16_f32 v39, v198, v200
	global_store_dwordx4 v118, v[36:39], s[10:11] offset:16
	v_cvt_pk_bf16_f32 v32, v202, v204
	v_cvt_pk_bf16_f32 v33, v206, v208
	v_cvt_pk_bf16_f32 v34, v210, v212
	v_cvt_pk_bf16_f32 v35, v214, v216
	global_store_dwordx4 v118, v[32:35], s[10:11] offset:32
	v_cvt_pk_bf16_f32 v36, v218, v220
	v_cvt_pk_bf16_f32 v37, v222, v224
	v_cvt_pk_bf16_f32 v38, v226, v228
	v_cvt_pk_bf16_f32 v39, v230, v232
	global_store_dwordx4 v118, v[36:39], s[10:11] offset:48
	v_cvt_pk_bf16_f32 v32, v234, v236
	v_cvt_pk_bf16_f32 v33, v238, v240
	v_cvt_pk_bf16_f32 v34, v242, v244
	v_cvt_pk_bf16_f32 v35, v246, v248
	global_store_dwordx4 v118, v[32:35], s[10:11] offset:64
	v_cvt_pk_bf16_f32 v36, v46, v48
	v_cvt_pk_bf16_f32 v37, v50, v52
	v_cvt_pk_bf16_f32 v38, v54, v56
	v_cvt_pk_bf16_f32 v39, v58, v60
	global_store_dwordx4 v118, v[36:39], s[10:11] offset:80
	v_cvt_pk_bf16_f32 v32, v62, v64
	v_cvt_pk_bf16_f32 v33, v66, v68
	v_cvt_pk_bf16_f32 v34, v70, v72
	v_cvt_pk_bf16_f32 v35, v74, v76
	global_store_dwordx4 v118, v[32:35], s[10:11] offset:96
	v_cvt_pk_bf16_f32 v36, v78, v80
	v_cvt_pk_bf16_f32 v37, v82, v84
	v_cvt_pk_bf16_f32 v38, v86, v88
	v_cvt_pk_bf16_f32 v39, v90, v96
	global_store_dwordx4 v118, v[36:39], s[10:11] offset:112
.Lfs_skip:
	s_or_b64 exec, exec, s[0:1]
	s_barrier
	s_and_saveexec_b64 s[0:1], s[8:9]
	s_cbranch_execz .LBB0_274
	v_cvt_pk_bf16_f32 v0, v171, v171
	ds_write_b16 v117, v0 offset:17408
	v_cvt_pk_bf16_f32 v0, v173, v173
	ds_write_b16 v117, v0 offset:17680
	v_cvt_pk_bf16_f32 v0, v175, v175
	ds_write_b16 v117, v0 offset:17952
	v_cvt_pk_bf16_f32 v0, v177, v177
	ds_write_b16 v117, v0 offset:18224
	v_cvt_pk_bf16_f32 v0, v179, v179
	ds_write_b16 v117, v0 offset:18496
	v_cvt_pk_bf16_f32 v0, v181, v181
	ds_write_b16 v117, v0 offset:18768
	v_cvt_pk_bf16_f32 v0, v183, v183
	ds_write_b16 v117, v0 offset:19040
	v_cvt_pk_bf16_f32 v0, v185, v185
	ds_write_b16 v117, v0 offset:19312
	v_cvt_pk_bf16_f32 v0, v187, v187
	ds_write_b16 v117, v0 offset:19584
	v_cvt_pk_bf16_f32 v0, v189, v189
	ds_write_b16 v117, v0 offset:19856
	v_cvt_pk_bf16_f32 v0, v191, v191
	ds_write_b16 v117, v0 offset:20128
	v_cvt_pk_bf16_f32 v0, v193, v193
	ds_write_b16 v117, v0 offset:20400
	v_cvt_pk_bf16_f32 v0, v195, v195
	ds_write_b16 v117, v0 offset:20672
	v_cvt_pk_bf16_f32 v0, v197, v197
	ds_write_b16 v117, v0 offset:20944
	v_cvt_pk_bf16_f32 v0, v199, v199
	ds_write_b16 v117, v0 offset:21216
	v_cvt_pk_bf16_f32 v0, v201, v201
	ds_write_b16 v117, v0 offset:21488
	v_cvt_pk_bf16_f32 v0, v203, v203
	ds_write_b16 v117, v0 offset:21760
	v_cvt_pk_bf16_f32 v0, v205, v205
	ds_write_b16 v117, v0 offset:22032
	v_cvt_pk_bf16_f32 v0, v207, v207
	ds_write_b16 v117, v0 offset:22304
	v_cvt_pk_bf16_f32 v0, v209, v209
	ds_write_b16 v117, v0 offset:22576
	v_cvt_pk_bf16_f32 v0, v211, v211
	ds_write_b16 v117, v0 offset:22848
	v_cvt_pk_bf16_f32 v0, v213, v213
	ds_write_b16 v117, v0 offset:23120
	v_cvt_pk_bf16_f32 v0, v215, v215
	ds_write_b16 v117, v0 offset:23392
	v_cvt_pk_bf16_f32 v0, v217, v217
	ds_write_b16 v117, v0 offset:23664
	v_cvt_pk_bf16_f32 v0, v219, v219
	ds_write_b16 v117, v0 offset:23936
	v_cvt_pk_bf16_f32 v0, v221, v221
	ds_write_b16 v117, v0 offset:24208
	v_cvt_pk_bf16_f32 v0, v223, v223
	ds_write_b16 v117, v0 offset:24480
	v_cvt_pk_bf16_f32 v0, v225, v225
	ds_write_b16 v117, v0 offset:24752
	v_cvt_pk_bf16_f32 v0, v227, v227
	ds_write_b16 v117, v0 offset:25024
	v_cvt_pk_bf16_f32 v0, v229, v229
	ds_write_b16 v117, v0 offset:25296
	v_cvt_pk_bf16_f32 v0, v231, v231
	ds_write_b16 v117, v0 offset:25568
	v_cvt_pk_bf16_f32 v0, v233, v233
	ds_write_b16 v117, v0 offset:25840
	v_cvt_pk_bf16_f32 v0, v235, v235
	ds_write_b16 v117, v0 offset:26112
	v_cvt_pk_bf16_f32 v0, v237, v237
	ds_write_b16 v117, v0 offset:26384
	v_cvt_pk_bf16_f32 v0, v239, v239
	ds_write_b16 v117, v0 offset:26656
	v_cvt_pk_bf16_f32 v0, v241, v241
	ds_write_b16 v117, v0 offset:26928
	v_cvt_pk_bf16_f32 v0, v243, v243
	ds_write_b16 v117, v0 offset:27200
	v_cvt_pk_bf16_f32 v0, v245, v245
	ds_write_b16 v117, v0 offset:27472
	v_cvt_pk_bf16_f32 v0, v247, v247
	ds_write_b16 v117, v0 offset:27744
	v_cvt_pk_bf16_f32 v0, v249, v249
	ds_write_b16 v117, v0 offset:28016
	v_cvt_pk_bf16_f32 v0, v47, v47
	ds_write_b16 v117, v0 offset:28288
	v_cvt_pk_bf16_f32 v0, v49, v49
	ds_write_b16 v117, v0 offset:28560
	v_cvt_pk_bf16_f32 v0, v51, v51
	ds_write_b16 v117, v0 offset:28832
	v_cvt_pk_bf16_f32 v0, v53, v53
	ds_write_b16 v117, v0 offset:29104
	v_cvt_pk_bf16_f32 v0, v55, v55
	ds_write_b16 v117, v0 offset:29376
	v_cvt_pk_bf16_f32 v0, v57, v57
	ds_write_b16 v117, v0 offset:29648
	v_cvt_pk_bf16_f32 v0, v59, v59
	ds_write_b16 v117, v0 offset:29920
	v_cvt_pk_bf16_f32 v0, v61, v61
	ds_write_b16 v117, v0 offset:30192
	v_cvt_pk_bf16_f32 v0, v63, v63
	ds_write_b16 v117, v0 offset:30464
	v_cvt_pk_bf16_f32 v0, v65, v65
	ds_write_b16 v117, v0 offset:30736
	v_cvt_pk_bf16_f32 v0, v67, v67
	ds_write_b16 v117, v0 offset:31008
	v_cvt_pk_bf16_f32 v0, v69, v69
	ds_write_b16 v117, v0 offset:31280
	v_cvt_pk_bf16_f32 v0, v71, v71
	ds_write_b16 v117, v0 offset:31552
	v_cvt_pk_bf16_f32 v0, v73, v73
	ds_write_b16 v117, v0 offset:31824
	v_cvt_pk_bf16_f32 v0, v75, v75
	ds_write_b16 v117, v0 offset:32096
	v_cvt_pk_bf16_f32 v0, v77, v77
	ds_write_b16 v117, v0 offset:32368
	v_cvt_pk_bf16_f32 v0, v79, v79
	ds_write_b16 v117, v0 offset:32640
	v_cvt_pk_bf16_f32 v0, v81, v81
	ds_write_b16 v117, v0 offset:32912
	v_cvt_pk_bf16_f32 v0, v83, v83
	ds_write_b16 v117, v0 offset:33184
	v_cvt_pk_bf16_f32 v0, v85, v85
	ds_write_b16 v117, v0 offset:33456
	v_cvt_pk_bf16_f32 v0, v87, v87
	ds_write_b16 v117, v0 offset:33728
	v_cvt_pk_bf16_f32 v0, v89, v89
	ds_write_b16 v117, v0 offset:34000
	v_cvt_pk_bf16_f32 v0, v91, v91
	ds_write_b16 v117, v0 offset:34272
	v_cvt_pk_bf16_f32 v0, v97, v97
	ds_write_b16 v117, v0 offset:34544
	s_branch .LBB0_274
